# P1/FF1 epilogues: packed-add tree for the row sums of squares, issued right after the wait (early in the row)
# speedup vs baseline: 1.0061x; 1.0061x over previous
; #define PG8_STAGE(bufoff, gbase, voff) do { _Pragma("unroll") for (int _i = 0; _i < 2; ++_i) \
;         __builtin_amdgcn_global_load_lds((const unsigned*)((const char*)(gbase) + (voff)[_i]), (LAS unsigned*)(lds + (bufoff) + ldsw + _i * 8192), 16, 0, 0); } while (0)
; #define PG8_LDA(dst, b, h) do { _Pragma("unroll") for (int m = 0; m < 4; ++m) _Pragma("unroll") for (int k = 0; k < 2; ++k) dst[m][k] = *(const LAS bf16x8*)(lds + PG8_SA(b, h) + aoff + m * 2048 + k * 1024); } while (0)
; #define PG8_LDB(dst, b, h) do { _Pragma("unroll") for (int n = 0; n < 2; ++n) _Pragma("unroll") for (int k = 0; k < 2; ++k) dst[n][k] = *(const LAS bf16x8*)(lds + PG8_SB(b, h) + boff + n * 2048 + k * 1024); } while (0)
; #define PG8_MMA(ai, bj, At, Bt) do { __builtin_amdgcn_s_setprio(1); _Pragma("unroll") for (int m = 0; m < 4; ++m) _Pragma("unroll") for (int n = 0; n < 2; ++n) _Pragma("unroll") for (int k = 0; k < 2; ++k) \
;         acc[ai][bj][m][n] = __builtin_amdgcn_mfma_f32_16x16x32_bf16(Bt[n][k], At[m][k], acc[ai][bj][m][n], 0, 0, 0); __builtin_amdgcn_s_setprio(0); } while (0)
; #define PG8_WAIT_L(n) asm volatile("s_waitcnt lgkmcnt(" #n ")" ::: "memory")
; #define PG8_BAR __builtin_amdgcn_s_barrier()
; #define PG8_SCHED __builtin_amdgcn_sched_barrier(0)
;     ...
;             PG8_LDB(B0, 0, 0); PG8_SCHED; PG8_LDA(At, 0, 0); PG8_STAGE(PG8_SA(1, 1), a1 + hA, voffA);
;             PG8_WAIT_L(8); PG8_BAR; PG8_WAIT_L(0); PG8_MMA(0, 0, At, B0); PG8_BAR; PG8_SCHED;
;             PG8_LDB(B1, 0, 1); PG8_STAGE(PG8_SB(0, 0), b2, voffB);
;             PG8_BAR; PG8_WAIT_L(0); PG8_MMA(0, 1, At, B1); PG8_BAR;
;             PG8_LDA(At, 0, 1); PG8_STAGE(PG8_SA(0, 0), a2, voffA);
;             PG8_BAR; PG8_WAIT_L(0); PG8_MMA(1, 0, At, B0); PG8_BAR; PG8_SCHED;
.LBB0_125:
	ds_read_b128 v[146:149], v155
	ds_read_b128 v[160:163], v155 offset:1024
	ds_read_b128 v[170:173], v155 offset:2048
	ds_read_b128 v[174:177], v155 offset:3072
	s_add_u32 s34, s30, 0xfffc0080
	s_addc_u32 s35, s31, -1
	s_cmp_eq_u32 s44, 12
	s_cselect_b32 s37, s7, s35
	s_cselect_b32 s36, s23, s34
	s_cselect_b32 s35, s21, s43
	s_cselect_b32 s34, s33, s42
	v_lshl_add_u64 v[150:151], s[30:31], 0, v[138:139]
	s_add_i32 m0, s29, 0xc000
	ds_read_b128 v[178:181], v156
	ds_read_b128 v[182:185], v156 offset:1024
	ds_read_b128 v[186:189], v156 offset:2048
	ds_read_b128 v[190:193], v156 offset:3072
	ds_read_b128 v[194:197], v156 offset:4096
	ds_read_b128 v[198:201], v156 offset:5120
	ds_read_b128 v[202:205], v156 offset:6144
	ds_read_b128 v[206:209], v156 offset:7168
	global_load_lds_dwordx4 v[150:151], off
	v_lshl_add_u64 v[150:151], s[30:31], 0, v[136:137]
	s_add_i32 m0, s29, 0xe000
	s_nop 0
	global_load_lds_dwordx4 v[150:151], off
	s_waitcnt lgkmcnt(8)
	s_barrier
	s_waitcnt lgkmcnt(0)
	s_setprio 1
	s_waitcnt lgkmcnt(0)
	v_mfma_f32_16x16x32_bf16 v[124:127], v[146:149], v[178:181], v[124:127]
	v_mfma_f32_16x16x32_bf16 v[120:123], v[170:173], v[178:181], v[120:123]
	v_mfma_f32_16x16x32_bf16 v[108:111], v[146:149], v[186:189], v[108:111]
	v_mfma_f32_16x16x32_bf16 v[104:107], v[170:173], v[186:189], v[104:107]
	v_mfma_f32_16x16x32_bf16 v[92:95], v[146:149], v[194:197], v[92:95]
	v_mfma_f32_16x16x32_bf16 v[88:91], v[170:173], v[194:197], v[88:91]
	v_mfma_f32_16x16x32_bf16 v[76:79], v[146:149], v[202:205], v[76:79]
	v_mfma_f32_16x16x32_bf16 v[72:75], v[170:173], v[202:205], v[72:75]
	v_mfma_f32_16x16x32_bf16 v[124:127], v[160:163], v[182:185], v[124:127]
	v_mfma_f32_16x16x32_bf16 v[120:123], v[174:177], v[182:185], v[120:123]
	v_mfma_f32_16x16x32_bf16 v[108:111], v[160:163], v[190:193], v[108:111]
	v_mfma_f32_16x16x32_bf16 v[104:107], v[174:177], v[190:193], v[104:107]
	v_mfma_f32_16x16x32_bf16 v[92:95], v[160:163], v[198:201], v[92:95]
	v_mfma_f32_16x16x32_bf16 v[88:91], v[174:177], v[198:201], v[88:91]
	v_mfma_f32_16x16x32_bf16 v[76:79], v[160:163], v[206:209], v[76:79]
	v_mfma_f32_16x16x32_bf16 v[72:75], v[174:177], v[206:209], v[72:75]
	s_setprio 0
	s_barrier
	s_add_i32 s45, s59, s51
	v_lshl_add_u64 v[150:151], s[34:35], 0, v[130:131]
	s_mov_b32 m0, s45
	ds_read_b128 v[210:213], v157
	ds_read_b128 v[214:217], v157 offset:1024
	ds_read_b128 v[218:221], v157 offset:2048
	ds_read_b128 v[222:225], v157 offset:3072
	global_load_lds_dwordx4 v[150:151], off
	v_lshl_add_u64 v[164:165], s[34:35], 0, v[134:135]
	s_add_i32 m0, s45, 0x2000
	s_nop 0
	global_load_lds_dwordx4 v[164:165], off
	s_barrier
	s_waitcnt lgkmcnt(0)
	s_setprio 1
	s_waitcnt lgkmcnt(0)
	v_mfma_f32_16x16x32_bf16 v[116:119], v[210:213], v[178:181], v[116:119]
	v_mfma_f32_16x16x32_bf16 v[112:115], v[218:221], v[178:181], v[112:115]
	v_mfma_f32_16x16x32_bf16 v[100:103], v[210:213], v[186:189], v[100:103]
	v_mfma_f32_16x16x32_bf16 v[96:99], v[218:221], v[186:189], v[96:99]
	v_mfma_f32_16x16x32_bf16 v[84:87], v[210:213], v[194:197], v[84:87]
	v_mfma_f32_16x16x32_bf16 v[80:83], v[218:221], v[194:197], v[80:83]
	v_mfma_f32_16x16x32_bf16 v[68:71], v[210:213], v[202:205], v[68:71]
	v_mfma_f32_16x16x32_bf16 v[64:67], v[218:221], v[202:205], v[64:67]
	v_mfma_f32_16x16x32_bf16 v[116:119], v[214:217], v[182:185], v[116:119]
	v_mfma_f32_16x16x32_bf16 v[112:115], v[222:225], v[182:185], v[112:115]
	v_mfma_f32_16x16x32_bf16 v[100:103], v[214:217], v[190:193], v[100:103]
	v_mfma_f32_16x16x32_bf16 v[96:99], v[222:225], v[190:193], v[96:99]
	v_mfma_f32_16x16x32_bf16 v[84:87], v[214:217], v[198:201], v[84:87]
	v_mfma_f32_16x16x32_bf16 v[80:83], v[222:225], v[198:201], v[80:83]
	v_mfma_f32_16x16x32_bf16 v[68:71], v[214:217], v[206:209], v[68:71]
	v_mfma_f32_16x16x32_bf16 v[64:67], v[222:225], v[206:209], v[64:67]
	s_setprio 0
	s_mov_b32 m0, s29
	v_lshl_add_u64 v[226:227], s[36:37], 0, v[128:129]
	s_barrier
	ds_read_b128 v[178:181], v156 offset:16384
	ds_read_b128 v[182:185], v156 offset:17408
	ds_read_b128 v[186:189], v156 offset:18432
	ds_read_b128 v[190:193], v156 offset:19456
	ds_read_b128 v[194:197], v156 offset:20480
	ds_read_b128 v[198:201], v156 offset:21504
	ds_read_b128 v[202:205], v156 offset:22528
	ds_read_b128 v[206:209], v156 offset:23552
	global_load_lds_dwordx4 v[226:227], off
	v_lshl_add_u64 v[228:229], s[36:37], 0, v[132:133]
	s_mov_b32 m0, s52
	s_nop 0
	global_load_lds_dwordx4 v[228:229], off
	s_barrier
	s_waitcnt lgkmcnt(0)
	s_setprio 1
	s_waitcnt lgkmcnt(0)
	v_mfma_f32_16x16x32_bf16 v[60:63], v[146:149], v[178:181], v[60:63]
	v_mfma_f32_16x16x32_bf16 v[56:59], v[170:173], v[178:181], v[56:59]
	v_mfma_f32_16x16x32_bf16 v[44:47], v[146:149], v[186:189], v[44:47]
	v_mfma_f32_16x16x32_bf16 v[40:43], v[170:173], v[186:189], v[40:43]
	v_mfma_f32_16x16x32_bf16 v[28:31], v[146:149], v[194:197], v[28:31]
	v_mfma_f32_16x16x32_bf16 v[24:27], v[170:173], v[194:197], v[24:27]
	v_mfma_f32_16x16x32_bf16 v[12:15], v[146:149], v[202:205], v[12:15]
	v_mfma_f32_16x16x32_bf16 v[8:11], v[170:173], v[202:205], v[8:11]
	v_mfma_f32_16x16x32_bf16 v[60:63], v[160:163], v[182:185], v[60:63]
	v_mfma_f32_16x16x32_bf16 v[56:59], v[174:177], v[182:185], v[56:59]
	v_mfma_f32_16x16x32_bf16 v[44:47], v[160:163], v[190:193], v[44:47]
	v_mfma_f32_16x16x32_bf16 v[40:43], v[174:177], v[190:193], v[40:43]
	v_mfma_f32_16x16x32_bf16 v[28:31], v[160:163], v[198:201], v[28:31]
	v_mfma_f32_16x16x32_bf16 v[24:27], v[174:177], v[198:201], v[24:27]
	v_mfma_f32_16x16x32_bf16 v[12:15], v[160:163], v[206:209], v[12:15]
	v_mfma_f32_16x16x32_bf16 v[8:11], v[174:177], v[206:209], v[8:11]
	s_setprio 0
	s_barrier
; #define PG8_STAGE(bufoff, gbase, voff) do { _Pragma("unroll") for (int _i = 0; _i < 2; ++_i) \
;         __builtin_amdgcn_global_load_lds((const unsigned*)((const char*)(gbase) + (voff)[_i]), (LAS unsigned*)(lds + (bufoff) + ldsw + _i * 8192), 16, 0, 0); } while (0)
; #define PG8_LDA(dst, b, h) do { _Pragma("unroll") for (int m = 0; m < 4; ++m) _Pragma("unroll") for (int k = 0; k < 2; ++k) dst[m][k] = *(const LAS bf16x8*)(lds + PG8_SA(b, h) + aoff + m * 2048 + k * 1024); } while (0)
; #define PG8_LDB(dst, b, h) do { _Pragma("unroll") for (int n = 0; n < 2; ++n) _Pragma("unroll") for (int k = 0; k < 2; ++k) dst[n][k] = *(const LAS bf16x8*)(lds + PG8_SB(b, h) + boff + n * 2048 + k * 1024); } while (0)
; #define PG8_MMA(ai, bj, At, Bt) do { __builtin_amdgcn_s_setprio(1); _Pragma("unroll") for (int m = 0; m < 4; ++m) _Pragma("unroll") for (int n = 0; n < 2; ++n) _Pragma("unroll") for (int k = 0; k < 2; ++k) \
;         acc[ai][bj][m][n] = __builtin_amdgcn_mfma_f32_16x16x32_bf16(Bt[n][k], At[m][k], acc[ai][bj][m][n], 0, 0, 0); __builtin_amdgcn_s_setprio(0); } while (0)
; #define PG8_WAIT_V(n) asm volatile("s_waitcnt vmcnt(" #n ")" ::: "memory")
; #define PG8_WAIT_L(n) asm volatile("s_waitcnt lgkmcnt(" #n ")" ::: "memory")
; #define PG8_BAR __builtin_amdgcn_s_barrier()
; #define PG8_SCHED __builtin_amdgcn_sched_barrier(0)
;     ...
;             PG8_STAGE(PG8_SB(0, 1), b2 + hB, voffB);
;             PG8_WAIT_V(6); PG8_BAR; PG8_MMA(1, 1, At, B1); PG8_BAR;
;             PG8_LDB(B0, 1, 0); PG8_SCHED; PG8_LDA(At, 1, 0); PG8_STAGE(PG8_SA(0, 1), a2 + hA, voffA);
;             PG8_WAIT_L(8); PG8_BAR; PG8_WAIT_L(0); PG8_MMA(0, 0, At, B0); PG8_BAR; PG8_SCHED;
;             PG8_LDB(B1, 1, 1); PG8_STAGE(PG8_SB(1, 0), b3, voffB);
;             PG8_BAR; PG8_WAIT_L(0); PG8_MMA(0, 1, At, B1); PG8_BAR;
;             PG8_LDA(At, 1, 1); PG8_STAGE(PG8_SA(1, 0), a3, voffA);
	s_add_u32 s64, s34, 0x40000
	s_addc_u32 s65, s35, 0
	s_add_i32 s45, s60, s51
	v_lshl_add_u64 v[146:147], s[64:65], 0, v[130:131]
	s_mov_b32 m0, s45
	s_nop 0
	global_load_lds_dwordx4 v[146:147], off
	v_lshl_add_u64 v[146:147], s[64:65], 0, v[134:135]
	s_add_i32 m0, s45, 0x2000
	s_nop 0
	global_load_lds_dwordx4 v[146:147], off
	s_waitcnt vmcnt(6)
	s_barrier
	s_setprio 1
	v_mfma_f32_16x16x32_bf16 v[52:55], v[210:213], v[178:181], v[52:55]
	v_mfma_f32_16x16x32_bf16 v[48:51], v[218:221], v[178:181], v[48:51]
	v_mfma_f32_16x16x32_bf16 v[36:39], v[210:213], v[186:189], v[36:39]
	v_mfma_f32_16x16x32_bf16 v[32:35], v[218:221], v[186:189], v[32:35]
	v_mfma_f32_16x16x32_bf16 v[20:23], v[210:213], v[194:197], v[20:23]
	v_mfma_f32_16x16x32_bf16 v[16:19], v[218:221], v[194:197], v[16:19]
	v_mfma_f32_16x16x32_bf16 v[4:7], v[210:213], v[202:205], v[4:7]
	v_mfma_f32_16x16x32_bf16 v[0:3], v[218:221], v[202:205], v[0:3]
	v_mfma_f32_16x16x32_bf16 v[52:55], v[214:217], v[182:185], v[52:55]
	v_mfma_f32_16x16x32_bf16 v[48:51], v[222:225], v[182:185], v[48:51]
	v_mfma_f32_16x16x32_bf16 v[36:39], v[214:217], v[190:193], v[36:39]
	v_mfma_f32_16x16x32_bf16 v[32:35], v[222:225], v[190:193], v[32:35]
	v_mfma_f32_16x16x32_bf16 v[20:23], v[214:217], v[198:201], v[20:23]
	v_mfma_f32_16x16x32_bf16 v[16:19], v[222:225], v[198:201], v[16:19]
	v_mfma_f32_16x16x32_bf16 v[4:7], v[214:217], v[206:209], v[4:7]
	v_mfma_f32_16x16x32_bf16 v[0:3], v[222:225], v[206:209], v[0:3]
	s_setprio 0
	s_add_i32 s45, 0, 0x18000
	v_add_u32_e32 v159, s45, v153
	s_barrier
	ds_read_b128 v[146:149], v159
	ds_read_b128 v[160:163], v159 offset:1024
	ds_read_b128 v[170:173], v159 offset:2048
	ds_read_b128 v[174:177], v159 offset:3072
	s_add_u32 s36, s36, 0x40000
	s_addc_u32 s37, s37, 0
	s_mov_b32 m0, s53
	v_lshl_add_u64 v[210:211], s[36:37], 0, v[128:129]
	ds_read_b128 v[178:181], v156 offset:32768
	ds_read_b128 v[182:185], v156 offset:33792
	ds_read_b128 v[186:189], v156 offset:34816
	ds_read_b128 v[190:193], v156 offset:35840
	ds_read_b128 v[194:197], v156 offset:36864
	ds_read_b128 v[198:201], v156 offset:37888
	ds_read_b128 v[202:205], v156 offset:38912
	ds_read_b128 v[206:209], v156 offset:39936
	global_load_lds_dwordx4 v[210:211], off
	v_lshl_add_u64 v[210:211], s[36:37], 0, v[132:133]
	s_mov_b32 m0, s54
	s_nop 0
	global_load_lds_dwordx4 v[210:211], off
	s_waitcnt lgkmcnt(8)
	s_barrier
	s_waitcnt lgkmcnt(0)
	s_setprio 1
	s_waitcnt lgkmcnt(0)
	v_mfma_f32_16x16x32_bf16 v[124:127], v[146:149], v[178:181], v[124:127]
	v_mfma_f32_16x16x32_bf16 v[120:123], v[170:173], v[178:181], v[120:123]
	v_mfma_f32_16x16x32_bf16 v[108:111], v[146:149], v[186:189], v[108:111]
	v_mfma_f32_16x16x32_bf16 v[104:107], v[170:173], v[186:189], v[104:107]
	v_mfma_f32_16x16x32_bf16 v[92:95], v[146:149], v[194:197], v[92:95]
	v_mfma_f32_16x16x32_bf16 v[88:91], v[170:173], v[194:197], v[88:91]
	v_mfma_f32_16x16x32_bf16 v[76:79], v[146:149], v[202:205], v[76:79]
	v_mfma_f32_16x16x32_bf16 v[72:75], v[170:173], v[202:205], v[72:75]
	v_mfma_f32_16x16x32_bf16 v[124:127], v[160:163], v[182:185], v[124:127]
	v_mfma_f32_16x16x32_bf16 v[120:123], v[174:177], v[182:185], v[120:123]
	v_mfma_f32_16x16x32_bf16 v[108:111], v[160:163], v[190:193], v[108:111]
	v_mfma_f32_16x16x32_bf16 v[104:107], v[174:177], v[190:193], v[104:107]
	v_mfma_f32_16x16x32_bf16 v[92:95], v[160:163], v[198:201], v[92:95]
	v_mfma_f32_16x16x32_bf16 v[88:91], v[174:177], v[198:201], v[88:91]
	v_mfma_f32_16x16x32_bf16 v[76:79], v[160:163], v[206:209], v[76:79]
	v_mfma_f32_16x16x32_bf16 v[72:75], v[174:177], v[206:209], v[72:75]
	s_setprio 0
	s_barrier
	s_add_i32 s36, 0, 0x1c000
	s_add_i32 s37, s45, s51
	v_add_u32_e32 v159, s36, v153
	v_lshl_add_u64 v[150:151], v[150:151], 0, s[18:19]
	s_mov_b32 m0, s37
	ds_read_b128 v[210:213], v159
	ds_read_b128 v[214:217], v159 offset:1024
	ds_read_b128 v[218:221], v159 offset:2048
	ds_read_b128 v[222:225], v159 offset:3072
	global_load_lds_dwordx4 v[150:151], off
	v_lshl_add_u64 v[150:151], v[164:165], 0, s[18:19]
	s_add_i32 m0, s37, 0x2000
	s_nop 0
	global_load_lds_dwordx4 v[150:151], off
	s_barrier
	s_waitcnt lgkmcnt(0)
	s_setprio 1
	s_waitcnt lgkmcnt(0)
	v_mfma_f32_16x16x32_bf16 v[116:119], v[210:213], v[178:181], v[116:119]
	v_mfma_f32_16x16x32_bf16 v[112:115], v[218:221], v[178:181], v[112:115]
	v_mfma_f32_16x16x32_bf16 v[100:103], v[210:213], v[186:189], v[100:103]
	v_mfma_f32_16x16x32_bf16 v[96:99], v[218:221], v[186:189], v[96:99]
	v_mfma_f32_16x16x32_bf16 v[84:87], v[210:213], v[194:197], v[84:87]
	v_mfma_f32_16x16x32_bf16 v[80:83], v[218:221], v[194:197], v[80:83]
	v_mfma_f32_16x16x32_bf16 v[68:71], v[210:213], v[202:205], v[68:71]
	v_mfma_f32_16x16x32_bf16 v[64:67], v[218:221], v[202:205], v[64:67]
	v_mfma_f32_16x16x32_bf16 v[116:119], v[214:217], v[182:185], v[116:119]
	v_mfma_f32_16x16x32_bf16 v[112:115], v[222:225], v[182:185], v[112:115]
	v_mfma_f32_16x16x32_bf16 v[100:103], v[214:217], v[190:193], v[100:103]
	v_mfma_f32_16x16x32_bf16 v[96:99], v[222:225], v[190:193], v[96:99]
	v_mfma_f32_16x16x32_bf16 v[84:87], v[214:217], v[198:201], v[84:87]
	v_mfma_f32_16x16x32_bf16 v[80:83], v[222:225], v[198:201], v[80:83]
	v_mfma_f32_16x16x32_bf16 v[68:71], v[214:217], v[206:209], v[68:71]
	v_mfma_f32_16x16x32_bf16 v[64:67], v[222:225], v[206:209], v[64:67]
	s_setprio 0
	s_mov_b32 m0, s56
	v_lshl_add_u64 v[150:151], v[226:227], 0, s[18:19]
	s_barrier
	ds_read_b128 v[178:181], v156 offset:49152
	ds_read_b128 v[182:185], v156 offset:50176
	ds_read_b128 v[186:189], v156 offset:51200
	ds_read_b128 v[190:193], v156 offset:52224
	ds_read_b128 v[194:197], v156 offset:53248
	ds_read_b128 v[198:201], v156 offset:54272
	ds_read_b128 v[202:205], v156 offset:55296
	ds_read_b128 v[206:209], v156 offset:56320
	global_load_lds_dwordx4 v[150:151], off
	v_lshl_add_u64 v[150:151], v[228:229], 0, s[18:19]
	s_mov_b32 m0, s57
	s_nop 0
	global_load_lds_dwordx4 v[150:151], off
	s_barrier
; #define PG8_STAGE(bufoff, gbase, voff) do { _Pragma("unroll") for (int _i = 0; _i < 2; ++_i) \
;         __builtin_amdgcn_global_load_lds((const unsigned*)((const char*)(gbase) + (voff)[_i]), (LAS unsigned*)(lds + (bufoff) + ldsw + _i * 8192), 16, 0, 0); } while (0)
; #define PG8_MMA(ai, bj, At, Bt) do { __builtin_amdgcn_s_setprio(1); _Pragma("unroll") for (int m = 0; m < 4; ++m) _Pragma("unroll") for (int n = 0; n < 2; ++n) _Pragma("unroll") for (int k = 0; k < 2; ++k) \
;         acc[ai][bj][m][n] = __builtin_amdgcn_mfma_f32_16x16x32_bf16(Bt[n][k], At[m][k], acc[ai][bj][m][n], 0, 0, 0); __builtin_amdgcn_s_setprio(0); } while (0)
; #define PG8_WAIT_V(n) asm volatile("s_waitcnt vmcnt(" #n ")" ::: "memory")
; #define PG8_WAIT_L(n) asm volatile("s_waitcnt lgkmcnt(" #n ")" ::: "memory")
; #define PG8_BAR __builtin_amdgcn_s_barrier()
; #define PG8_SCHED __builtin_amdgcn_sched_barrier(0)
; __device__ __forceinline__ u32x4 pack8(const f32x4 v0, const f32x4 v1) { u32x4 w; w.x = pk2(v0[0], v0[1]); w.y = pk2(v0[2], v0[3]); w.z = pk2(v1[0], v1[1]); w.w = pk2(v1[2], v1[3]); return w; }
;     ...
;             PG8_BAR; PG8_WAIT_L(0); PG8_MMA(1, 0, At, B0); PG8_BAR; PG8_SCHED;
;             PG8_STAGE(PG8_SB(1, 1), b3 + hB, voffB);
;             PG8_WAIT_V(6); PG8_BAR; PG8_MMA(1, 1, At, B1); PG8_BAR;
;         }
;         E(acc, cur, wr, wc, fr, fq);
;     __device__ __forceinline__ void operator()(const f32x4 (&acc)[2][2][4][2], const Unit& u, int wr, int wc, int fr, int fq) const {
;         const int row0 = u.pm * 256 + wr * 64 + fr, col0 = u.pn * 256 + wc * 32 + 8 * fq;
; #pragma unroll
;         for (int ai = 0; ai < 2; ++ai)
; #pragma unroll
;             for (int m = 0; m < 4; ++m) {
;                 const int row = row0 + ai * 128 + m * 16; const float rs = row_rstd(ssq, row);
;                 bf16_t* rowp = O + (size_t)row * ldc + col0;
; #pragma unroll
;                 for (int bj = 0; bj < 2; ++bj) { f32x4 v0 = acc[ai][bj][m][0] * rs, v1 = acc[ai][bj][m][1] * rs;
;                     if (ACT == 1) {
; #pragma unroll
;                         for (int j = 0; j < 4; ++j) { const float a = fmaxf(v0[j], 0.f), b = fmaxf(v1[j], 0.f); v0[j] = a * a; v1[j] = b * b; } }
;                     *(u32x4*)(rowp + bj * 128) = pack8(v0, v1); }
	s_waitcnt lgkmcnt(0)
	s_setprio 1
	s_waitcnt lgkmcnt(0)
	v_mfma_f32_16x16x32_bf16 v[60:63], v[146:149], v[178:181], v[60:63]
	v_mfma_f32_16x16x32_bf16 v[56:59], v[170:173], v[178:181], v[56:59]
	v_mfma_f32_16x16x32_bf16 v[44:47], v[146:149], v[186:189], v[44:47]
	v_mfma_f32_16x16x32_bf16 v[40:43], v[170:173], v[186:189], v[40:43]
	v_mfma_f32_16x16x32_bf16 v[28:31], v[146:149], v[194:197], v[28:31]
	v_mfma_f32_16x16x32_bf16 v[24:27], v[170:173], v[194:197], v[24:27]
	v_mfma_f32_16x16x32_bf16 v[12:15], v[146:149], v[202:205], v[12:15]
	v_mfma_f32_16x16x32_bf16 v[8:11], v[170:173], v[202:205], v[8:11]
	v_mfma_f32_16x16x32_bf16 v[60:63], v[160:163], v[182:185], v[60:63]
	v_mfma_f32_16x16x32_bf16 v[56:59], v[174:177], v[182:185], v[56:59]
	v_mfma_f32_16x16x32_bf16 v[44:47], v[160:163], v[190:193], v[44:47]
	v_mfma_f32_16x16x32_bf16 v[40:43], v[174:177], v[190:193], v[40:43]
	v_mfma_f32_16x16x32_bf16 v[28:31], v[160:163], v[198:201], v[28:31]
	v_mfma_f32_16x16x32_bf16 v[24:27], v[174:177], v[198:201], v[24:27]
	v_mfma_f32_16x16x32_bf16 v[12:15], v[160:163], v[206:209], v[12:15]
	v_mfma_f32_16x16x32_bf16 v[8:11], v[174:177], v[206:209], v[8:11]
	s_setprio 0
	s_barrier
	s_add_u32 s34, s34, 0x40080
	s_addc_u32 s35, s35, 0
	s_add_i32 s36, s36, s51
	v_lshl_add_u64 v[146:147], s[34:35], 0, v[130:131]
	s_mov_b32 m0, s36
	s_nop 0
	global_load_lds_dwordx4 v[146:147], off
	v_lshl_add_u64 v[146:147], s[34:35], 0, v[134:135]
	s_add_i32 m0, s36, 0x2000
	s_nop 0
	global_load_lds_dwordx4 v[146:147], off
	s_waitcnt vmcnt(6)
	s_barrier
	s_setprio 1
	v_mfma_f32_16x16x32_bf16 v[52:55], v[210:213], v[178:181], v[52:55]
	v_mfma_f32_16x16x32_bf16 v[48:51], v[218:221], v[178:181], v[48:51]
	v_mfma_f32_16x16x32_bf16 v[36:39], v[210:213], v[186:189], v[36:39]
	v_mfma_f32_16x16x32_bf16 v[32:35], v[218:221], v[186:189], v[32:35]
	v_mfma_f32_16x16x32_bf16 v[20:23], v[210:213], v[194:197], v[20:23]
	v_mfma_f32_16x16x32_bf16 v[16:19], v[218:221], v[194:197], v[16:19]
	v_mfma_f32_16x16x32_bf16 v[4:7], v[210:213], v[202:205], v[4:7]
	v_mfma_f32_16x16x32_bf16 v[0:3], v[218:221], v[202:205], v[0:3]
	v_mfma_f32_16x16x32_bf16 v[52:55], v[214:217], v[182:185], v[52:55]
	v_mfma_f32_16x16x32_bf16 v[48:51], v[222:225], v[182:185], v[48:51]
	v_mfma_f32_16x16x32_bf16 v[36:39], v[214:217], v[190:193], v[36:39]
	v_mfma_f32_16x16x32_bf16 v[32:35], v[222:225], v[190:193], v[32:35]
	v_mfma_f32_16x16x32_bf16 v[20:23], v[214:217], v[198:201], v[20:23]
	v_mfma_f32_16x16x32_bf16 v[16:19], v[222:225], v[198:201], v[16:19]
	v_mfma_f32_16x16x32_bf16 v[4:7], v[214:217], v[206:209], v[4:7]
	v_mfma_f32_16x16x32_bf16 v[0:3], v[222:225], v[206:209], v[0:3]
	s_setprio 0
	s_add_i32 s44, s44, 2
	s_add_u32 s42, s42, 0x100
	s_addc_u32 s43, s43, 0
	s_add_u32 s30, s30, 0x100
	s_addc_u32 s31, s31, 0
	s_cmp_gt_u32 s44, 13
	s_barrier
	s_cbranch_scc0 .LBB0_125
	v_lshl_add_u32 v150, s28, 8, v152
	v_ashrrev_i32_e32 v151, 31, v150
	v_lshlrev_b64 v[146:147], 6, v[150:151]
	v_lshl_add_u64 v[146:147], s[16:17], 0, v[146:147]
	v_subrev_u32_e32 v186, s16, v146
	v_add_u32_e32 v187, 0x0, v186
	global_load_dwordx4 v[188:191], v187, s[16:17]
	v_add_u32_e32 v187, 0x20, v186
	global_load_dwordx4 v[192:195], v187, s[16:17]
	v_add_u32_e32 v187, 0x10, v186
	global_load_dwordx4 v[196:199], v187, s[16:17]
	v_add_u32_e32 v187, 0x30, v186
	global_load_dwordx4 v[200:203], v187, s[16:17]
	v_add_u32_e32 v187, 0x400, v186
	global_load_dwordx4 v[204:207], v187, s[16:17]
	v_add_u32_e32 v187, 0x410, v186
	global_load_dwordx4 v[208:211], v187, s[16:17]
	v_add_u32_e32 v187, 0x420, v186
	global_load_dwordx4 v[212:215], v187, s[16:17]
	v_add_u32_e32 v187, 0x430, v186
	global_load_dwordx4 v[216:219], v187, s[16:17]
	v_add_u32_e32 v187, 0x800, v186
	global_load_dwordx4 v[220:223], v187, s[16:17]
	v_add_u32_e32 v187, 0x810, v186
	global_load_dwordx4 v[232:235], v187, s[16:17]
	v_add_u32_e32 v187, 0x820, v186
	global_load_dwordx4 v[236:239], v187, s[16:17]
	v_add_u32_e32 v187, 0x830, v186
	global_load_dwordx4 v[240:243], v187, s[16:17]
	v_lshl_or_b32 v148, s6, 8, v154
	v_mov_b64_e32 v[146:147], s[14:15]
	v_ashrrev_i32_e32 v149, 31, v148
	v_mad_i64_i32 v[164:165], s[6:7], v150, s62, v[146:147]
	v_or_b32_e32 v182, 16, v150
	v_lshlrev_b64 v[148:149], 1, v[148:149]
	v_ashrrev_i32_e32 v183, 31, v182
	s_mov_b64 s[34:35], s[24:25]
	s_mov_b32 s28, s22
	s_mov_b64 s[30:31], s[26:27]
	s_waitcnt vmcnt(8)
	v_pk_add_f32 v[160:161], v[188:189], v[190:191]
	v_pk_add_f32 v[170:171], v[192:193], v[194:195]
	v_pk_add_f32 v[172:173], v[196:197], v[198:199]
	v_pk_add_f32 v[174:175], v[200:201], v[202:203]
	v_pk_add_f32 v[160:161], v[160:161], v[170:171]
	v_pk_add_f32 v[172:173], v[172:173], v[174:175]
	v_pk_add_f32 v[160:161], v[160:161], v[172:173]
	v_add_f32_e32 v151, v160, v161
	s_nop 0
	v_lshlrev_b64 v[162:163], 6, v[182:183]
	v_fmamk_f32 v151, v151, 0x3a800000, v158
	v_mul_f32_e32 v159, 0x4b800000, v151
	v_cmp_gt_f32_e32 vcc, s61, v151
	v_lshl_add_u64 v[160:161], v[164:165], 0, v[148:149]
	v_lshl_add_u64 v[162:163], s[16:17], 0, v[162:163]
	v_cndmask_b32_e32 v151, v151, v159, vcc
	v_rsq_f32_e32 v151, v151
	s_nop 0
	v_mul_f32_e32 v159, 0x45800000, v151
	v_cndmask_b32_e32 v164, v151, v159, vcc
	v_pk_mul_f32 v[126:127], v[126:127], v[164:165] op_sel_hi:[1,0]
	v_pk_mul_f32 v[124:125], v[124:125], v[164:165] op_sel_hi:[1,0]
	v_pk_mul_f32 v[122:123], v[122:123], v[164:165] op_sel_hi:[1,0]
	v_pk_mul_f32 v[120:121], v[120:121], v[164:165] op_sel_hi:[1,0]
	v_pk_mul_f32 v[118:119], v[118:119], v[164:165] op_sel_hi:[1,0]
	v_pk_mul_f32 v[116:117], v[116:117], v[164:165] op_sel_hi:[1,0]
	v_pk_mul_f32 v[170:171], v[114:115], v[164:165] op_sel_hi:[1,0]
	v_pk_mul_f32 v[164:165], v[112:113], v[164:165] op_sel_hi:[1,0]
	v_cvt_pk_bf16_f32 v112, v124, v125
	v_cvt_pk_bf16_f32 v113, v126, v127
	v_cvt_pk_bf16_f32 v114, v120, v121
	v_cvt_pk_bf16_f32 v115, v122, v123
	global_store_dwordx4 v[160:161], v[112:115], off sc1
	s_nop 1
	v_cvt_pk_bf16_f32 v112, v116, v117
	v_cvt_pk_bf16_f32 v113, v118, v119
	v_cvt_pk_bf16_f32 v114, v164, v165
	v_cvt_pk_bf16_f32 v115, v170, v171
	global_store_dwordx4 v[160:161], v[112:115], off offset:256 sc1
	s_nop 0
	v_or_b32_e32 v160, 32, v150
	v_mad_i64_i32 v[162:163], s[6:7], v182, s62, v[146:147]
	v_ashrrev_i32_e32 v161, 31, v160
	v_add_u32_e32 v187, 0xc00, v186
	global_load_dwordx4 v[188:191], v187, s[16:17]
	v_add_u32_e32 v187, 0xc10, v186
	global_load_dwordx4 v[192:195], v187, s[16:17]
	v_add_u32_e32 v187, 0xc20, v186
	global_load_dwordx4 v[196:199], v187, s[16:17]
	v_add_u32_e32 v187, 0xc30, v186
	global_load_dwordx4 v[200:203], v187, s[16:17]
	s_waitcnt vmcnt(10)
; __device__ __forceinline__ u32x4 pack8(const f32x4 v0, const f32x4 v1) { u32x4 w; w.x = pk2(v0[0], v0[1]); w.y = pk2(v0[2], v0[3]); w.z = pk2(v1[0], v1[1]); w.w = pk2(v1[2], v1[3]); return w; }
; __device__ __forceinline__ float row_rstd(const float* ssq, int row) {
;     const f32x4* p = (const f32x4*)(ssq + (size_t)row * 16);
;     const f32x4 a = p[0], b = p[1], c = p[2], d = p[3];
;     const float s = ((a[0] + a[1]) + (a[2] + a[3])) + ((b[0] + b[1]) + (b[2] + b[3])) + ((c[0] + c[1]) + (c[2] + c[3])) + ((d[0] + d[1]) + (d[2] + d[3]));
;     return rsqrtf(s * (1.0f / 1024.0f) + 1e-6f);
;     __device__ __forceinline__ void operator()(const f32x4 (&acc)[2][2][4][2], const Unit& u, int wr, int wc, int fr, int fq) const {
;     ...
;             for (int m = 0; m < 4; ++m) {
;                 const int row = row0 + ai * 128 + m * 16; const float rs = row_rstd(ssq, row);
;                 bf16_t* rowp = O + (size_t)row * ldc + col0;
; #pragma unroll
;                 for (int bj = 0; bj < 2; ++bj) { f32x4 v0 = acc[ai][bj][m][0] * rs, v1 = acc[ai][bj][m][1] * rs;
;                     if (ACT == 1) {
; #pragma unroll
;                         for (int j = 0; j < 4; ++j) { const float a = fmaxf(v0[j], 0.f), b = fmaxf(v1[j], 0.f); v0[j] = a * a; v1[j] = b * b; } }
;                     *(u32x4*)(rowp + bj * 128) = pack8(v0, v1); }
	v_pk_add_f32 v[112:113], v[204:205], v[206:207]
	v_pk_add_f32 v[116:117], v[208:209], v[210:211]
	v_pk_add_f32 v[118:119], v[212:213], v[214:215]
	v_pk_add_f32 v[120:121], v[216:217], v[218:219]
	v_pk_add_f32 v[112:113], v[112:113], v[116:117]
	v_pk_add_f32 v[118:119], v[118:119], v[120:121]
	v_pk_add_f32 v[112:113], v[112:113], v[118:119]
	v_add_f32_e32 v112, v112, v113
	v_lshlrev_b64 v[114:115], 6, v[160:161]
	v_lshl_add_u64 v[114:115], s[16:17], 0, v[114:115]
	v_fmamk_f32 v112, v112, 0x3a800000, v158
	v_mul_f32_e32 v113, 0x4b800000, v112
	v_cmp_gt_f32_e32 vcc, s61, v112
	s_nop 1
	v_cndmask_b32_e32 v112, v112, v113, vcc
	v_rsq_f32_e32 v116, v112
	v_lshl_add_u64 v[112:113], v[162:163], 0, v[148:149]
	v_mul_f32_e32 v117, 0x45800000, v116
	v_cndmask_b32_e32 v116, v116, v117, vcc
	v_pk_mul_f32 v[110:111], v[110:111], v[116:117] op_sel_hi:[1,0]
	v_pk_mul_f32 v[108:109], v[108:109], v[116:117] op_sel_hi:[1,0]
	v_pk_mul_f32 v[106:107], v[106:107], v[116:117] op_sel_hi:[1,0]
	v_pk_mul_f32 v[104:105], v[104:105], v[116:117] op_sel_hi:[1,0]
	v_pk_mul_f32 v[102:103], v[102:103], v[116:117] op_sel_hi:[1,0]
	v_pk_mul_f32 v[100:101], v[100:101], v[116:117] op_sel_hi:[1,0]
	v_pk_mul_f32 v[118:119], v[98:99], v[116:117] op_sel_hi:[1,0]
	v_pk_mul_f32 v[116:117], v[96:97], v[116:117] op_sel_hi:[1,0]
	v_cvt_pk_bf16_f32 v96, v108, v109
	v_cvt_pk_bf16_f32 v97, v110, v111
	v_cvt_pk_bf16_f32 v98, v104, v105
	v_cvt_pk_bf16_f32 v99, v106, v107
	global_store_dwordx4 v[112:113], v[96:99], off sc1
	s_nop 1
	v_cvt_pk_bf16_f32 v96, v100, v101
	v_cvt_pk_bf16_f32 v97, v102, v103
	v_cvt_pk_bf16_f32 v98, v116, v117
	v_cvt_pk_bf16_f32 v99, v118, v119
	global_store_dwordx4 v[112:113], v[96:99], off offset:256 sc1
	s_nop 0
	v_or_b32_e32 v112, 48, v150
	v_mad_i64_i32 v[114:115], s[6:7], v160, s62, v[146:147]
	v_ashrrev_i32_e32 v113, 31, v112
	v_add_u32_e32 v187, 0x2000, v186
	global_load_dwordx4 v[204:207], v187, s[16:17]
	v_add_u32_e32 v187, 0x2010, v186
	global_load_dwordx4 v[208:211], v187, s[16:17]
	v_add_u32_e32 v187, 0x2020, v186
	global_load_dwordx4 v[212:215], v187, s[16:17]
	v_add_u32_e32 v187, 0x2030, v186
	global_load_dwordx4 v[216:219], v187, s[16:17]
	s_waitcnt vmcnt(12)
	v_pk_add_f32 v[96:97], v[220:221], v[222:223]
	v_pk_add_f32 v[100:101], v[232:233], v[234:235]
	v_pk_add_f32 v[102:103], v[236:237], v[238:239]
	v_pk_add_f32 v[104:105], v[240:241], v[242:243]
	v_pk_add_f32 v[96:97], v[96:97], v[100:101]
	v_pk_add_f32 v[102:103], v[102:103], v[104:105]
	v_pk_add_f32 v[96:97], v[96:97], v[102:103]
	v_add_f32_e32 v96, v96, v97
	v_lshlrev_b64 v[98:99], 6, v[112:113]
	v_lshl_add_u64 v[98:99], s[16:17], 0, v[98:99]
	v_fmamk_f32 v96, v96, 0x3a800000, v158
	v_mul_f32_e32 v97, 0x4b800000, v96
	v_cmp_gt_f32_e32 vcc, s61, v96
	s_nop 1
	v_cndmask_b32_e32 v96, v96, v97, vcc
	v_rsq_f32_e32 v100, v96
	v_lshl_add_u64 v[96:97], v[114:115], 0, v[148:149]
	v_mul_f32_e32 v101, 0x45800000, v100
	v_cndmask_b32_e32 v100, v100, v101, vcc
	v_pk_mul_f32 v[94:95], v[94:95], v[100:101] op_sel_hi:[1,0]
	v_pk_mul_f32 v[92:93], v[92:93], v[100:101] op_sel_hi:[1,0]
	v_pk_mul_f32 v[90:91], v[90:91], v[100:101] op_sel_hi:[1,0]
	v_pk_mul_f32 v[88:89], v[88:89], v[100:101] op_sel_hi:[1,0]
	v_pk_mul_f32 v[86:87], v[86:87], v[100:101] op_sel_hi:[1,0]
	v_pk_mul_f32 v[84:85], v[84:85], v[100:101] op_sel_hi:[1,0]
	v_pk_mul_f32 v[102:103], v[82:83], v[100:101] op_sel_hi:[1,0]
	v_pk_mul_f32 v[100:101], v[80:81], v[100:101] op_sel_hi:[1,0]
	v_cvt_pk_bf16_f32 v80, v92, v93
	v_cvt_pk_bf16_f32 v81, v94, v95
	v_cvt_pk_bf16_f32 v82, v88, v89
	v_cvt_pk_bf16_f32 v83, v90, v91
	global_store_dwordx4 v[96:97], v[80:83], off sc1
	s_nop 1
	v_cvt_pk_bf16_f32 v80, v84, v85
	v_cvt_pk_bf16_f32 v81, v86, v87
	v_cvt_pk_bf16_f32 v82, v100, v101
	v_cvt_pk_bf16_f32 v83, v102, v103
	global_store_dwordx4 v[96:97], v[80:83], off offset:256 sc1
	s_nop 0
	v_add_u32_e32 v96, 0x80, v150
	v_mad_i64_i32 v[98:99], s[6:7], v112, s62, v[146:147]
	v_ashrrev_i32_e32 v97, 31, v96
	v_add_u32_e32 v187, 0x2400, v186
	global_load_dwordx4 v[220:223], v187, s[16:17]
	v_add_u32_e32 v187, 0x2410, v186
	global_load_dwordx4 v[232:235], v187, s[16:17]
	v_add_u32_e32 v187, 0x2420, v186
	global_load_dwordx4 v[236:239], v187, s[16:17]
	v_add_u32_e32 v187, 0x2430, v186
	global_load_dwordx4 v[240:243], v187, s[16:17]
	s_waitcnt vmcnt(12)
	v_pk_add_f32 v[80:81], v[188:189], v[190:191]
	v_pk_add_f32 v[84:85], v[192:193], v[194:195]
	v_pk_add_f32 v[86:87], v[196:197], v[198:199]
	v_pk_add_f32 v[88:89], v[200:201], v[202:203]
	v_pk_add_f32 v[80:81], v[80:81], v[84:85]
	v_pk_add_f32 v[86:87], v[86:87], v[88:89]
	v_pk_add_f32 v[80:81], v[80:81], v[86:87]
	v_add_f32_e32 v80, v80, v81
	v_lshlrev_b64 v[82:83], 6, v[96:97]
	v_lshl_add_u64 v[82:83], s[16:17], 0, v[82:83]
	v_fmamk_f32 v80, v80, 0x3a800000, v158
	v_mul_f32_e32 v81, 0x4b800000, v80
	v_cmp_gt_f32_e32 vcc, s61, v80
	s_nop 1
	v_cndmask_b32_e32 v80, v80, v81, vcc
	v_rsq_f32_e32 v84, v80
	v_lshl_add_u64 v[80:81], v[98:99], 0, v[148:149]
	v_mul_f32_e32 v85, 0x45800000, v84
	v_cndmask_b32_e32 v84, v84, v85, vcc
	v_pk_mul_f32 v[78:79], v[78:79], v[84:85] op_sel_hi:[1,0]
	v_pk_mul_f32 v[76:77], v[76:77], v[84:85] op_sel_hi:[1,0]
	v_pk_mul_f32 v[74:75], v[74:75], v[84:85] op_sel_hi:[1,0]
	v_pk_mul_f32 v[72:73], v[72:73], v[84:85] op_sel_hi:[1,0]
	v_pk_mul_f32 v[70:71], v[70:71], v[84:85] op_sel_hi:[1,0]
	v_pk_mul_f32 v[68:69], v[68:69], v[84:85] op_sel_hi:[1,0]
	v_pk_mul_f32 v[86:87], v[66:67], v[84:85] op_sel_hi:[1,0]
	v_pk_mul_f32 v[84:85], v[64:65], v[84:85] op_sel_hi:[1,0]
	v_cvt_pk_bf16_f32 v64, v76, v77
	v_cvt_pk_bf16_f32 v65, v78, v79
	v_cvt_pk_bf16_f32 v66, v72, v73
	v_cvt_pk_bf16_f32 v67, v74, v75
	global_store_dwordx4 v[80:81], v[64:67], off sc1
	s_nop 1
	v_cvt_pk_bf16_f32 v64, v68, v69
	v_cvt_pk_bf16_f32 v65, v70, v71
	v_cvt_pk_bf16_f32 v66, v84, v85
	v_cvt_pk_bf16_f32 v67, v86, v87
	global_store_dwordx4 v[80:81], v[64:67], off offset:256 sc1
	s_nop 0
	v_add_u32_e32 v80, 0x90, v150
	v_mad_i64_i32 v[82:83], s[6:7], v96, s62, v[146:147]
	v_ashrrev_i32_e32 v81, 31, v80
	v_add_u32_e32 v187, 0x2800, v186
	global_load_dwordx4 v[188:191], v187, s[16:17]
	v_add_u32_e32 v187, 0x2810, v186
	global_load_dwordx4 v[192:195], v187, s[16:17]
	v_add_u32_e32 v187, 0x2820, v186
	global_load_dwordx4 v[196:199], v187, s[16:17]
	v_add_u32_e32 v187, 0x2830, v186
	global_load_dwordx4 v[200:203], v187, s[16:17]
	s_waitcnt vmcnt(12)
; __device__ __forceinline__ u32x4 pack8(const f32x4 v0, const f32x4 v1) { u32x4 w; w.x = pk2(v0[0], v0[1]); w.y = pk2(v0[2], v0[3]); w.z = pk2(v1[0], v1[1]); w.w = pk2(v1[2], v1[3]); return w; }
; __device__ __forceinline__ float row_rstd(const float* ssq, int row) {
;     const f32x4* p = (const f32x4*)(ssq + (size_t)row * 16);
;     const f32x4 a = p[0], b = p[1], c = p[2], d = p[3];
;     const float s = ((a[0] + a[1]) + (a[2] + a[3])) + ((b[0] + b[1]) + (b[2] + b[3])) + ((c[0] + c[1]) + (c[2] + c[3])) + ((d[0] + d[1]) + (d[2] + d[3]));
;     return rsqrtf(s * (1.0f / 1024.0f) + 1e-6f);
;     __device__ __forceinline__ void operator()(const f32x4 (&acc)[2][2][4][2], const Unit& u, int wr, int wc, int fr, int fq) const {
;     ...
;             for (int m = 0; m < 4; ++m) {
;                 const int row = row0 + ai * 128 + m * 16; const float rs = row_rstd(ssq, row);
;                 bf16_t* rowp = O + (size_t)row * ldc + col0;
; #pragma unroll
;                 for (int bj = 0; bj < 2; ++bj) { f32x4 v0 = acc[ai][bj][m][0] * rs, v1 = acc[ai][bj][m][1] * rs;
;                     if (ACT == 1) {
; #pragma unroll
;                         for (int j = 0; j < 4; ++j) { const float a = fmaxf(v0[j], 0.f), b = fmaxf(v1[j], 0.f); v0[j] = a * a; v1[j] = b * b; } }
;                     *(u32x4*)(rowp + bj * 128) = pack8(v0, v1); }
	v_pk_add_f32 v[64:65], v[204:205], v[206:207]
	v_pk_add_f32 v[68:69], v[208:209], v[210:211]
	v_pk_add_f32 v[70:71], v[212:213], v[214:215]
	v_pk_add_f32 v[72:73], v[216:217], v[218:219]
	v_pk_add_f32 v[64:65], v[64:65], v[68:69]
	v_pk_add_f32 v[70:71], v[70:71], v[72:73]
	v_pk_add_f32 v[64:65], v[64:65], v[70:71]
	v_add_f32_e32 v64, v64, v65
	v_lshlrev_b64 v[66:67], 6, v[80:81]
	v_lshl_add_u64 v[66:67], s[16:17], 0, v[66:67]
	v_fmamk_f32 v64, v64, 0x3a800000, v158
	v_mul_f32_e32 v65, 0x4b800000, v64
	v_cmp_gt_f32_e32 vcc, s61, v64
	s_nop 1
	v_cndmask_b32_e32 v64, v64, v65, vcc
	v_rsq_f32_e32 v68, v64
	v_lshl_add_u64 v[64:65], v[82:83], 0, v[148:149]
	v_mul_f32_e32 v69, 0x45800000, v68
	v_cndmask_b32_e32 v68, v68, v69, vcc
	v_pk_mul_f32 v[62:63], v[62:63], v[68:69] op_sel_hi:[1,0]
	v_pk_mul_f32 v[60:61], v[60:61], v[68:69] op_sel_hi:[1,0]
	v_pk_mul_f32 v[58:59], v[58:59], v[68:69] op_sel_hi:[1,0]
	v_pk_mul_f32 v[56:57], v[56:57], v[68:69] op_sel_hi:[1,0]
	v_pk_mul_f32 v[54:55], v[54:55], v[68:69] op_sel_hi:[1,0]
	v_pk_mul_f32 v[52:53], v[52:53], v[68:69] op_sel_hi:[1,0]
	v_pk_mul_f32 v[70:71], v[50:51], v[68:69] op_sel_hi:[1,0]
	v_pk_mul_f32 v[68:69], v[48:49], v[68:69] op_sel_hi:[1,0]
	v_cvt_pk_bf16_f32 v48, v60, v61
	v_cvt_pk_bf16_f32 v49, v62, v63
	v_cvt_pk_bf16_f32 v50, v56, v57
	v_cvt_pk_bf16_f32 v51, v58, v59
	global_store_dwordx4 v[64:65], v[48:51], off sc1
	s_nop 1
	v_cvt_pk_bf16_f32 v48, v52, v53
	v_cvt_pk_bf16_f32 v49, v54, v55
	v_cvt_pk_bf16_f32 v50, v68, v69
	v_cvt_pk_bf16_f32 v51, v70, v71
	global_store_dwordx4 v[64:65], v[48:51], off offset:256 sc1
	s_nop 0
	v_add_u32_e32 v64, 0xa0, v150
	v_mad_i64_i32 v[66:67], s[6:7], v80, s62, v[146:147]
	v_ashrrev_i32_e32 v65, 31, v64
	v_add_u32_e32 v187, 0x2c00, v186
	global_load_dwordx4 v[204:207], v187, s[16:17]
	v_add_u32_e32 v187, 0x2c10, v186
	global_load_dwordx4 v[208:211], v187, s[16:17]
	v_add_u32_e32 v187, 0x2c20, v186
	global_load_dwordx4 v[212:215], v187, s[16:17]
	v_add_u32_e32 v187, 0x2c30, v186
	global_load_dwordx4 v[216:219], v187, s[16:17]
	s_waitcnt vmcnt(12)
	v_pk_add_f32 v[48:49], v[220:221], v[222:223]
	v_pk_add_f32 v[52:53], v[232:233], v[234:235]
	v_pk_add_f32 v[54:55], v[236:237], v[238:239]
	v_pk_add_f32 v[56:57], v[240:241], v[242:243]
	v_pk_add_f32 v[48:49], v[48:49], v[52:53]
	v_pk_add_f32 v[54:55], v[54:55], v[56:57]
	v_pk_add_f32 v[48:49], v[48:49], v[54:55]
	v_add_f32_e32 v48, v48, v49
	v_lshlrev_b64 v[50:51], 6, v[64:65]
	v_lshl_add_u64 v[50:51], s[16:17], 0, v[50:51]
	v_fmamk_f32 v48, v48, 0x3a800000, v158
	v_mul_f32_e32 v49, 0x4b800000, v48
	v_cmp_gt_f32_e32 vcc, s61, v48
	s_nop 1
	v_cndmask_b32_e32 v48, v48, v49, vcc
	v_rsq_f32_e32 v52, v48
	v_lshl_add_u64 v[48:49], v[66:67], 0, v[148:149]
	v_mul_f32_e32 v53, 0x45800000, v52
	v_cndmask_b32_e32 v52, v52, v53, vcc
	v_pk_mul_f32 v[46:47], v[46:47], v[52:53] op_sel_hi:[1,0]
	v_pk_mul_f32 v[44:45], v[44:45], v[52:53] op_sel_hi:[1,0]
	v_pk_mul_f32 v[42:43], v[42:43], v[52:53] op_sel_hi:[1,0]
	v_pk_mul_f32 v[40:41], v[40:41], v[52:53] op_sel_hi:[1,0]
	v_pk_mul_f32 v[38:39], v[38:39], v[52:53] op_sel_hi:[1,0]
	v_pk_mul_f32 v[36:37], v[36:37], v[52:53] op_sel_hi:[1,0]
	v_pk_mul_f32 v[54:55], v[34:35], v[52:53] op_sel_hi:[1,0]
	v_pk_mul_f32 v[52:53], v[32:33], v[52:53] op_sel_hi:[1,0]
	v_cvt_pk_bf16_f32 v32, v44, v45
	v_cvt_pk_bf16_f32 v33, v46, v47
	v_cvt_pk_bf16_f32 v34, v40, v41
	v_cvt_pk_bf16_f32 v35, v42, v43
	global_store_dwordx4 v[48:49], v[32:35], off sc1
	s_nop 1
	v_cvt_pk_bf16_f32 v32, v36, v37
	v_cvt_pk_bf16_f32 v33, v38, v39
	v_cvt_pk_bf16_f32 v34, v52, v53
	v_cvt_pk_bf16_f32 v35, v54, v55
	global_store_dwordx4 v[48:49], v[32:35], off offset:256 sc1
	s_nop 0
	v_add_u32_e32 v48, 0xb0, v150
	v_mad_i64_i32 v[50:51], s[6:7], v64, s62, v[146:147]
	v_ashrrev_i32_e32 v49, 31, v48
	s_mov_b32 s6, s20
	s_waitcnt vmcnt(8)
	v_pk_add_f32 v[32:33], v[188:189], v[190:191]
	v_pk_add_f32 v[36:37], v[192:193], v[194:195]
	v_pk_add_f32 v[38:39], v[196:197], v[198:199]
	v_pk_add_f32 v[40:41], v[200:201], v[202:203]
	v_pk_add_f32 v[32:33], v[32:33], v[36:37]
	v_pk_add_f32 v[38:39], v[38:39], v[40:41]
	v_pk_add_f32 v[32:33], v[32:33], v[38:39]
	v_add_f32_e32 v32, v32, v33
	v_lshlrev_b64 v[34:35], 6, v[48:49]
	v_lshl_add_u64 v[34:35], s[16:17], 0, v[34:35]
	v_fmamk_f32 v32, v32, 0x3a800000, v158
	v_mul_f32_e32 v33, 0x4b800000, v32
	v_cmp_gt_f32_e32 vcc, s61, v32
	s_nop 1
	v_cndmask_b32_e32 v32, v32, v33, vcc
	v_rsq_f32_e32 v36, v32
	v_lshl_add_u64 v[32:33], v[50:51], 0, v[148:149]
	v_mul_f32_e32 v37, 0x45800000, v36
	v_cndmask_b32_e32 v36, v36, v37, vcc
	v_pk_mul_f32 v[30:31], v[30:31], v[36:37] op_sel_hi:[1,0]
	v_pk_mul_f32 v[28:29], v[28:29], v[36:37] op_sel_hi:[1,0]
	v_pk_mul_f32 v[26:27], v[26:27], v[36:37] op_sel_hi:[1,0]
	v_pk_mul_f32 v[24:25], v[24:25], v[36:37] op_sel_hi:[1,0]
	v_pk_mul_f32 v[22:23], v[22:23], v[36:37] op_sel_hi:[1,0]
	v_pk_mul_f32 v[20:21], v[20:21], v[36:37] op_sel_hi:[1,0]
	v_pk_mul_f32 v[38:39], v[18:19], v[36:37] op_sel_hi:[1,0]
	v_pk_mul_f32 v[36:37], v[16:17], v[36:37] op_sel_hi:[1,0]
	v_cvt_pk_bf16_f32 v16, v28, v29
	v_cvt_pk_bf16_f32 v17, v30, v31
	v_cvt_pk_bf16_f32 v18, v24, v25
	v_cvt_pk_bf16_f32 v19, v26, v27
	global_store_dwordx4 v[32:33], v[16:19], off sc1
	s_and_b64 vcc, exec, s[8:9]
	s_nop 0
	v_cvt_pk_bf16_f32 v16, v20, v21
	v_cvt_pk_bf16_f32 v17, v22, v23
	v_cvt_pk_bf16_f32 v18, v36, v37
	v_cvt_pk_bf16_f32 v19, v38, v39
	global_store_dwordx4 v[32:33], v[16:19], off offset:256 sc1
	s_nop 0
	s_waitcnt vmcnt(4)
	v_pk_add_f32 v[16:17], v[204:205], v[206:207]
	v_pk_add_f32 v[18:19], v[208:209], v[210:211]
	v_pk_add_f32 v[20:21], v[212:213], v[214:215]
	v_pk_add_f32 v[22:23], v[216:217], v[218:219]
	v_pk_add_f32 v[16:17], v[16:17], v[18:19]
	v_pk_add_f32 v[20:21], v[20:21], v[22:23]
	v_pk_add_f32 v[16:17], v[16:17], v[20:21]
	v_add_f32_e32 v16, v16, v17
	s_nop 0
	s_nop 0
	v_fmamk_f32 v16, v16, 0x3a800000, v158
	v_mul_f32_e32 v17, 0x4b800000, v16
	v_cmp_gt_f32_e64 s[8:9], s61, v16
	s_nop 1
	v_cndmask_b32_e64 v16, v16, v17, s[8:9]
	v_rsq_f32_e32 v18, v16
	v_mad_i64_i32 v[16:17], s[24:25], v48, s62, v[146:147]
	v_lshl_add_u64 v[16:17], v[16:17], 0, v[148:149]
	v_mul_f32_e32 v19, 0x45800000, v18
	v_cndmask_b32_e64 v18, v18, v19, s[8:9]
	v_pk_mul_f32 v[14:15], v[14:15], v[18:19] op_sel_hi:[1,0]
	v_pk_mul_f32 v[12:13], v[12:13], v[18:19] op_sel_hi:[1,0]
	v_pk_mul_f32 v[10:11], v[10:11], v[18:19] op_sel_hi:[1,0]
	v_pk_mul_f32 v[8:9], v[8:9], v[18:19] op_sel_hi:[1,0]
	v_pk_mul_f32 v[6:7], v[6:7], v[18:19] op_sel_hi:[1,0]
	v_pk_mul_f32 v[4:5], v[4:5], v[18:19] op_sel_hi:[1,0]
	v_pk_mul_f32 v[20:21], v[2:3], v[18:19] op_sel_hi:[1,0]
	v_pk_mul_f32 v[18:19], v[0:1], v[18:19] op_sel_hi:[1,0]
	v_cvt_pk_bf16_f32 v0, v12, v13
	v_cvt_pk_bf16_f32 v1, v14, v15
	v_cvt_pk_bf16_f32 v2, v8, v9
	v_cvt_pk_bf16_f32 v3, v10, v11
	global_store_dwordx4 v[16:17], v[0:3], off sc1
	s_nop 1
	v_cvt_pk_bf16_f32 v0, v4, v5
	v_cvt_pk_bf16_f32 v1, v6, v7
	v_cvt_pk_bf16_f32 v2, v18, v19
	v_cvt_pk_bf16_f32 v3, v20, v21
	global_store_dwordx4 v[16:17], v[0:3], off offset:256 sc1
	s_cbranch_vccz .LBB0_118
; #define PG8_WAIT_V(n) asm volatile("s_waitcnt vmcnt(" #n ")" ::: "memory")
; #define PG8_BAR __builtin_amdgcn_s_barrier()
;     ...
;     PG8_WAIT_V(0);
;     if (wr == 0) PG8_BAR;
;     PG8_BAR;
	s_waitcnt vmcnt(0)
	s_cmpk_gt_u32 s40, 0xff
	s_cbranch_scc1 .LBB0_129
	s_barrier

; #define PG8_STAGE(bufoff, gbase, voff) do { _Pragma("unroll") for (int _i = 0; _i < 2; ++_i) \
;         __builtin_amdgcn_global_load_lds((const unsigned*)((const char*)(gbase) + (voff)[_i]), (LAS unsigned*)(lds + (bufoff) + ldsw + _i * 8192), 16, 0, 0); } while (0)
; #define PG8_LDA(dst, b, h) do { _Pragma("unroll") for (int m = 0; m < 4; ++m) _Pragma("unroll") for (int k = 0; k < 2; ++k) dst[m][k] = *(const LAS bf16x8*)(lds + PG8_SA(b, h) + aoff + m * 2048 + k * 1024); } while (0)
; #define PG8_LDB(dst, b, h) do { _Pragma("unroll") for (int n = 0; n < 2; ++n) _Pragma("unroll") for (int k = 0; k < 2; ++k) dst[n][k] = *(const LAS bf16x8*)(lds + PG8_SB(b, h) + boff + n * 2048 + k * 1024); } while (0)
; #define PG8_MMA(ai, bj, At, Bt) do { __builtin_amdgcn_s_setprio(1); _Pragma("unroll") for (int m = 0; m < 4; ++m) _Pragma("unroll") for (int n = 0; n < 2; ++n) _Pragma("unroll") for (int k = 0; k < 2; ++k) \
;         acc[ai][bj][m][n] = __builtin_amdgcn_mfma_f32_16x16x32_bf16(Bt[n][k], At[m][k], acc[ai][bj][m][n], 0, 0, 0); __builtin_amdgcn_s_setprio(0); } while (0)
; #define PG8_WAIT_V(n) asm volatile("s_waitcnt vmcnt(" #n ")" ::: "memory")
;     ...
;             PG8_LDB(B0, 0, 0); PG8_SCHED; PG8_LDA(At, 0, 0); PG8_STAGE(PG8_SA(1, 1), a1 + hA, voffA);
;             PG8_WAIT_L(8); PG8_BAR; PG8_WAIT_L(0); PG8_MMA(0, 0, At, B0); PG8_BAR; PG8_SCHED;
;             PG8_LDB(B1, 0, 1); PG8_STAGE(PG8_SB(0, 0), b2, voffB);
;             PG8_BAR; PG8_WAIT_L(0); PG8_MMA(0, 1, At, B1); PG8_BAR;
;             PG8_LDA(At, 0, 1); PG8_STAGE(PG8_SA(0, 0), a2, voffA);
;             PG8_BAR; PG8_WAIT_L(0); PG8_MMA(1, 0, At, B0); PG8_BAR; PG8_SCHED;
;             PG8_STAGE(PG8_SB(0, 1), b2 + hB, voffB);
;             PG8_WAIT_V(6); PG8_BAR; PG8_MMA(1, 1, At, B1); PG8_BAR;
;             PG8_LDB(B0, 1, 0); PG8_SCHED; PG8_LDA(At, 1, 0); PG8_STAGE(PG8_SA(0, 1), a2 + hA, voffA);
;             PG8_WAIT_L(8); PG8_BAR; PG8_WAIT_L(0); PG8_MMA(0, 0, At, B0); PG8_BAR; PG8_SCHED;
;             PG8_LDB(B1, 1, 1); PG8_STAGE(PG8_SB(1, 0), b3, voffB);
;             PG8_BAR; PG8_WAIT_L(0); PG8_MMA(0, 1, At, B1); PG8_BAR;
;             PG8_LDA(At, 1, 1); PG8_STAGE(PG8_SA(1, 0), a3, voffA);
;             PG8_BAR; PG8_WAIT_L(0); PG8_MMA(1, 0, At, B0); PG8_BAR; PG8_SCHED;
;             PG8_STAGE(PG8_SB(1, 1), b3 + hB, voffB);
;             PG8_WAIT_V(6); PG8_BAR; PG8_MMA(1, 1, At, B1); PG8_BAR;
.LBB0_958:
	ds_read_b128 v[156:159], v151
	ds_read_b128 v[160:163], v151 offset:1024
	ds_read_b128 v[170:173], v151 offset:2048
	ds_read_b128 v[174:177], v151 offset:3072
	s_add_u32 s43, s40, 0xfffc0080
	s_addc_u32 s44, s41, -1
	s_cmp_eq_u32 s42, 12
	s_cselect_b32 s57, s7, s44
	s_cselect_b32 s56, s8, s43
	s_cselect_b32 s55, s9, s39
	s_cselect_b32 s54, s29, s33
	v_lshl_add_u64 v[146:147], s[40:41], 0, v[138:139]
	s_add_i32 m0, s61, 0xc000
	ds_read_b128 v[178:181], v152
	ds_read_b128 v[182:185], v152 offset:1024
	ds_read_b128 v[186:189], v152 offset:2048
	ds_read_b128 v[190:193], v152 offset:3072
	ds_read_b128 v[194:197], v152 offset:4096
	ds_read_b128 v[198:201], v152 offset:5120
	ds_read_b128 v[202:205], v152 offset:6144
	ds_read_b128 v[206:209], v152 offset:7168
	global_load_lds_dwordx4 v[146:147], off
	v_lshl_add_u64 v[146:147], s[40:41], 0, v[136:137]
	s_add_i32 m0, s61, 0xe000
	s_nop 0
	global_load_lds_dwordx4 v[146:147], off
	s_waitcnt lgkmcnt(8)
	s_barrier
	s_waitcnt lgkmcnt(0)
	s_setprio 1
	s_waitcnt lgkmcnt(0)
	v_mfma_f32_16x16x32_bf16 v[124:127], v[156:159], v[178:181], v[124:127]
	v_mfma_f32_16x16x32_bf16 v[120:123], v[170:173], v[178:181], v[120:123]
	v_mfma_f32_16x16x32_bf16 v[108:111], v[156:159], v[186:189], v[108:111]
	v_mfma_f32_16x16x32_bf16 v[104:107], v[170:173], v[186:189], v[104:107]
	v_mfma_f32_16x16x32_bf16 v[92:95], v[156:159], v[194:197], v[92:95]
	v_mfma_f32_16x16x32_bf16 v[88:91], v[170:173], v[194:197], v[88:91]
	v_mfma_f32_16x16x32_bf16 v[76:79], v[156:159], v[202:205], v[76:79]
	v_mfma_f32_16x16x32_bf16 v[72:75], v[170:173], v[202:205], v[72:75]
	v_mfma_f32_16x16x32_bf16 v[124:127], v[160:163], v[182:185], v[124:127]
	v_mfma_f32_16x16x32_bf16 v[120:123], v[174:177], v[182:185], v[120:123]
	v_mfma_f32_16x16x32_bf16 v[108:111], v[160:163], v[190:193], v[108:111]
	v_mfma_f32_16x16x32_bf16 v[104:107], v[174:177], v[190:193], v[104:107]
	v_mfma_f32_16x16x32_bf16 v[92:95], v[160:163], v[198:201], v[92:95]
	v_mfma_f32_16x16x32_bf16 v[88:91], v[174:177], v[198:201], v[88:91]
	v_mfma_f32_16x16x32_bf16 v[76:79], v[160:163], v[206:209], v[76:79]
	v_mfma_f32_16x16x32_bf16 v[72:75], v[174:177], v[206:209], v[72:75]
	s_setprio 0
	s_barrier
	s_add_i32 s43, s69, s60
	v_lshl_add_u64 v[146:147], s[54:55], 0, v[130:131]
	s_mov_b32 m0, s43
	ds_read_b128 v[210:213], v153
	ds_read_b128 v[214:217], v153 offset:1024
	ds_read_b128 v[218:221], v153 offset:2048
	ds_read_b128 v[222:225], v153 offset:3072
	global_load_lds_dwordx4 v[146:147], off
	v_lshl_add_u64 v[164:165], s[54:55], 0, v[134:135]
	s_add_i32 m0, s43, 0x2000
	s_nop 0
	global_load_lds_dwordx4 v[164:165], off
	s_barrier
	s_waitcnt lgkmcnt(0)
	s_setprio 1
	s_waitcnt lgkmcnt(0)
	v_mfma_f32_16x16x32_bf16 v[116:119], v[210:213], v[178:181], v[116:119]
	v_mfma_f32_16x16x32_bf16 v[112:115], v[218:221], v[178:181], v[112:115]
	v_mfma_f32_16x16x32_bf16 v[100:103], v[210:213], v[186:189], v[100:103]
	v_mfma_f32_16x16x32_bf16 v[96:99], v[218:221], v[186:189], v[96:99]
	v_mfma_f32_16x16x32_bf16 v[84:87], v[210:213], v[194:197], v[84:87]
	v_mfma_f32_16x16x32_bf16 v[80:83], v[218:221], v[194:197], v[80:83]
	v_mfma_f32_16x16x32_bf16 v[68:71], v[210:213], v[202:205], v[68:71]
	v_mfma_f32_16x16x32_bf16 v[64:67], v[218:221], v[202:205], v[64:67]
	v_mfma_f32_16x16x32_bf16 v[116:119], v[214:217], v[182:185], v[116:119]
	v_mfma_f32_16x16x32_bf16 v[112:115], v[222:225], v[182:185], v[112:115]
	v_mfma_f32_16x16x32_bf16 v[100:103], v[214:217], v[190:193], v[100:103]
	v_mfma_f32_16x16x32_bf16 v[96:99], v[222:225], v[190:193], v[96:99]
	v_mfma_f32_16x16x32_bf16 v[84:87], v[214:217], v[198:201], v[84:87]
	v_mfma_f32_16x16x32_bf16 v[80:83], v[222:225], v[198:201], v[80:83]
	v_mfma_f32_16x16x32_bf16 v[68:71], v[214:217], v[206:209], v[68:71]
	v_mfma_f32_16x16x32_bf16 v[64:67], v[222:225], v[206:209], v[64:67]
	s_setprio 0
	s_mov_b32 m0, s61
	v_lshl_add_u64 v[226:227], s[56:57], 0, v[128:129]
	s_barrier
	ds_read_b128 v[178:181], v152 offset:16384
	ds_read_b128 v[182:185], v152 offset:17408
	ds_read_b128 v[186:189], v152 offset:18432
	ds_read_b128 v[190:193], v152 offset:19456
	ds_read_b128 v[194:197], v152 offset:20480
	ds_read_b128 v[198:201], v152 offset:21504
	ds_read_b128 v[202:205], v152 offset:22528
	ds_read_b128 v[206:209], v152 offset:23552
	global_load_lds_dwordx4 v[226:227], off
	v_lshl_add_u64 v[228:229], s[56:57], 0, v[132:133]
	s_mov_b32 m0, s62
	s_nop 0
	global_load_lds_dwordx4 v[228:229], off
	s_barrier
	s_waitcnt lgkmcnt(0)
	s_setprio 1
	s_waitcnt lgkmcnt(0)
	v_mfma_f32_16x16x32_bf16 v[60:63], v[156:159], v[178:181], v[60:63]
	v_mfma_f32_16x16x32_bf16 v[56:59], v[170:173], v[178:181], v[56:59]
	v_mfma_f32_16x16x32_bf16 v[44:47], v[156:159], v[186:189], v[44:47]
	v_mfma_f32_16x16x32_bf16 v[40:43], v[170:173], v[186:189], v[40:43]
	v_mfma_f32_16x16x32_bf16 v[28:31], v[156:159], v[194:197], v[28:31]
	v_mfma_f32_16x16x32_bf16 v[24:27], v[170:173], v[194:197], v[24:27]
	v_mfma_f32_16x16x32_bf16 v[12:15], v[156:159], v[202:205], v[12:15]
	v_mfma_f32_16x16x32_bf16 v[8:11], v[170:173], v[202:205], v[8:11]
	v_mfma_f32_16x16x32_bf16 v[60:63], v[160:163], v[182:185], v[60:63]
	v_mfma_f32_16x16x32_bf16 v[56:59], v[174:177], v[182:185], v[56:59]
	v_mfma_f32_16x16x32_bf16 v[44:47], v[160:163], v[190:193], v[44:47]
	v_mfma_f32_16x16x32_bf16 v[40:43], v[174:177], v[190:193], v[40:43]
	v_mfma_f32_16x16x32_bf16 v[28:31], v[160:163], v[198:201], v[28:31]
	v_mfma_f32_16x16x32_bf16 v[24:27], v[174:177], v[198:201], v[24:27]
	v_mfma_f32_16x16x32_bf16 v[12:15], v[160:163], v[206:209], v[12:15]
	v_mfma_f32_16x16x32_bf16 v[8:11], v[174:177], v[206:209], v[8:11]
	s_setprio 0
	s_barrier
; #define PG8_STAGE(bufoff, gbase, voff) do { _Pragma("unroll") for (int _i = 0; _i < 2; ++_i) \
;         __builtin_amdgcn_global_load_lds((const unsigned*)((const char*)(gbase) + (voff)[_i]), (LAS unsigned*)(lds + (bufoff) + ldsw + _i * 8192), 16, 0, 0); } while (0)
; #define PG8_LDA(dst, b, h) do { _Pragma("unroll") for (int m = 0; m < 4; ++m) _Pragma("unroll") for (int k = 0; k < 2; ++k) dst[m][k] = *(const LAS bf16x8*)(lds + PG8_SA(b, h) + aoff + m * 2048 + k * 1024); } while (0)
; #define PG8_LDB(dst, b, h) do { _Pragma("unroll") for (int n = 0; n < 2; ++n) _Pragma("unroll") for (int k = 0; k < 2; ++k) dst[n][k] = *(const LAS bf16x8*)(lds + PG8_SB(b, h) + boff + n * 2048 + k * 1024); } while (0)
; #define PG8_MMA(ai, bj, At, Bt) do { __builtin_amdgcn_s_setprio(1); _Pragma("unroll") for (int m = 0; m < 4; ++m) _Pragma("unroll") for (int n = 0; n < 2; ++n) _Pragma("unroll") for (int k = 0; k < 2; ++k) \
;         acc[ai][bj][m][n] = __builtin_amdgcn_mfma_f32_16x16x32_bf16(Bt[n][k], At[m][k], acc[ai][bj][m][n], 0, 0, 0); __builtin_amdgcn_s_setprio(0); } while (0)
; #define PG8_WAIT_V(n) asm volatile("s_waitcnt vmcnt(" #n ")" ::: "memory")
; #define PG8_WAIT_L(n) asm volatile("s_waitcnt lgkmcnt(" #n ")" ::: "memory")
; #define PG8_BAR __builtin_amdgcn_s_barrier()
; #define PG8_SCHED __builtin_amdgcn_sched_barrier(0)
;     ...
;             PG8_STAGE(PG8_SB(0, 1), b2 + hB, voffB);
;             PG8_WAIT_V(6); PG8_BAR; PG8_MMA(1, 1, At, B1); PG8_BAR;
;             PG8_LDB(B0, 1, 0); PG8_SCHED; PG8_LDA(At, 1, 0); PG8_STAGE(PG8_SA(0, 1), a2 + hA, voffA);
;             PG8_WAIT_L(8); PG8_BAR; PG8_WAIT_L(0); PG8_MMA(0, 0, At, B0); PG8_BAR; PG8_SCHED;
;             PG8_LDB(B1, 1, 1); PG8_STAGE(PG8_SB(1, 0), b3, voffB);
;             PG8_BAR; PG8_WAIT_L(0); PG8_MMA(0, 1, At, B1); PG8_BAR;
;             PG8_LDA(At, 1, 1); PG8_STAGE(PG8_SA(1, 0), a3, voffA);
;             PG8_BAR; PG8_WAIT_L(0); PG8_MMA(1, 0, At, B0); PG8_BAR; PG8_SCHED;
	s_add_u32 s44, s54, 0x40000
	s_addc_u32 s45, s55, 0
	s_add_i32 s43, s70, s60
	v_lshl_add_u64 v[156:157], s[44:45], 0, v[130:131]
	s_mov_b32 m0, s43
	s_nop 0
	global_load_lds_dwordx4 v[156:157], off
	v_lshl_add_u64 v[156:157], s[44:45], 0, v[134:135]
	s_add_i32 m0, s43, 0x2000
	s_nop 0
	global_load_lds_dwordx4 v[156:157], off
	s_waitcnt vmcnt(6)
	s_barrier
	s_setprio 1
	v_mfma_f32_16x16x32_bf16 v[52:55], v[210:213], v[178:181], v[52:55]
	v_mfma_f32_16x16x32_bf16 v[48:51], v[218:221], v[178:181], v[48:51]
	v_mfma_f32_16x16x32_bf16 v[36:39], v[210:213], v[186:189], v[36:39]
	v_mfma_f32_16x16x32_bf16 v[32:35], v[218:221], v[186:189], v[32:35]
	v_mfma_f32_16x16x32_bf16 v[20:23], v[210:213], v[194:197], v[20:23]
	v_mfma_f32_16x16x32_bf16 v[16:19], v[218:221], v[194:197], v[16:19]
	v_mfma_f32_16x16x32_bf16 v[4:7], v[210:213], v[202:205], v[4:7]
	v_mfma_f32_16x16x32_bf16 v[0:3], v[218:221], v[202:205], v[0:3]
	v_mfma_f32_16x16x32_bf16 v[52:55], v[214:217], v[182:185], v[52:55]
	v_mfma_f32_16x16x32_bf16 v[48:51], v[222:225], v[182:185], v[48:51]
	v_mfma_f32_16x16x32_bf16 v[36:39], v[214:217], v[190:193], v[36:39]
	v_mfma_f32_16x16x32_bf16 v[32:35], v[222:225], v[190:193], v[32:35]
	v_mfma_f32_16x16x32_bf16 v[20:23], v[214:217], v[198:201], v[20:23]
	v_mfma_f32_16x16x32_bf16 v[16:19], v[222:225], v[198:201], v[16:19]
	v_mfma_f32_16x16x32_bf16 v[4:7], v[214:217], v[206:209], v[4:7]
	v_mfma_f32_16x16x32_bf16 v[0:3], v[222:225], v[206:209], v[0:3]
	s_setprio 0
	s_add_i32 s43, 0, 0x18000
	v_add_u32_e32 v155, s43, v149
	s_barrier
	ds_read_b128 v[156:159], v155
	ds_read_b128 v[160:163], v155 offset:1024
	ds_read_b128 v[170:173], v155 offset:2048
	ds_read_b128 v[174:177], v155 offset:3072
	s_add_u32 s44, s56, 0x40000
	s_addc_u32 s45, s57, 0
	s_mov_b32 m0, s63
	v_lshl_add_u64 v[210:211], s[44:45], 0, v[128:129]
	ds_read_b128 v[178:181], v152 offset:32768
	ds_read_b128 v[182:185], v152 offset:33792
	ds_read_b128 v[186:189], v152 offset:34816
	ds_read_b128 v[190:193], v152 offset:35840
	ds_read_b128 v[194:197], v152 offset:36864
	ds_read_b128 v[198:201], v152 offset:37888
	ds_read_b128 v[202:205], v152 offset:38912
	ds_read_b128 v[206:209], v152 offset:39936
	global_load_lds_dwordx4 v[210:211], off
	v_lshl_add_u64 v[210:211], s[44:45], 0, v[132:133]
	s_mov_b32 m0, s64
	s_nop 0
	global_load_lds_dwordx4 v[210:211], off
	s_waitcnt lgkmcnt(8)
	s_barrier
	s_waitcnt lgkmcnt(0)
	s_setprio 1
	s_waitcnt lgkmcnt(0)
	v_mfma_f32_16x16x32_bf16 v[124:127], v[156:159], v[178:181], v[124:127]
	v_mfma_f32_16x16x32_bf16 v[120:123], v[170:173], v[178:181], v[120:123]
	v_mfma_f32_16x16x32_bf16 v[108:111], v[156:159], v[186:189], v[108:111]
	v_mfma_f32_16x16x32_bf16 v[104:107], v[170:173], v[186:189], v[104:107]
	v_mfma_f32_16x16x32_bf16 v[92:95], v[156:159], v[194:197], v[92:95]
	v_mfma_f32_16x16x32_bf16 v[88:91], v[170:173], v[194:197], v[88:91]
	v_mfma_f32_16x16x32_bf16 v[76:79], v[156:159], v[202:205], v[76:79]
	v_mfma_f32_16x16x32_bf16 v[72:75], v[170:173], v[202:205], v[72:75]
	v_mfma_f32_16x16x32_bf16 v[124:127], v[160:163], v[182:185], v[124:127]
	v_mfma_f32_16x16x32_bf16 v[120:123], v[174:177], v[182:185], v[120:123]
	v_mfma_f32_16x16x32_bf16 v[108:111], v[160:163], v[190:193], v[108:111]
	v_mfma_f32_16x16x32_bf16 v[104:107], v[174:177], v[190:193], v[104:107]
	v_mfma_f32_16x16x32_bf16 v[92:95], v[160:163], v[198:201], v[92:95]
	v_mfma_f32_16x16x32_bf16 v[88:91], v[174:177], v[198:201], v[88:91]
	v_mfma_f32_16x16x32_bf16 v[76:79], v[160:163], v[206:209], v[76:79]
	v_mfma_f32_16x16x32_bf16 v[72:75], v[174:177], v[206:209], v[72:75]
	s_setprio 0
	s_barrier
	s_add_i32 s56, 0, 0x1c000
	s_add_i32 s43, s43, s60
	v_add_u32_e32 v155, s56, v149
	v_lshl_add_u64 v[146:147], v[146:147], 0, s[30:31]
	s_mov_b32 m0, s43
	ds_read_b128 v[210:213], v155
	ds_read_b128 v[214:217], v155 offset:1024
	ds_read_b128 v[218:221], v155 offset:2048
	ds_read_b128 v[222:225], v155 offset:3072
	global_load_lds_dwordx4 v[146:147], off
	v_lshl_add_u64 v[146:147], v[164:165], 0, s[30:31]
	s_add_i32 m0, s43, 0x2000
	s_nop 0
	global_load_lds_dwordx4 v[146:147], off
	s_barrier
	s_waitcnt lgkmcnt(0)
	s_setprio 1
	s_waitcnt lgkmcnt(0)
	v_mfma_f32_16x16x32_bf16 v[116:119], v[210:213], v[178:181], v[116:119]
	v_mfma_f32_16x16x32_bf16 v[112:115], v[218:221], v[178:181], v[112:115]
	v_mfma_f32_16x16x32_bf16 v[100:103], v[210:213], v[186:189], v[100:103]
	v_mfma_f32_16x16x32_bf16 v[96:99], v[218:221], v[186:189], v[96:99]
	v_mfma_f32_16x16x32_bf16 v[84:87], v[210:213], v[194:197], v[84:87]
	v_mfma_f32_16x16x32_bf16 v[80:83], v[218:221], v[194:197], v[80:83]
	v_mfma_f32_16x16x32_bf16 v[68:71], v[210:213], v[202:205], v[68:71]
	v_mfma_f32_16x16x32_bf16 v[64:67], v[218:221], v[202:205], v[64:67]
	v_mfma_f32_16x16x32_bf16 v[116:119], v[214:217], v[182:185], v[116:119]
	v_mfma_f32_16x16x32_bf16 v[112:115], v[222:225], v[182:185], v[112:115]
	v_mfma_f32_16x16x32_bf16 v[100:103], v[214:217], v[190:193], v[100:103]
	v_mfma_f32_16x16x32_bf16 v[96:99], v[222:225], v[190:193], v[96:99]
	v_mfma_f32_16x16x32_bf16 v[84:87], v[214:217], v[198:201], v[84:87]
	v_mfma_f32_16x16x32_bf16 v[80:83], v[222:225], v[198:201], v[80:83]
	v_mfma_f32_16x16x32_bf16 v[68:71], v[214:217], v[206:209], v[68:71]
	v_mfma_f32_16x16x32_bf16 v[64:67], v[222:225], v[206:209], v[64:67]
	s_setprio 0
	s_mov_b32 m0, s66
	v_lshl_add_u64 v[146:147], v[226:227], 0, s[30:31]
	s_barrier
	ds_read_b128 v[178:181], v152 offset:49152
	ds_read_b128 v[182:185], v152 offset:50176
	ds_read_b128 v[186:189], v152 offset:51200
	ds_read_b128 v[190:193], v152 offset:52224
	ds_read_b128 v[194:197], v152 offset:53248
	ds_read_b128 v[198:201], v152 offset:54272
	ds_read_b128 v[202:205], v152 offset:55296
	ds_read_b128 v[206:209], v152 offset:56320
	global_load_lds_dwordx4 v[146:147], off
	v_lshl_add_u64 v[146:147], v[228:229], 0, s[30:31]
	s_mov_b32 m0, s67
	s_nop 0
	global_load_lds_dwordx4 v[146:147], off
	s_barrier
; #define PG8_STAGE(bufoff, gbase, voff) do { _Pragma("unroll") for (int _i = 0; _i < 2; ++_i) \
;         __builtin_amdgcn_global_load_lds((const unsigned*)((const char*)(gbase) + (voff)[_i]), (LAS unsigned*)(lds + (bufoff) + ldsw + _i * 8192), 16, 0, 0); } while (0)
; #define PG8_LDA(dst, b, h) do { _Pragma("unroll") for (int m = 0; m < 4; ++m) _Pragma("unroll") for (int k = 0; k < 2; ++k) dst[m][k] = *(const LAS bf16x8*)(lds + PG8_SA(b, h) + aoff + m * 2048 + k * 1024); } while (0)
; #define PG8_LDB(dst, b, h) do { _Pragma("unroll") for (int n = 0; n < 2; ++n) _Pragma("unroll") for (int k = 0; k < 2; ++k) dst[n][k] = *(const LAS bf16x8*)(lds + PG8_SB(b, h) + boff + n * 2048 + k * 1024); } while (0)
; #define PG8_MMA(ai, bj, At, Bt) do { __builtin_amdgcn_s_setprio(1); _Pragma("unroll") for (int m = 0; m < 4; ++m) _Pragma("unroll") for (int n = 0; n < 2; ++n) _Pragma("unroll") for (int k = 0; k < 2; ++k) \
;         acc[ai][bj][m][n] = __builtin_amdgcn_mfma_f32_16x16x32_bf16(Bt[n][k], At[m][k], acc[ai][bj][m][n], 0, 0, 0); __builtin_amdgcn_s_setprio(0); } while (0)
; #define PG8_WAIT_V(n) asm volatile("s_waitcnt vmcnt(" #n ")" ::: "memory")
; #define PG8_WAIT_L(n) asm volatile("s_waitcnt lgkmcnt(" #n ")" ::: "memory")
; #define PG8_BAR __builtin_amdgcn_s_barrier()
;     ...
;             PG8_WAIT_L(8); PG8_BAR; PG8_WAIT_L(0); PG8_MMA(0, 0, At, B0); PG8_BAR; PG8_SCHED;
;             PG8_LDB(B1, 1, 1); PG8_STAGE(PG8_SB(1, 0), b3, voffB);
;             PG8_BAR; PG8_WAIT_L(0); PG8_MMA(0, 1, At, B1); PG8_BAR;
;             PG8_LDA(At, 1, 1); PG8_STAGE(PG8_SA(1, 0), a3, voffA);
;             PG8_BAR; PG8_WAIT_L(0); PG8_MMA(1, 0, At, B0); PG8_BAR; PG8_SCHED;
;             PG8_STAGE(PG8_SB(1, 1), b3 + hB, voffB);
;             PG8_WAIT_V(6); PG8_BAR; PG8_MMA(1, 1, At, B1); PG8_BAR;
;         }
;     __device__ __forceinline__ void operator()(const f32x4 (&acc)[2][2][4][2], const Unit& u, int wr, int wc, int fr, int fq) const {
;         const __amdgpu_buffer_rsrc_t rsrc = __builtin_amdgcn_make_buffer_rsrc((void*)O, 0, T_ALL * DFF * 2, 0x00020000);
;         const int row0 = row_off + u.pm * 256 + wr * 64 + fr, col0 = u.pn * 256 + wc * 32 + 8 * fq;
; #pragma unroll
;         for (int ai = 0; ai < 2; ++ai)
; #pragma unroll
;             for (int m = 0; m < 4; ++m) {
;                 const int row = row0 + ai * 128 + m * 16; const float rs = row_rstd(ssq, row);
	s_waitcnt lgkmcnt(0)
	s_setprio 1
	s_waitcnt lgkmcnt(0)
	v_mfma_f32_16x16x32_bf16 v[60:63], v[156:159], v[178:181], v[60:63]
	v_mfma_f32_16x16x32_bf16 v[56:59], v[170:173], v[178:181], v[56:59]
	v_mfma_f32_16x16x32_bf16 v[44:47], v[156:159], v[186:189], v[44:47]
	v_mfma_f32_16x16x32_bf16 v[40:43], v[170:173], v[186:189], v[40:43]
	v_mfma_f32_16x16x32_bf16 v[28:31], v[156:159], v[194:197], v[28:31]
	v_mfma_f32_16x16x32_bf16 v[24:27], v[170:173], v[194:197], v[24:27]
	v_mfma_f32_16x16x32_bf16 v[12:15], v[156:159], v[202:205], v[12:15]
	v_mfma_f32_16x16x32_bf16 v[8:11], v[170:173], v[202:205], v[8:11]
	v_mfma_f32_16x16x32_bf16 v[60:63], v[160:163], v[182:185], v[60:63]
	v_mfma_f32_16x16x32_bf16 v[56:59], v[174:177], v[182:185], v[56:59]
	v_mfma_f32_16x16x32_bf16 v[44:47], v[160:163], v[190:193], v[44:47]
	v_mfma_f32_16x16x32_bf16 v[40:43], v[174:177], v[190:193], v[40:43]
	v_mfma_f32_16x16x32_bf16 v[28:31], v[160:163], v[198:201], v[28:31]
	v_mfma_f32_16x16x32_bf16 v[24:27], v[174:177], v[198:201], v[24:27]
	v_mfma_f32_16x16x32_bf16 v[12:15], v[160:163], v[206:209], v[12:15]
	v_mfma_f32_16x16x32_bf16 v[8:11], v[174:177], v[206:209], v[8:11]
	s_setprio 0
	s_barrier
	s_add_u32 s44, s54, 0x40080
	s_addc_u32 s45, s55, 0
	s_add_i32 s43, s56, s60
	v_lshl_add_u64 v[146:147], s[44:45], 0, v[130:131]
	s_mov_b32 m0, s43
	s_nop 0
	global_load_lds_dwordx4 v[146:147], off
	v_lshl_add_u64 v[146:147], s[44:45], 0, v[134:135]
	s_add_i32 m0, s43, 0x2000
	s_nop 0
	global_load_lds_dwordx4 v[146:147], off
	s_waitcnt vmcnt(6)
	s_barrier
	s_setprio 1
	v_mfma_f32_16x16x32_bf16 v[52:55], v[210:213], v[178:181], v[52:55]
	v_mfma_f32_16x16x32_bf16 v[48:51], v[218:221], v[178:181], v[48:51]
	v_mfma_f32_16x16x32_bf16 v[36:39], v[210:213], v[186:189], v[36:39]
	v_mfma_f32_16x16x32_bf16 v[32:35], v[218:221], v[186:189], v[32:35]
	v_mfma_f32_16x16x32_bf16 v[20:23], v[210:213], v[194:197], v[20:23]
	v_mfma_f32_16x16x32_bf16 v[16:19], v[218:221], v[194:197], v[16:19]
	v_mfma_f32_16x16x32_bf16 v[4:7], v[210:213], v[202:205], v[4:7]
	v_mfma_f32_16x16x32_bf16 v[0:3], v[218:221], v[202:205], v[0:3]
	v_mfma_f32_16x16x32_bf16 v[52:55], v[214:217], v[182:185], v[52:55]
	v_mfma_f32_16x16x32_bf16 v[48:51], v[222:225], v[182:185], v[48:51]
	v_mfma_f32_16x16x32_bf16 v[36:39], v[214:217], v[190:193], v[36:39]
	v_mfma_f32_16x16x32_bf16 v[32:35], v[222:225], v[190:193], v[32:35]
	v_mfma_f32_16x16x32_bf16 v[20:23], v[214:217], v[198:201], v[20:23]
	v_mfma_f32_16x16x32_bf16 v[16:19], v[222:225], v[198:201], v[16:19]
	v_mfma_f32_16x16x32_bf16 v[4:7], v[214:217], v[206:209], v[4:7]
	v_mfma_f32_16x16x32_bf16 v[0:3], v[222:225], v[206:209], v[0:3]
	s_setprio 0
	s_add_i32 s42, s42, 2
	s_add_u32 s33, s33, 0x100
	s_addc_u32 s39, s39, 0
	s_add_u32 s40, s40, 0x100
	s_addc_u32 s41, s41, 0
	s_cmp_gt_u32 s42, 13
	s_barrier
	s_cbranch_scc0 .LBB0_958
	v_lshl_add_u32 v146, s75, 8, v148
	v_ashrrev_i32_e32 v147, 31, v146
	v_lshlrev_b64 v[156:157], 6, v[146:147]
	v_lshl_add_u64 v[164:165], s[26:27], 0, v[156:157]
	v_subrev_u32_e32 v180, s26, v164
	v_add_u32_e32 v181, 0x0, v180
	global_load_dwordx4 v[182:185], v181, s[26:27]
	v_add_u32_e32 v181, 0x10, v180
	global_load_dwordx4 v[186:189], v181, s[26:27]
	v_add_u32_e32 v181, 0x20, v180
	global_load_dwordx4 v[190:193], v181, s[26:27]
	v_add_u32_e32 v181, 0x30, v180
	global_load_dwordx4 v[194:197], v181, s[26:27]
	v_add_u32_e32 v181, 0x400, v180
	global_load_dwordx4 v[198:201], v181, s[26:27]
	v_add_u32_e32 v181, 0x410, v180
	global_load_dwordx4 v[202:205], v181, s[26:27]
	v_add_u32_e32 v181, 0x420, v180
	global_load_dwordx4 v[206:209], v181, s[26:27]
	v_add_u32_e32 v181, 0x430, v180
	global_load_dwordx4 v[210:213], v181, s[26:27]
	v_add_u32_e32 v181, 0x800, v180
	global_load_dwordx4 v[214:217], v181, s[26:27]
	v_add_u32_e32 v181, 0x810, v180
	global_load_dwordx4 v[218:221], v181, s[26:27]
	v_add_u32_e32 v181, 0x820, v180
	global_load_dwordx4 v[222:225], v181, s[26:27]
	v_add_u32_e32 v181, 0x830, v180
	global_load_dwordx4 v[232:235], v181, s[26:27]
	v_add_u32_e32 v181, 0xc00, v180
	global_load_dwordx4 v[236:239], v181, s[26:27]
	v_add_u32_e32 v181, 0xc10, v180
	global_load_dwordx4 v[240:243], v181, s[26:27]
	v_add_u32_e32 v181, 0xc20, v180
	global_load_dwordx4 v[244:247], v181, s[26:27]
	v_add_u32_e32 v181, 0xc30, v180
	global_load_dwordx4 v[248:251], v181, s[26:27]
	v_or_b32_e32 v164, 16, v146
	v_lshl_or_b32 v147, s6, 9, v150
	v_ashrrev_i32_e32 v165, 31, v164
	v_lshl_add_u32 v155, v146, 13, v147
	s_waitcnt vmcnt(12)
; __device__ __forceinline__ u32x4 pack8(const f32x4 v0, const f32x4 v1) { u32x4 w; w.x = pk2(v0[0], v0[1]); w.y = pk2(v0[2], v0[3]); w.z = pk2(v1[0], v1[1]); w.w = pk2(v1[2], v1[3]); return w; }
; __device__ __forceinline__ float row_rstd(const float* ssq, int row) {
;     const f32x4* p = (const f32x4*)(ssq + (size_t)row * 16);
;     const f32x4 a = p[0], b = p[1], c = p[2], d = p[3];
;     const float s = ((a[0] + a[1]) + (a[2] + a[3])) + ((b[0] + b[1]) + (b[2] + b[3])) + ((c[0] + c[1]) + (c[2] + c[3])) + ((d[0] + d[1]) + (d[2] + d[3]));
;     return rsqrtf(s * (1.0f / 1024.0f) + 1e-6f);
;     __device__ __forceinline__ void operator()(const f32x4 (&acc)[2][2][4][2], const Unit& u, int wr, int wc, int fr, int fq) const {
;     ...
;                 const int row = row0 + ai * 128 + m * 16; const float rs = row_rstd(ssq, row);
; #pragma unroll
;                 for (int bj = 0; bj < 2; ++bj) { f32x4 v0 = acc[ai][bj][m][0] * rs, v1 = acc[ai][bj][m][1] * rs;
; #pragma unroll
;                     for (int j = 0; j < 4; ++j) { const float a = fmaxf(v0[j], 0.f), b = fmaxf(v1[j], 0.f); v0[j] = a * a; v1[j] = b * b; }
;                     __builtin_amdgcn_raw_buffer_store_b128(pack8(v0, v1), rsrc, (unsigned)(((size_t)row * DFF + col0 + bj * 128) * 2), 0, 16  ); }
	v_pk_add_f32 v[156:157], v[182:183], v[184:185]
	v_pk_add_f32 v[158:159], v[186:187], v[188:189]
	v_pk_add_f32 v[160:161], v[190:191], v[192:193]
	v_pk_add_f32 v[162:163], v[194:195], v[196:197]
	v_pk_add_f32 v[156:157], v[156:157], v[158:159]
	v_pk_add_f32 v[160:161], v[160:161], v[162:163]
	v_pk_add_f32 v[156:157], v[156:157], v[160:161]
	v_add_f32_e32 v156, v156, v157
	s_nop 0
	s_nop 0
	v_fmamk_f32 v156, v156, 0x3a800000, v154
	v_mul_f32_e32 v157, 0x4b800000, v156
	v_cmp_gt_f32_e32 vcc, s71, v156
	s_nop 1
	v_cndmask_b32_e32 v156, v156, v157, vcc
	v_rsq_f32_e32 v158, v156
	v_lshlrev_b64 v[156:157], 6, v[164:165]
	v_lshl_add_u64 v[156:157], s[26:27], 0, v[156:157]
	v_mul_f32_e32 v159, 0x45800000, v158
	v_cndmask_b32_e32 v158, v158, v159, vcc
	v_pk_mul_f32 v[126:127], v[126:127], v[158:159] op_sel_hi:[1,0]
	v_pk_mul_f32 v[124:125], v[124:125], v[158:159] op_sel_hi:[1,0]
	v_pk_mul_f32 v[122:123], v[122:123], v[158:159] op_sel_hi:[1,0]
	v_pk_mul_f32 v[120:121], v[120:121], v[158:159] op_sel_hi:[1,0]
	v_pk_mul_f32 v[114:115], v[114:115], v[158:159] op_sel_hi:[1,0]
	v_pk_mul_f32 v[112:113], v[112:113], v[158:159] op_sel_hi:[1,0]
	v_pk_mul_f32 v[118:119], v[118:119], v[158:159] op_sel_hi:[1,0]
	v_pk_mul_f32 v[116:117], v[116:117], v[158:159] op_sel_hi:[1,0]
	v_max_f32_e32 v124, 0, v124
	v_max_f32_e32 v120, 0, v120
	v_max_f32_e32 v125, 0, v125
	v_max_f32_e32 v121, 0, v121
	v_max_f32_e32 v126, 0, v126
	v_max_f32_e32 v122, 0, v122
	v_max_f32_e32 v127, 0, v127
	v_max_f32_e32 v123, 0, v123
	v_max_f32_e32 v112, 0, v112
	v_max_f32_e32 v113, 0, v113
	v_max_f32_e32 v114, 0, v114
	v_max_f32_e32 v115, 0, v115
	v_max_f32_e32 v116, 0, v116
	v_max_f32_e32 v117, 0, v117
	v_max_f32_e32 v118, 0, v118
	v_max_f32_e32 v119, 0, v119
	v_pk_mul_f32 v[124:125], v[124:125], v[124:125]
	v_pk_mul_f32 v[120:121], v[120:121], v[120:121]
	v_pk_mul_f32 v[126:127], v[126:127], v[126:127]
	v_pk_mul_f32 v[122:123], v[122:123], v[122:123]
	v_pk_mul_f32 v[158:159], v[112:113], v[112:113]
	v_pk_mul_f32 v[160:161], v[114:115], v[114:115]
	v_cvt_pk_bf16_f32 v112, v124, v125
	v_cvt_pk_bf16_f32 v113, v126, v127
	v_cvt_pk_bf16_f32 v114, v120, v121
	v_cvt_pk_bf16_f32 v115, v122, v123
	v_pk_mul_f32 v[116:117], v[116:117], v[116:117]
	v_pk_mul_f32 v[118:119], v[118:119], v[118:119]
	buffer_store_dwordx4 v[112:115], v155, s[16:19], 0 offen sc1
	s_nop 1
	v_cvt_pk_bf16_f32 v112, v116, v117
	v_cvt_pk_bf16_f32 v113, v118, v119
	v_cvt_pk_bf16_f32 v114, v158, v159
	v_cvt_pk_bf16_f32 v115, v160, v161
	buffer_store_dwordx4 v[112:115], v155, s[16:19], 0 offen offset:256 sc1
	s_nop 0
	v_or_b32_e32 v156, 32, v146
	v_ashrrev_i32_e32 v157, 31, v156
	v_lshl_add_u32 v155, v164, 13, v147
	v_add_u32_e32 v181, 0x2000, v180
	global_load_dwordx4 v[182:185], v181, s[26:27]
	v_add_u32_e32 v181, 0x2010, v180
	global_load_dwordx4 v[186:189], v181, s[26:27]
	v_add_u32_e32 v181, 0x2020, v180
	global_load_dwordx4 v[190:193], v181, s[26:27]
	v_add_u32_e32 v181, 0x2030, v180
	global_load_dwordx4 v[194:197], v181, s[26:27]
	s_waitcnt vmcnt(14)
	v_pk_add_f32 v[112:113], v[198:199], v[200:201]
	v_pk_add_f32 v[114:115], v[202:203], v[204:205]
	v_pk_add_f32 v[116:117], v[206:207], v[208:209]
	v_pk_add_f32 v[118:119], v[210:211], v[212:213]
	v_pk_add_f32 v[112:113], v[112:113], v[114:115]
	v_pk_add_f32 v[116:117], v[116:117], v[118:119]
	v_pk_add_f32 v[112:113], v[112:113], v[116:117]
	v_add_f32_e32 v112, v112, v113
	s_nop 0
	s_nop 0
	v_fmamk_f32 v112, v112, 0x3a800000, v154
	v_mul_f32_e32 v113, 0x4b800000, v112
	v_cmp_gt_f32_e32 vcc, s71, v112
	s_nop 1
	v_cndmask_b32_e32 v112, v112, v113, vcc
	v_rsq_f32_e32 v114, v112
	v_lshlrev_b64 v[112:113], 6, v[156:157]
	v_lshl_add_u64 v[112:113], s[26:27], 0, v[112:113]
	v_mul_f32_e32 v115, 0x45800000, v114
	v_cndmask_b32_e32 v114, v114, v115, vcc
	v_pk_mul_f32 v[110:111], v[110:111], v[114:115] op_sel_hi:[1,0]
	v_pk_mul_f32 v[108:109], v[108:109], v[114:115] op_sel_hi:[1,0]
	v_pk_mul_f32 v[106:107], v[106:107], v[114:115] op_sel_hi:[1,0]
	v_pk_mul_f32 v[104:105], v[104:105], v[114:115] op_sel_hi:[1,0]
	v_pk_mul_f32 v[98:99], v[98:99], v[114:115] op_sel_hi:[1,0]
	v_pk_mul_f32 v[96:97], v[96:97], v[114:115] op_sel_hi:[1,0]
	v_pk_mul_f32 v[102:103], v[102:103], v[114:115] op_sel_hi:[1,0]
	v_pk_mul_f32 v[100:101], v[100:101], v[114:115] op_sel_hi:[1,0]
	v_max_f32_e32 v108, 0, v108
	v_max_f32_e32 v104, 0, v104
	v_max_f32_e32 v109, 0, v109
	v_max_f32_e32 v105, 0, v105
	v_max_f32_e32 v110, 0, v110
	v_max_f32_e32 v106, 0, v106
	v_max_f32_e32 v111, 0, v111
	v_max_f32_e32 v107, 0, v107
	v_max_f32_e32 v96, 0, v96
	v_max_f32_e32 v97, 0, v97
	v_max_f32_e32 v98, 0, v98
	v_max_f32_e32 v99, 0, v99
	v_max_f32_e32 v100, 0, v100
	v_max_f32_e32 v101, 0, v101
	v_max_f32_e32 v102, 0, v102
	v_max_f32_e32 v103, 0, v103
	v_pk_mul_f32 v[108:109], v[108:109], v[108:109]
	v_pk_mul_f32 v[104:105], v[104:105], v[104:105]
	v_pk_mul_f32 v[110:111], v[110:111], v[110:111]
	v_pk_mul_f32 v[106:107], v[106:107], v[106:107]
	v_pk_mul_f32 v[114:115], v[96:97], v[96:97]
	v_pk_mul_f32 v[116:117], v[98:99], v[98:99]
	v_cvt_pk_bf16_f32 v96, v108, v109
	v_cvt_pk_bf16_f32 v97, v110, v111
	v_cvt_pk_bf16_f32 v98, v104, v105
	v_cvt_pk_bf16_f32 v99, v106, v107
	v_pk_mul_f32 v[100:101], v[100:101], v[100:101]
	v_pk_mul_f32 v[102:103], v[102:103], v[102:103]
	buffer_store_dwordx4 v[96:99], v155, s[16:19], 0 offen sc1
	s_nop 1
	v_cvt_pk_bf16_f32 v96, v100, v101
	v_cvt_pk_bf16_f32 v97, v102, v103
	v_cvt_pk_bf16_f32 v98, v114, v115
	v_cvt_pk_bf16_f32 v99, v116, v117
	buffer_store_dwordx4 v[96:99], v155, s[16:19], 0 offen offset:256 sc1
	s_nop 0
	v_or_b32_e32 v112, 48, v146
	v_ashrrev_i32_e32 v113, 31, v112
	v_lshl_add_u32 v116, v156, 13, v147
	v_add_u32_e32 v181, 0x2400, v180
	global_load_dwordx4 v[198:201], v181, s[26:27]
	v_add_u32_e32 v181, 0x2410, v180
	global_load_dwordx4 v[202:205], v181, s[26:27]
	v_add_u32_e32 v181, 0x2420, v180
	global_load_dwordx4 v[206:209], v181, s[26:27]
	v_add_u32_e32 v181, 0x2430, v180
	global_load_dwordx4 v[210:213], v181, s[26:27]
	s_waitcnt vmcnt(16)
; __device__ __forceinline__ u32x4 pack8(const f32x4 v0, const f32x4 v1) { u32x4 w; w.x = pk2(v0[0], v0[1]); w.y = pk2(v0[2], v0[3]); w.z = pk2(v1[0], v1[1]); w.w = pk2(v1[2], v1[3]); return w; }
; __device__ __forceinline__ float row_rstd(const float* ssq, int row) {
;     const f32x4* p = (const f32x4*)(ssq + (size_t)row * 16);
;     const f32x4 a = p[0], b = p[1], c = p[2], d = p[3];
;     const float s = ((a[0] + a[1]) + (a[2] + a[3])) + ((b[0] + b[1]) + (b[2] + b[3])) + ((c[0] + c[1]) + (c[2] + c[3])) + ((d[0] + d[1]) + (d[2] + d[3]));
;     return rsqrtf(s * (1.0f / 1024.0f) + 1e-6f);
;     __device__ __forceinline__ void operator()(const f32x4 (&acc)[2][2][4][2], const Unit& u, int wr, int wc, int fr, int fq) const {
;     ...
;                 const int row = row0 + ai * 128 + m * 16; const float rs = row_rstd(ssq, row);
; #pragma unroll
;                 for (int bj = 0; bj < 2; ++bj) { f32x4 v0 = acc[ai][bj][m][0] * rs, v1 = acc[ai][bj][m][1] * rs;
; #pragma unroll
;                     for (int j = 0; j < 4; ++j) { const float a = fmaxf(v0[j], 0.f), b = fmaxf(v1[j], 0.f); v0[j] = a * a; v1[j] = b * b; }
;                     __builtin_amdgcn_raw_buffer_store_b128(pack8(v0, v1), rsrc, (unsigned)(((size_t)row * DFF + col0 + bj * 128) * 2), 0, 16  ); }
	v_pk_add_f32 v[96:97], v[214:215], v[216:217]
	v_pk_add_f32 v[98:99], v[218:219], v[220:221]
	v_pk_add_f32 v[100:101], v[222:223], v[224:225]
	v_pk_add_f32 v[102:103], v[232:233], v[234:235]
	v_pk_add_f32 v[96:97], v[96:97], v[98:99]
	v_pk_add_f32 v[100:101], v[100:101], v[102:103]
	v_pk_add_f32 v[96:97], v[96:97], v[100:101]
	v_add_f32_e32 v96, v96, v97
	s_nop 0
	s_nop 0
	v_fmamk_f32 v96, v96, 0x3a800000, v154
	v_mul_f32_e32 v97, 0x4b800000, v96
	v_cmp_gt_f32_e32 vcc, s71, v96
	s_nop 1
	v_cndmask_b32_e32 v96, v96, v97, vcc
	v_rsq_f32_e32 v98, v96
	v_lshlrev_b64 v[96:97], 6, v[112:113]
	v_lshl_add_u64 v[96:97], s[26:27], 0, v[96:97]
	v_mul_f32_e32 v99, 0x45800000, v98
	v_cndmask_b32_e32 v98, v98, v99, vcc
	v_pk_mul_f32 v[94:95], v[94:95], v[98:99] op_sel_hi:[1,0]
	v_pk_mul_f32 v[92:93], v[92:93], v[98:99] op_sel_hi:[1,0]
	v_pk_mul_f32 v[90:91], v[90:91], v[98:99] op_sel_hi:[1,0]
	v_pk_mul_f32 v[88:89], v[88:89], v[98:99] op_sel_hi:[1,0]
	v_pk_mul_f32 v[82:83], v[82:83], v[98:99] op_sel_hi:[1,0]
	v_pk_mul_f32 v[80:81], v[80:81], v[98:99] op_sel_hi:[1,0]
	v_pk_mul_f32 v[86:87], v[86:87], v[98:99] op_sel_hi:[1,0]
	v_pk_mul_f32 v[84:85], v[84:85], v[98:99] op_sel_hi:[1,0]
	v_max_f32_e32 v92, 0, v92
	v_max_f32_e32 v88, 0, v88
	v_max_f32_e32 v93, 0, v93
	v_max_f32_e32 v89, 0, v89
	v_max_f32_e32 v94, 0, v94
	v_max_f32_e32 v90, 0, v90
	v_max_f32_e32 v95, 0, v95
	v_max_f32_e32 v91, 0, v91
	v_max_f32_e32 v80, 0, v80
	v_max_f32_e32 v81, 0, v81
	v_max_f32_e32 v82, 0, v82
	v_max_f32_e32 v83, 0, v83
	v_max_f32_e32 v84, 0, v84
	v_max_f32_e32 v85, 0, v85
	v_max_f32_e32 v86, 0, v86
	v_max_f32_e32 v87, 0, v87
	v_pk_mul_f32 v[92:93], v[92:93], v[92:93]
	v_pk_mul_f32 v[88:89], v[88:89], v[88:89]
	v_pk_mul_f32 v[94:95], v[94:95], v[94:95]
	v_pk_mul_f32 v[90:91], v[90:91], v[90:91]
	v_pk_mul_f32 v[98:99], v[80:81], v[80:81]
	v_pk_mul_f32 v[100:101], v[82:83], v[82:83]
	v_cvt_pk_bf16_f32 v80, v92, v93
	v_cvt_pk_bf16_f32 v81, v94, v95
	v_cvt_pk_bf16_f32 v82, v88, v89
	v_cvt_pk_bf16_f32 v83, v90, v91
	v_pk_mul_f32 v[84:85], v[84:85], v[84:85]
	v_pk_mul_f32 v[86:87], v[86:87], v[86:87]
	buffer_store_dwordx4 v[80:83], v116, s[16:19], 0 offen sc1
	s_nop 1
	v_cvt_pk_bf16_f32 v80, v84, v85
	v_cvt_pk_bf16_f32 v81, v86, v87
	v_cvt_pk_bf16_f32 v82, v98, v99
	v_cvt_pk_bf16_f32 v83, v100, v101
	buffer_store_dwordx4 v[80:83], v116, s[16:19], 0 offen offset:256 sc1
	s_nop 0
	v_add_u32_e32 v96, 0x80, v146
	v_ashrrev_i32_e32 v97, 31, v96
	v_lshl_add_u32 v100, v112, 13, v147
	v_add_u32_e32 v181, 0x2800, v180
	global_load_dwordx4 v[214:217], v181, s[26:27]
	v_add_u32_e32 v181, 0x2810, v180
	global_load_dwordx4 v[218:221], v181, s[26:27]
	v_add_u32_e32 v181, 0x2820, v180
	global_load_dwordx4 v[222:225], v181, s[26:27]
	v_add_u32_e32 v181, 0x2830, v180
	global_load_dwordx4 v[232:235], v181, s[26:27]
	s_waitcnt vmcnt(18)
	v_pk_add_f32 v[80:81], v[236:237], v[238:239]
	v_pk_add_f32 v[82:83], v[240:241], v[242:243]
	v_pk_add_f32 v[84:85], v[244:245], v[246:247]
	v_pk_add_f32 v[86:87], v[248:249], v[250:251]
	v_pk_add_f32 v[80:81], v[80:81], v[82:83]
	v_pk_add_f32 v[84:85], v[84:85], v[86:87]
	v_pk_add_f32 v[80:81], v[80:81], v[84:85]
	v_add_f32_e32 v80, v80, v81
	s_nop 0
	s_nop 0
	v_fmamk_f32 v80, v80, 0x3a800000, v154
	v_mul_f32_e32 v81, 0x4b800000, v80
	v_cmp_gt_f32_e32 vcc, s71, v80
	s_nop 1
	v_cndmask_b32_e32 v80, v80, v81, vcc
	v_rsq_f32_e32 v82, v80
	v_lshlrev_b64 v[80:81], 6, v[96:97]
	v_lshl_add_u64 v[80:81], s[26:27], 0, v[80:81]
	v_mul_f32_e32 v83, 0x45800000, v82
	v_cndmask_b32_e32 v82, v82, v83, vcc
	v_pk_mul_f32 v[78:79], v[78:79], v[82:83] op_sel_hi:[1,0]
	v_pk_mul_f32 v[76:77], v[76:77], v[82:83] op_sel_hi:[1,0]
	v_pk_mul_f32 v[74:75], v[74:75], v[82:83] op_sel_hi:[1,0]
	v_pk_mul_f32 v[72:73], v[72:73], v[82:83] op_sel_hi:[1,0]
	v_pk_mul_f32 v[66:67], v[66:67], v[82:83] op_sel_hi:[1,0]
	v_pk_mul_f32 v[64:65], v[64:65], v[82:83] op_sel_hi:[1,0]
	v_pk_mul_f32 v[70:71], v[70:71], v[82:83] op_sel_hi:[1,0]
	v_pk_mul_f32 v[68:69], v[68:69], v[82:83] op_sel_hi:[1,0]
	v_max_f32_e32 v76, 0, v76
	v_max_f32_e32 v72, 0, v72
	v_max_f32_e32 v77, 0, v77
	v_max_f32_e32 v73, 0, v73
	v_max_f32_e32 v78, 0, v78
	v_max_f32_e32 v74, 0, v74
	v_max_f32_e32 v79, 0, v79
	v_max_f32_e32 v75, 0, v75
	v_max_f32_e32 v64, 0, v64
	v_max_f32_e32 v65, 0, v65
	v_max_f32_e32 v66, 0, v66
	v_max_f32_e32 v67, 0, v67
	v_max_f32_e32 v68, 0, v68
	v_max_f32_e32 v69, 0, v69
	v_max_f32_e32 v70, 0, v70
	v_max_f32_e32 v71, 0, v71
	v_pk_mul_f32 v[76:77], v[76:77], v[76:77]
	v_pk_mul_f32 v[72:73], v[72:73], v[72:73]
	v_pk_mul_f32 v[78:79], v[78:79], v[78:79]
	v_pk_mul_f32 v[74:75], v[74:75], v[74:75]
	v_pk_mul_f32 v[82:83], v[64:65], v[64:65]
	v_pk_mul_f32 v[84:85], v[66:67], v[66:67]
	v_cvt_pk_bf16_f32 v64, v76, v77
	v_cvt_pk_bf16_f32 v65, v78, v79
	v_cvt_pk_bf16_f32 v66, v72, v73
	v_cvt_pk_bf16_f32 v67, v74, v75
	v_pk_mul_f32 v[68:69], v[68:69], v[68:69]
	v_pk_mul_f32 v[70:71], v[70:71], v[70:71]
	buffer_store_dwordx4 v[64:67], v100, s[16:19], 0 offen sc1
	s_nop 1
	v_cvt_pk_bf16_f32 v64, v68, v69
	v_cvt_pk_bf16_f32 v65, v70, v71
	v_cvt_pk_bf16_f32 v66, v82, v83
	v_cvt_pk_bf16_f32 v67, v84, v85
	buffer_store_dwordx4 v[64:67], v100, s[16:19], 0 offen offset:256 sc1
	s_nop 0
	v_add_u32_e32 v80, 0x90, v146
	v_ashrrev_i32_e32 v81, 31, v80
	v_lshl_add_u32 v84, v96, 13, v147
	v_add_u32_e32 v181, 0x2c00, v180
	global_load_dwordx4 v[236:239], v181, s[26:27]
	v_add_u32_e32 v181, 0x2c10, v180
	global_load_dwordx4 v[240:243], v181, s[26:27]
	v_add_u32_e32 v181, 0x2c20, v180
	global_load_dwordx4 v[244:247], v181, s[26:27]
	v_add_u32_e32 v181, 0x2c30, v180
	global_load_dwordx4 v[248:251], v181, s[26:27]
	s_waitcnt vmcnt(18)
; __device__ __forceinline__ u32x4 pack8(const f32x4 v0, const f32x4 v1) { u32x4 w; w.x = pk2(v0[0], v0[1]); w.y = pk2(v0[2], v0[3]); w.z = pk2(v1[0], v1[1]); w.w = pk2(v1[2], v1[3]); return w; }
; __device__ __forceinline__ float row_rstd(const float* ssq, int row) {
;     const f32x4* p = (const f32x4*)(ssq + (size_t)row * 16);
;     const f32x4 a = p[0], b = p[1], c = p[2], d = p[3];
;     const float s = ((a[0] + a[1]) + (a[2] + a[3])) + ((b[0] + b[1]) + (b[2] + b[3])) + ((c[0] + c[1]) + (c[2] + c[3])) + ((d[0] + d[1]) + (d[2] + d[3]));
;     return rsqrtf(s * (1.0f / 1024.0f) + 1e-6f);
;     __device__ __forceinline__ void operator()(const f32x4 (&acc)[2][2][4][2], const Unit& u, int wr, int wc, int fr, int fq) const {
;     ...
;                 const int row = row0 + ai * 128 + m * 16; const float rs = row_rstd(ssq, row);
; #pragma unroll
;                 for (int bj = 0; bj < 2; ++bj) { f32x4 v0 = acc[ai][bj][m][0] * rs, v1 = acc[ai][bj][m][1] * rs;
; #pragma unroll
;                     for (int j = 0; j < 4; ++j) { const float a = fmaxf(v0[j], 0.f), b = fmaxf(v1[j], 0.f); v0[j] = a * a; v1[j] = b * b; }
;                     __builtin_amdgcn_raw_buffer_store_b128(pack8(v0, v1), rsrc, (unsigned)(((size_t)row * DFF + col0 + bj * 128) * 2), 0, 16  ); }
	v_pk_add_f32 v[64:65], v[182:183], v[184:185]
	v_pk_add_f32 v[66:67], v[186:187], v[188:189]
	v_pk_add_f32 v[68:69], v[190:191], v[192:193]
	v_pk_add_f32 v[70:71], v[194:195], v[196:197]
	v_pk_add_f32 v[64:65], v[64:65], v[66:67]
	v_pk_add_f32 v[68:69], v[68:69], v[70:71]
	v_pk_add_f32 v[64:65], v[64:65], v[68:69]
	v_add_f32_e32 v64, v64, v65
	s_nop 0
	s_nop 0
	v_fmamk_f32 v64, v64, 0x3a800000, v154
	v_mul_f32_e32 v65, 0x4b800000, v64
	v_cmp_gt_f32_e32 vcc, s71, v64
	s_nop 1
	v_cndmask_b32_e32 v64, v64, v65, vcc
	v_rsq_f32_e32 v66, v64
	v_lshlrev_b64 v[64:65], 6, v[80:81]
	v_lshl_add_u64 v[64:65], s[26:27], 0, v[64:65]
	v_mul_f32_e32 v67, 0x45800000, v66
	v_cndmask_b32_e32 v66, v66, v67, vcc
	v_pk_mul_f32 v[62:63], v[62:63], v[66:67] op_sel_hi:[1,0]
	v_pk_mul_f32 v[60:61], v[60:61], v[66:67] op_sel_hi:[1,0]
	v_pk_mul_f32 v[58:59], v[58:59], v[66:67] op_sel_hi:[1,0]
	v_pk_mul_f32 v[56:57], v[56:57], v[66:67] op_sel_hi:[1,0]
	v_pk_mul_f32 v[50:51], v[50:51], v[66:67] op_sel_hi:[1,0]
	v_pk_mul_f32 v[48:49], v[48:49], v[66:67] op_sel_hi:[1,0]
	v_pk_mul_f32 v[54:55], v[54:55], v[66:67] op_sel_hi:[1,0]
	v_pk_mul_f32 v[52:53], v[52:53], v[66:67] op_sel_hi:[1,0]
	v_max_f32_e32 v60, 0, v60
	v_max_f32_e32 v56, 0, v56
	v_max_f32_e32 v61, 0, v61
	v_max_f32_e32 v57, 0, v57
	v_max_f32_e32 v62, 0, v62
	v_max_f32_e32 v58, 0, v58
	v_max_f32_e32 v63, 0, v63
	v_max_f32_e32 v59, 0, v59
	v_max_f32_e32 v48, 0, v48
	v_max_f32_e32 v49, 0, v49
	v_max_f32_e32 v50, 0, v50
	v_max_f32_e32 v51, 0, v51
	v_max_f32_e32 v52, 0, v52
	v_max_f32_e32 v53, 0, v53
	v_max_f32_e32 v54, 0, v54
	v_max_f32_e32 v55, 0, v55
	v_pk_mul_f32 v[60:61], v[60:61], v[60:61]
	v_pk_mul_f32 v[56:57], v[56:57], v[56:57]
	v_pk_mul_f32 v[62:63], v[62:63], v[62:63]
	v_pk_mul_f32 v[58:59], v[58:59], v[58:59]
	v_pk_mul_f32 v[66:67], v[48:49], v[48:49]
	v_pk_mul_f32 v[68:69], v[50:51], v[50:51]
	v_cvt_pk_bf16_f32 v48, v60, v61
	v_cvt_pk_bf16_f32 v49, v62, v63
	v_cvt_pk_bf16_f32 v50, v56, v57
	v_cvt_pk_bf16_f32 v51, v58, v59
	v_pk_mul_f32 v[52:53], v[52:53], v[52:53]
	v_pk_mul_f32 v[54:55], v[54:55], v[54:55]
	buffer_store_dwordx4 v[48:51], v84, s[16:19], 0 offen sc1
	s_nop 1
	v_cvt_pk_bf16_f32 v48, v52, v53
	v_cvt_pk_bf16_f32 v49, v54, v55
	v_cvt_pk_bf16_f32 v50, v66, v67
	v_cvt_pk_bf16_f32 v51, v68, v69
	buffer_store_dwordx4 v[48:51], v84, s[16:19], 0 offen offset:256 sc1
	s_nop 0
	v_add_u32_e32 v64, 0xa0, v146
	v_ashrrev_i32_e32 v65, 31, v64
	v_lshl_add_u32 v68, v80, 13, v147
	s_waitcnt vmcnt(14)
	v_pk_add_f32 v[48:49], v[198:199], v[200:201]
	v_pk_add_f32 v[50:51], v[202:203], v[204:205]
	v_pk_add_f32 v[52:53], v[206:207], v[208:209]
	v_pk_add_f32 v[54:55], v[210:211], v[212:213]
	v_pk_add_f32 v[48:49], v[48:49], v[50:51]
	v_pk_add_f32 v[52:53], v[52:53], v[54:55]
	v_pk_add_f32 v[48:49], v[48:49], v[52:53]
	v_add_f32_e32 v48, v48, v49
	s_nop 0
	s_nop 0
	v_fmamk_f32 v48, v48, 0x3a800000, v154
	v_mul_f32_e32 v49, 0x4b800000, v48
	v_cmp_gt_f32_e32 vcc, s71, v48
	s_nop 1
	v_cndmask_b32_e32 v48, v48, v49, vcc
	v_rsq_f32_e32 v50, v48
	v_lshlrev_b64 v[48:49], 6, v[64:65]
	v_lshl_add_u64 v[48:49], s[26:27], 0, v[48:49]
	v_mul_f32_e32 v51, 0x45800000, v50
	v_cndmask_b32_e32 v50, v50, v51, vcc
	v_pk_mul_f32 v[46:47], v[46:47], v[50:51] op_sel_hi:[1,0]
	v_pk_mul_f32 v[44:45], v[44:45], v[50:51] op_sel_hi:[1,0]
	v_pk_mul_f32 v[42:43], v[42:43], v[50:51] op_sel_hi:[1,0]
	v_pk_mul_f32 v[40:41], v[40:41], v[50:51] op_sel_hi:[1,0]
	v_pk_mul_f32 v[34:35], v[34:35], v[50:51] op_sel_hi:[1,0]
	v_pk_mul_f32 v[32:33], v[32:33], v[50:51] op_sel_hi:[1,0]
	v_pk_mul_f32 v[38:39], v[38:39], v[50:51] op_sel_hi:[1,0]
	v_pk_mul_f32 v[36:37], v[36:37], v[50:51] op_sel_hi:[1,0]
	v_max_f32_e32 v44, 0, v44
	v_max_f32_e32 v40, 0, v40
	v_max_f32_e32 v45, 0, v45
	v_max_f32_e32 v41, 0, v41
	v_max_f32_e32 v46, 0, v46
	v_max_f32_e32 v42, 0, v42
	v_max_f32_e32 v47, 0, v47
	v_max_f32_e32 v43, 0, v43
	v_max_f32_e32 v32, 0, v32
	v_max_f32_e32 v33, 0, v33
	v_max_f32_e32 v34, 0, v34
	v_max_f32_e32 v35, 0, v35
	v_max_f32_e32 v36, 0, v36
	v_max_f32_e32 v37, 0, v37
	v_max_f32_e32 v38, 0, v38
	v_max_f32_e32 v39, 0, v39
	v_pk_mul_f32 v[44:45], v[44:45], v[44:45]
	v_pk_mul_f32 v[40:41], v[40:41], v[40:41]
	v_pk_mul_f32 v[46:47], v[46:47], v[46:47]
	v_pk_mul_f32 v[42:43], v[42:43], v[42:43]
	v_pk_mul_f32 v[50:51], v[32:33], v[32:33]
	v_pk_mul_f32 v[52:53], v[34:35], v[34:35]
	v_cvt_pk_bf16_f32 v32, v44, v45
	v_cvt_pk_bf16_f32 v33, v46, v47
	v_cvt_pk_bf16_f32 v34, v40, v41
	v_cvt_pk_bf16_f32 v35, v42, v43
	v_pk_mul_f32 v[36:37], v[36:37], v[36:37]
	v_pk_mul_f32 v[38:39], v[38:39], v[38:39]
	buffer_store_dwordx4 v[32:35], v68, s[16:19], 0 offen sc1
	s_nop 1
	v_cvt_pk_bf16_f32 v32, v36, v37
	v_cvt_pk_bf16_f32 v33, v38, v39
	v_cvt_pk_bf16_f32 v34, v50, v51
	v_cvt_pk_bf16_f32 v35, v52, v53
	buffer_store_dwordx4 v[32:35], v68, s[16:19], 0 offen offset:256 sc1
	s_nop 0
	v_add_u32_e32 v48, 0xb0, v146
	v_ashrrev_i32_e32 v49, 31, v48
	v_lshl_add_u32 v52, v64, 13, v147
	s_waitcnt vmcnt(10)
; __device__ __forceinline__ u32x4 pack8(const f32x4 v0, const f32x4 v1) { u32x4 w; w.x = pk2(v0[0], v0[1]); w.y = pk2(v0[2], v0[3]); w.z = pk2(v1[0], v1[1]); w.w = pk2(v1[2], v1[3]); return w; }
; __device__ __forceinline__ float row_rstd(const float* ssq, int row) {
;     const f32x4* p = (const f32x4*)(ssq + (size_t)row * 16);
;     const f32x4 a = p[0], b = p[1], c = p[2], d = p[3];
;     const float s = ((a[0] + a[1]) + (a[2] + a[3])) + ((b[0] + b[1]) + (b[2] + b[3])) + ((c[0] + c[1]) + (c[2] + c[3])) + ((d[0] + d[1]) + (d[2] + d[3]));
;     return rsqrtf(s * (1.0f / 1024.0f) + 1e-6f);
;     __device__ __forceinline__ void operator()(const f32x4 (&acc)[2][2][4][2], const Unit& u, int wr, int wc, int fr, int fq) const {
;     ...
;                 const int row = row0 + ai * 128 + m * 16; const float rs = row_rstd(ssq, row);
; #pragma unroll
;                 for (int bj = 0; bj < 2; ++bj) { f32x4 v0 = acc[ai][bj][m][0] * rs, v1 = acc[ai][bj][m][1] * rs;
; #pragma unroll
;                     for (int j = 0; j < 4; ++j) { const float a = fmaxf(v0[j], 0.f), b = fmaxf(v1[j], 0.f); v0[j] = a * a; v1[j] = b * b; }
;                     __builtin_amdgcn_raw_buffer_store_b128(pack8(v0, v1), rsrc, (unsigned)(((size_t)row * DFF + col0 + bj * 128) * 2), 0, 16  ); }
;             }
;         asm volatile("s_waitcnt vmcnt(0)" ::: "memory");
;         if (fr == 0 && fq == 0) (void)__hip_atomic_fetch_add(ready + 64 * (pm_off + u.pm), 1u, __ATOMIC_RELAXED, __HIP_MEMORY_SCOPE_AGENT);
	v_pk_add_f32 v[32:33], v[214:215], v[216:217]
	v_pk_add_f32 v[34:35], v[218:219], v[220:221]
	v_pk_add_f32 v[36:37], v[222:223], v[224:225]
	v_pk_add_f32 v[38:39], v[232:233], v[234:235]
	v_pk_add_f32 v[32:33], v[32:33], v[34:35]
	v_pk_add_f32 v[36:37], v[36:37], v[38:39]
	v_pk_add_f32 v[32:33], v[32:33], v[36:37]
	v_add_f32_e32 v32, v32, v33
	s_nop 0
	s_nop 0
	v_fmamk_f32 v32, v32, 0x3a800000, v154
	v_mul_f32_e32 v33, 0x4b800000, v32
	v_cmp_gt_f32_e32 vcc, s71, v32
	s_nop 1
	v_cndmask_b32_e32 v32, v32, v33, vcc
	v_rsq_f32_e32 v34, v32
	v_lshlrev_b64 v[32:33], 6, v[48:49]
	v_lshl_add_u64 v[32:33], s[26:27], 0, v[32:33]
	v_mul_f32_e32 v35, 0x45800000, v34
	v_cndmask_b32_e32 v34, v34, v35, vcc
	v_pk_mul_f32 v[30:31], v[30:31], v[34:35] op_sel_hi:[1,0]
	v_pk_mul_f32 v[28:29], v[28:29], v[34:35] op_sel_hi:[1,0]
	v_pk_mul_f32 v[26:27], v[26:27], v[34:35] op_sel_hi:[1,0]
	v_pk_mul_f32 v[24:25], v[24:25], v[34:35] op_sel_hi:[1,0]
	v_pk_mul_f32 v[18:19], v[18:19], v[34:35] op_sel_hi:[1,0]
	v_pk_mul_f32 v[16:17], v[16:17], v[34:35] op_sel_hi:[1,0]
	v_pk_mul_f32 v[22:23], v[22:23], v[34:35] op_sel_hi:[1,0]
	v_pk_mul_f32 v[20:21], v[20:21], v[34:35] op_sel_hi:[1,0]
	v_max_f32_e32 v28, 0, v28
	v_max_f32_e32 v24, 0, v24
	v_max_f32_e32 v29, 0, v29
	v_max_f32_e32 v25, 0, v25
	v_max_f32_e32 v30, 0, v30
	v_max_f32_e32 v26, 0, v26
	v_max_f32_e32 v31, 0, v31
	v_max_f32_e32 v27, 0, v27
	v_max_f32_e32 v16, 0, v16
	v_max_f32_e32 v17, 0, v17
	v_max_f32_e32 v18, 0, v18
	v_max_f32_e32 v19, 0, v19
	v_max_f32_e32 v20, 0, v20
	v_max_f32_e32 v21, 0, v21
	v_max_f32_e32 v22, 0, v22
	v_max_f32_e32 v23, 0, v23
	v_pk_mul_f32 v[28:29], v[28:29], v[28:29]
	v_pk_mul_f32 v[24:25], v[24:25], v[24:25]
	v_pk_mul_f32 v[30:31], v[30:31], v[30:31]
	v_pk_mul_f32 v[26:27], v[26:27], v[26:27]
	v_pk_mul_f32 v[34:35], v[16:17], v[16:17]
	v_pk_mul_f32 v[36:37], v[18:19], v[18:19]
	v_cvt_pk_bf16_f32 v16, v28, v29
	v_cvt_pk_bf16_f32 v17, v30, v31
	v_cvt_pk_bf16_f32 v18, v24, v25
	v_cvt_pk_bf16_f32 v19, v26, v27
	v_pk_mul_f32 v[20:21], v[20:21], v[20:21]
	v_pk_mul_f32 v[22:23], v[22:23], v[22:23]
	buffer_store_dwordx4 v[16:19], v52, s[16:19], 0 offen sc1
	s_nop 1
	v_cvt_pk_bf16_f32 v16, v20, v21
	v_cvt_pk_bf16_f32 v17, v22, v23
	v_cvt_pk_bf16_f32 v18, v34, v35
	v_cvt_pk_bf16_f32 v19, v36, v37
	buffer_store_dwordx4 v[16:19], v52, s[16:19], 0 offen offset:256 sc1
	s_nop 0
	s_waitcnt vmcnt(6)
	v_pk_add_f32 v[16:17], v[236:237], v[238:239]
	v_pk_add_f32 v[18:19], v[240:241], v[242:243]
	v_pk_add_f32 v[20:21], v[244:245], v[246:247]
	v_pk_add_f32 v[22:23], v[248:249], v[250:251]
	v_pk_add_f32 v[16:17], v[16:17], v[18:19]
	v_pk_add_f32 v[20:21], v[20:21], v[22:23]
	v_pk_add_f32 v[16:17], v[16:17], v[20:21]
	v_add_f32_e32 v16, v16, v17
	s_nop 0
	s_nop 0
	v_fmamk_f32 v16, v16, 0x3a800000, v154
	v_mul_f32_e32 v17, 0x4b800000, v16
	v_cmp_gt_f32_e32 vcc, s71, v16
	s_nop 1
	v_cndmask_b32_e32 v16, v16, v17, vcc
	v_rsq_f32_e32 v16, v16
	v_lshl_add_u32 v17, v48, 13, v147
	v_mul_f32_e32 v18, 0x45800000, v16
	v_cndmask_b32_e32 v16, v16, v18, vcc
	v_pk_mul_f32 v[14:15], v[14:15], v[16:17] op_sel_hi:[1,0]
	v_pk_mul_f32 v[12:13], v[12:13], v[16:17] op_sel_hi:[1,0]
	v_pk_mul_f32 v[10:11], v[10:11], v[16:17] op_sel_hi:[1,0]
	v_pk_mul_f32 v[8:9], v[8:9], v[16:17] op_sel_hi:[1,0]
	v_pk_mul_f32 v[2:3], v[2:3], v[16:17] op_sel_hi:[1,0]
	v_pk_mul_f32 v[0:1], v[0:1], v[16:17] op_sel_hi:[1,0]
	v_pk_mul_f32 v[6:7], v[6:7], v[16:17] op_sel_hi:[1,0]
	v_pk_mul_f32 v[4:5], v[4:5], v[16:17] op_sel_hi:[1,0]
	v_max_f32_e32 v12, 0, v12
	v_max_f32_e32 v8, 0, v8
	v_max_f32_e32 v13, 0, v13
	v_max_f32_e32 v9, 0, v9
	v_max_f32_e32 v14, 0, v14
	v_max_f32_e32 v10, 0, v10
	v_max_f32_e32 v15, 0, v15
	v_max_f32_e32 v11, 0, v11
	v_max_f32_e32 v0, 0, v0
	v_max_f32_e32 v1, 0, v1
	v_max_f32_e32 v2, 0, v2
	v_max_f32_e32 v3, 0, v3
	v_max_f32_e32 v4, 0, v4
	v_max_f32_e32 v5, 0, v5
	v_max_f32_e32 v6, 0, v6
	v_max_f32_e32 v7, 0, v7
	v_pk_mul_f32 v[12:13], v[12:13], v[12:13]
	v_pk_mul_f32 v[8:9], v[8:9], v[8:9]
	v_pk_mul_f32 v[14:15], v[14:15], v[14:15]
	v_pk_mul_f32 v[10:11], v[10:11], v[10:11]
	v_mul_f32_e32 v16, v0, v0
	v_mul_f32_e32 v18, v1, v1
	v_mul_f32_e32 v19, v2, v2
	v_mul_f32_e32 v20, v3, v3
	v_cvt_pk_bf16_f32 v0, v12, v13
	v_cvt_pk_bf16_f32 v1, v14, v15
	v_cvt_pk_bf16_f32 v2, v8, v9
	v_cvt_pk_bf16_f32 v3, v10, v11
	v_pk_mul_f32 v[4:5], v[4:5], v[4:5]
	v_pk_mul_f32 v[6:7], v[6:7], v[6:7]
	buffer_store_dwordx4 v[0:3], v17, s[16:19], 0 offen sc1
	s_nop 1
	v_cvt_pk_bf16_f32 v0, v4, v5
	v_cvt_pk_bf16_f32 v1, v6, v7
	v_cvt_pk_bf16_f32 v2, v16, v18
	v_cvt_pk_bf16_f32 v3, v19, v20
	buffer_store_dwordx4 v[0:3], v17, s[16:19], 0 offen offset:256 sc1
	s_waitcnt vmcnt(0)
	s_and_saveexec_b64 s[40:41], s[10:11]
	s_cbranch_execz .LBB0_950
	s_mov_b64 s[54:55], exec
	v_mbcnt_lo_u32_b32 v0, s54, 0
	v_mbcnt_hi_u32_b32 v0, s55, v0
	v_cmp_eq_u32_e32 vcc, 0, v0
	s_and_b64 s[6:7], exec, vcc
	s_mov_b64 exec, s[6:7]
	s_cbranch_execz .LBB0_950
	s_lshl_b32 s6, s75, 6
	s_ashr_i32 s7, s6, 31
	s_lshl_b64 s[6:7], s[6:7], 2
	s_add_u32 s6, s73, s6
	s_addc_u32 s7, s74, s7
	s_bcnt1_i32_b64 s8, s[54:55]
	v_mov_b32_e32 v0, s8
	global_atomic_add v131, v0, s[6:7]
	s_branch .LBB0_950

; #define PG8_STAGE(bufoff, gbase, voff) do { _Pragma("unroll") for (int _i = 0; _i < 2; ++_i) \
;         __builtin_amdgcn_global_load_lds((const unsigned*)((const char*)(gbase) + (voff)[_i]), (LAS unsigned*)(lds + (bufoff) + ldsw + _i * 8192), 16, 0, 0); } while (0)
; #define PG8_LDA(dst, b, h) do { _Pragma("unroll") for (int m = 0; m < 4; ++m) _Pragma("unroll") for (int k = 0; k < 2; ++k) dst[m][k] = *(const LAS bf16x8*)(lds + PG8_SA(b, h) + aoff + m * 2048 + k * 1024); } while (0)
; #define PG8_LDB(dst, b, h) do { _Pragma("unroll") for (int n = 0; n < 2; ++n) _Pragma("unroll") for (int k = 0; k < 2; ++k) dst[n][k] = *(const LAS bf16x8*)(lds + PG8_SB(b, h) + boff + n * 2048 + k * 1024); } while (0)
; #define PG8_MMA(ai, bj, At, Bt) do { __builtin_amdgcn_s_setprio(1); _Pragma("unroll") for (int m = 0; m < 4; ++m) _Pragma("unroll") for (int n = 0; n < 2; ++n) _Pragma("unroll") for (int k = 0; k < 2; ++k) \
;         acc[ai][bj][m][n] = __builtin_amdgcn_mfma_f32_16x16x32_bf16(Bt[n][k], At[m][k], acc[ai][bj][m][n], 0, 0, 0); __builtin_amdgcn_s_setprio(0); } while (0)
; #define PG8_WAIT_V(n) asm volatile("s_waitcnt vmcnt(" #n ")" ::: "memory")
;     ...
;             PG8_LDB(B0, 0, 0); PG8_SCHED; PG8_LDA(At, 0, 0); PG8_STAGE(PG8_SA(1, 1), a1 + hA, voffA);
;             PG8_WAIT_L(8); PG8_BAR; PG8_WAIT_L(0); PG8_MMA(0, 0, At, B0); PG8_BAR; PG8_SCHED;
;             PG8_LDB(B1, 0, 1); PG8_STAGE(PG8_SB(0, 0), b2, voffB);
;             PG8_BAR; PG8_WAIT_L(0); PG8_MMA(0, 1, At, B1); PG8_BAR;
;             PG8_LDA(At, 0, 1); PG8_STAGE(PG8_SA(0, 0), a2, voffA);
;             PG8_BAR; PG8_WAIT_L(0); PG8_MMA(1, 0, At, B0); PG8_BAR; PG8_SCHED;
;             PG8_STAGE(PG8_SB(0, 1), b2 + hB, voffB);
;             PG8_WAIT_V(6); PG8_BAR; PG8_MMA(1, 1, At, B1); PG8_BAR;
;             PG8_LDB(B0, 1, 0); PG8_SCHED; PG8_LDA(At, 1, 0); PG8_STAGE(PG8_SA(0, 1), a2 + hA, voffA);
;             PG8_WAIT_L(8); PG8_BAR; PG8_WAIT_L(0); PG8_MMA(0, 0, At, B0); PG8_BAR; PG8_SCHED;
;             PG8_LDB(B1, 1, 1); PG8_STAGE(PG8_SB(1, 0), b3, voffB);
;             PG8_BAR; PG8_WAIT_L(0); PG8_MMA(0, 1, At, B1); PG8_BAR;
;             PG8_LDA(At, 1, 1); PG8_STAGE(PG8_SA(1, 0), a3, voffA);
;             PG8_BAR; PG8_WAIT_L(0); PG8_MMA(1, 0, At, B0); PG8_BAR; PG8_SCHED;
;             PG8_STAGE(PG8_SB(1, 1), b3 + hB, voffB);
;             PG8_WAIT_V(6); PG8_BAR; PG8_MMA(1, 1, At, B1); PG8_BAR;
.LBB0_981:
	ds_read_b128 v[150:153], v143
	ds_read_b128 v[154:157], v143 offset:1024
	ds_read_b128 v[158:161], v143 offset:2048
	ds_read_b128 v[162:165], v143 offset:3072
	s_add_u32 s40, s38, 0xfffc0080
	s_addc_u32 s41, s39, -1
	s_cmp_eq_u32 s42, 12
	s_cselect_b32 s55, s7, s41
	s_cselect_b32 s54, s8, s40
	s_cselect_b32 s41, s9, s35
	s_cselect_b32 s40, s25, s33
	v_lshl_add_u64 v[202:203], s[38:39], 0, v[138:139]
	s_add_i32 m0, s61, 0xc000
	ds_read_b128 v[170:173], v146
	ds_read_b128 v[174:177], v146 offset:1024
	ds_read_b128 v[178:181], v146 offset:2048
	ds_read_b128 v[182:185], v146 offset:3072
	ds_read_b128 v[186:189], v146 offset:4096
	ds_read_b128 v[190:193], v146 offset:5120
	ds_read_b128 v[194:197], v146 offset:6144
	ds_read_b128 v[198:201], v146 offset:7168
	global_load_lds_dwordx4 v[202:203], off
	v_lshl_add_u64 v[202:203], s[38:39], 0, v[136:137]
	s_add_i32 m0, s61, 0xe000
	s_nop 0
	global_load_lds_dwordx4 v[202:203], off
	s_waitcnt lgkmcnt(8)
	s_barrier
	s_waitcnt lgkmcnt(0)
	s_setprio 1
	s_waitcnt lgkmcnt(0)
	v_mfma_f32_16x16x32_bf16 v[124:127], v[150:153], v[170:173], v[124:127]
	v_mfma_f32_16x16x32_bf16 v[120:123], v[158:161], v[170:173], v[120:123]
	v_mfma_f32_16x16x32_bf16 v[108:111], v[150:153], v[178:181], v[108:111]
	v_mfma_f32_16x16x32_bf16 v[104:107], v[158:161], v[178:181], v[104:107]
	v_mfma_f32_16x16x32_bf16 v[92:95], v[150:153], v[186:189], v[92:95]
	v_mfma_f32_16x16x32_bf16 v[88:91], v[158:161], v[186:189], v[88:91]
	v_mfma_f32_16x16x32_bf16 v[76:79], v[150:153], v[194:197], v[76:79]
	v_mfma_f32_16x16x32_bf16 v[72:75], v[158:161], v[194:197], v[72:75]
	v_mfma_f32_16x16x32_bf16 v[124:127], v[154:157], v[174:177], v[124:127]
	v_mfma_f32_16x16x32_bf16 v[120:123], v[162:165], v[174:177], v[120:123]
	v_mfma_f32_16x16x32_bf16 v[108:111], v[154:157], v[182:185], v[108:111]
	v_mfma_f32_16x16x32_bf16 v[104:107], v[162:165], v[182:185], v[104:107]
	v_mfma_f32_16x16x32_bf16 v[92:95], v[154:157], v[190:193], v[92:95]
	v_mfma_f32_16x16x32_bf16 v[88:91], v[162:165], v[190:193], v[88:91]
	v_mfma_f32_16x16x32_bf16 v[76:79], v[154:157], v[198:201], v[76:79]
	v_mfma_f32_16x16x32_bf16 v[72:75], v[162:165], v[198:201], v[72:75]
	s_setprio 0
	s_barrier
	s_add_i32 s43, s69, s60
	v_lshl_add_u64 v[218:219], s[40:41], 0, v[130:131]
	s_mov_b32 m0, s43
	ds_read_b128 v[202:205], v147
	ds_read_b128 v[206:209], v147 offset:1024
	ds_read_b128 v[210:213], v147 offset:2048
	ds_read_b128 v[214:217], v147 offset:3072
	global_load_lds_dwordx4 v[218:219], off
	v_lshl_add_u64 v[220:221], s[40:41], 0, v[134:135]
	s_add_i32 m0, s43, 0x2000
	s_nop 0
	global_load_lds_dwordx4 v[220:221], off
	s_barrier
	s_waitcnt lgkmcnt(0)
	s_setprio 1
	s_waitcnt lgkmcnt(0)
	v_mfma_f32_16x16x32_bf16 v[116:119], v[202:205], v[170:173], v[116:119]
	v_mfma_f32_16x16x32_bf16 v[112:115], v[210:213], v[170:173], v[112:115]
	v_mfma_f32_16x16x32_bf16 v[100:103], v[202:205], v[178:181], v[100:103]
	v_mfma_f32_16x16x32_bf16 v[96:99], v[210:213], v[178:181], v[96:99]
	v_mfma_f32_16x16x32_bf16 v[84:87], v[202:205], v[186:189], v[84:87]
	v_mfma_f32_16x16x32_bf16 v[80:83], v[210:213], v[186:189], v[80:83]
	v_mfma_f32_16x16x32_bf16 v[68:71], v[202:205], v[194:197], v[68:71]
	v_mfma_f32_16x16x32_bf16 v[64:67], v[210:213], v[194:197], v[64:67]
	v_mfma_f32_16x16x32_bf16 v[116:119], v[206:209], v[174:177], v[116:119]
	v_mfma_f32_16x16x32_bf16 v[112:115], v[214:217], v[174:177], v[112:115]
	v_mfma_f32_16x16x32_bf16 v[100:103], v[206:209], v[182:185], v[100:103]
	v_mfma_f32_16x16x32_bf16 v[96:99], v[214:217], v[182:185], v[96:99]
	v_mfma_f32_16x16x32_bf16 v[84:87], v[206:209], v[190:193], v[84:87]
	v_mfma_f32_16x16x32_bf16 v[80:83], v[214:217], v[190:193], v[80:83]
	v_mfma_f32_16x16x32_bf16 v[68:71], v[206:209], v[198:201], v[68:71]
	v_mfma_f32_16x16x32_bf16 v[64:67], v[214:217], v[198:201], v[64:67]
	s_setprio 0
	s_mov_b32 m0, s61
	v_lshl_add_u64 v[222:223], s[54:55], 0, v[128:129]
	s_barrier
	ds_read_b128 v[170:173], v146 offset:16384
	ds_read_b128 v[174:177], v146 offset:17408
	ds_read_b128 v[178:181], v146 offset:18432
	ds_read_b128 v[182:185], v146 offset:19456
	ds_read_b128 v[186:189], v146 offset:20480
	ds_read_b128 v[190:193], v146 offset:21504
	ds_read_b128 v[194:197], v146 offset:22528
	ds_read_b128 v[198:201], v146 offset:23552
	global_load_lds_dwordx4 v[222:223], off
	v_lshl_add_u64 v[224:225], s[54:55], 0, v[132:133]
	s_mov_b32 m0, s62
	s_nop 0
	global_load_lds_dwordx4 v[224:225], off
	s_barrier
	s_waitcnt lgkmcnt(0)
	s_setprio 1
	s_waitcnt lgkmcnt(0)
	v_mfma_f32_16x16x32_bf16 v[60:63], v[150:153], v[170:173], v[60:63]
	v_mfma_f32_16x16x32_bf16 v[56:59], v[158:161], v[170:173], v[56:59]
	v_mfma_f32_16x16x32_bf16 v[44:47], v[150:153], v[178:181], v[44:47]
	v_mfma_f32_16x16x32_bf16 v[40:43], v[158:161], v[178:181], v[40:43]
	v_mfma_f32_16x16x32_bf16 v[28:31], v[150:153], v[186:189], v[28:31]
	v_mfma_f32_16x16x32_bf16 v[24:27], v[158:161], v[186:189], v[24:27]
	v_mfma_f32_16x16x32_bf16 v[12:15], v[150:153], v[194:197], v[12:15]
	v_mfma_f32_16x16x32_bf16 v[8:11], v[158:161], v[194:197], v[8:11]
	v_mfma_f32_16x16x32_bf16 v[60:63], v[154:157], v[174:177], v[60:63]
	v_mfma_f32_16x16x32_bf16 v[56:59], v[162:165], v[174:177], v[56:59]
	v_mfma_f32_16x16x32_bf16 v[44:47], v[154:157], v[182:185], v[44:47]
	v_mfma_f32_16x16x32_bf16 v[40:43], v[162:165], v[182:185], v[40:43]
	v_mfma_f32_16x16x32_bf16 v[28:31], v[154:157], v[190:193], v[28:31]
	v_mfma_f32_16x16x32_bf16 v[24:27], v[162:165], v[190:193], v[24:27]
	v_mfma_f32_16x16x32_bf16 v[12:15], v[154:157], v[198:201], v[12:15]
	v_mfma_f32_16x16x32_bf16 v[8:11], v[162:165], v[198:201], v[8:11]
	s_setprio 0
	s_barrier
; #define PG8_STAGE(bufoff, gbase, voff) do { _Pragma("unroll") for (int _i = 0; _i < 2; ++_i) \
;         __builtin_amdgcn_global_load_lds((const unsigned*)((const char*)(gbase) + (voff)[_i]), (LAS unsigned*)(lds + (bufoff) + ldsw + _i * 8192), 16, 0, 0); } while (0)
; #define PG8_LDA(dst, b, h) do { _Pragma("unroll") for (int m = 0; m < 4; ++m) _Pragma("unroll") for (int k = 0; k < 2; ++k) dst[m][k] = *(const LAS bf16x8*)(lds + PG8_SA(b, h) + aoff + m * 2048 + k * 1024); } while (0)
; #define PG8_LDB(dst, b, h) do { _Pragma("unroll") for (int n = 0; n < 2; ++n) _Pragma("unroll") for (int k = 0; k < 2; ++k) dst[n][k] = *(const LAS bf16x8*)(lds + PG8_SB(b, h) + boff + n * 2048 + k * 1024); } while (0)
; #define PG8_MMA(ai, bj, At, Bt) do { __builtin_amdgcn_s_setprio(1); _Pragma("unroll") for (int m = 0; m < 4; ++m) _Pragma("unroll") for (int n = 0; n < 2; ++n) _Pragma("unroll") for (int k = 0; k < 2; ++k) \
;         acc[ai][bj][m][n] = __builtin_amdgcn_mfma_f32_16x16x32_bf16(Bt[n][k], At[m][k], acc[ai][bj][m][n], 0, 0, 0); __builtin_amdgcn_s_setprio(0); } while (0)
; #define PG8_WAIT_V(n) asm volatile("s_waitcnt vmcnt(" #n ")" ::: "memory")
; #define PG8_WAIT_L(n) asm volatile("s_waitcnt lgkmcnt(" #n ")" ::: "memory")
; #define PG8_BAR __builtin_amdgcn_s_barrier()
; #define PG8_SCHED __builtin_amdgcn_sched_barrier(0)
;     ...
;             PG8_STAGE(PG8_SB(0, 1), b2 + hB, voffB);
;             PG8_WAIT_V(6); PG8_BAR; PG8_MMA(1, 1, At, B1); PG8_BAR;
;             PG8_LDB(B0, 1, 0); PG8_SCHED; PG8_LDA(At, 1, 0); PG8_STAGE(PG8_SA(0, 1), a2 + hA, voffA);
;             PG8_WAIT_L(8); PG8_BAR; PG8_WAIT_L(0); PG8_MMA(0, 0, At, B0); PG8_BAR; PG8_SCHED;
;             PG8_LDB(B1, 1, 1); PG8_STAGE(PG8_SB(1, 0), b3, voffB);
;             PG8_BAR; PG8_WAIT_L(0); PG8_MMA(0, 1, At, B1); PG8_BAR;
;             PG8_LDA(At, 1, 1); PG8_STAGE(PG8_SA(1, 0), a3, voffA);
;             PG8_BAR; PG8_WAIT_L(0); PG8_MMA(1, 0, At, B0); PG8_BAR; PG8_SCHED;
	s_add_u32 s44, s40, 0x40000
	s_addc_u32 s45, s41, 0
	s_add_i32 s43, s70, s60
	v_lshl_add_u64 v[150:151], s[44:45], 0, v[130:131]
	s_mov_b32 m0, s43
	s_nop 0
	global_load_lds_dwordx4 v[150:151], off
	v_lshl_add_u64 v[150:151], s[44:45], 0, v[134:135]
	s_add_i32 m0, s43, 0x2000
	s_nop 0
	global_load_lds_dwordx4 v[150:151], off
	s_waitcnt vmcnt(6)
	s_barrier
	s_setprio 1
	v_mfma_f32_16x16x32_bf16 v[52:55], v[202:205], v[170:173], v[52:55]
	v_mfma_f32_16x16x32_bf16 v[48:51], v[210:213], v[170:173], v[48:51]
	v_mfma_f32_16x16x32_bf16 v[36:39], v[202:205], v[178:181], v[36:39]
	v_mfma_f32_16x16x32_bf16 v[32:35], v[210:213], v[178:181], v[32:35]
	v_mfma_f32_16x16x32_bf16 v[20:23], v[202:205], v[186:189], v[20:23]
	v_mfma_f32_16x16x32_bf16 v[16:19], v[210:213], v[186:189], v[16:19]
	v_mfma_f32_16x16x32_bf16 v[4:7], v[202:205], v[194:197], v[4:7]
	v_mfma_f32_16x16x32_bf16 v[0:3], v[210:213], v[194:197], v[0:3]
	v_mfma_f32_16x16x32_bf16 v[52:55], v[206:209], v[174:177], v[52:55]
	v_mfma_f32_16x16x32_bf16 v[48:51], v[214:217], v[174:177], v[48:51]
	v_mfma_f32_16x16x32_bf16 v[36:39], v[206:209], v[182:185], v[36:39]
	v_mfma_f32_16x16x32_bf16 v[32:35], v[214:217], v[182:185], v[32:35]
	v_mfma_f32_16x16x32_bf16 v[20:23], v[206:209], v[190:193], v[20:23]
	v_mfma_f32_16x16x32_bf16 v[16:19], v[214:217], v[190:193], v[16:19]
	v_mfma_f32_16x16x32_bf16 v[4:7], v[206:209], v[198:201], v[4:7]
	v_mfma_f32_16x16x32_bf16 v[0:3], v[214:217], v[198:201], v[0:3]
	s_setprio 0
	s_add_i32 s43, 0, 0x18000
	v_add_u32_e32 v149, s43, v141
	s_barrier
	ds_read_b128 v[150:153], v149
	ds_read_b128 v[154:157], v149 offset:1024
	ds_read_b128 v[158:161], v149 offset:2048
	ds_read_b128 v[162:165], v149 offset:3072
	s_add_u32 s44, s54, 0x40000
	s_addc_u32 s45, s55, 0
	s_mov_b32 m0, s63
	v_lshl_add_u64 v[202:203], s[44:45], 0, v[128:129]
	ds_read_b128 v[170:173], v146 offset:32768
	ds_read_b128 v[174:177], v146 offset:33792
	ds_read_b128 v[178:181], v146 offset:34816
	ds_read_b128 v[182:185], v146 offset:35840
	ds_read_b128 v[186:189], v146 offset:36864
	ds_read_b128 v[190:193], v146 offset:37888
	ds_read_b128 v[194:197], v146 offset:38912
	ds_read_b128 v[198:201], v146 offset:39936
	global_load_lds_dwordx4 v[202:203], off
	v_lshl_add_u64 v[202:203], s[44:45], 0, v[132:133]
	s_mov_b32 m0, s64
	s_nop 0
	global_load_lds_dwordx4 v[202:203], off
	s_waitcnt lgkmcnt(8)
	s_barrier
	s_waitcnt lgkmcnt(0)
	s_setprio 1
	s_waitcnt lgkmcnt(0)
	v_mfma_f32_16x16x32_bf16 v[124:127], v[150:153], v[170:173], v[124:127]
	v_mfma_f32_16x16x32_bf16 v[120:123], v[158:161], v[170:173], v[120:123]
	v_mfma_f32_16x16x32_bf16 v[108:111], v[150:153], v[178:181], v[108:111]
	v_mfma_f32_16x16x32_bf16 v[104:107], v[158:161], v[178:181], v[104:107]
	v_mfma_f32_16x16x32_bf16 v[92:95], v[150:153], v[186:189], v[92:95]
	v_mfma_f32_16x16x32_bf16 v[88:91], v[158:161], v[186:189], v[88:91]
	v_mfma_f32_16x16x32_bf16 v[76:79], v[150:153], v[194:197], v[76:79]
	v_mfma_f32_16x16x32_bf16 v[72:75], v[158:161], v[194:197], v[72:75]
	v_mfma_f32_16x16x32_bf16 v[124:127], v[154:157], v[174:177], v[124:127]
	v_mfma_f32_16x16x32_bf16 v[120:123], v[162:165], v[174:177], v[120:123]
	v_mfma_f32_16x16x32_bf16 v[108:111], v[154:157], v[182:185], v[108:111]
	v_mfma_f32_16x16x32_bf16 v[104:107], v[162:165], v[182:185], v[104:107]
	v_mfma_f32_16x16x32_bf16 v[92:95], v[154:157], v[190:193], v[92:95]
	v_mfma_f32_16x16x32_bf16 v[88:91], v[162:165], v[190:193], v[88:91]
	v_mfma_f32_16x16x32_bf16 v[76:79], v[154:157], v[198:201], v[76:79]
	v_mfma_f32_16x16x32_bf16 v[72:75], v[162:165], v[198:201], v[72:75]
	s_setprio 0
	s_barrier
	s_add_i32 s44, 0, 0x1c000
	s_add_i32 s43, s43, s60
	v_add_u32_e32 v149, s44, v141
	v_lshl_add_u64 v[218:219], v[218:219], 0, s[26:27]
	s_mov_b32 m0, s43
	ds_read_b128 v[202:205], v149
	ds_read_b128 v[206:209], v149 offset:1024
	ds_read_b128 v[210:213], v149 offset:2048
	ds_read_b128 v[214:217], v149 offset:3072
	global_load_lds_dwordx4 v[218:219], off
	v_lshl_add_u64 v[218:219], v[220:221], 0, s[26:27]
	s_add_i32 m0, s43, 0x2000
	s_nop 0
	global_load_lds_dwordx4 v[218:219], off
	s_barrier
	s_waitcnt lgkmcnt(0)
	s_setprio 1
	s_waitcnt lgkmcnt(0)
	v_mfma_f32_16x16x32_bf16 v[116:119], v[202:205], v[170:173], v[116:119]
	v_mfma_f32_16x16x32_bf16 v[112:115], v[210:213], v[170:173], v[112:115]
	v_mfma_f32_16x16x32_bf16 v[100:103], v[202:205], v[178:181], v[100:103]
	v_mfma_f32_16x16x32_bf16 v[96:99], v[210:213], v[178:181], v[96:99]
	v_mfma_f32_16x16x32_bf16 v[84:87], v[202:205], v[186:189], v[84:87]
	v_mfma_f32_16x16x32_bf16 v[80:83], v[210:213], v[186:189], v[80:83]
	v_mfma_f32_16x16x32_bf16 v[68:71], v[202:205], v[194:197], v[68:71]
	v_mfma_f32_16x16x32_bf16 v[64:67], v[210:213], v[194:197], v[64:67]
	v_mfma_f32_16x16x32_bf16 v[116:119], v[206:209], v[174:177], v[116:119]
	v_mfma_f32_16x16x32_bf16 v[112:115], v[214:217], v[174:177], v[112:115]
	v_mfma_f32_16x16x32_bf16 v[100:103], v[206:209], v[182:185], v[100:103]
	v_mfma_f32_16x16x32_bf16 v[96:99], v[214:217], v[182:185], v[96:99]
	v_mfma_f32_16x16x32_bf16 v[84:87], v[206:209], v[190:193], v[84:87]
	v_mfma_f32_16x16x32_bf16 v[80:83], v[214:217], v[190:193], v[80:83]
	v_mfma_f32_16x16x32_bf16 v[68:71], v[206:209], v[198:201], v[68:71]
	v_mfma_f32_16x16x32_bf16 v[64:67], v[214:217], v[198:201], v[64:67]
	s_setprio 0
	s_mov_b32 m0, s66
	v_lshl_add_u64 v[218:219], v[222:223], 0, s[26:27]
	s_barrier
	ds_read_b128 v[170:173], v146 offset:49152
	ds_read_b128 v[174:177], v146 offset:50176
	ds_read_b128 v[178:181], v146 offset:51200
	ds_read_b128 v[182:185], v146 offset:52224
	ds_read_b128 v[186:189], v146 offset:53248
	ds_read_b128 v[190:193], v146 offset:54272
	ds_read_b128 v[194:197], v146 offset:55296
	ds_read_b128 v[198:201], v146 offset:56320
	global_load_lds_dwordx4 v[218:219], off
	v_lshl_add_u64 v[218:219], v[224:225], 0, s[26:27]
	s_mov_b32 m0, s67
	s_nop 0
	global_load_lds_dwordx4 v[218:219], off
	s_barrier
; #define PG8_STAGE(bufoff, gbase, voff) do { _Pragma("unroll") for (int _i = 0; _i < 2; ++_i) \
;         __builtin_amdgcn_global_load_lds((const unsigned*)((const char*)(gbase) + (voff)[_i]), (LAS unsigned*)(lds + (bufoff) + ldsw + _i * 8192), 16, 0, 0); } while (0)
; #define PG8_LDA(dst, b, h) do { _Pragma("unroll") for (int m = 0; m < 4; ++m) _Pragma("unroll") for (int k = 0; k < 2; ++k) dst[m][k] = *(const LAS bf16x8*)(lds + PG8_SA(b, h) + aoff + m * 2048 + k * 1024); } while (0)
; #define PG8_LDB(dst, b, h) do { _Pragma("unroll") for (int n = 0; n < 2; ++n) _Pragma("unroll") for (int k = 0; k < 2; ++k) dst[n][k] = *(const LAS bf16x8*)(lds + PG8_SB(b, h) + boff + n * 2048 + k * 1024); } while (0)
; #define PG8_MMA(ai, bj, At, Bt) do { __builtin_amdgcn_s_setprio(1); _Pragma("unroll") for (int m = 0; m < 4; ++m) _Pragma("unroll") for (int n = 0; n < 2; ++n) _Pragma("unroll") for (int k = 0; k < 2; ++k) \
;         acc[ai][bj][m][n] = __builtin_amdgcn_mfma_f32_16x16x32_bf16(Bt[n][k], At[m][k], acc[ai][bj][m][n], 0, 0, 0); __builtin_amdgcn_s_setprio(0); } while (0)
; #define PG8_WAIT_V(n) asm volatile("s_waitcnt vmcnt(" #n ")" ::: "memory")
; #define PG8_WAIT_L(n) asm volatile("s_waitcnt lgkmcnt(" #n ")" ::: "memory")
; #define PG8_BAR __builtin_amdgcn_s_barrier()
;     ...
;             PG8_WAIT_L(8); PG8_BAR; PG8_WAIT_L(0); PG8_MMA(0, 0, At, B0); PG8_BAR; PG8_SCHED;
;             PG8_LDB(B1, 1, 1); PG8_STAGE(PG8_SB(1, 0), b3, voffB);
;             PG8_BAR; PG8_WAIT_L(0); PG8_MMA(0, 1, At, B1); PG8_BAR;
;             PG8_LDA(At, 1, 1); PG8_STAGE(PG8_SA(1, 0), a3, voffA);
;             PG8_BAR; PG8_WAIT_L(0); PG8_MMA(1, 0, At, B0); PG8_BAR; PG8_SCHED;
;             PG8_STAGE(PG8_SB(1, 1), b3 + hB, voffB);
;             PG8_WAIT_V(6); PG8_BAR; PG8_MMA(1, 1, At, B1); PG8_BAR;
;         }
;     __device__ __forceinline__ void operator()(const f32x4 (&acc)[2][2][4][2], const Unit& u, int wr, int wc, int fr, int fq) const {
;         const __amdgpu_buffer_rsrc_t rsrc = __builtin_amdgcn_make_buffer_rsrc((void*)O, 0, T_ALL * DFF * 2, 0x00020000);
;         const int row0 = row_off + u.pm * 256 + wr * 64 + fr, col0 = u.pn * 256 + wc * 32 + 8 * fq;
; #pragma unroll
;         for (int ai = 0; ai < 2; ++ai)
; #pragma unroll
;             for (int m = 0; m < 4; ++m) {
;                 const int row = row0 + ai * 128 + m * 16; const float rs = row_rstd(ssq, row);
	s_waitcnt lgkmcnt(0)
	s_setprio 1
	s_waitcnt lgkmcnt(0)
	v_mfma_f32_16x16x32_bf16 v[60:63], v[150:153], v[170:173], v[60:63]
	v_mfma_f32_16x16x32_bf16 v[56:59], v[158:161], v[170:173], v[56:59]
	v_mfma_f32_16x16x32_bf16 v[44:47], v[150:153], v[178:181], v[44:47]
	v_mfma_f32_16x16x32_bf16 v[40:43], v[158:161], v[178:181], v[40:43]
	v_mfma_f32_16x16x32_bf16 v[28:31], v[150:153], v[186:189], v[28:31]
	v_mfma_f32_16x16x32_bf16 v[24:27], v[158:161], v[186:189], v[24:27]
	v_mfma_f32_16x16x32_bf16 v[12:15], v[150:153], v[194:197], v[12:15]
	v_mfma_f32_16x16x32_bf16 v[8:11], v[158:161], v[194:197], v[8:11]
	v_mfma_f32_16x16x32_bf16 v[60:63], v[154:157], v[174:177], v[60:63]
	v_mfma_f32_16x16x32_bf16 v[56:59], v[162:165], v[174:177], v[56:59]
	v_mfma_f32_16x16x32_bf16 v[44:47], v[154:157], v[182:185], v[44:47]
	v_mfma_f32_16x16x32_bf16 v[40:43], v[162:165], v[182:185], v[40:43]
	v_mfma_f32_16x16x32_bf16 v[28:31], v[154:157], v[190:193], v[28:31]
	v_mfma_f32_16x16x32_bf16 v[24:27], v[162:165], v[190:193], v[24:27]
	v_mfma_f32_16x16x32_bf16 v[12:15], v[154:157], v[198:201], v[12:15]
	v_mfma_f32_16x16x32_bf16 v[8:11], v[162:165], v[198:201], v[8:11]
	s_setprio 0
	s_barrier
	s_add_u32 s40, s40, 0x40080
	s_addc_u32 s41, s41, 0
	s_add_i32 s43, s44, s60
	v_lshl_add_u64 v[150:151], s[40:41], 0, v[130:131]
	s_mov_b32 m0, s43
	s_nop 0
	global_load_lds_dwordx4 v[150:151], off
	v_lshl_add_u64 v[150:151], s[40:41], 0, v[134:135]
	s_add_i32 m0, s43, 0x2000
	s_nop 0
	global_load_lds_dwordx4 v[150:151], off
	s_waitcnt vmcnt(6)
	s_barrier
	s_setprio 1
	v_mfma_f32_16x16x32_bf16 v[52:55], v[202:205], v[170:173], v[52:55]
	v_mfma_f32_16x16x32_bf16 v[48:51], v[210:213], v[170:173], v[48:51]
	v_mfma_f32_16x16x32_bf16 v[36:39], v[202:205], v[178:181], v[36:39]
	v_mfma_f32_16x16x32_bf16 v[32:35], v[210:213], v[178:181], v[32:35]
	v_mfma_f32_16x16x32_bf16 v[20:23], v[202:205], v[186:189], v[20:23]
	v_mfma_f32_16x16x32_bf16 v[16:19], v[210:213], v[186:189], v[16:19]
	v_mfma_f32_16x16x32_bf16 v[4:7], v[202:205], v[194:197], v[4:7]
	v_mfma_f32_16x16x32_bf16 v[0:3], v[210:213], v[194:197], v[0:3]
	v_mfma_f32_16x16x32_bf16 v[52:55], v[206:209], v[174:177], v[52:55]
	v_mfma_f32_16x16x32_bf16 v[48:51], v[214:217], v[174:177], v[48:51]
	v_mfma_f32_16x16x32_bf16 v[36:39], v[206:209], v[182:185], v[36:39]
	v_mfma_f32_16x16x32_bf16 v[32:35], v[214:217], v[182:185], v[32:35]
	v_mfma_f32_16x16x32_bf16 v[20:23], v[206:209], v[190:193], v[20:23]
	v_mfma_f32_16x16x32_bf16 v[16:19], v[214:217], v[190:193], v[16:19]
	v_mfma_f32_16x16x32_bf16 v[4:7], v[206:209], v[198:201], v[4:7]
	v_mfma_f32_16x16x32_bf16 v[0:3], v[214:217], v[198:201], v[0:3]
	s_setprio 0
	s_add_i32 s42, s42, 2
	s_add_u32 s33, s33, 0x100
	s_addc_u32 s35, s35, 0
	s_add_u32 s38, s38, 0x100
	s_addc_u32 s39, s39, 0
	s_cmp_gt_u32 s42, 13
	s_barrier
	s_cbranch_scc0 .LBB0_981
	v_lshl_add_u32 v150, s75, 8, v140
	v_add_u32_e32 v164, 0x4000, v150
	v_ashrrev_i32_e32 v165, 31, v164
	v_lshlrev_b64 v[152:153], 6, v[164:165]
	v_lshl_add_u64 v[170:171], s[18:19], 0, v[152:153]
	v_subrev_u32_e32 v176, s18, v170
	v_add_u32_e32 v177, 0x0, v176
	global_load_dwordx4 v[178:181], v177, s[18:19]
	v_add_u32_e32 v177, 0x10, v176
	global_load_dwordx4 v[182:185], v177, s[18:19]
	v_add_u32_e32 v177, 0x20, v176
	global_load_dwordx4 v[186:189], v177, s[18:19]
	v_add_u32_e32 v177, 0x30, v176
	global_load_dwordx4 v[190:193], v177, s[18:19]
	v_add_u32_e32 v177, 0x400, v176
	global_load_dwordx4 v[194:197], v177, s[18:19]
	v_add_u32_e32 v177, 0x410, v176
	global_load_dwordx4 v[198:201], v177, s[18:19]
	v_add_u32_e32 v177, 0x420, v176
	global_load_dwordx4 v[202:205], v177, s[18:19]
	v_add_u32_e32 v177, 0x430, v176
	global_load_dwordx4 v[206:209], v177, s[18:19]
	v_add_u32_e32 v177, 0x800, v176
	global_load_dwordx4 v[210:213], v177, s[18:19]
	v_add_u32_e32 v177, 0x810, v176
	global_load_dwordx4 v[214:217], v177, s[18:19]
	v_add_u32_e32 v177, 0x820, v176
	global_load_dwordx4 v[232:235], v177, s[18:19]
	v_add_u32_e32 v177, 0x830, v176
	global_load_dwordx4 v[236:239], v177, s[18:19]
	v_add_u32_e32 v177, 0xc00, v176
	global_load_dwordx4 v[240:243], v177, s[18:19]
	v_add_u32_e32 v177, 0xc10, v176
	global_load_dwordx4 v[244:247], v177, s[18:19]
	v_add_u32_e32 v177, 0xc20, v176
	global_load_dwordx4 v[248:251], v177, s[18:19]
	v_add_u32_e32 v177, 0xc30, v176
	global_load_dwordx4 v[252:255], v177, s[18:19]
	s_nop 0
	v_lshl_or_b32 v149, s6, 9, v142
	v_lshl_add_u32 v151, v164, 13, v149
	v_add_u32_e32 v174, 0x4010, v150
	v_ashrrev_i32_e32 v175, 31, v174
	s_waitcnt vmcnt(12)
; __device__ __forceinline__ u32x4 pack8(const f32x4 v0, const f32x4 v1) { u32x4 w; w.x = pk2(v0[0], v0[1]); w.y = pk2(v0[2], v0[3]); w.z = pk2(v1[0], v1[1]); w.w = pk2(v1[2], v1[3]); return w; }
; __device__ __forceinline__ float row_rstd(const float* ssq, int row) {
;     const f32x4* p = (const f32x4*)(ssq + (size_t)row * 16);
;     const f32x4 a = p[0], b = p[1], c = p[2], d = p[3];
;     const float s = ((a[0] + a[1]) + (a[2] + a[3])) + ((b[0] + b[1]) + (b[2] + b[3])) + ((c[0] + c[1]) + (c[2] + c[3])) + ((d[0] + d[1]) + (d[2] + d[3]));
;     return rsqrtf(s * (1.0f / 1024.0f) + 1e-6f);
;     __device__ __forceinline__ void operator()(const f32x4 (&acc)[2][2][4][2], const Unit& u, int wr, int wc, int fr, int fq) const {
;     ...
;                 const int row = row0 + ai * 128 + m * 16; const float rs = row_rstd(ssq, row);
; #pragma unroll
;                 for (int bj = 0; bj < 2; ++bj) { f32x4 v0 = acc[ai][bj][m][0] * rs, v1 = acc[ai][bj][m][1] * rs;
; #pragma unroll
;                     for (int j = 0; j < 4; ++j) { const float a = fmaxf(v0[j], 0.f), b = fmaxf(v1[j], 0.f); v0[j] = a * a; v1[j] = b * b; }
;                     __builtin_amdgcn_raw_buffer_store_b128(pack8(v0, v1), rsrc, (unsigned)(((size_t)row * DFF + col0 + bj * 128) * 2), 0, 16  ); }
	v_pk_add_f32 v[152:153], v[178:179], v[180:181]
	v_pk_add_f32 v[154:155], v[182:183], v[184:185]
	v_pk_add_f32 v[156:157], v[186:187], v[188:189]
	v_pk_add_f32 v[158:159], v[190:191], v[192:193]
	v_pk_add_f32 v[152:153], v[152:153], v[154:155]
	v_pk_add_f32 v[156:157], v[156:157], v[158:159]
	v_pk_add_f32 v[152:153], v[152:153], v[156:157]
	v_add_f32_e32 v152, v152, v153
	s_nop 0
	s_nop 0
	v_fmamk_f32 v152, v152, 0x3a800000, v148
	v_mul_f32_e32 v153, 0x4b800000, v152
	v_cmp_gt_f32_e32 vcc, s71, v152
	s_nop 1
	v_cndmask_b32_e32 v152, v152, v153, vcc
	v_rsq_f32_e32 v154, v152
	v_lshlrev_b64 v[152:153], 6, v[174:175]
	v_lshl_add_u64 v[152:153], s[18:19], 0, v[152:153]
	v_mul_f32_e32 v155, 0x45800000, v154
	v_cndmask_b32_e32 v154, v154, v155, vcc
	v_pk_mul_f32 v[126:127], v[126:127], v[154:155] op_sel_hi:[1,0]
	v_pk_mul_f32 v[124:125], v[124:125], v[154:155] op_sel_hi:[1,0]
	v_pk_mul_f32 v[122:123], v[122:123], v[154:155] op_sel_hi:[1,0]
	v_pk_mul_f32 v[120:121], v[120:121], v[154:155] op_sel_hi:[1,0]
	v_pk_mul_f32 v[114:115], v[114:115], v[154:155] op_sel_hi:[1,0]
	v_pk_mul_f32 v[112:113], v[112:113], v[154:155] op_sel_hi:[1,0]
	v_pk_mul_f32 v[118:119], v[118:119], v[154:155] op_sel_hi:[1,0]
	v_pk_mul_f32 v[116:117], v[116:117], v[154:155] op_sel_hi:[1,0]
	v_max_f32_e32 v124, 0, v124
	v_max_f32_e32 v120, 0, v120
	v_max_f32_e32 v125, 0, v125
	v_max_f32_e32 v121, 0, v121
	v_max_f32_e32 v126, 0, v126
	v_max_f32_e32 v122, 0, v122
	v_max_f32_e32 v127, 0, v127
	v_max_f32_e32 v123, 0, v123
	v_max_f32_e32 v112, 0, v112
	v_max_f32_e32 v113, 0, v113
	v_max_f32_e32 v114, 0, v114
	v_max_f32_e32 v115, 0, v115
	v_max_f32_e32 v116, 0, v116
	v_max_f32_e32 v117, 0, v117
	v_max_f32_e32 v118, 0, v118
	v_max_f32_e32 v119, 0, v119
	v_pk_mul_f32 v[124:125], v[124:125], v[124:125]
	v_pk_mul_f32 v[120:121], v[120:121], v[120:121]
	v_pk_mul_f32 v[126:127], v[126:127], v[126:127]
	v_pk_mul_f32 v[122:123], v[122:123], v[122:123]
	v_pk_mul_f32 v[154:155], v[112:113], v[112:113]
	v_pk_mul_f32 v[156:157], v[114:115], v[114:115]
	v_cvt_pk_bf16_f32 v112, v124, v125
	v_cvt_pk_bf16_f32 v113, v126, v127
	v_cvt_pk_bf16_f32 v114, v120, v121
	v_cvt_pk_bf16_f32 v115, v122, v123
	v_pk_mul_f32 v[116:117], v[116:117], v[116:117]
	v_pk_mul_f32 v[118:119], v[118:119], v[118:119]
	buffer_store_dwordx4 v[112:115], v151, s[12:15], 0 offen sc1
	s_nop 1
	v_cvt_pk_bf16_f32 v112, v116, v117
	v_cvt_pk_bf16_f32 v113, v118, v119
	v_cvt_pk_bf16_f32 v114, v154, v155
	v_cvt_pk_bf16_f32 v115, v156, v157
	buffer_store_dwordx4 v[112:115], v151, s[12:15], 0 offen offset:256 sc1
	s_nop 0
	v_add_u32_e32 v152, 0x4020, v150
	v_ashrrev_i32_e32 v153, 31, v152
	v_lshl_add_u32 v151, v174, 13, v149
	v_add_u32_e32 v177, 0x2000, v176
	global_load_dwordx4 v[178:181], v177, s[18:19]
	v_add_u32_e32 v177, 0x2010, v176
	global_load_dwordx4 v[182:185], v177, s[18:19]
	v_add_u32_e32 v177, 0x2020, v176
	global_load_dwordx4 v[186:189], v177, s[18:19]
	v_add_u32_e32 v177, 0x2030, v176
	global_load_dwordx4 v[190:193], v177, s[18:19]
	s_waitcnt vmcnt(14)
	v_pk_add_f32 v[112:113], v[194:195], v[196:197]
	v_pk_add_f32 v[114:115], v[198:199], v[200:201]
	v_pk_add_f32 v[116:117], v[202:203], v[204:205]
	v_pk_add_f32 v[118:119], v[206:207], v[208:209]
	v_pk_add_f32 v[112:113], v[112:113], v[114:115]
	v_pk_add_f32 v[116:117], v[116:117], v[118:119]
	v_pk_add_f32 v[112:113], v[112:113], v[116:117]
	v_add_f32_e32 v112, v112, v113
	s_nop 0
	s_nop 0
	v_fmamk_f32 v112, v112, 0x3a800000, v148
	v_mul_f32_e32 v113, 0x4b800000, v112
	v_cmp_gt_f32_e32 vcc, s71, v112
	s_nop 1
	v_cndmask_b32_e32 v112, v112, v113, vcc
	v_rsq_f32_e32 v114, v112
	v_lshlrev_b64 v[112:113], 6, v[152:153]
	v_lshl_add_u64 v[112:113], s[18:19], 0, v[112:113]
	v_mul_f32_e32 v115, 0x45800000, v114
	v_cndmask_b32_e32 v114, v114, v115, vcc
	v_pk_mul_f32 v[110:111], v[110:111], v[114:115] op_sel_hi:[1,0]
	v_pk_mul_f32 v[108:109], v[108:109], v[114:115] op_sel_hi:[1,0]
	v_pk_mul_f32 v[106:107], v[106:107], v[114:115] op_sel_hi:[1,0]
	v_pk_mul_f32 v[104:105], v[104:105], v[114:115] op_sel_hi:[1,0]
	v_pk_mul_f32 v[98:99], v[98:99], v[114:115] op_sel_hi:[1,0]
	v_pk_mul_f32 v[96:97], v[96:97], v[114:115] op_sel_hi:[1,0]
	v_pk_mul_f32 v[102:103], v[102:103], v[114:115] op_sel_hi:[1,0]
	v_pk_mul_f32 v[100:101], v[100:101], v[114:115] op_sel_hi:[1,0]
	v_max_f32_e32 v108, 0, v108
	v_max_f32_e32 v104, 0, v104
	v_max_f32_e32 v109, 0, v109
	v_max_f32_e32 v105, 0, v105
	v_max_f32_e32 v110, 0, v110
	v_max_f32_e32 v106, 0, v106
	v_max_f32_e32 v111, 0, v111
	v_max_f32_e32 v107, 0, v107
	v_max_f32_e32 v96, 0, v96
	v_max_f32_e32 v97, 0, v97
	v_max_f32_e32 v98, 0, v98
	v_max_f32_e32 v99, 0, v99
	v_max_f32_e32 v100, 0, v100
	v_max_f32_e32 v101, 0, v101
	v_max_f32_e32 v102, 0, v102
	v_max_f32_e32 v103, 0, v103
	v_pk_mul_f32 v[108:109], v[108:109], v[108:109]
	v_pk_mul_f32 v[104:105], v[104:105], v[104:105]
	v_pk_mul_f32 v[110:111], v[110:111], v[110:111]
	v_pk_mul_f32 v[106:107], v[106:107], v[106:107]
	v_pk_mul_f32 v[114:115], v[96:97], v[96:97]
	v_pk_mul_f32 v[116:117], v[98:99], v[98:99]
	v_cvt_pk_bf16_f32 v96, v108, v109
	v_cvt_pk_bf16_f32 v97, v110, v111
	v_cvt_pk_bf16_f32 v98, v104, v105
	v_cvt_pk_bf16_f32 v99, v106, v107
	v_pk_mul_f32 v[100:101], v[100:101], v[100:101]
	v_pk_mul_f32 v[102:103], v[102:103], v[102:103]
	buffer_store_dwordx4 v[96:99], v151, s[12:15], 0 offen sc1
	s_nop 1
	v_cvt_pk_bf16_f32 v96, v100, v101
	v_cvt_pk_bf16_f32 v97, v102, v103
	v_cvt_pk_bf16_f32 v98, v114, v115
	v_cvt_pk_bf16_f32 v99, v116, v117
	buffer_store_dwordx4 v[96:99], v151, s[12:15], 0 offen offset:256 sc1
	s_nop 0
	v_add_u32_e32 v112, 0x4030, v150
	v_ashrrev_i32_e32 v113, 31, v112
	v_lshl_add_u32 v116, v152, 13, v149
	v_add_u32_e32 v177, 0x2400, v176
	global_load_dwordx4 v[194:197], v177, s[18:19]
	v_add_u32_e32 v177, 0x2410, v176
	global_load_dwordx4 v[198:201], v177, s[18:19]
	v_add_u32_e32 v177, 0x2420, v176
	global_load_dwordx4 v[202:205], v177, s[18:19]
	v_add_u32_e32 v177, 0x2430, v176
	global_load_dwordx4 v[206:209], v177, s[18:19]
	s_waitcnt vmcnt(16)
; __device__ __forceinline__ u32x4 pack8(const f32x4 v0, const f32x4 v1) { u32x4 w; w.x = pk2(v0[0], v0[1]); w.y = pk2(v0[2], v0[3]); w.z = pk2(v1[0], v1[1]); w.w = pk2(v1[2], v1[3]); return w; }
; __device__ __forceinline__ float row_rstd(const float* ssq, int row) {
;     const f32x4* p = (const f32x4*)(ssq + (size_t)row * 16);
;     const f32x4 a = p[0], b = p[1], c = p[2], d = p[3];
;     const float s = ((a[0] + a[1]) + (a[2] + a[3])) + ((b[0] + b[1]) + (b[2] + b[3])) + ((c[0] + c[1]) + (c[2] + c[3])) + ((d[0] + d[1]) + (d[2] + d[3]));
;     return rsqrtf(s * (1.0f / 1024.0f) + 1e-6f);
;     __device__ __forceinline__ void operator()(const f32x4 (&acc)[2][2][4][2], const Unit& u, int wr, int wc, int fr, int fq) const {
;     ...
;                 const int row = row0 + ai * 128 + m * 16; const float rs = row_rstd(ssq, row);
; #pragma unroll
;                 for (int bj = 0; bj < 2; ++bj) { f32x4 v0 = acc[ai][bj][m][0] * rs, v1 = acc[ai][bj][m][1] * rs;
; #pragma unroll
;                     for (int j = 0; j < 4; ++j) { const float a = fmaxf(v0[j], 0.f), b = fmaxf(v1[j], 0.f); v0[j] = a * a; v1[j] = b * b; }
;                     __builtin_amdgcn_raw_buffer_store_b128(pack8(v0, v1), rsrc, (unsigned)(((size_t)row * DFF + col0 + bj * 128) * 2), 0, 16  ); }
	v_pk_add_f32 v[96:97], v[210:211], v[212:213]
	v_pk_add_f32 v[98:99], v[214:215], v[216:217]
	v_pk_add_f32 v[100:101], v[232:233], v[234:235]
	v_pk_add_f32 v[102:103], v[236:237], v[238:239]
	v_pk_add_f32 v[96:97], v[96:97], v[98:99]
	v_pk_add_f32 v[100:101], v[100:101], v[102:103]
	v_pk_add_f32 v[96:97], v[96:97], v[100:101]
	v_add_f32_e32 v96, v96, v97
	s_nop 0
	s_nop 0
	v_fmamk_f32 v96, v96, 0x3a800000, v148
	v_mul_f32_e32 v97, 0x4b800000, v96
	v_cmp_gt_f32_e32 vcc, s71, v96
	s_nop 1
	v_cndmask_b32_e32 v96, v96, v97, vcc
	v_rsq_f32_e32 v98, v96
	v_lshlrev_b64 v[96:97], 6, v[112:113]
	v_lshl_add_u64 v[96:97], s[18:19], 0, v[96:97]
	v_mul_f32_e32 v99, 0x45800000, v98
	v_cndmask_b32_e32 v98, v98, v99, vcc
	v_pk_mul_f32 v[94:95], v[94:95], v[98:99] op_sel_hi:[1,0]
	v_pk_mul_f32 v[92:93], v[92:93], v[98:99] op_sel_hi:[1,0]
	v_pk_mul_f32 v[90:91], v[90:91], v[98:99] op_sel_hi:[1,0]
	v_pk_mul_f32 v[88:89], v[88:89], v[98:99] op_sel_hi:[1,0]
	v_pk_mul_f32 v[82:83], v[82:83], v[98:99] op_sel_hi:[1,0]
	v_pk_mul_f32 v[80:81], v[80:81], v[98:99] op_sel_hi:[1,0]
	v_pk_mul_f32 v[86:87], v[86:87], v[98:99] op_sel_hi:[1,0]
	v_pk_mul_f32 v[84:85], v[84:85], v[98:99] op_sel_hi:[1,0]
	v_max_f32_e32 v92, 0, v92
	v_max_f32_e32 v88, 0, v88
	v_max_f32_e32 v93, 0, v93
	v_max_f32_e32 v89, 0, v89
	v_max_f32_e32 v94, 0, v94
	v_max_f32_e32 v90, 0, v90
	v_max_f32_e32 v95, 0, v95
	v_max_f32_e32 v91, 0, v91
	v_max_f32_e32 v80, 0, v80
	v_max_f32_e32 v81, 0, v81
	v_max_f32_e32 v82, 0, v82
	v_max_f32_e32 v83, 0, v83
	v_max_f32_e32 v84, 0, v84
	v_max_f32_e32 v85, 0, v85
	v_max_f32_e32 v86, 0, v86
	v_max_f32_e32 v87, 0, v87
	v_pk_mul_f32 v[92:93], v[92:93], v[92:93]
	v_pk_mul_f32 v[88:89], v[88:89], v[88:89]
	v_pk_mul_f32 v[94:95], v[94:95], v[94:95]
	v_pk_mul_f32 v[90:91], v[90:91], v[90:91]
	v_pk_mul_f32 v[98:99], v[80:81], v[80:81]
	v_pk_mul_f32 v[100:101], v[82:83], v[82:83]
	v_cvt_pk_bf16_f32 v80, v92, v93
	v_cvt_pk_bf16_f32 v81, v94, v95
	v_cvt_pk_bf16_f32 v82, v88, v89
	v_cvt_pk_bf16_f32 v83, v90, v91
	v_pk_mul_f32 v[84:85], v[84:85], v[84:85]
	v_pk_mul_f32 v[86:87], v[86:87], v[86:87]
	buffer_store_dwordx4 v[80:83], v116, s[12:15], 0 offen sc1
	s_nop 1
	v_cvt_pk_bf16_f32 v80, v84, v85
	v_cvt_pk_bf16_f32 v81, v86, v87
	v_cvt_pk_bf16_f32 v82, v98, v99
	v_cvt_pk_bf16_f32 v83, v100, v101
	buffer_store_dwordx4 v[80:83], v116, s[12:15], 0 offen offset:256 sc1
	s_nop 0
	v_add_u32_e32 v96, 0x4080, v150
	v_ashrrev_i32_e32 v97, 31, v96
	v_lshl_add_u32 v100, v112, 13, v149
	v_add_u32_e32 v177, 0x2800, v176
	global_load_dwordx4 v[210:213], v177, s[18:19]
	v_add_u32_e32 v177, 0x2810, v176
	global_load_dwordx4 v[214:217], v177, s[18:19]
	v_add_u32_e32 v177, 0x2820, v176
	global_load_dwordx4 v[232:235], v177, s[18:19]
	v_add_u32_e32 v177, 0x2830, v176
	global_load_dwordx4 v[236:239], v177, s[18:19]
	s_waitcnt vmcnt(18)
	v_pk_add_f32 v[80:81], v[240:241], v[242:243]
	v_pk_add_f32 v[82:83], v[244:245], v[246:247]
	v_pk_add_f32 v[84:85], v[248:249], v[250:251]
	v_pk_add_f32 v[86:87], v[252:253], v[254:255]
	v_pk_add_f32 v[80:81], v[80:81], v[82:83]
	v_pk_add_f32 v[84:85], v[84:85], v[86:87]
	v_pk_add_f32 v[80:81], v[80:81], v[84:85]
	v_add_f32_e32 v80, v80, v81
	s_nop 0
	s_nop 0
	v_fmamk_f32 v80, v80, 0x3a800000, v148
	v_mul_f32_e32 v81, 0x4b800000, v80
	v_cmp_gt_f32_e32 vcc, s71, v80
	s_nop 1
	v_cndmask_b32_e32 v80, v80, v81, vcc
	v_rsq_f32_e32 v82, v80
	v_lshlrev_b64 v[80:81], 6, v[96:97]
	v_lshl_add_u64 v[80:81], s[18:19], 0, v[80:81]
	v_mul_f32_e32 v83, 0x45800000, v82
	v_cndmask_b32_e32 v82, v82, v83, vcc
	v_pk_mul_f32 v[78:79], v[78:79], v[82:83] op_sel_hi:[1,0]
	v_pk_mul_f32 v[76:77], v[76:77], v[82:83] op_sel_hi:[1,0]
	v_pk_mul_f32 v[74:75], v[74:75], v[82:83] op_sel_hi:[1,0]
	v_pk_mul_f32 v[72:73], v[72:73], v[82:83] op_sel_hi:[1,0]
	v_pk_mul_f32 v[66:67], v[66:67], v[82:83] op_sel_hi:[1,0]
	v_pk_mul_f32 v[64:65], v[64:65], v[82:83] op_sel_hi:[1,0]
	v_pk_mul_f32 v[70:71], v[70:71], v[82:83] op_sel_hi:[1,0]
	v_pk_mul_f32 v[68:69], v[68:69], v[82:83] op_sel_hi:[1,0]
	v_max_f32_e32 v76, 0, v76
	v_max_f32_e32 v72, 0, v72
	v_max_f32_e32 v77, 0, v77
	v_max_f32_e32 v73, 0, v73
	v_max_f32_e32 v78, 0, v78
	v_max_f32_e32 v74, 0, v74
	v_max_f32_e32 v79, 0, v79
	v_max_f32_e32 v75, 0, v75
	v_max_f32_e32 v64, 0, v64
	v_max_f32_e32 v65, 0, v65
	v_max_f32_e32 v66, 0, v66
	v_max_f32_e32 v67, 0, v67
	v_max_f32_e32 v68, 0, v68
	v_max_f32_e32 v69, 0, v69
	v_max_f32_e32 v70, 0, v70
	v_max_f32_e32 v71, 0, v71
	v_pk_mul_f32 v[76:77], v[76:77], v[76:77]
	v_pk_mul_f32 v[72:73], v[72:73], v[72:73]
	v_pk_mul_f32 v[78:79], v[78:79], v[78:79]
	v_pk_mul_f32 v[74:75], v[74:75], v[74:75]
	v_pk_mul_f32 v[82:83], v[64:65], v[64:65]
	v_pk_mul_f32 v[84:85], v[66:67], v[66:67]
	v_cvt_pk_bf16_f32 v64, v76, v77
	v_cvt_pk_bf16_f32 v65, v78, v79
	v_cvt_pk_bf16_f32 v66, v72, v73
	v_cvt_pk_bf16_f32 v67, v74, v75
	v_pk_mul_f32 v[68:69], v[68:69], v[68:69]
	v_pk_mul_f32 v[70:71], v[70:71], v[70:71]
	buffer_store_dwordx4 v[64:67], v100, s[12:15], 0 offen sc1
	s_nop 1
	v_cvt_pk_bf16_f32 v64, v68, v69
	v_cvt_pk_bf16_f32 v65, v70, v71
	v_cvt_pk_bf16_f32 v66, v82, v83
	v_cvt_pk_bf16_f32 v67, v84, v85
	buffer_store_dwordx4 v[64:67], v100, s[12:15], 0 offen offset:256 sc1
	s_nop 0
	v_add_u32_e32 v80, 0x4090, v150
	v_ashrrev_i32_e32 v81, 31, v80
	v_lshl_add_u32 v84, v96, 13, v149
	v_add_u32_e32 v177, 0x2c00, v176
	global_load_dwordx4 v[240:243], v177, s[18:19]
	v_add_u32_e32 v177, 0x2c10, v176
	global_load_dwordx4 v[244:247], v177, s[18:19]
	v_add_u32_e32 v177, 0x2c20, v176
	global_load_dwordx4 v[248:251], v177, s[18:19]
	v_add_u32_e32 v177, 0x2c30, v176
	global_load_dwordx4 v[252:255], v177, s[18:19]
	s_waitcnt vmcnt(18)
; __device__ __forceinline__ u32x4 pack8(const f32x4 v0, const f32x4 v1) { u32x4 w; w.x = pk2(v0[0], v0[1]); w.y = pk2(v0[2], v0[3]); w.z = pk2(v1[0], v1[1]); w.w = pk2(v1[2], v1[3]); return w; }
; __device__ __forceinline__ float row_rstd(const float* ssq, int row) {
;     const f32x4* p = (const f32x4*)(ssq + (size_t)row * 16);
;     const f32x4 a = p[0], b = p[1], c = p[2], d = p[3];
;     const float s = ((a[0] + a[1]) + (a[2] + a[3])) + ((b[0] + b[1]) + (b[2] + b[3])) + ((c[0] + c[1]) + (c[2] + c[3])) + ((d[0] + d[1]) + (d[2] + d[3]));
;     return rsqrtf(s * (1.0f / 1024.0f) + 1e-6f);
;     __device__ __forceinline__ void operator()(const f32x4 (&acc)[2][2][4][2], const Unit& u, int wr, int wc, int fr, int fq) const {
;     ...
;                 const int row = row0 + ai * 128 + m * 16; const float rs = row_rstd(ssq, row);
; #pragma unroll
;                 for (int bj = 0; bj < 2; ++bj) { f32x4 v0 = acc[ai][bj][m][0] * rs, v1 = acc[ai][bj][m][1] * rs;
; #pragma unroll
;                     for (int j = 0; j < 4; ++j) { const float a = fmaxf(v0[j], 0.f), b = fmaxf(v1[j], 0.f); v0[j] = a * a; v1[j] = b * b; }
;                     __builtin_amdgcn_raw_buffer_store_b128(pack8(v0, v1), rsrc, (unsigned)(((size_t)row * DFF + col0 + bj * 128) * 2), 0, 16  ); }
	v_pk_add_f32 v[64:65], v[178:179], v[180:181]
	v_pk_add_f32 v[66:67], v[182:183], v[184:185]
	v_pk_add_f32 v[68:69], v[186:187], v[188:189]
	v_pk_add_f32 v[70:71], v[190:191], v[192:193]
	v_pk_add_f32 v[64:65], v[64:65], v[66:67]
	v_pk_add_f32 v[68:69], v[68:69], v[70:71]
	v_pk_add_f32 v[64:65], v[64:65], v[68:69]
	v_add_f32_e32 v64, v64, v65
	s_nop 0
	s_nop 0
	v_fmamk_f32 v64, v64, 0x3a800000, v148
	v_mul_f32_e32 v65, 0x4b800000, v64
	v_cmp_gt_f32_e32 vcc, s71, v64
	s_nop 1
	v_cndmask_b32_e32 v64, v64, v65, vcc
	v_rsq_f32_e32 v66, v64
	v_lshlrev_b64 v[64:65], 6, v[80:81]
	v_lshl_add_u64 v[64:65], s[18:19], 0, v[64:65]
	v_mul_f32_e32 v67, 0x45800000, v66
	v_cndmask_b32_e32 v66, v66, v67, vcc
	v_pk_mul_f32 v[62:63], v[62:63], v[66:67] op_sel_hi:[1,0]
	v_pk_mul_f32 v[60:61], v[60:61], v[66:67] op_sel_hi:[1,0]
	v_pk_mul_f32 v[58:59], v[58:59], v[66:67] op_sel_hi:[1,0]
	v_pk_mul_f32 v[56:57], v[56:57], v[66:67] op_sel_hi:[1,0]
	v_pk_mul_f32 v[50:51], v[50:51], v[66:67] op_sel_hi:[1,0]
	v_pk_mul_f32 v[48:49], v[48:49], v[66:67] op_sel_hi:[1,0]
	v_pk_mul_f32 v[54:55], v[54:55], v[66:67] op_sel_hi:[1,0]
	v_pk_mul_f32 v[52:53], v[52:53], v[66:67] op_sel_hi:[1,0]
	v_max_f32_e32 v60, 0, v60
	v_max_f32_e32 v56, 0, v56
	v_max_f32_e32 v61, 0, v61
	v_max_f32_e32 v57, 0, v57
	v_max_f32_e32 v62, 0, v62
	v_max_f32_e32 v58, 0, v58
	v_max_f32_e32 v63, 0, v63
	v_max_f32_e32 v59, 0, v59
	v_max_f32_e32 v48, 0, v48
	v_max_f32_e32 v49, 0, v49
	v_max_f32_e32 v50, 0, v50
	v_max_f32_e32 v51, 0, v51
	v_max_f32_e32 v52, 0, v52
	v_max_f32_e32 v53, 0, v53
	v_max_f32_e32 v54, 0, v54
	v_max_f32_e32 v55, 0, v55
	v_pk_mul_f32 v[60:61], v[60:61], v[60:61]
	v_pk_mul_f32 v[56:57], v[56:57], v[56:57]
	v_pk_mul_f32 v[62:63], v[62:63], v[62:63]
	v_pk_mul_f32 v[58:59], v[58:59], v[58:59]
	v_pk_mul_f32 v[66:67], v[48:49], v[48:49]
	v_pk_mul_f32 v[68:69], v[50:51], v[50:51]
	v_cvt_pk_bf16_f32 v48, v60, v61
	v_cvt_pk_bf16_f32 v49, v62, v63
	v_cvt_pk_bf16_f32 v50, v56, v57
	v_cvt_pk_bf16_f32 v51, v58, v59
	v_pk_mul_f32 v[52:53], v[52:53], v[52:53]
	v_pk_mul_f32 v[54:55], v[54:55], v[54:55]
	buffer_store_dwordx4 v[48:51], v84, s[12:15], 0 offen sc1
	s_nop 1
	v_cvt_pk_bf16_f32 v48, v52, v53
	v_cvt_pk_bf16_f32 v49, v54, v55
	v_cvt_pk_bf16_f32 v50, v66, v67
	v_cvt_pk_bf16_f32 v51, v68, v69
	buffer_store_dwordx4 v[48:51], v84, s[12:15], 0 offen offset:256 sc1
	s_nop 0
	v_add_u32_e32 v64, 0x40a0, v150
	v_ashrrev_i32_e32 v65, 31, v64
	v_lshl_add_u32 v68, v80, 13, v149
	s_waitcnt vmcnt(14)
	v_pk_add_f32 v[48:49], v[194:195], v[196:197]
	v_pk_add_f32 v[50:51], v[198:199], v[200:201]
	v_pk_add_f32 v[52:53], v[202:203], v[204:205]
	v_pk_add_f32 v[54:55], v[206:207], v[208:209]
	v_pk_add_f32 v[48:49], v[48:49], v[50:51]
	v_pk_add_f32 v[52:53], v[52:53], v[54:55]
	v_pk_add_f32 v[48:49], v[48:49], v[52:53]
	v_add_f32_e32 v48, v48, v49
	s_nop 0
	s_nop 0
	v_fmamk_f32 v48, v48, 0x3a800000, v148
	v_mul_f32_e32 v49, 0x4b800000, v48
	v_cmp_gt_f32_e32 vcc, s71, v48
	s_nop 1
	v_cndmask_b32_e32 v48, v48, v49, vcc
	v_rsq_f32_e32 v50, v48
	v_lshlrev_b64 v[48:49], 6, v[64:65]
	v_lshl_add_u64 v[48:49], s[18:19], 0, v[48:49]
	v_mul_f32_e32 v51, 0x45800000, v50
	v_cndmask_b32_e32 v50, v50, v51, vcc
	v_pk_mul_f32 v[46:47], v[46:47], v[50:51] op_sel_hi:[1,0]
	v_pk_mul_f32 v[44:45], v[44:45], v[50:51] op_sel_hi:[1,0]
	v_pk_mul_f32 v[42:43], v[42:43], v[50:51] op_sel_hi:[1,0]
	v_pk_mul_f32 v[40:41], v[40:41], v[50:51] op_sel_hi:[1,0]
	v_pk_mul_f32 v[34:35], v[34:35], v[50:51] op_sel_hi:[1,0]
	v_pk_mul_f32 v[32:33], v[32:33], v[50:51] op_sel_hi:[1,0]
	v_pk_mul_f32 v[38:39], v[38:39], v[50:51] op_sel_hi:[1,0]
	v_pk_mul_f32 v[36:37], v[36:37], v[50:51] op_sel_hi:[1,0]
	v_max_f32_e32 v44, 0, v44
	v_max_f32_e32 v40, 0, v40
	v_max_f32_e32 v45, 0, v45
	v_max_f32_e32 v41, 0, v41
	v_max_f32_e32 v46, 0, v46
	v_max_f32_e32 v42, 0, v42
	v_max_f32_e32 v47, 0, v47
	v_max_f32_e32 v43, 0, v43
	v_max_f32_e32 v32, 0, v32
	v_max_f32_e32 v33, 0, v33
	v_max_f32_e32 v34, 0, v34
	v_max_f32_e32 v35, 0, v35
	v_max_f32_e32 v36, 0, v36
	v_max_f32_e32 v37, 0, v37
	v_max_f32_e32 v38, 0, v38
	v_max_f32_e32 v39, 0, v39
	v_pk_mul_f32 v[44:45], v[44:45], v[44:45]
	v_pk_mul_f32 v[40:41], v[40:41], v[40:41]
	v_pk_mul_f32 v[46:47], v[46:47], v[46:47]
	v_pk_mul_f32 v[42:43], v[42:43], v[42:43]
	v_pk_mul_f32 v[50:51], v[32:33], v[32:33]
	v_pk_mul_f32 v[52:53], v[34:35], v[34:35]
	v_cvt_pk_bf16_f32 v32, v44, v45
	v_cvt_pk_bf16_f32 v33, v46, v47
	v_cvt_pk_bf16_f32 v34, v40, v41
	v_cvt_pk_bf16_f32 v35, v42, v43
	v_pk_mul_f32 v[36:37], v[36:37], v[36:37]
	v_pk_mul_f32 v[38:39], v[38:39], v[38:39]
	buffer_store_dwordx4 v[32:35], v68, s[12:15], 0 offen sc1
	s_nop 1
	v_cvt_pk_bf16_f32 v32, v36, v37
	v_cvt_pk_bf16_f32 v33, v38, v39
	v_cvt_pk_bf16_f32 v34, v50, v51
	v_cvt_pk_bf16_f32 v35, v52, v53
	buffer_store_dwordx4 v[32:35], v68, s[12:15], 0 offen offset:256 sc1
	s_nop 0
	v_add_u32_e32 v48, 0x40b0, v150
	v_ashrrev_i32_e32 v49, 31, v48
	v_lshl_add_u32 v52, v64, 13, v149
	s_waitcnt vmcnt(10)
; __device__ __forceinline__ u32x4 pack8(const f32x4 v0, const f32x4 v1) { u32x4 w; w.x = pk2(v0[0], v0[1]); w.y = pk2(v0[2], v0[3]); w.z = pk2(v1[0], v1[1]); w.w = pk2(v1[2], v1[3]); return w; }
; __device__ __forceinline__ float row_rstd(const float* ssq, int row) {
;     const f32x4* p = (const f32x4*)(ssq + (size_t)row * 16);
;     const f32x4 a = p[0], b = p[1], c = p[2], d = p[3];
;     const float s = ((a[0] + a[1]) + (a[2] + a[3])) + ((b[0] + b[1]) + (b[2] + b[3])) + ((c[0] + c[1]) + (c[2] + c[3])) + ((d[0] + d[1]) + (d[2] + d[3]));
;     return rsqrtf(s * (1.0f / 1024.0f) + 1e-6f);
;     __device__ __forceinline__ void operator()(const f32x4 (&acc)[2][2][4][2], const Unit& u, int wr, int wc, int fr, int fq) const {
;     ...
;                 const int row = row0 + ai * 128 + m * 16; const float rs = row_rstd(ssq, row);
; #pragma unroll
;                 for (int bj = 0; bj < 2; ++bj) { f32x4 v0 = acc[ai][bj][m][0] * rs, v1 = acc[ai][bj][m][1] * rs;
; #pragma unroll
;                     for (int j = 0; j < 4; ++j) { const float a = fmaxf(v0[j], 0.f), b = fmaxf(v1[j], 0.f); v0[j] = a * a; v1[j] = b * b; }
;                     __builtin_amdgcn_raw_buffer_store_b128(pack8(v0, v1), rsrc, (unsigned)(((size_t)row * DFF + col0 + bj * 128) * 2), 0, 16  ); }
;             }
;         asm volatile("s_waitcnt vmcnt(0)" ::: "memory");
;         if (fr == 0 && fq == 0) (void)__hip_atomic_fetch_add(ready + 64 * (pm_off + u.pm), 1u, __ATOMIC_RELAXED, __HIP_MEMORY_SCOPE_AGENT);
	v_pk_add_f32 v[32:33], v[210:211], v[212:213]
	v_pk_add_f32 v[34:35], v[214:215], v[216:217]
	v_pk_add_f32 v[36:37], v[232:233], v[234:235]
	v_pk_add_f32 v[38:39], v[236:237], v[238:239]
	v_pk_add_f32 v[32:33], v[32:33], v[34:35]
	v_pk_add_f32 v[36:37], v[36:37], v[38:39]
	v_pk_add_f32 v[32:33], v[32:33], v[36:37]
	v_add_f32_e32 v32, v32, v33
	s_nop 0
	s_nop 0
	v_fmamk_f32 v32, v32, 0x3a800000, v148
	v_mul_f32_e32 v33, 0x4b800000, v32
	v_cmp_gt_f32_e32 vcc, s71, v32
	s_nop 1
	v_cndmask_b32_e32 v32, v32, v33, vcc
	v_rsq_f32_e32 v34, v32
	v_lshlrev_b64 v[32:33], 6, v[48:49]
	v_lshl_add_u64 v[32:33], s[18:19], 0, v[32:33]
	v_mul_f32_e32 v35, 0x45800000, v34
	v_cndmask_b32_e32 v34, v34, v35, vcc
	v_pk_mul_f32 v[30:31], v[30:31], v[34:35] op_sel_hi:[1,0]
	v_pk_mul_f32 v[28:29], v[28:29], v[34:35] op_sel_hi:[1,0]
	v_pk_mul_f32 v[26:27], v[26:27], v[34:35] op_sel_hi:[1,0]
	v_pk_mul_f32 v[24:25], v[24:25], v[34:35] op_sel_hi:[1,0]
	v_pk_mul_f32 v[18:19], v[18:19], v[34:35] op_sel_hi:[1,0]
	v_pk_mul_f32 v[16:17], v[16:17], v[34:35] op_sel_hi:[1,0]
	v_pk_mul_f32 v[22:23], v[22:23], v[34:35] op_sel_hi:[1,0]
	v_pk_mul_f32 v[20:21], v[20:21], v[34:35] op_sel_hi:[1,0]
	v_max_f32_e32 v28, 0, v28
	v_max_f32_e32 v24, 0, v24
	v_max_f32_e32 v29, 0, v29
	v_max_f32_e32 v25, 0, v25
	v_max_f32_e32 v30, 0, v30
	v_max_f32_e32 v26, 0, v26
	v_max_f32_e32 v31, 0, v31
	v_max_f32_e32 v27, 0, v27
	v_max_f32_e32 v16, 0, v16
	v_max_f32_e32 v17, 0, v17
	v_max_f32_e32 v18, 0, v18
	v_max_f32_e32 v19, 0, v19
	v_max_f32_e32 v20, 0, v20
	v_max_f32_e32 v21, 0, v21
	v_max_f32_e32 v22, 0, v22
	v_max_f32_e32 v23, 0, v23
	v_pk_mul_f32 v[28:29], v[28:29], v[28:29]
	v_pk_mul_f32 v[24:25], v[24:25], v[24:25]
	v_pk_mul_f32 v[30:31], v[30:31], v[30:31]
	v_pk_mul_f32 v[26:27], v[26:27], v[26:27]
	v_pk_mul_f32 v[34:35], v[16:17], v[16:17]
	v_pk_mul_f32 v[36:37], v[18:19], v[18:19]
	v_cvt_pk_bf16_f32 v16, v28, v29
	v_cvt_pk_bf16_f32 v17, v30, v31
	v_cvt_pk_bf16_f32 v18, v24, v25
	v_cvt_pk_bf16_f32 v19, v26, v27
	v_pk_mul_f32 v[20:21], v[20:21], v[20:21]
	v_pk_mul_f32 v[22:23], v[22:23], v[22:23]
	buffer_store_dwordx4 v[16:19], v52, s[12:15], 0 offen sc1
	s_nop 1
	v_cvt_pk_bf16_f32 v16, v20, v21
	v_cvt_pk_bf16_f32 v17, v22, v23
	v_cvt_pk_bf16_f32 v18, v34, v35
	v_cvt_pk_bf16_f32 v19, v36, v37
	buffer_store_dwordx4 v[16:19], v52, s[12:15], 0 offen offset:256 sc1
	s_nop 0
	s_waitcnt vmcnt(6)
	v_pk_add_f32 v[16:17], v[240:241], v[242:243]
	v_pk_add_f32 v[18:19], v[244:245], v[246:247]
	v_pk_add_f32 v[20:21], v[248:249], v[250:251]
	v_pk_add_f32 v[22:23], v[252:253], v[254:255]
	v_pk_add_f32 v[16:17], v[16:17], v[18:19]
	v_pk_add_f32 v[20:21], v[20:21], v[22:23]
	v_pk_add_f32 v[16:17], v[16:17], v[20:21]
	v_add_f32_e32 v16, v16, v17
	s_nop 0
	s_nop 0
	v_fmamk_f32 v16, v16, 0x3a800000, v148
	v_mul_f32_e32 v17, 0x4b800000, v16
	v_cmp_gt_f32_e32 vcc, s71, v16
	s_nop 1
	v_cndmask_b32_e32 v16, v16, v17, vcc
	v_rsq_f32_e32 v16, v16
	v_lshl_add_u32 v17, v48, 13, v149
	v_mul_f32_e32 v18, 0x45800000, v16
	v_cndmask_b32_e32 v16, v16, v18, vcc
	v_pk_mul_f32 v[14:15], v[14:15], v[16:17] op_sel_hi:[1,0]
	v_pk_mul_f32 v[12:13], v[12:13], v[16:17] op_sel_hi:[1,0]
	v_pk_mul_f32 v[10:11], v[10:11], v[16:17] op_sel_hi:[1,0]
	v_pk_mul_f32 v[8:9], v[8:9], v[16:17] op_sel_hi:[1,0]
	v_pk_mul_f32 v[2:3], v[2:3], v[16:17] op_sel_hi:[1,0]
	v_pk_mul_f32 v[0:1], v[0:1], v[16:17] op_sel_hi:[1,0]
	v_pk_mul_f32 v[6:7], v[6:7], v[16:17] op_sel_hi:[1,0]
	v_pk_mul_f32 v[4:5], v[4:5], v[16:17] op_sel_hi:[1,0]
	v_max_f32_e32 v12, 0, v12
	v_max_f32_e32 v8, 0, v8
	v_max_f32_e32 v13, 0, v13
	v_max_f32_e32 v9, 0, v9
	v_max_f32_e32 v14, 0, v14
	v_max_f32_e32 v10, 0, v10
	v_max_f32_e32 v15, 0, v15
	v_max_f32_e32 v11, 0, v11
	v_max_f32_e32 v0, 0, v0
	v_max_f32_e32 v1, 0, v1
	v_max_f32_e32 v2, 0, v2
	v_max_f32_e32 v3, 0, v3
	v_max_f32_e32 v4, 0, v4
	v_max_f32_e32 v5, 0, v5
	v_max_f32_e32 v6, 0, v6
	v_max_f32_e32 v7, 0, v7
	v_pk_mul_f32 v[12:13], v[12:13], v[12:13]
	v_pk_mul_f32 v[8:9], v[8:9], v[8:9]
	v_pk_mul_f32 v[14:15], v[14:15], v[14:15]
	v_pk_mul_f32 v[10:11], v[10:11], v[10:11]
	v_mul_f32_e32 v16, v0, v0
	v_mul_f32_e32 v18, v1, v1
	v_mul_f32_e32 v19, v2, v2
	v_mul_f32_e32 v20, v3, v3
	v_cvt_pk_bf16_f32 v0, v12, v13
	v_cvt_pk_bf16_f32 v1, v14, v15
	v_cvt_pk_bf16_f32 v2, v8, v9
	v_cvt_pk_bf16_f32 v3, v10, v11
	v_pk_mul_f32 v[4:5], v[4:5], v[4:5]
	v_pk_mul_f32 v[6:7], v[6:7], v[6:7]
	buffer_store_dwordx4 v[0:3], v17, s[12:15], 0 offen sc1
	s_nop 1
	v_cvt_pk_bf16_f32 v0, v4, v5
	v_cvt_pk_bf16_f32 v1, v6, v7
	v_cvt_pk_bf16_f32 v2, v16, v18
	v_cvt_pk_bf16_f32 v3, v19, v20
	buffer_store_dwordx4 v[0:3], v17, s[12:15], 0 offen offset:256 sc1
	s_waitcnt vmcnt(0)
	s_and_saveexec_b64 s[38:39], s[10:11]
	s_cbranch_execz .LBB0_973
	s_mov_b64 s[40:41], exec
	v_mbcnt_lo_u32_b32 v0, s40, 0
	v_mbcnt_hi_u32_b32 v0, s41, v0
	v_cmp_eq_u32_e32 vcc, 0, v0
	s_and_b64 s[6:7], exec, vcc
	s_mov_b64 exec, s[6:7]
	s_cbranch_execz .LBB0_973
	s_lshl_b32 s6, s75, 6
	s_addk_i32 s6, 0x1000
	s_ashr_i32 s7, s6, 31
	s_lshl_b64 s[6:7], s[6:7], 2
	s_add_u32 s6, s73, s6
	s_addc_u32 s7, s74, s7
	s_bcnt1_i32_b64 s8, s[40:41]
	v_mov_b32_e32 v0, s8
	global_atomic_add v131, v0, s[6:7]
	s_branch .LBB0_973

; #define PG8_STAGE(bufoff, gbase, voff) do { _Pragma("unroll") for (int _i = 0; _i < 2; ++_i) \
;         __builtin_amdgcn_global_load_lds((const unsigned*)((const char*)(gbase) + (voff)[_i]), (LAS unsigned*)(lds + (bufoff) + ldsw + _i * 8192), 16, 0, 0); } while (0)
; #define PG8_LDA(dst, b, h) do { _Pragma("unroll") for (int m = 0; m < 4; ++m) _Pragma("unroll") for (int k = 0; k < 2; ++k) dst[m][k] = *(const LAS bf16x8*)(lds + PG8_SA(b, h) + aoff + m * 2048 + k * 1024); } while (0)
; #define PG8_LDB(dst, b, h) do { _Pragma("unroll") for (int n = 0; n < 2; ++n) _Pragma("unroll") for (int k = 0; k < 2; ++k) dst[n][k] = *(const LAS bf16x8*)(lds + PG8_SB(b, h) + boff + n * 2048 + k * 1024); } while (0)
; #define PG8_MMA(ai, bj, At, Bt) do { __builtin_amdgcn_s_setprio(1); _Pragma("unroll") for (int m = 0; m < 4; ++m) _Pragma("unroll") for (int n = 0; n < 2; ++n) _Pragma("unroll") for (int k = 0; k < 2; ++k) \
;         acc[ai][bj][m][n] = __builtin_amdgcn_mfma_f32_16x16x32_bf16(Bt[n][k], At[m][k], acc[ai][bj][m][n], 0, 0, 0); __builtin_amdgcn_s_setprio(0); } while (0)
; #define PG8_WAIT_V(n) asm volatile("s_waitcnt vmcnt(" #n ")" ::: "memory")
;     ...
;             PG8_LDB(B0, 0, 0); PG8_SCHED; PG8_LDA(At, 0, 0); PG8_STAGE(PG8_SA(1, 1), a1 + hA, voffA);
;             PG8_WAIT_L(8); PG8_BAR; PG8_WAIT_L(0); PG8_MMA(0, 0, At, B0); PG8_BAR; PG8_SCHED;
;             PG8_LDB(B1, 0, 1); PG8_STAGE(PG8_SB(0, 0), b2, voffB);
;             PG8_BAR; PG8_WAIT_L(0); PG8_MMA(0, 1, At, B1); PG8_BAR;
;             PG8_LDA(At, 0, 1); PG8_STAGE(PG8_SA(0, 0), a2, voffA);
;             PG8_BAR; PG8_WAIT_L(0); PG8_MMA(1, 0, At, B0); PG8_BAR; PG8_SCHED;
;             PG8_STAGE(PG8_SB(0, 1), b2 + hB, voffB);
;             PG8_WAIT_V(6); PG8_BAR; PG8_MMA(1, 1, At, B1); PG8_BAR;
;             PG8_LDB(B0, 1, 0); PG8_SCHED; PG8_LDA(At, 1, 0); PG8_STAGE(PG8_SA(0, 1), a2 + hA, voffA);
;             PG8_WAIT_L(8); PG8_BAR; PG8_WAIT_L(0); PG8_MMA(0, 0, At, B0); PG8_BAR; PG8_SCHED;
;             PG8_LDB(B1, 1, 1); PG8_STAGE(PG8_SB(1, 0), b3, voffB);
;             PG8_BAR; PG8_WAIT_L(0); PG8_MMA(0, 1, At, B1); PG8_BAR;
;             PG8_LDA(At, 1, 1); PG8_STAGE(PG8_SA(1, 0), a3, voffA);
;             PG8_BAR; PG8_WAIT_L(0); PG8_MMA(1, 0, At, B0); PG8_BAR; PG8_SCHED;
;             PG8_STAGE(PG8_SB(1, 1), b3 + hB, voffB);
;             PG8_WAIT_V(6); PG8_BAR; PG8_MMA(1, 1, At, B1); PG8_BAR;
.LBB0_1288:
	ds_read_b128 v[146:149], v155
	ds_read_b128 v[160:163], v155 offset:1024
	ds_read_b128 v[170:173], v155 offset:2048
	ds_read_b128 v[174:177], v155 offset:3072
	s_add_u32 s36, s34, 0xfffc0080
	s_addc_u32 s37, s35, -1
	s_cmp_eq_u32 s42, 12
	s_cselect_b32 s39, s7, s37
	s_cselect_b32 s38, s8, s36
	s_cselect_b32 s37, s9, s33
	s_cselect_b32 s36, s23, s25
	v_lshl_add_u64 v[150:151], s[34:35], 0, v[138:139]
	s_add_i32 m0, s31, 0xc000
	ds_read_b128 v[178:181], v156
	ds_read_b128 v[182:185], v156 offset:1024
	ds_read_b128 v[186:189], v156 offset:2048
	ds_read_b128 v[190:193], v156 offset:3072
	ds_read_b128 v[194:197], v156 offset:4096
	ds_read_b128 v[198:201], v156 offset:5120
	ds_read_b128 v[202:205], v156 offset:6144
	ds_read_b128 v[206:209], v156 offset:7168
	global_load_lds_dwordx4 v[150:151], off
	v_lshl_add_u64 v[150:151], s[34:35], 0, v[136:137]
	s_add_i32 m0, s31, 0xe000
	s_nop 0
	global_load_lds_dwordx4 v[150:151], off
	s_waitcnt lgkmcnt(8)
	s_barrier
	s_waitcnt lgkmcnt(0)
	s_setprio 1
	s_waitcnt lgkmcnt(0)
	v_mfma_f32_16x16x32_bf16 v[124:127], v[146:149], v[178:181], v[124:127]
	v_mfma_f32_16x16x32_bf16 v[120:123], v[170:173], v[178:181], v[120:123]
	v_mfma_f32_16x16x32_bf16 v[108:111], v[146:149], v[186:189], v[108:111]
	v_mfma_f32_16x16x32_bf16 v[104:107], v[170:173], v[186:189], v[104:107]
	v_mfma_f32_16x16x32_bf16 v[92:95], v[146:149], v[194:197], v[92:95]
	v_mfma_f32_16x16x32_bf16 v[88:91], v[170:173], v[194:197], v[88:91]
	v_mfma_f32_16x16x32_bf16 v[76:79], v[146:149], v[202:205], v[76:79]
	v_mfma_f32_16x16x32_bf16 v[72:75], v[170:173], v[202:205], v[72:75]
	v_mfma_f32_16x16x32_bf16 v[124:127], v[160:163], v[182:185], v[124:127]
	v_mfma_f32_16x16x32_bf16 v[120:123], v[174:177], v[182:185], v[120:123]
	v_mfma_f32_16x16x32_bf16 v[108:111], v[160:163], v[190:193], v[108:111]
	v_mfma_f32_16x16x32_bf16 v[104:107], v[174:177], v[190:193], v[104:107]
	v_mfma_f32_16x16x32_bf16 v[92:95], v[160:163], v[198:201], v[92:95]
	v_mfma_f32_16x16x32_bf16 v[88:91], v[174:177], v[198:201], v[88:91]
	v_mfma_f32_16x16x32_bf16 v[76:79], v[160:163], v[206:209], v[76:79]
	v_mfma_f32_16x16x32_bf16 v[72:75], v[174:177], v[206:209], v[72:75]
	s_setprio 0
	s_barrier
	s_add_i32 s43, s63, s55
	v_lshl_add_u64 v[150:151], s[36:37], 0, v[130:131]
	s_mov_b32 m0, s43
	ds_read_b128 v[210:213], v157
	ds_read_b128 v[214:217], v157 offset:1024
	ds_read_b128 v[218:221], v157 offset:2048
	ds_read_b128 v[222:225], v157 offset:3072
	global_load_lds_dwordx4 v[150:151], off
	v_lshl_add_u64 v[164:165], s[36:37], 0, v[134:135]
	s_add_i32 m0, s43, 0x2000
	s_nop 0
	global_load_lds_dwordx4 v[164:165], off
	s_barrier
	s_waitcnt lgkmcnt(0)
	s_setprio 1
	s_waitcnt lgkmcnt(0)
	v_mfma_f32_16x16x32_bf16 v[116:119], v[210:213], v[178:181], v[116:119]
	v_mfma_f32_16x16x32_bf16 v[112:115], v[218:221], v[178:181], v[112:115]
	v_mfma_f32_16x16x32_bf16 v[100:103], v[210:213], v[186:189], v[100:103]
	v_mfma_f32_16x16x32_bf16 v[96:99], v[218:221], v[186:189], v[96:99]
	v_mfma_f32_16x16x32_bf16 v[84:87], v[210:213], v[194:197], v[84:87]
	v_mfma_f32_16x16x32_bf16 v[80:83], v[218:221], v[194:197], v[80:83]
	v_mfma_f32_16x16x32_bf16 v[68:71], v[210:213], v[202:205], v[68:71]
	v_mfma_f32_16x16x32_bf16 v[64:67], v[218:221], v[202:205], v[64:67]
	v_mfma_f32_16x16x32_bf16 v[116:119], v[214:217], v[182:185], v[116:119]
	v_mfma_f32_16x16x32_bf16 v[112:115], v[222:225], v[182:185], v[112:115]
	v_mfma_f32_16x16x32_bf16 v[100:103], v[214:217], v[190:193], v[100:103]
	v_mfma_f32_16x16x32_bf16 v[96:99], v[222:225], v[190:193], v[96:99]
	v_mfma_f32_16x16x32_bf16 v[84:87], v[214:217], v[198:201], v[84:87]
	v_mfma_f32_16x16x32_bf16 v[80:83], v[222:225], v[198:201], v[80:83]
	v_mfma_f32_16x16x32_bf16 v[68:71], v[214:217], v[206:209], v[68:71]
	v_mfma_f32_16x16x32_bf16 v[64:67], v[222:225], v[206:209], v[64:67]
	s_setprio 0
	s_mov_b32 m0, s31
	v_lshl_add_u64 v[226:227], s[38:39], 0, v[128:129]
	s_barrier
	ds_read_b128 v[178:181], v156 offset:16384
	ds_read_b128 v[182:185], v156 offset:17408
	ds_read_b128 v[186:189], v156 offset:18432
	ds_read_b128 v[190:193], v156 offset:19456
	ds_read_b128 v[194:197], v156 offset:20480
	ds_read_b128 v[198:201], v156 offset:21504
	ds_read_b128 v[202:205], v156 offset:22528
	ds_read_b128 v[206:209], v156 offset:23552
	global_load_lds_dwordx4 v[226:227], off
	v_lshl_add_u64 v[228:229], s[38:39], 0, v[132:133]
	s_mov_b32 m0, s56
	s_nop 0
	global_load_lds_dwordx4 v[228:229], off
	s_barrier
	s_waitcnt lgkmcnt(0)
	s_setprio 1
	s_waitcnt lgkmcnt(0)
	v_mfma_f32_16x16x32_bf16 v[60:63], v[146:149], v[178:181], v[60:63]
	v_mfma_f32_16x16x32_bf16 v[56:59], v[170:173], v[178:181], v[56:59]
	v_mfma_f32_16x16x32_bf16 v[44:47], v[146:149], v[186:189], v[44:47]
	v_mfma_f32_16x16x32_bf16 v[40:43], v[170:173], v[186:189], v[40:43]
	v_mfma_f32_16x16x32_bf16 v[28:31], v[146:149], v[194:197], v[28:31]
	v_mfma_f32_16x16x32_bf16 v[24:27], v[170:173], v[194:197], v[24:27]
	v_mfma_f32_16x16x32_bf16 v[12:15], v[146:149], v[202:205], v[12:15]
	v_mfma_f32_16x16x32_bf16 v[8:11], v[170:173], v[202:205], v[8:11]
	v_mfma_f32_16x16x32_bf16 v[60:63], v[160:163], v[182:185], v[60:63]
	v_mfma_f32_16x16x32_bf16 v[56:59], v[174:177], v[182:185], v[56:59]
	v_mfma_f32_16x16x32_bf16 v[44:47], v[160:163], v[190:193], v[44:47]
	v_mfma_f32_16x16x32_bf16 v[40:43], v[174:177], v[190:193], v[40:43]
	v_mfma_f32_16x16x32_bf16 v[28:31], v[160:163], v[198:201], v[28:31]
	v_mfma_f32_16x16x32_bf16 v[24:27], v[174:177], v[198:201], v[24:27]
	v_mfma_f32_16x16x32_bf16 v[12:15], v[160:163], v[206:209], v[12:15]
	v_mfma_f32_16x16x32_bf16 v[8:11], v[174:177], v[206:209], v[8:11]
	s_setprio 0
	s_barrier
; #define PG8_STAGE(bufoff, gbase, voff) do { _Pragma("unroll") for (int _i = 0; _i < 2; ++_i) \
;         __builtin_amdgcn_global_load_lds((const unsigned*)((const char*)(gbase) + (voff)[_i]), (LAS unsigned*)(lds + (bufoff) + ldsw + _i * 8192), 16, 0, 0); } while (0)
; #define PG8_LDA(dst, b, h) do { _Pragma("unroll") for (int m = 0; m < 4; ++m) _Pragma("unroll") for (int k = 0; k < 2; ++k) dst[m][k] = *(const LAS bf16x8*)(lds + PG8_SA(b, h) + aoff + m * 2048 + k * 1024); } while (0)
; #define PG8_LDB(dst, b, h) do { _Pragma("unroll") for (int n = 0; n < 2; ++n) _Pragma("unroll") for (int k = 0; k < 2; ++k) dst[n][k] = *(const LAS bf16x8*)(lds + PG8_SB(b, h) + boff + n * 2048 + k * 1024); } while (0)
; #define PG8_MMA(ai, bj, At, Bt) do { __builtin_amdgcn_s_setprio(1); _Pragma("unroll") for (int m = 0; m < 4; ++m) _Pragma("unroll") for (int n = 0; n < 2; ++n) _Pragma("unroll") for (int k = 0; k < 2; ++k) \
;         acc[ai][bj][m][n] = __builtin_amdgcn_mfma_f32_16x16x32_bf16(Bt[n][k], At[m][k], acc[ai][bj][m][n], 0, 0, 0); __builtin_amdgcn_s_setprio(0); } while (0)
; #define PG8_WAIT_V(n) asm volatile("s_waitcnt vmcnt(" #n ")" ::: "memory")
; #define PG8_WAIT_L(n) asm volatile("s_waitcnt lgkmcnt(" #n ")" ::: "memory")
; #define PG8_BAR __builtin_amdgcn_s_barrier()
; #define PG8_SCHED __builtin_amdgcn_sched_barrier(0)
;     ...
;             PG8_STAGE(PG8_SB(0, 1), b2 + hB, voffB);
;             PG8_WAIT_V(6); PG8_BAR; PG8_MMA(1, 1, At, B1); PG8_BAR;
;             PG8_LDB(B0, 1, 0); PG8_SCHED; PG8_LDA(At, 1, 0); PG8_STAGE(PG8_SA(0, 1), a2 + hA, voffA);
;             PG8_WAIT_L(8); PG8_BAR; PG8_WAIT_L(0); PG8_MMA(0, 0, At, B0); PG8_BAR; PG8_SCHED;
;             PG8_LDB(B1, 1, 1); PG8_STAGE(PG8_SB(1, 0), b3, voffB);
;             PG8_BAR; PG8_WAIT_L(0); PG8_MMA(0, 1, At, B1); PG8_BAR;
;             PG8_LDA(At, 1, 1); PG8_STAGE(PG8_SA(1, 0), a3, voffA);
;             PG8_BAR; PG8_WAIT_L(0); PG8_MMA(1, 0, At, B0); PG8_BAR; PG8_SCHED;
	s_add_u32 s44, s36, 0x40000
	s_addc_u32 s45, s37, 0
	s_add_i32 s43, s64, s55
	v_lshl_add_u64 v[146:147], s[44:45], 0, v[130:131]
	s_mov_b32 m0, s43
	s_nop 0
	global_load_lds_dwordx4 v[146:147], off
	v_lshl_add_u64 v[146:147], s[44:45], 0, v[134:135]
	s_add_i32 m0, s43, 0x2000
	s_nop 0
	global_load_lds_dwordx4 v[146:147], off
	s_waitcnt vmcnt(6)
	s_barrier
	s_setprio 1
	v_mfma_f32_16x16x32_bf16 v[52:55], v[210:213], v[178:181], v[52:55]
	v_mfma_f32_16x16x32_bf16 v[48:51], v[218:221], v[178:181], v[48:51]
	v_mfma_f32_16x16x32_bf16 v[36:39], v[210:213], v[186:189], v[36:39]
	v_mfma_f32_16x16x32_bf16 v[32:35], v[218:221], v[186:189], v[32:35]
	v_mfma_f32_16x16x32_bf16 v[20:23], v[210:213], v[194:197], v[20:23]
	v_mfma_f32_16x16x32_bf16 v[16:19], v[218:221], v[194:197], v[16:19]
	v_mfma_f32_16x16x32_bf16 v[4:7], v[210:213], v[202:205], v[4:7]
	v_mfma_f32_16x16x32_bf16 v[0:3], v[218:221], v[202:205], v[0:3]
	v_mfma_f32_16x16x32_bf16 v[52:55], v[214:217], v[182:185], v[52:55]
	v_mfma_f32_16x16x32_bf16 v[48:51], v[222:225], v[182:185], v[48:51]
	v_mfma_f32_16x16x32_bf16 v[36:39], v[214:217], v[190:193], v[36:39]
	v_mfma_f32_16x16x32_bf16 v[32:35], v[222:225], v[190:193], v[32:35]
	v_mfma_f32_16x16x32_bf16 v[20:23], v[214:217], v[198:201], v[20:23]
	v_mfma_f32_16x16x32_bf16 v[16:19], v[222:225], v[198:201], v[16:19]
	v_mfma_f32_16x16x32_bf16 v[4:7], v[214:217], v[206:209], v[4:7]
	v_mfma_f32_16x16x32_bf16 v[0:3], v[222:225], v[206:209], v[0:3]
	s_setprio 0
	s_add_i32 s43, 0, 0x18000
	v_add_u32_e32 v159, s43, v153
	s_barrier
	ds_read_b128 v[146:149], v159
	ds_read_b128 v[160:163], v159 offset:1024
	ds_read_b128 v[170:173], v159 offset:2048
	ds_read_b128 v[174:177], v159 offset:3072
	s_add_u32 s38, s38, 0x40000
	s_addc_u32 s39, s39, 0
	s_mov_b32 m0, s57
	v_lshl_add_u64 v[210:211], s[38:39], 0, v[128:129]
	ds_read_b128 v[178:181], v156 offset:32768
	ds_read_b128 v[182:185], v156 offset:33792
	ds_read_b128 v[186:189], v156 offset:34816
	ds_read_b128 v[190:193], v156 offset:35840
	ds_read_b128 v[194:197], v156 offset:36864
	ds_read_b128 v[198:201], v156 offset:37888
	ds_read_b128 v[202:205], v156 offset:38912
	ds_read_b128 v[206:209], v156 offset:39936
	global_load_lds_dwordx4 v[210:211], off
	v_lshl_add_u64 v[210:211], s[38:39], 0, v[132:133]
	s_mov_b32 m0, s58
	s_nop 0
	global_load_lds_dwordx4 v[210:211], off
	s_waitcnt lgkmcnt(8)
	s_barrier
	s_waitcnt lgkmcnt(0)
	s_setprio 1
	s_waitcnt lgkmcnt(0)
	v_mfma_f32_16x16x32_bf16 v[124:127], v[146:149], v[178:181], v[124:127]
	v_mfma_f32_16x16x32_bf16 v[120:123], v[170:173], v[178:181], v[120:123]
	v_mfma_f32_16x16x32_bf16 v[108:111], v[146:149], v[186:189], v[108:111]
	v_mfma_f32_16x16x32_bf16 v[104:107], v[170:173], v[186:189], v[104:107]
	v_mfma_f32_16x16x32_bf16 v[92:95], v[146:149], v[194:197], v[92:95]
	v_mfma_f32_16x16x32_bf16 v[88:91], v[170:173], v[194:197], v[88:91]
	v_mfma_f32_16x16x32_bf16 v[76:79], v[146:149], v[202:205], v[76:79]
	v_mfma_f32_16x16x32_bf16 v[72:75], v[170:173], v[202:205], v[72:75]
	v_mfma_f32_16x16x32_bf16 v[124:127], v[160:163], v[182:185], v[124:127]
	v_mfma_f32_16x16x32_bf16 v[120:123], v[174:177], v[182:185], v[120:123]
	v_mfma_f32_16x16x32_bf16 v[108:111], v[160:163], v[190:193], v[108:111]
	v_mfma_f32_16x16x32_bf16 v[104:107], v[174:177], v[190:193], v[104:107]
	v_mfma_f32_16x16x32_bf16 v[92:95], v[160:163], v[198:201], v[92:95]
	v_mfma_f32_16x16x32_bf16 v[88:91], v[174:177], v[198:201], v[88:91]
	v_mfma_f32_16x16x32_bf16 v[76:79], v[160:163], v[206:209], v[76:79]
	v_mfma_f32_16x16x32_bf16 v[72:75], v[174:177], v[206:209], v[72:75]
	s_setprio 0
	s_barrier
	s_add_i32 s38, 0, 0x1c000
	s_add_i32 s39, s43, s55
	v_add_u32_e32 v159, s38, v153
	v_lshl_add_u64 v[150:151], v[150:151], 0, s[20:21]
	s_mov_b32 m0, s39
	ds_read_b128 v[210:213], v159
	ds_read_b128 v[214:217], v159 offset:1024
	ds_read_b128 v[218:221], v159 offset:2048
	ds_read_b128 v[222:225], v159 offset:3072
	global_load_lds_dwordx4 v[150:151], off
	v_lshl_add_u64 v[150:151], v[164:165], 0, s[20:21]
	s_add_i32 m0, s39, 0x2000
	s_nop 0
	global_load_lds_dwordx4 v[150:151], off
	s_barrier
	s_waitcnt lgkmcnt(0)
	s_setprio 1
	s_waitcnt lgkmcnt(0)
	v_mfma_f32_16x16x32_bf16 v[116:119], v[210:213], v[178:181], v[116:119]
	v_mfma_f32_16x16x32_bf16 v[112:115], v[218:221], v[178:181], v[112:115]
	v_mfma_f32_16x16x32_bf16 v[100:103], v[210:213], v[186:189], v[100:103]
	v_mfma_f32_16x16x32_bf16 v[96:99], v[218:221], v[186:189], v[96:99]
	v_mfma_f32_16x16x32_bf16 v[84:87], v[210:213], v[194:197], v[84:87]
	v_mfma_f32_16x16x32_bf16 v[80:83], v[218:221], v[194:197], v[80:83]
	v_mfma_f32_16x16x32_bf16 v[68:71], v[210:213], v[202:205], v[68:71]
	v_mfma_f32_16x16x32_bf16 v[64:67], v[218:221], v[202:205], v[64:67]
	v_mfma_f32_16x16x32_bf16 v[116:119], v[214:217], v[182:185], v[116:119]
	v_mfma_f32_16x16x32_bf16 v[112:115], v[222:225], v[182:185], v[112:115]
	v_mfma_f32_16x16x32_bf16 v[100:103], v[214:217], v[190:193], v[100:103]
	v_mfma_f32_16x16x32_bf16 v[96:99], v[222:225], v[190:193], v[96:99]
	v_mfma_f32_16x16x32_bf16 v[84:87], v[214:217], v[198:201], v[84:87]
	v_mfma_f32_16x16x32_bf16 v[80:83], v[222:225], v[198:201], v[80:83]
	v_mfma_f32_16x16x32_bf16 v[68:71], v[214:217], v[206:209], v[68:71]
	v_mfma_f32_16x16x32_bf16 v[64:67], v[222:225], v[206:209], v[64:67]
	s_setprio 0
	s_mov_b32 m0, s60
	v_lshl_add_u64 v[150:151], v[226:227], 0, s[20:21]
	s_barrier
	ds_read_b128 v[178:181], v156 offset:49152
	ds_read_b128 v[182:185], v156 offset:50176
	ds_read_b128 v[186:189], v156 offset:51200
	ds_read_b128 v[190:193], v156 offset:52224
	ds_read_b128 v[194:197], v156 offset:53248
	ds_read_b128 v[198:201], v156 offset:54272
	ds_read_b128 v[202:205], v156 offset:55296
	ds_read_b128 v[206:209], v156 offset:56320
	global_load_lds_dwordx4 v[150:151], off
	v_lshl_add_u64 v[150:151], v[228:229], 0, s[20:21]
	s_mov_b32 m0, s61
	s_nop 0
	global_load_lds_dwordx4 v[150:151], off
	s_barrier
; __device__ __forceinline__ float bflo(unsigned w) { return __uint_as_float(w << 16); }
; #define PG8_WAIT_V(n) asm volatile("s_waitcnt vmcnt(" #n ")" ::: "memory")
;     ...
;             PG8_WAIT_L(8); PG8_BAR; PG8_WAIT_L(0); PG8_MMA(0, 0, At, B0); PG8_BAR; PG8_SCHED;
;             PG8_LDB(B1, 1, 1); PG8_STAGE(PG8_SB(1, 0), b3, voffB);
;             PG8_BAR; PG8_WAIT_L(0); PG8_MMA(0, 1, At, B1); PG8_BAR;
;             PG8_LDA(At, 1, 1); PG8_STAGE(PG8_SA(1, 0), a3, voffA);
;             PG8_BAR; PG8_WAIT_L(0); PG8_MMA(1, 0, At, B0); PG8_BAR; PG8_SCHED;
;             PG8_STAGE(PG8_SB(1, 1), b3 + hB, voffB);
;             PG8_WAIT_V(6); PG8_BAR; PG8_MMA(1, 1, At, B1); PG8_BAR;
;         }
; __device__ __forceinline__ float row_rstd(const float* ssq, int row) {
;     const f32x4* p = (const f32x4*)(ssq + (size_t)row * 16);
;     const f32x4 a = p[0], b = p[1], c = p[2], d = p[3];
;     const float s = ((a[0] + a[1]) + (a[2] + a[3])) + ((b[0] + b[1]) + (b[2] + b[3])) + ((c[0] + c[1]) + (c[2] + c[3])) + ((d[0] + d[1]) + (d[2] + d[3]));
;     return rsqrtf(s * (1.0f / 1024.0f) + 1e-6f);
; }
; __device__ __forceinline__ u32x4 pack8(const f32x4 v0, const f32x4 v1) { u32x4 w; w.x = pk2(v0[0], v0[1]); w.y = pk2(v0[2], v0[3]); w.z = pk2(v1[0], v1[1]); w.w = pk2(v1[2], v1[3]); return w; }
; __device__ __forceinline__ void unpack8(const u32x4 w, f32x4& v0, f32x4& v1) { v0 = (f32x4){bflo(w.x), bfhi(w.x), bflo(w.y), bfhi(w.y)}; v1 = (f32x4){bflo(w.z), bfhi(w.z), bflo(w.w), bfhi(w.w)}; }
;     __device__ __forceinline__ void operator()(const f32x4 (&acc)[2][2][4][2], const Unit& u, int wr, int wc, int fr, int fq) const {
;         const int row0 = u.pm * 256 + wr * 64 + fr, col0 = u.pn * 256 + wc * 32 + 8 * fq;
; #pragma unroll
;         for (int ai = 0; ai < 2; ++ai)
; #pragma unroll
;             for (int m = 0; m < 4; ++m) {
;                 const int row = row0 + ai * 128 + m * 16; const float rs = row_rstd(ssq, row);
;                 bf16_t* rowp = O + (size_t)row * ldc + col0;
; #pragma unroll
;                 for (int bj = 0; bj < 2; ++bj) { f32x4 v0 = acc[ai][bj][m][0] * rs, v1 = acc[ai][bj][m][1] * rs;
;                     if (ACT == 1) {
; #pragma unroll
;                         for (int j = 0; j < 4; ++j) { const float a = fmaxf(v0[j], 0.f), b = fmaxf(v1[j], 0.f); v0[j] = a * a; v1[j] = b * b; } }
;                     *(u32x4*)(rowp + bj * 128) = pack8(v0, v1); }
	s_waitcnt lgkmcnt(0)
	s_setprio 1
	s_waitcnt lgkmcnt(0)
	v_mfma_f32_16x16x32_bf16 v[60:63], v[146:149], v[178:181], v[60:63]
	v_mfma_f32_16x16x32_bf16 v[56:59], v[170:173], v[178:181], v[56:59]
	v_mfma_f32_16x16x32_bf16 v[44:47], v[146:149], v[186:189], v[44:47]
	v_mfma_f32_16x16x32_bf16 v[40:43], v[170:173], v[186:189], v[40:43]
	v_mfma_f32_16x16x32_bf16 v[28:31], v[146:149], v[194:197], v[28:31]
	v_mfma_f32_16x16x32_bf16 v[24:27], v[170:173], v[194:197], v[24:27]
	v_mfma_f32_16x16x32_bf16 v[12:15], v[146:149], v[202:205], v[12:15]
	v_mfma_f32_16x16x32_bf16 v[8:11], v[170:173], v[202:205], v[8:11]
	v_mfma_f32_16x16x32_bf16 v[60:63], v[160:163], v[182:185], v[60:63]
	v_mfma_f32_16x16x32_bf16 v[56:59], v[174:177], v[182:185], v[56:59]
	v_mfma_f32_16x16x32_bf16 v[44:47], v[160:163], v[190:193], v[44:47]
	v_mfma_f32_16x16x32_bf16 v[40:43], v[174:177], v[190:193], v[40:43]
	v_mfma_f32_16x16x32_bf16 v[28:31], v[160:163], v[198:201], v[28:31]
	v_mfma_f32_16x16x32_bf16 v[24:27], v[174:177], v[198:201], v[24:27]
	v_mfma_f32_16x16x32_bf16 v[12:15], v[160:163], v[206:209], v[12:15]
	v_mfma_f32_16x16x32_bf16 v[8:11], v[174:177], v[206:209], v[8:11]
	s_setprio 0
	s_barrier
	s_add_u32 s36, s36, 0x40080
	s_addc_u32 s37, s37, 0
	s_add_i32 s38, s38, s55
	v_lshl_add_u64 v[146:147], s[36:37], 0, v[130:131]
	s_mov_b32 m0, s38
	s_nop 0
	global_load_lds_dwordx4 v[146:147], off
	v_lshl_add_u64 v[146:147], s[36:37], 0, v[134:135]
	s_add_i32 m0, s38, 0x2000
	s_nop 0
	global_load_lds_dwordx4 v[146:147], off
	s_waitcnt vmcnt(6)
	s_barrier
	s_setprio 1
	v_mfma_f32_16x16x32_bf16 v[52:55], v[210:213], v[178:181], v[52:55]
	v_mfma_f32_16x16x32_bf16 v[48:51], v[218:221], v[178:181], v[48:51]
	v_mfma_f32_16x16x32_bf16 v[36:39], v[210:213], v[186:189], v[36:39]
	v_mfma_f32_16x16x32_bf16 v[32:35], v[218:221], v[186:189], v[32:35]
	v_mfma_f32_16x16x32_bf16 v[20:23], v[210:213], v[194:197], v[20:23]
	v_mfma_f32_16x16x32_bf16 v[16:19], v[218:221], v[194:197], v[16:19]
	v_mfma_f32_16x16x32_bf16 v[4:7], v[210:213], v[202:205], v[4:7]
	v_mfma_f32_16x16x32_bf16 v[0:3], v[218:221], v[202:205], v[0:3]
	v_mfma_f32_16x16x32_bf16 v[52:55], v[214:217], v[182:185], v[52:55]
	v_mfma_f32_16x16x32_bf16 v[48:51], v[222:225], v[182:185], v[48:51]
	v_mfma_f32_16x16x32_bf16 v[36:39], v[214:217], v[190:193], v[36:39]
	v_mfma_f32_16x16x32_bf16 v[32:35], v[222:225], v[190:193], v[32:35]
	v_mfma_f32_16x16x32_bf16 v[20:23], v[214:217], v[198:201], v[20:23]
	v_mfma_f32_16x16x32_bf16 v[16:19], v[222:225], v[198:201], v[16:19]
	v_mfma_f32_16x16x32_bf16 v[4:7], v[214:217], v[206:209], v[4:7]
	v_mfma_f32_16x16x32_bf16 v[0:3], v[222:225], v[206:209], v[0:3]
	s_setprio 0
	s_add_i32 s42, s42, 2
	s_add_u32 s25, s25, 0x100
	s_addc_u32 s33, s33, 0
	s_add_u32 s34, s34, 0x100
	s_addc_u32 s35, s35, 0
	s_cmp_gt_u32 s42, 13
	s_barrier
	s_cbranch_scc0 .LBB0_1288
	v_lshl_add_u32 v150, s30, 8, v152
	v_ashrrev_i32_e32 v151, 31, v150
	v_lshlrev_b64 v[146:147], 6, v[150:151]
	v_lshl_add_u64 v[146:147], s[18:19], 0, v[146:147]
	v_subrev_u32_e32 v186, s18, v146
	v_add_u32_e32 v187, 0x0, v186
	global_load_dwordx4 v[188:191], v187, s[18:19]
	v_add_u32_e32 v187, 0x10, v186
	global_load_dwordx4 v[192:195], v187, s[18:19]
	v_add_u32_e32 v187, 0x20, v186
	global_load_dwordx4 v[196:199], v187, s[18:19]
	v_add_u32_e32 v187, 0x30, v186
	global_load_dwordx4 v[200:203], v187, s[18:19]
	v_add_u32_e32 v187, 0x400, v186
	global_load_dwordx4 v[204:207], v187, s[18:19]
	v_add_u32_e32 v187, 0x410, v186
	global_load_dwordx4 v[208:211], v187, s[18:19]
	v_add_u32_e32 v187, 0x420, v186
	global_load_dwordx4 v[212:215], v187, s[18:19]
	v_add_u32_e32 v187, 0x430, v186
	global_load_dwordx4 v[216:219], v187, s[18:19]
	v_add_u32_e32 v187, 0x800, v186
	global_load_dwordx4 v[220:223], v187, s[18:19]
	v_add_u32_e32 v187, 0x810, v186
	global_load_dwordx4 v[232:235], v187, s[18:19]
	v_add_u32_e32 v187, 0x820, v186
	global_load_dwordx4 v[236:239], v187, s[18:19]
	v_add_u32_e32 v187, 0x830, v186
	global_load_dwordx4 v[240:243], v187, s[18:19]
	v_lshl_or_b32 v148, s6, 8, v154
	v_mov_b64_e32 v[146:147], s[16:17]
	v_ashrrev_i32_e32 v149, 31, v148
	v_mad_i64_i32 v[164:165], s[6:7], v150, s66, v[146:147]
	v_or_b32_e32 v182, 16, v150
	v_lshlrev_b64 v[148:149], 1, v[148:149]
	v_ashrrev_i32_e32 v183, 31, v182
	s_mov_b32 s30, s24
	s_mov_b64 s[34:35], s[28:29]
	s_mov_b64 s[36:37], s[26:27]
	s_waitcnt vmcnt(8)
	v_pk_add_f32 v[160:161], v[188:189], v[190:191]
	v_pk_add_f32 v[170:171], v[192:193], v[194:195]
	v_pk_add_f32 v[172:173], v[196:197], v[198:199]
	v_pk_add_f32 v[174:175], v[200:201], v[202:203]
	v_pk_add_f32 v[160:161], v[160:161], v[170:171]
	v_pk_add_f32 v[172:173], v[172:173], v[174:175]
	v_pk_add_f32 v[160:161], v[160:161], v[172:173]
	v_add_f32_e32 v151, v160, v161
	v_lshlrev_b64 v[162:163], 6, v[182:183]
	v_lshl_add_u64 v[162:163], s[18:19], 0, v[162:163]
	v_fmamk_f32 v151, v151, 0x3a800000, v158
	v_mul_f32_e32 v159, 0x4b800000, v151
	v_cmp_gt_f32_e32 vcc, s65, v151
	v_lshl_add_u64 v[160:161], v[164:165], 0, v[148:149]
	s_nop 0
	v_cndmask_b32_e32 v151, v151, v159, vcc
	v_rsq_f32_e32 v151, v151
	s_nop 0
	v_mul_f32_e32 v159, 0x45800000, v151
	v_cndmask_b32_e32 v164, v151, v159, vcc
	v_pk_mul_f32 v[126:127], v[126:127], v[164:165] op_sel_hi:[1,0]
	v_pk_mul_f32 v[124:125], v[124:125], v[164:165] op_sel_hi:[1,0]
	v_pk_mul_f32 v[122:123], v[122:123], v[164:165] op_sel_hi:[1,0]
	v_pk_mul_f32 v[120:121], v[120:121], v[164:165] op_sel_hi:[1,0]
	v_pk_mul_f32 v[118:119], v[118:119], v[164:165] op_sel_hi:[1,0]
	v_pk_mul_f32 v[116:117], v[116:117], v[164:165] op_sel_hi:[1,0]
	v_pk_mul_f32 v[170:171], v[114:115], v[164:165] op_sel_hi:[1,0]
	v_pk_mul_f32 v[164:165], v[112:113], v[164:165] op_sel_hi:[1,0]
	v_cvt_pk_bf16_f32 v112, v124, v125
	v_cvt_pk_bf16_f32 v113, v126, v127
	v_cvt_pk_bf16_f32 v114, v120, v121
	v_cvt_pk_bf16_f32 v115, v122, v123
	global_store_dwordx4 v[160:161], v[112:115], off sc1
	s_nop 1
	v_cvt_pk_bf16_f32 v112, v116, v117
	v_cvt_pk_bf16_f32 v113, v118, v119
	v_cvt_pk_bf16_f32 v114, v164, v165
	v_cvt_pk_bf16_f32 v115, v170, v171
	global_store_dwordx4 v[160:161], v[112:115], off offset:256 sc1
	s_nop 0
	v_or_b32_e32 v160, 32, v150
	v_mad_i64_i32 v[162:163], s[6:7], v182, s66, v[146:147]
	v_ashrrev_i32_e32 v161, 31, v160
	v_add_u32_e32 v187, 0xc00, v186
	global_load_dwordx4 v[188:191], v187, s[18:19]
	v_add_u32_e32 v187, 0xc10, v186
	global_load_dwordx4 v[192:195], v187, s[18:19]
	v_add_u32_e32 v187, 0xc20, v186
	global_load_dwordx4 v[196:199], v187, s[18:19]
	v_add_u32_e32 v187, 0xc30, v186
	global_load_dwordx4 v[200:203], v187, s[18:19]
	s_waitcnt vmcnt(10)
; __device__ __forceinline__ u32x4 pack8(const f32x4 v0, const f32x4 v1) { u32x4 w; w.x = pk2(v0[0], v0[1]); w.y = pk2(v0[2], v0[3]); w.z = pk2(v1[0], v1[1]); w.w = pk2(v1[2], v1[3]); return w; }
; __device__ __forceinline__ float row_rstd(const float* ssq, int row) {
;     const f32x4* p = (const f32x4*)(ssq + (size_t)row * 16);
;     const f32x4 a = p[0], b = p[1], c = p[2], d = p[3];
;     const float s = ((a[0] + a[1]) + (a[2] + a[3])) + ((b[0] + b[1]) + (b[2] + b[3])) + ((c[0] + c[1]) + (c[2] + c[3])) + ((d[0] + d[1]) + (d[2] + d[3]));
;     return rsqrtf(s * (1.0f / 1024.0f) + 1e-6f);
;     __device__ __forceinline__ void operator()(const f32x4 (&acc)[2][2][4][2], const Unit& u, int wr, int wc, int fr, int fq) const {
;     ...
;             for (int m = 0; m < 4; ++m) {
;                 const int row = row0 + ai * 128 + m * 16; const float rs = row_rstd(ssq, row);
;                 bf16_t* rowp = O + (size_t)row * ldc + col0;
; #pragma unroll
;                 for (int bj = 0; bj < 2; ++bj) { f32x4 v0 = acc[ai][bj][m][0] * rs, v1 = acc[ai][bj][m][1] * rs;
;                     if (ACT == 1) {
; #pragma unroll
;                         for (int j = 0; j < 4; ++j) { const float a = fmaxf(v0[j], 0.f), b = fmaxf(v1[j], 0.f); v0[j] = a * a; v1[j] = b * b; } }
;                     *(u32x4*)(rowp + bj * 128) = pack8(v0, v1); }
	v_pk_add_f32 v[112:113], v[204:205], v[206:207]
	v_pk_add_f32 v[116:117], v[208:209], v[210:211]
	v_pk_add_f32 v[118:119], v[212:213], v[214:215]
	v_pk_add_f32 v[120:121], v[216:217], v[218:219]
	v_pk_add_f32 v[112:113], v[112:113], v[116:117]
	v_pk_add_f32 v[118:119], v[118:119], v[120:121]
	v_pk_add_f32 v[112:113], v[112:113], v[118:119]
	v_add_f32_e32 v112, v112, v113
	v_lshlrev_b64 v[114:115], 6, v[160:161]
	v_lshl_add_u64 v[114:115], s[18:19], 0, v[114:115]
	v_fmamk_f32 v112, v112, 0x3a800000, v158
	v_mul_f32_e32 v113, 0x4b800000, v112
	v_cmp_gt_f32_e32 vcc, s65, v112
	s_nop 1
	v_cndmask_b32_e32 v112, v112, v113, vcc
	v_rsq_f32_e32 v116, v112
	v_lshl_add_u64 v[112:113], v[162:163], 0, v[148:149]
	v_mul_f32_e32 v117, 0x45800000, v116
	v_cndmask_b32_e32 v116, v116, v117, vcc
	v_pk_mul_f32 v[110:111], v[110:111], v[116:117] op_sel_hi:[1,0]
	v_pk_mul_f32 v[108:109], v[108:109], v[116:117] op_sel_hi:[1,0]
	v_pk_mul_f32 v[106:107], v[106:107], v[116:117] op_sel_hi:[1,0]
	v_pk_mul_f32 v[104:105], v[104:105], v[116:117] op_sel_hi:[1,0]
	v_pk_mul_f32 v[102:103], v[102:103], v[116:117] op_sel_hi:[1,0]
	v_pk_mul_f32 v[100:101], v[100:101], v[116:117] op_sel_hi:[1,0]
	v_pk_mul_f32 v[118:119], v[98:99], v[116:117] op_sel_hi:[1,0]
	v_pk_mul_f32 v[116:117], v[96:97], v[116:117] op_sel_hi:[1,0]
	v_cvt_pk_bf16_f32 v96, v108, v109
	v_cvt_pk_bf16_f32 v97, v110, v111
	v_cvt_pk_bf16_f32 v98, v104, v105
	v_cvt_pk_bf16_f32 v99, v106, v107
	global_store_dwordx4 v[112:113], v[96:99], off sc1
	s_nop 1
	v_cvt_pk_bf16_f32 v96, v100, v101
	v_cvt_pk_bf16_f32 v97, v102, v103
	v_cvt_pk_bf16_f32 v98, v116, v117
	v_cvt_pk_bf16_f32 v99, v118, v119
	global_store_dwordx4 v[112:113], v[96:99], off offset:256 sc1
	s_nop 0
	v_or_b32_e32 v112, 48, v150
	v_mad_i64_i32 v[114:115], s[6:7], v160, s66, v[146:147]
	v_ashrrev_i32_e32 v113, 31, v112
	v_add_u32_e32 v187, 0x2000, v186
	global_load_dwordx4 v[204:207], v187, s[18:19]
	v_add_u32_e32 v187, 0x2010, v186
	global_load_dwordx4 v[208:211], v187, s[18:19]
	v_add_u32_e32 v187, 0x2020, v186
	global_load_dwordx4 v[212:215], v187, s[18:19]
	v_add_u32_e32 v187, 0x2030, v186
	global_load_dwordx4 v[216:219], v187, s[18:19]
	s_waitcnt vmcnt(12)
	v_pk_add_f32 v[96:97], v[220:221], v[222:223]
	v_pk_add_f32 v[100:101], v[232:233], v[234:235]
	v_pk_add_f32 v[102:103], v[236:237], v[238:239]
	v_pk_add_f32 v[104:105], v[240:241], v[242:243]
	v_pk_add_f32 v[96:97], v[96:97], v[100:101]
	v_pk_add_f32 v[102:103], v[102:103], v[104:105]
	v_pk_add_f32 v[96:97], v[96:97], v[102:103]
	v_add_f32_e32 v96, v96, v97
	v_lshlrev_b64 v[98:99], 6, v[112:113]
	v_lshl_add_u64 v[98:99], s[18:19], 0, v[98:99]
	v_fmamk_f32 v96, v96, 0x3a800000, v158
	v_mul_f32_e32 v97, 0x4b800000, v96
	v_cmp_gt_f32_e32 vcc, s65, v96
	s_nop 1
	v_cndmask_b32_e32 v96, v96, v97, vcc
	v_rsq_f32_e32 v100, v96
	v_lshl_add_u64 v[96:97], v[114:115], 0, v[148:149]
	v_mul_f32_e32 v101, 0x45800000, v100
	v_cndmask_b32_e32 v100, v100, v101, vcc
	v_pk_mul_f32 v[94:95], v[94:95], v[100:101] op_sel_hi:[1,0]
	v_pk_mul_f32 v[92:93], v[92:93], v[100:101] op_sel_hi:[1,0]
	v_pk_mul_f32 v[90:91], v[90:91], v[100:101] op_sel_hi:[1,0]
	v_pk_mul_f32 v[88:89], v[88:89], v[100:101] op_sel_hi:[1,0]
	v_pk_mul_f32 v[86:87], v[86:87], v[100:101] op_sel_hi:[1,0]
	v_pk_mul_f32 v[84:85], v[84:85], v[100:101] op_sel_hi:[1,0]
	v_pk_mul_f32 v[102:103], v[82:83], v[100:101] op_sel_hi:[1,0]
	v_pk_mul_f32 v[100:101], v[80:81], v[100:101] op_sel_hi:[1,0]
	v_cvt_pk_bf16_f32 v80, v92, v93
	v_cvt_pk_bf16_f32 v81, v94, v95
	v_cvt_pk_bf16_f32 v82, v88, v89
	v_cvt_pk_bf16_f32 v83, v90, v91
	global_store_dwordx4 v[96:97], v[80:83], off sc1
	s_nop 1
	v_cvt_pk_bf16_f32 v80, v84, v85
	v_cvt_pk_bf16_f32 v81, v86, v87
	v_cvt_pk_bf16_f32 v82, v100, v101
	v_cvt_pk_bf16_f32 v83, v102, v103
	global_store_dwordx4 v[96:97], v[80:83], off offset:256 sc1
	s_nop 0
	v_add_u32_e32 v96, 0x80, v150
	v_mad_i64_i32 v[98:99], s[6:7], v112, s66, v[146:147]
	v_ashrrev_i32_e32 v97, 31, v96
	v_add_u32_e32 v187, 0x2400, v186
	global_load_dwordx4 v[220:223], v187, s[18:19]
	v_add_u32_e32 v187, 0x2410, v186
	global_load_dwordx4 v[232:235], v187, s[18:19]
	v_add_u32_e32 v187, 0x2420, v186
	global_load_dwordx4 v[236:239], v187, s[18:19]
	v_add_u32_e32 v187, 0x2430, v186
	global_load_dwordx4 v[240:243], v187, s[18:19]
	s_waitcnt vmcnt(12)
	v_pk_add_f32 v[80:81], v[188:189], v[190:191]
	v_pk_add_f32 v[84:85], v[192:193], v[194:195]
	v_pk_add_f32 v[86:87], v[196:197], v[198:199]
	v_pk_add_f32 v[88:89], v[200:201], v[202:203]
	v_pk_add_f32 v[80:81], v[80:81], v[84:85]
	v_pk_add_f32 v[86:87], v[86:87], v[88:89]
	v_pk_add_f32 v[80:81], v[80:81], v[86:87]
	v_add_f32_e32 v80, v80, v81
	v_lshlrev_b64 v[82:83], 6, v[96:97]
	v_lshl_add_u64 v[82:83], s[18:19], 0, v[82:83]
	v_fmamk_f32 v80, v80, 0x3a800000, v158
	v_mul_f32_e32 v81, 0x4b800000, v80
	v_cmp_gt_f32_e32 vcc, s65, v80
	s_nop 1
	v_cndmask_b32_e32 v80, v80, v81, vcc
	v_rsq_f32_e32 v84, v80
	v_lshl_add_u64 v[80:81], v[98:99], 0, v[148:149]
	v_mul_f32_e32 v85, 0x45800000, v84
	v_cndmask_b32_e32 v84, v84, v85, vcc
	v_pk_mul_f32 v[78:79], v[78:79], v[84:85] op_sel_hi:[1,0]
	v_pk_mul_f32 v[76:77], v[76:77], v[84:85] op_sel_hi:[1,0]
	v_pk_mul_f32 v[74:75], v[74:75], v[84:85] op_sel_hi:[1,0]
	v_pk_mul_f32 v[72:73], v[72:73], v[84:85] op_sel_hi:[1,0]
	v_pk_mul_f32 v[70:71], v[70:71], v[84:85] op_sel_hi:[1,0]
	v_pk_mul_f32 v[68:69], v[68:69], v[84:85] op_sel_hi:[1,0]
	v_pk_mul_f32 v[86:87], v[66:67], v[84:85] op_sel_hi:[1,0]
	v_pk_mul_f32 v[84:85], v[64:65], v[84:85] op_sel_hi:[1,0]
	v_cvt_pk_bf16_f32 v64, v76, v77
	v_cvt_pk_bf16_f32 v65, v78, v79
	v_cvt_pk_bf16_f32 v66, v72, v73
	v_cvt_pk_bf16_f32 v67, v74, v75
	global_store_dwordx4 v[80:81], v[64:67], off sc1
	s_nop 1
	v_cvt_pk_bf16_f32 v64, v68, v69
	v_cvt_pk_bf16_f32 v65, v70, v71
	v_cvt_pk_bf16_f32 v66, v84, v85
	v_cvt_pk_bf16_f32 v67, v86, v87
	global_store_dwordx4 v[80:81], v[64:67], off offset:256 sc1
	s_nop 0
	v_add_u32_e32 v80, 0x90, v150
	v_mad_i64_i32 v[82:83], s[6:7], v96, s66, v[146:147]
	v_ashrrev_i32_e32 v81, 31, v80
	v_add_u32_e32 v187, 0x2800, v186
	global_load_dwordx4 v[188:191], v187, s[18:19]
	v_add_u32_e32 v187, 0x2810, v186
	global_load_dwordx4 v[192:195], v187, s[18:19]
	v_add_u32_e32 v187, 0x2820, v186
	global_load_dwordx4 v[196:199], v187, s[18:19]
	v_add_u32_e32 v187, 0x2830, v186
	global_load_dwordx4 v[200:203], v187, s[18:19]
	s_waitcnt vmcnt(12)
; __device__ __forceinline__ u32x4 pack8(const f32x4 v0, const f32x4 v1) { u32x4 w; w.x = pk2(v0[0], v0[1]); w.y = pk2(v0[2], v0[3]); w.z = pk2(v1[0], v1[1]); w.w = pk2(v1[2], v1[3]); return w; }
; __device__ __forceinline__ float row_rstd(const float* ssq, int row) {
;     const f32x4* p = (const f32x4*)(ssq + (size_t)row * 16);
;     const f32x4 a = p[0], b = p[1], c = p[2], d = p[3];
;     const float s = ((a[0] + a[1]) + (a[2] + a[3])) + ((b[0] + b[1]) + (b[2] + b[3])) + ((c[0] + c[1]) + (c[2] + c[3])) + ((d[0] + d[1]) + (d[2] + d[3]));
;     return rsqrtf(s * (1.0f / 1024.0f) + 1e-6f);
;     __device__ __forceinline__ void operator()(const f32x4 (&acc)[2][2][4][2], const Unit& u, int wr, int wc, int fr, int fq) const {
;     ...
;             for (int m = 0; m < 4; ++m) {
;                 const int row = row0 + ai * 128 + m * 16; const float rs = row_rstd(ssq, row);
;                 bf16_t* rowp = O + (size_t)row * ldc + col0;
; #pragma unroll
;                 for (int bj = 0; bj < 2; ++bj) { f32x4 v0 = acc[ai][bj][m][0] * rs, v1 = acc[ai][bj][m][1] * rs;
;                     if (ACT == 1) {
; #pragma unroll
;                         for (int j = 0; j < 4; ++j) { const float a = fmaxf(v0[j], 0.f), b = fmaxf(v1[j], 0.f); v0[j] = a * a; v1[j] = b * b; } }
;                     *(u32x4*)(rowp + bj * 128) = pack8(v0, v1); }
	v_pk_add_f32 v[64:65], v[204:205], v[206:207]
	v_pk_add_f32 v[68:69], v[208:209], v[210:211]
	v_pk_add_f32 v[70:71], v[212:213], v[214:215]
	v_pk_add_f32 v[72:73], v[216:217], v[218:219]
	v_pk_add_f32 v[64:65], v[64:65], v[68:69]
	v_pk_add_f32 v[70:71], v[70:71], v[72:73]
	v_pk_add_f32 v[64:65], v[64:65], v[70:71]
	v_add_f32_e32 v64, v64, v65
	v_lshlrev_b64 v[66:67], 6, v[80:81]
	v_lshl_add_u64 v[66:67], s[18:19], 0, v[66:67]
	v_fmamk_f32 v64, v64, 0x3a800000, v158
	v_mul_f32_e32 v65, 0x4b800000, v64
	v_cmp_gt_f32_e32 vcc, s65, v64
	s_nop 1
	v_cndmask_b32_e32 v64, v64, v65, vcc
	v_rsq_f32_e32 v68, v64
	v_lshl_add_u64 v[64:65], v[82:83], 0, v[148:149]
	v_mul_f32_e32 v69, 0x45800000, v68
	v_cndmask_b32_e32 v68, v68, v69, vcc
	v_pk_mul_f32 v[62:63], v[62:63], v[68:69] op_sel_hi:[1,0]
	v_pk_mul_f32 v[60:61], v[60:61], v[68:69] op_sel_hi:[1,0]
	v_pk_mul_f32 v[58:59], v[58:59], v[68:69] op_sel_hi:[1,0]
	v_pk_mul_f32 v[56:57], v[56:57], v[68:69] op_sel_hi:[1,0]
	v_pk_mul_f32 v[54:55], v[54:55], v[68:69] op_sel_hi:[1,0]
	v_pk_mul_f32 v[52:53], v[52:53], v[68:69] op_sel_hi:[1,0]
	v_pk_mul_f32 v[70:71], v[50:51], v[68:69] op_sel_hi:[1,0]
	v_pk_mul_f32 v[68:69], v[48:49], v[68:69] op_sel_hi:[1,0]
	v_cvt_pk_bf16_f32 v48, v60, v61
	v_cvt_pk_bf16_f32 v49, v62, v63
	v_cvt_pk_bf16_f32 v50, v56, v57
	v_cvt_pk_bf16_f32 v51, v58, v59
	global_store_dwordx4 v[64:65], v[48:51], off sc1
	s_nop 1
	v_cvt_pk_bf16_f32 v48, v52, v53
	v_cvt_pk_bf16_f32 v49, v54, v55
	v_cvt_pk_bf16_f32 v50, v68, v69
	v_cvt_pk_bf16_f32 v51, v70, v71
	global_store_dwordx4 v[64:65], v[48:51], off offset:256 sc1
	s_nop 0
	v_add_u32_e32 v64, 0xa0, v150
	v_mad_i64_i32 v[66:67], s[6:7], v80, s66, v[146:147]
	v_ashrrev_i32_e32 v65, 31, v64
	v_add_u32_e32 v187, 0x2c00, v186
	global_load_dwordx4 v[204:207], v187, s[18:19]
	v_add_u32_e32 v187, 0x2c10, v186
	global_load_dwordx4 v[208:211], v187, s[18:19]
	v_add_u32_e32 v187, 0x2c20, v186
	global_load_dwordx4 v[212:215], v187, s[18:19]
	v_add_u32_e32 v187, 0x2c30, v186
	global_load_dwordx4 v[216:219], v187, s[18:19]
	s_waitcnt vmcnt(12)
	v_pk_add_f32 v[48:49], v[220:221], v[222:223]
	v_pk_add_f32 v[52:53], v[232:233], v[234:235]
	v_pk_add_f32 v[54:55], v[236:237], v[238:239]
	v_pk_add_f32 v[56:57], v[240:241], v[242:243]
	v_pk_add_f32 v[48:49], v[48:49], v[52:53]
	v_pk_add_f32 v[54:55], v[54:55], v[56:57]
	v_pk_add_f32 v[48:49], v[48:49], v[54:55]
	v_add_f32_e32 v48, v48, v49
	v_lshlrev_b64 v[50:51], 6, v[64:65]
	v_lshl_add_u64 v[50:51], s[18:19], 0, v[50:51]
	v_fmamk_f32 v48, v48, 0x3a800000, v158
	v_mul_f32_e32 v49, 0x4b800000, v48
	v_cmp_gt_f32_e32 vcc, s65, v48
	s_nop 1
	v_cndmask_b32_e32 v48, v48, v49, vcc
	v_rsq_f32_e32 v52, v48
	v_lshl_add_u64 v[48:49], v[66:67], 0, v[148:149]
	v_mul_f32_e32 v53, 0x45800000, v52
	v_cndmask_b32_e32 v52, v52, v53, vcc
	v_pk_mul_f32 v[46:47], v[46:47], v[52:53] op_sel_hi:[1,0]
	v_pk_mul_f32 v[44:45], v[44:45], v[52:53] op_sel_hi:[1,0]
	v_pk_mul_f32 v[42:43], v[42:43], v[52:53] op_sel_hi:[1,0]
	v_pk_mul_f32 v[40:41], v[40:41], v[52:53] op_sel_hi:[1,0]
	v_pk_mul_f32 v[38:39], v[38:39], v[52:53] op_sel_hi:[1,0]
	v_pk_mul_f32 v[36:37], v[36:37], v[52:53] op_sel_hi:[1,0]
	v_pk_mul_f32 v[54:55], v[34:35], v[52:53] op_sel_hi:[1,0]
	v_pk_mul_f32 v[52:53], v[32:33], v[52:53] op_sel_hi:[1,0]
	v_cvt_pk_bf16_f32 v32, v44, v45
	v_cvt_pk_bf16_f32 v33, v46, v47
	v_cvt_pk_bf16_f32 v34, v40, v41
	v_cvt_pk_bf16_f32 v35, v42, v43
	global_store_dwordx4 v[48:49], v[32:35], off sc1
	s_nop 1
	v_cvt_pk_bf16_f32 v32, v36, v37
	v_cvt_pk_bf16_f32 v33, v38, v39
	v_cvt_pk_bf16_f32 v34, v52, v53
	v_cvt_pk_bf16_f32 v35, v54, v55
	global_store_dwordx4 v[48:49], v[32:35], off offset:256 sc1
	s_nop 0
	v_add_u32_e32 v48, 0xb0, v150
	v_mad_i64_i32 v[50:51], s[6:7], v64, s66, v[146:147]
	v_ashrrev_i32_e32 v49, 31, v48
	s_mov_b32 s6, s22
	s_waitcnt vmcnt(8)
; #define PG8_WAIT_V(n) asm volatile("s_waitcnt vmcnt(" #n ")" ::: "memory")
; #define PG8_BAR __builtin_amdgcn_s_barrier()
; __device__ __forceinline__ u32x4 pack8(const f32x4 v0, const f32x4 v1) { u32x4 w; w.x = pk2(v0[0], v0[1]); w.y = pk2(v0[2], v0[3]); w.z = pk2(v1[0], v1[1]); w.w = pk2(v1[2], v1[3]); return w; }
;     ...
;     PG8_WAIT_V(0);
;     if (wr == 0) PG8_BAR;
;     PG8_BAR;
; __device__ __forceinline__ float row_rstd(const float* ssq, int row) {
;     const f32x4* p = (const f32x4*)(ssq + (size_t)row * 16);
;     const f32x4 a = p[0], b = p[1], c = p[2], d = p[3];
;     const float s = ((a[0] + a[1]) + (a[2] + a[3])) + ((b[0] + b[1]) + (b[2] + b[3])) + ((c[0] + c[1]) + (c[2] + c[3])) + ((d[0] + d[1]) + (d[2] + d[3]));
;     return rsqrtf(s * (1.0f / 1024.0f) + 1e-6f);
;     __device__ __forceinline__ void operator()(const f32x4 (&acc)[2][2][4][2], const Unit& u, int wr, int wc, int fr, int fq) const {
;     ...
;             for (int m = 0; m < 4; ++m) {
;                 const int row = row0 + ai * 128 + m * 16; const float rs = row_rstd(ssq, row);
;                 bf16_t* rowp = O + (size_t)row * ldc + col0;
; #pragma unroll
;                 for (int bj = 0; bj < 2; ++bj) { f32x4 v0 = acc[ai][bj][m][0] * rs, v1 = acc[ai][bj][m][1] * rs;
;                     if (ACT == 1) {
; #pragma unroll
;                         for (int j = 0; j < 4; ++j) { const float a = fmaxf(v0[j], 0.f), b = fmaxf(v1[j], 0.f); v0[j] = a * a; v1[j] = b * b; } }
;                     *(u32x4*)(rowp + bj * 128) = pack8(v0, v1); }
	v_pk_add_f32 v[32:33], v[188:189], v[190:191]
	v_pk_add_f32 v[36:37], v[192:193], v[194:195]
	v_pk_add_f32 v[38:39], v[196:197], v[198:199]
	v_pk_add_f32 v[40:41], v[200:201], v[202:203]
	v_pk_add_f32 v[32:33], v[32:33], v[36:37]
	v_pk_add_f32 v[38:39], v[38:39], v[40:41]
	v_pk_add_f32 v[32:33], v[32:33], v[38:39]
	v_add_f32_e32 v32, v32, v33
	v_lshlrev_b64 v[34:35], 6, v[48:49]
	v_lshl_add_u64 v[34:35], s[18:19], 0, v[34:35]
	v_fmamk_f32 v32, v32, 0x3a800000, v158
	v_mul_f32_e32 v33, 0x4b800000, v32
	v_cmp_gt_f32_e32 vcc, s65, v32
	s_nop 1
	v_cndmask_b32_e32 v32, v32, v33, vcc
	v_rsq_f32_e32 v36, v32
	v_lshl_add_u64 v[32:33], v[50:51], 0, v[148:149]
	v_mul_f32_e32 v37, 0x45800000, v36
	v_cndmask_b32_e32 v36, v36, v37, vcc
	v_pk_mul_f32 v[30:31], v[30:31], v[36:37] op_sel_hi:[1,0]
	v_pk_mul_f32 v[28:29], v[28:29], v[36:37] op_sel_hi:[1,0]
	v_pk_mul_f32 v[26:27], v[26:27], v[36:37] op_sel_hi:[1,0]
	v_pk_mul_f32 v[24:25], v[24:25], v[36:37] op_sel_hi:[1,0]
	v_pk_mul_f32 v[22:23], v[22:23], v[36:37] op_sel_hi:[1,0]
	v_pk_mul_f32 v[20:21], v[20:21], v[36:37] op_sel_hi:[1,0]
	v_pk_mul_f32 v[38:39], v[18:19], v[36:37] op_sel_hi:[1,0]
	v_pk_mul_f32 v[36:37], v[16:17], v[36:37] op_sel_hi:[1,0]
	v_cvt_pk_bf16_f32 v16, v28, v29
	v_cvt_pk_bf16_f32 v17, v30, v31
	v_cvt_pk_bf16_f32 v18, v24, v25
	v_cvt_pk_bf16_f32 v19, v26, v27
	global_store_dwordx4 v[32:33], v[16:19], off sc1
	s_and_b64 vcc, exec, s[10:11]
	s_nop 0
	v_cvt_pk_bf16_f32 v16, v20, v21
	v_cvt_pk_bf16_f32 v17, v22, v23
	v_cvt_pk_bf16_f32 v18, v36, v37
	v_cvt_pk_bf16_f32 v19, v38, v39
	global_store_dwordx4 v[32:33], v[16:19], off offset:256 sc1
	s_nop 0
	s_waitcnt vmcnt(4)
	v_pk_add_f32 v[16:17], v[204:205], v[206:207]
	v_pk_add_f32 v[18:19], v[208:209], v[210:211]
	v_pk_add_f32 v[20:21], v[212:213], v[214:215]
	v_pk_add_f32 v[22:23], v[216:217], v[218:219]
	v_pk_add_f32 v[16:17], v[16:17], v[18:19]
	v_pk_add_f32 v[20:21], v[20:21], v[22:23]
	v_pk_add_f32 v[16:17], v[16:17], v[20:21]
	v_add_f32_e32 v16, v16, v17
	s_nop 0
	s_nop 0
	v_fmamk_f32 v16, v16, 0x3a800000, v158
	v_mul_f32_e32 v17, 0x4b800000, v16
	v_cmp_gt_f32_e64 s[10:11], s65, v16
	s_nop 1
	v_cndmask_b32_e64 v16, v16, v17, s[10:11]
	v_rsq_f32_e32 v18, v16
	v_mad_i64_i32 v[16:17], s[8:9], v48, s66, v[146:147]
	v_lshl_add_u64 v[16:17], v[16:17], 0, v[148:149]
	v_mul_f32_e32 v19, 0x45800000, v18
	v_cndmask_b32_e64 v18, v18, v19, s[10:11]
	v_pk_mul_f32 v[14:15], v[14:15], v[18:19] op_sel_hi:[1,0]
	v_pk_mul_f32 v[12:13], v[12:13], v[18:19] op_sel_hi:[1,0]
	v_pk_mul_f32 v[10:11], v[10:11], v[18:19] op_sel_hi:[1,0]
	v_pk_mul_f32 v[8:9], v[8:9], v[18:19] op_sel_hi:[1,0]
	v_pk_mul_f32 v[6:7], v[6:7], v[18:19] op_sel_hi:[1,0]
	v_pk_mul_f32 v[4:5], v[4:5], v[18:19] op_sel_hi:[1,0]
	v_pk_mul_f32 v[20:21], v[2:3], v[18:19] op_sel_hi:[1,0]
	v_pk_mul_f32 v[18:19], v[0:1], v[18:19] op_sel_hi:[1,0]
	v_cvt_pk_bf16_f32 v0, v12, v13
	v_cvt_pk_bf16_f32 v1, v14, v15
	v_cvt_pk_bf16_f32 v2, v8, v9
	v_cvt_pk_bf16_f32 v3, v10, v11
	global_store_dwordx4 v[16:17], v[0:3], off sc1
	s_nop 1
	v_cvt_pk_bf16_f32 v0, v4, v5
	v_cvt_pk_bf16_f32 v1, v6, v7
	v_cvt_pk_bf16_f32 v2, v18, v19
	v_cvt_pk_bf16_f32 v3, v20, v21
	global_store_dwordx4 v[16:17], v[0:3], off offset:256 sc1
	s_cbranch_vccz .LBB0_1281
	s_waitcnt vmcnt(0)
	s_cmpk_gt_u32 s53, 0xff
	s_cbranch_scc1 .LBB0_1292
	s_barrier

.LBB0_2099:
	ds_read_b128 v[156:159], v151
	ds_read_b128 v[160:163], v151 offset:1024
	ds_read_b128 v[170:173], v151 offset:2048
	ds_read_b128 v[174:177], v151 offset:3072
	s_add_u32 s38, s36, 0xfffc0080
	s_addc_u32 s39, s37, -1
	s_cmp_eq_u32 s71, 12
	s_cselect_b32 s41, s25, s39
	s_cselect_b32 s40, s44, s38
	s_cselect_b32 s39, s35, s70
	s_cselect_b32 s38, s45, s69
	v_lshl_add_u64 v[146:147], s[36:37], 0, v[138:139]
	s_add_i32 m0, s53, 0xc000
	ds_read_b128 v[178:181], v152
	ds_read_b128 v[182:185], v152 offset:1024
	ds_read_b128 v[186:189], v152 offset:2048
	ds_read_b128 v[190:193], v152 offset:3072
	ds_read_b128 v[194:197], v152 offset:4096
	ds_read_b128 v[198:201], v152 offset:5120
	ds_read_b128 v[202:205], v152 offset:6144
	ds_read_b128 v[206:209], v152 offset:7168
	global_load_lds_dwordx4 v[146:147], off
	v_lshl_add_u64 v[146:147], s[36:37], 0, v[136:137]
	s_add_i32 m0, s53, 0xe000
	s_nop 0
	global_load_lds_dwordx4 v[146:147], off
	s_waitcnt lgkmcnt(8)
	s_barrier
	s_waitcnt lgkmcnt(0)
	s_setprio 1
	s_waitcnt lgkmcnt(0)
	v_mfma_f32_16x16x32_bf16 v[124:127], v[156:159], v[178:181], v[124:127]
	v_mfma_f32_16x16x32_bf16 v[120:123], v[170:173], v[178:181], v[120:123]
	v_mfma_f32_16x16x32_bf16 v[108:111], v[156:159], v[186:189], v[108:111]
	v_mfma_f32_16x16x32_bf16 v[104:107], v[170:173], v[186:189], v[104:107]
	v_mfma_f32_16x16x32_bf16 v[92:95], v[156:159], v[194:197], v[92:95]
	v_mfma_f32_16x16x32_bf16 v[88:91], v[170:173], v[194:197], v[88:91]
	v_mfma_f32_16x16x32_bf16 v[76:79], v[156:159], v[202:205], v[76:79]
	v_mfma_f32_16x16x32_bf16 v[72:75], v[170:173], v[202:205], v[72:75]
	v_mfma_f32_16x16x32_bf16 v[124:127], v[160:163], v[182:185], v[124:127]
	v_mfma_f32_16x16x32_bf16 v[120:123], v[174:177], v[182:185], v[120:123]
	v_mfma_f32_16x16x32_bf16 v[108:111], v[160:163], v[190:193], v[108:111]
	v_mfma_f32_16x16x32_bf16 v[104:107], v[174:177], v[190:193], v[104:107]
	v_mfma_f32_16x16x32_bf16 v[92:95], v[160:163], v[198:201], v[92:95]
	v_mfma_f32_16x16x32_bf16 v[88:91], v[174:177], v[198:201], v[88:91]
	v_mfma_f32_16x16x32_bf16 v[76:79], v[160:163], v[206:209], v[76:79]
	v_mfma_f32_16x16x32_bf16 v[72:75], v[174:177], v[206:209], v[72:75]
	s_setprio 0
	s_barrier
	s_add_i32 s72, s61, s52
	v_lshl_add_u64 v[146:147], s[38:39], 0, v[130:131]
	s_mov_b32 m0, s72
	ds_read_b128 v[210:213], v153
	ds_read_b128 v[214:217], v153 offset:1024
	ds_read_b128 v[218:221], v153 offset:2048
	ds_read_b128 v[222:225], v153 offset:3072
	global_load_lds_dwordx4 v[146:147], off
	v_lshl_add_u64 v[164:165], s[38:39], 0, v[134:135]
	s_add_i32 m0, s72, 0x2000
	s_nop 0
	global_load_lds_dwordx4 v[164:165], off
	s_barrier
	s_waitcnt lgkmcnt(0)
	s_setprio 1
	s_waitcnt lgkmcnt(0)
	v_mfma_f32_16x16x32_bf16 v[116:119], v[210:213], v[178:181], v[116:119]
	v_mfma_f32_16x16x32_bf16 v[112:115], v[218:221], v[178:181], v[112:115]
	v_mfma_f32_16x16x32_bf16 v[100:103], v[210:213], v[186:189], v[100:103]
	v_mfma_f32_16x16x32_bf16 v[96:99], v[218:221], v[186:189], v[96:99]
	v_mfma_f32_16x16x32_bf16 v[84:87], v[210:213], v[194:197], v[84:87]
	v_mfma_f32_16x16x32_bf16 v[80:83], v[218:221], v[194:197], v[80:83]
	v_mfma_f32_16x16x32_bf16 v[68:71], v[210:213], v[202:205], v[68:71]
	v_mfma_f32_16x16x32_bf16 v[64:67], v[218:221], v[202:205], v[64:67]
	v_mfma_f32_16x16x32_bf16 v[116:119], v[214:217], v[182:185], v[116:119]
	v_mfma_f32_16x16x32_bf16 v[112:115], v[222:225], v[182:185], v[112:115]
	v_mfma_f32_16x16x32_bf16 v[100:103], v[214:217], v[190:193], v[100:103]
	v_mfma_f32_16x16x32_bf16 v[96:99], v[222:225], v[190:193], v[96:99]
	v_mfma_f32_16x16x32_bf16 v[84:87], v[214:217], v[198:201], v[84:87]
	v_mfma_f32_16x16x32_bf16 v[80:83], v[222:225], v[198:201], v[80:83]
	v_mfma_f32_16x16x32_bf16 v[68:71], v[214:217], v[206:209], v[68:71]
	v_mfma_f32_16x16x32_bf16 v[64:67], v[222:225], v[206:209], v[64:67]
	s_setprio 0
	s_mov_b32 m0, s53
	v_lshl_add_u64 v[226:227], s[40:41], 0, v[128:129]
	s_barrier
	ds_read_b128 v[178:181], v152 offset:16384
	ds_read_b128 v[182:185], v152 offset:17408
	ds_read_b128 v[186:189], v152 offset:18432
	ds_read_b128 v[190:193], v152 offset:19456
	ds_read_b128 v[194:197], v152 offset:20480
	ds_read_b128 v[198:201], v152 offset:21504
	ds_read_b128 v[202:205], v152 offset:22528
	ds_read_b128 v[206:209], v152 offset:23552
	global_load_lds_dwordx4 v[226:227], off
	v_lshl_add_u64 v[228:229], s[40:41], 0, v[132:133]
	s_mov_b32 m0, s54
	s_nop 0
	global_load_lds_dwordx4 v[228:229], off
	s_barrier
	s_waitcnt lgkmcnt(0)
	s_setprio 1
	s_waitcnt lgkmcnt(0)
	v_mfma_f32_16x16x32_bf16 v[60:63], v[156:159], v[178:181], v[60:63]
	v_mfma_f32_16x16x32_bf16 v[56:59], v[170:173], v[178:181], v[56:59]
	v_mfma_f32_16x16x32_bf16 v[44:47], v[156:159], v[186:189], v[44:47]
	v_mfma_f32_16x16x32_bf16 v[40:43], v[170:173], v[186:189], v[40:43]
	v_mfma_f32_16x16x32_bf16 v[28:31], v[156:159], v[194:197], v[28:31]
	v_mfma_f32_16x16x32_bf16 v[24:27], v[170:173], v[194:197], v[24:27]
	v_mfma_f32_16x16x32_bf16 v[12:15], v[156:159], v[202:205], v[12:15]
	v_mfma_f32_16x16x32_bf16 v[8:11], v[170:173], v[202:205], v[8:11]
	v_mfma_f32_16x16x32_bf16 v[60:63], v[160:163], v[182:185], v[60:63]
	v_mfma_f32_16x16x32_bf16 v[56:59], v[174:177], v[182:185], v[56:59]
	v_mfma_f32_16x16x32_bf16 v[44:47], v[160:163], v[190:193], v[44:47]
	v_mfma_f32_16x16x32_bf16 v[40:43], v[174:177], v[190:193], v[40:43]
	v_mfma_f32_16x16x32_bf16 v[28:31], v[160:163], v[198:201], v[28:31]
	v_mfma_f32_16x16x32_bf16 v[24:27], v[174:177], v[198:201], v[24:27]
	v_mfma_f32_16x16x32_bf16 v[12:15], v[160:163], v[206:209], v[12:15]
	v_mfma_f32_16x16x32_bf16 v[8:11], v[174:177], v[206:209], v[8:11]
	s_setprio 0
	s_barrier
	s_add_u32 s72, s38, 0x40000
	s_addc_u32 s73, s39, 0
	s_add_i32 s74, s62, s52
	v_lshl_add_u64 v[156:157], s[72:73], 0, v[130:131]
	s_mov_b32 m0, s74
	s_nop 0
	global_load_lds_dwordx4 v[156:157], off
	v_lshl_add_u64 v[156:157], s[72:73], 0, v[134:135]
	s_add_i32 m0, s74, 0x2000
	s_nop 0
	global_load_lds_dwordx4 v[156:157], off
	s_waitcnt vmcnt(6)
	s_barrier
	s_setprio 1
	v_mfma_f32_16x16x32_bf16 v[52:55], v[210:213], v[178:181], v[52:55]
	v_mfma_f32_16x16x32_bf16 v[48:51], v[218:221], v[178:181], v[48:51]
	v_mfma_f32_16x16x32_bf16 v[36:39], v[210:213], v[186:189], v[36:39]
	v_mfma_f32_16x16x32_bf16 v[32:35], v[218:221], v[186:189], v[32:35]
	v_mfma_f32_16x16x32_bf16 v[20:23], v[210:213], v[194:197], v[20:23]
	v_mfma_f32_16x16x32_bf16 v[16:19], v[218:221], v[194:197], v[16:19]
	v_mfma_f32_16x16x32_bf16 v[4:7], v[210:213], v[202:205], v[4:7]
	v_mfma_f32_16x16x32_bf16 v[0:3], v[218:221], v[202:205], v[0:3]
	v_mfma_f32_16x16x32_bf16 v[52:55], v[214:217], v[182:185], v[52:55]
	v_mfma_f32_16x16x32_bf16 v[48:51], v[222:225], v[182:185], v[48:51]
	v_mfma_f32_16x16x32_bf16 v[36:39], v[214:217], v[190:193], v[36:39]
	v_mfma_f32_16x16x32_bf16 v[32:35], v[222:225], v[190:193], v[32:35]
	v_mfma_f32_16x16x32_bf16 v[20:23], v[214:217], v[198:201], v[20:23]
	v_mfma_f32_16x16x32_bf16 v[16:19], v[222:225], v[198:201], v[16:19]
	v_mfma_f32_16x16x32_bf16 v[4:7], v[214:217], v[206:209], v[4:7]
	v_mfma_f32_16x16x32_bf16 v[0:3], v[222:225], v[206:209], v[0:3]
	s_setprio 0
	s_add_i32 s72, 0, 0x18000
	v_add_u32_e32 v155, s72, v149
	s_barrier
	ds_read_b128 v[156:159], v155
	ds_read_b128 v[160:163], v155 offset:1024
	ds_read_b128 v[170:173], v155 offset:2048
	ds_read_b128 v[174:177], v155 offset:3072
	s_add_u32 s40, s40, 0x40000
	s_addc_u32 s41, s41, 0
	s_mov_b32 m0, s55
	v_lshl_add_u64 v[210:211], s[40:41], 0, v[128:129]
	ds_read_b128 v[178:181], v152 offset:32768
	ds_read_b128 v[182:185], v152 offset:33792
	ds_read_b128 v[186:189], v152 offset:34816
	ds_read_b128 v[190:193], v152 offset:35840
	ds_read_b128 v[194:197], v152 offset:36864
	ds_read_b128 v[198:201], v152 offset:37888
	ds_read_b128 v[202:205], v152 offset:38912
	ds_read_b128 v[206:209], v152 offset:39936
	global_load_lds_dwordx4 v[210:211], off
	v_lshl_add_u64 v[210:211], s[40:41], 0, v[132:133]
	s_mov_b32 m0, s56
	s_nop 0
	global_load_lds_dwordx4 v[210:211], off
	s_waitcnt lgkmcnt(8)
	s_barrier
	s_waitcnt lgkmcnt(0)
	s_setprio 1
	s_waitcnt lgkmcnt(0)
	v_mfma_f32_16x16x32_bf16 v[124:127], v[156:159], v[178:181], v[124:127]
	v_mfma_f32_16x16x32_bf16 v[120:123], v[170:173], v[178:181], v[120:123]
	v_mfma_f32_16x16x32_bf16 v[108:111], v[156:159], v[186:189], v[108:111]
	v_mfma_f32_16x16x32_bf16 v[104:107], v[170:173], v[186:189], v[104:107]
	v_mfma_f32_16x16x32_bf16 v[92:95], v[156:159], v[194:197], v[92:95]
	v_mfma_f32_16x16x32_bf16 v[88:91], v[170:173], v[194:197], v[88:91]
	v_mfma_f32_16x16x32_bf16 v[76:79], v[156:159], v[202:205], v[76:79]
	v_mfma_f32_16x16x32_bf16 v[72:75], v[170:173], v[202:205], v[72:75]
	v_mfma_f32_16x16x32_bf16 v[124:127], v[160:163], v[182:185], v[124:127]
	v_mfma_f32_16x16x32_bf16 v[120:123], v[174:177], v[182:185], v[120:123]
	v_mfma_f32_16x16x32_bf16 v[108:111], v[160:163], v[190:193], v[108:111]
	v_mfma_f32_16x16x32_bf16 v[104:107], v[174:177], v[190:193], v[104:107]
	v_mfma_f32_16x16x32_bf16 v[92:95], v[160:163], v[198:201], v[92:95]
	v_mfma_f32_16x16x32_bf16 v[88:91], v[174:177], v[198:201], v[88:91]
	v_mfma_f32_16x16x32_bf16 v[76:79], v[160:163], v[206:209], v[76:79]
	v_mfma_f32_16x16x32_bf16 v[72:75], v[174:177], v[206:209], v[72:75]
	s_setprio 0
	s_barrier
	s_add_i32 s40, 0, 0x1c000
	s_add_i32 s41, s72, s52
	v_add_u32_e32 v155, s40, v149
	v_lshl_add_u64 v[146:147], v[146:147], 0, s[26:27]
	s_mov_b32 m0, s41
	ds_read_b128 v[210:213], v155
	ds_read_b128 v[214:217], v155 offset:1024
	ds_read_b128 v[218:221], v155 offset:2048
	ds_read_b128 v[222:225], v155 offset:3072
	global_load_lds_dwordx4 v[146:147], off
	v_lshl_add_u64 v[146:147], v[164:165], 0, s[26:27]
	s_add_i32 m0, s41, 0x2000
	s_nop 0
	global_load_lds_dwordx4 v[146:147], off
	s_barrier
	s_waitcnt lgkmcnt(0)
	s_setprio 1
	s_waitcnt lgkmcnt(0)
	v_mfma_f32_16x16x32_bf16 v[116:119], v[210:213], v[178:181], v[116:119]
	v_mfma_f32_16x16x32_bf16 v[112:115], v[218:221], v[178:181], v[112:115]
	v_mfma_f32_16x16x32_bf16 v[100:103], v[210:213], v[186:189], v[100:103]
	v_mfma_f32_16x16x32_bf16 v[96:99], v[218:221], v[186:189], v[96:99]
	v_mfma_f32_16x16x32_bf16 v[84:87], v[210:213], v[194:197], v[84:87]
	v_mfma_f32_16x16x32_bf16 v[80:83], v[218:221], v[194:197], v[80:83]
	v_mfma_f32_16x16x32_bf16 v[68:71], v[210:213], v[202:205], v[68:71]
	v_mfma_f32_16x16x32_bf16 v[64:67], v[218:221], v[202:205], v[64:67]
	v_mfma_f32_16x16x32_bf16 v[116:119], v[214:217], v[182:185], v[116:119]
	v_mfma_f32_16x16x32_bf16 v[112:115], v[222:225], v[182:185], v[112:115]
	v_mfma_f32_16x16x32_bf16 v[100:103], v[214:217], v[190:193], v[100:103]
	v_mfma_f32_16x16x32_bf16 v[96:99], v[222:225], v[190:193], v[96:99]
	v_mfma_f32_16x16x32_bf16 v[84:87], v[214:217], v[198:201], v[84:87]
	v_mfma_f32_16x16x32_bf16 v[80:83], v[222:225], v[198:201], v[80:83]
	v_mfma_f32_16x16x32_bf16 v[68:71], v[214:217], v[206:209], v[68:71]
	v_mfma_f32_16x16x32_bf16 v[64:67], v[222:225], v[206:209], v[64:67]
	s_setprio 0
	s_mov_b32 m0, s58
	v_lshl_add_u64 v[146:147], v[226:227], 0, s[26:27]
	s_barrier
	ds_read_b128 v[178:181], v152 offset:49152
	ds_read_b128 v[182:185], v152 offset:50176
	ds_read_b128 v[186:189], v152 offset:51200
	ds_read_b128 v[190:193], v152 offset:52224
	ds_read_b128 v[194:197], v152 offset:53248
	ds_read_b128 v[198:201], v152 offset:54272
	ds_read_b128 v[202:205], v152 offset:55296
	ds_read_b128 v[206:209], v152 offset:56320
	global_load_lds_dwordx4 v[146:147], off
	v_lshl_add_u64 v[146:147], v[228:229], 0, s[26:27]
	s_mov_b32 m0, s59
	s_nop 0
	global_load_lds_dwordx4 v[146:147], off
	s_barrier
	s_waitcnt lgkmcnt(0)
	s_setprio 1
	s_waitcnt lgkmcnt(0)
	v_mfma_f32_16x16x32_bf16 v[60:63], v[156:159], v[178:181], v[60:63]
	v_mfma_f32_16x16x32_bf16 v[56:59], v[170:173], v[178:181], v[56:59]
	v_mfma_f32_16x16x32_bf16 v[44:47], v[156:159], v[186:189], v[44:47]
	v_mfma_f32_16x16x32_bf16 v[40:43], v[170:173], v[186:189], v[40:43]
	v_mfma_f32_16x16x32_bf16 v[28:31], v[156:159], v[194:197], v[28:31]
	v_mfma_f32_16x16x32_bf16 v[24:27], v[170:173], v[194:197], v[24:27]
	v_mfma_f32_16x16x32_bf16 v[12:15], v[156:159], v[202:205], v[12:15]
	v_mfma_f32_16x16x32_bf16 v[8:11], v[170:173], v[202:205], v[8:11]
	v_mfma_f32_16x16x32_bf16 v[60:63], v[160:163], v[182:185], v[60:63]
	v_mfma_f32_16x16x32_bf16 v[56:59], v[174:177], v[182:185], v[56:59]
	v_mfma_f32_16x16x32_bf16 v[44:47], v[160:163], v[190:193], v[44:47]
	v_mfma_f32_16x16x32_bf16 v[40:43], v[174:177], v[190:193], v[40:43]
	v_mfma_f32_16x16x32_bf16 v[28:31], v[160:163], v[198:201], v[28:31]
	v_mfma_f32_16x16x32_bf16 v[24:27], v[174:177], v[198:201], v[24:27]
	v_mfma_f32_16x16x32_bf16 v[12:15], v[160:163], v[206:209], v[12:15]
	v_mfma_f32_16x16x32_bf16 v[8:11], v[174:177], v[206:209], v[8:11]
	s_setprio 0
	s_barrier
	s_add_u32 s38, s38, 0x40080
	s_addc_u32 s39, s39, 0
	s_add_i32 s40, s40, s52
	v_lshl_add_u64 v[146:147], s[38:39], 0, v[130:131]
	s_mov_b32 m0, s40
	s_nop 0
	global_load_lds_dwordx4 v[146:147], off
	v_lshl_add_u64 v[146:147], s[38:39], 0, v[134:135]
	s_add_i32 m0, s40, 0x2000
	s_nop 0
	global_load_lds_dwordx4 v[146:147], off
	s_waitcnt vmcnt(6)
	s_barrier
	s_setprio 1
	v_mfma_f32_16x16x32_bf16 v[52:55], v[210:213], v[178:181], v[52:55]
	v_mfma_f32_16x16x32_bf16 v[48:51], v[218:221], v[178:181], v[48:51]
	v_mfma_f32_16x16x32_bf16 v[36:39], v[210:213], v[186:189], v[36:39]
	v_mfma_f32_16x16x32_bf16 v[32:35], v[218:221], v[186:189], v[32:35]
	v_mfma_f32_16x16x32_bf16 v[20:23], v[210:213], v[194:197], v[20:23]
	v_mfma_f32_16x16x32_bf16 v[16:19], v[218:221], v[194:197], v[16:19]
	v_mfma_f32_16x16x32_bf16 v[4:7], v[210:213], v[202:205], v[4:7]
	v_mfma_f32_16x16x32_bf16 v[0:3], v[218:221], v[202:205], v[0:3]
	v_mfma_f32_16x16x32_bf16 v[52:55], v[214:217], v[182:185], v[52:55]
	v_mfma_f32_16x16x32_bf16 v[48:51], v[222:225], v[182:185], v[48:51]
	v_mfma_f32_16x16x32_bf16 v[36:39], v[214:217], v[190:193], v[36:39]
	v_mfma_f32_16x16x32_bf16 v[32:35], v[222:225], v[190:193], v[32:35]
	v_mfma_f32_16x16x32_bf16 v[20:23], v[214:217], v[198:201], v[20:23]
	v_mfma_f32_16x16x32_bf16 v[16:19], v[222:225], v[198:201], v[16:19]
	v_mfma_f32_16x16x32_bf16 v[4:7], v[214:217], v[206:209], v[4:7]
	v_mfma_f32_16x16x32_bf16 v[0:3], v[222:225], v[206:209], v[0:3]
	s_setprio 0
	s_add_i32 s71, s71, 2
	s_add_u32 s69, s69, 0x100
	s_addc_u32 s70, s70, 0
	s_add_u32 s36, s36, 0x100
	s_addc_u32 s37, s37, 0
	s_cmp_gt_u32 s71, 13
	s_barrier
	s_cbranch_scc0 .LBB0_2099
	v_lshl_add_u32 v146, s68, 8, v148
	v_ashrrev_i32_e32 v147, 31, v146
	v_lshlrev_b64 v[156:157], 6, v[146:147]
	v_lshl_add_u64 v[164:165], s[22:23], 0, v[156:157]
	v_subrev_u32_e32 v180, s22, v164
	v_add_u32_e32 v181, 0x0, v180
	global_load_dwordx4 v[182:185], v181, s[22:23]
	v_add_u32_e32 v181, 0x10, v180
	global_load_dwordx4 v[186:189], v181, s[22:23]
	v_add_u32_e32 v181, 0x20, v180
	global_load_dwordx4 v[190:193], v181, s[22:23]
	v_add_u32_e32 v181, 0x30, v180
	global_load_dwordx4 v[194:197], v181, s[22:23]
	v_add_u32_e32 v181, 0x400, v180
	global_load_dwordx4 v[198:201], v181, s[22:23]
	v_add_u32_e32 v181, 0x410, v180
	global_load_dwordx4 v[202:205], v181, s[22:23]
	v_add_u32_e32 v181, 0x420, v180
	global_load_dwordx4 v[206:209], v181, s[22:23]
	v_add_u32_e32 v181, 0x430, v180
	global_load_dwordx4 v[210:213], v181, s[22:23]
	v_add_u32_e32 v181, 0x800, v180
	global_load_dwordx4 v[214:217], v181, s[22:23]
	v_add_u32_e32 v181, 0x810, v180
	global_load_dwordx4 v[218:221], v181, s[22:23]
	v_add_u32_e32 v181, 0x820, v180
	global_load_dwordx4 v[222:225], v181, s[22:23]
	v_add_u32_e32 v181, 0x830, v180
	global_load_dwordx4 v[232:235], v181, s[22:23]
	v_add_u32_e32 v181, 0xc00, v180
	global_load_dwordx4 v[236:239], v181, s[22:23]
	v_add_u32_e32 v181, 0xc10, v180
	global_load_dwordx4 v[240:243], v181, s[22:23]
	v_add_u32_e32 v181, 0xc20, v180
	global_load_dwordx4 v[244:247], v181, s[22:23]
	v_add_u32_e32 v181, 0xc30, v180
	global_load_dwordx4 v[248:251], v181, s[22:23]
	v_or_b32_e32 v164, 16, v146
	v_lshl_or_b32 v147, s33, 9, v150
	v_ashrrev_i32_e32 v165, 31, v164
	v_lshl_add_u32 v155, v146, 13, v147
	s_waitcnt vmcnt(12)
	v_pk_add_f32 v[156:157], v[182:183], v[184:185]
	v_pk_add_f32 v[158:159], v[186:187], v[188:189]
	v_pk_add_f32 v[160:161], v[190:191], v[192:193]
	v_pk_add_f32 v[162:163], v[194:195], v[196:197]
	v_pk_add_f32 v[156:157], v[156:157], v[158:159]
	v_pk_add_f32 v[160:161], v[160:161], v[162:163]
	v_pk_add_f32 v[156:157], v[156:157], v[160:161]
	v_add_f32_e32 v156, v156, v157
	s_nop 0
	s_nop 0
	v_fmamk_f32 v156, v156, 0x3a800000, v154
	v_mul_f32_e32 v157, 0x4b800000, v156
	v_cmp_gt_f32_e32 vcc, s63, v156
	s_nop 1
	v_cndmask_b32_e32 v156, v156, v157, vcc
	v_rsq_f32_e32 v158, v156
	v_lshlrev_b64 v[156:157], 6, v[164:165]
	v_lshl_add_u64 v[156:157], s[22:23], 0, v[156:157]
	v_mul_f32_e32 v159, 0x45800000, v158
	v_cndmask_b32_e32 v158, v158, v159, vcc
	v_pk_mul_f32 v[126:127], v[126:127], v[158:159] op_sel_hi:[1,0]
	v_pk_mul_f32 v[124:125], v[124:125], v[158:159] op_sel_hi:[1,0]
	v_pk_mul_f32 v[122:123], v[122:123], v[158:159] op_sel_hi:[1,0]
	v_pk_mul_f32 v[120:121], v[120:121], v[158:159] op_sel_hi:[1,0]
	v_pk_mul_f32 v[114:115], v[114:115], v[158:159] op_sel_hi:[1,0]
	v_pk_mul_f32 v[112:113], v[112:113], v[158:159] op_sel_hi:[1,0]
	v_pk_mul_f32 v[118:119], v[118:119], v[158:159] op_sel_hi:[1,0]
	v_pk_mul_f32 v[116:117], v[116:117], v[158:159] op_sel_hi:[1,0]
	v_max_f32_e32 v124, 0, v124
	v_max_f32_e32 v120, 0, v120
	v_max_f32_e32 v125, 0, v125
	v_max_f32_e32 v121, 0, v121
	v_max_f32_e32 v126, 0, v126
	v_max_f32_e32 v122, 0, v122
	v_max_f32_e32 v127, 0, v127
	v_max_f32_e32 v123, 0, v123
	v_max_f32_e32 v112, 0, v112
	v_max_f32_e32 v113, 0, v113
	v_max_f32_e32 v114, 0, v114
	v_max_f32_e32 v115, 0, v115
	v_max_f32_e32 v116, 0, v116
	v_max_f32_e32 v117, 0, v117
	v_max_f32_e32 v118, 0, v118
	v_max_f32_e32 v119, 0, v119
	v_pk_mul_f32 v[124:125], v[124:125], v[124:125]
	v_pk_mul_f32 v[120:121], v[120:121], v[120:121]
	v_pk_mul_f32 v[126:127], v[126:127], v[126:127]
	v_pk_mul_f32 v[122:123], v[122:123], v[122:123]
	v_pk_mul_f32 v[158:159], v[112:113], v[112:113]
	v_pk_mul_f32 v[160:161], v[114:115], v[114:115]
	v_cvt_pk_bf16_f32 v112, v124, v125
	v_cvt_pk_bf16_f32 v113, v126, v127
	v_cvt_pk_bf16_f32 v114, v120, v121
	v_cvt_pk_bf16_f32 v115, v122, v123
	v_pk_mul_f32 v[116:117], v[116:117], v[116:117]
	v_pk_mul_f32 v[118:119], v[118:119], v[118:119]
	buffer_store_dwordx4 v[112:115], v155, s[12:15], 0 offen sc1
	s_nop 1
	v_cvt_pk_bf16_f32 v112, v116, v117
	v_cvt_pk_bf16_f32 v113, v118, v119
	v_cvt_pk_bf16_f32 v114, v158, v159
	v_cvt_pk_bf16_f32 v115, v160, v161
	buffer_store_dwordx4 v[112:115], v155, s[12:15], 0 offen offset:256 sc1
	s_nop 0
	v_or_b32_e32 v156, 32, v146
	v_ashrrev_i32_e32 v157, 31, v156
	v_lshl_add_u32 v155, v164, 13, v147
	v_add_u32_e32 v181, 0x2000, v180
	global_load_dwordx4 v[182:185], v181, s[22:23]
	v_add_u32_e32 v181, 0x2010, v180
	global_load_dwordx4 v[186:189], v181, s[22:23]
	v_add_u32_e32 v181, 0x2020, v180
	global_load_dwordx4 v[190:193], v181, s[22:23]
	v_add_u32_e32 v181, 0x2030, v180
	global_load_dwordx4 v[194:197], v181, s[22:23]
	s_waitcnt vmcnt(14)
	v_pk_add_f32 v[112:113], v[198:199], v[200:201]
	v_pk_add_f32 v[114:115], v[202:203], v[204:205]
	v_pk_add_f32 v[116:117], v[206:207], v[208:209]
	v_pk_add_f32 v[118:119], v[210:211], v[212:213]
	v_pk_add_f32 v[112:113], v[112:113], v[114:115]
	v_pk_add_f32 v[116:117], v[116:117], v[118:119]
	v_pk_add_f32 v[112:113], v[112:113], v[116:117]
	v_add_f32_e32 v112, v112, v113
	s_nop 0
	s_nop 0
	v_fmamk_f32 v112, v112, 0x3a800000, v154
	v_mul_f32_e32 v113, 0x4b800000, v112
	v_cmp_gt_f32_e32 vcc, s63, v112
	s_nop 1
	v_cndmask_b32_e32 v112, v112, v113, vcc
	v_rsq_f32_e32 v114, v112
	v_lshlrev_b64 v[112:113], 6, v[156:157]
	v_lshl_add_u64 v[112:113], s[22:23], 0, v[112:113]
	v_mul_f32_e32 v115, 0x45800000, v114
	v_cndmask_b32_e32 v114, v114, v115, vcc
	v_pk_mul_f32 v[110:111], v[110:111], v[114:115] op_sel_hi:[1,0]
	v_pk_mul_f32 v[108:109], v[108:109], v[114:115] op_sel_hi:[1,0]
	v_pk_mul_f32 v[106:107], v[106:107], v[114:115] op_sel_hi:[1,0]
	v_pk_mul_f32 v[104:105], v[104:105], v[114:115] op_sel_hi:[1,0]
	v_pk_mul_f32 v[98:99], v[98:99], v[114:115] op_sel_hi:[1,0]
	v_pk_mul_f32 v[96:97], v[96:97], v[114:115] op_sel_hi:[1,0]
	v_pk_mul_f32 v[102:103], v[102:103], v[114:115] op_sel_hi:[1,0]
	v_pk_mul_f32 v[100:101], v[100:101], v[114:115] op_sel_hi:[1,0]
	v_max_f32_e32 v108, 0, v108
	v_max_f32_e32 v104, 0, v104
	v_max_f32_e32 v109, 0, v109
	v_max_f32_e32 v105, 0, v105
	v_max_f32_e32 v110, 0, v110
	v_max_f32_e32 v106, 0, v106
	v_max_f32_e32 v111, 0, v111
	v_max_f32_e32 v107, 0, v107
	v_max_f32_e32 v96, 0, v96
	v_max_f32_e32 v97, 0, v97
	v_max_f32_e32 v98, 0, v98
	v_max_f32_e32 v99, 0, v99
	v_max_f32_e32 v100, 0, v100
	v_max_f32_e32 v101, 0, v101
	v_max_f32_e32 v102, 0, v102
	v_max_f32_e32 v103, 0, v103
	v_pk_mul_f32 v[108:109], v[108:109], v[108:109]
	v_pk_mul_f32 v[104:105], v[104:105], v[104:105]
	v_pk_mul_f32 v[110:111], v[110:111], v[110:111]
	v_pk_mul_f32 v[106:107], v[106:107], v[106:107]
	v_pk_mul_f32 v[114:115], v[96:97], v[96:97]
	v_pk_mul_f32 v[116:117], v[98:99], v[98:99]
	v_cvt_pk_bf16_f32 v96, v108, v109
	v_cvt_pk_bf16_f32 v97, v110, v111
	v_cvt_pk_bf16_f32 v98, v104, v105
	v_cvt_pk_bf16_f32 v99, v106, v107
	v_pk_mul_f32 v[100:101], v[100:101], v[100:101]
	v_pk_mul_f32 v[102:103], v[102:103], v[102:103]
	buffer_store_dwordx4 v[96:99], v155, s[12:15], 0 offen sc1
	s_nop 1
	v_cvt_pk_bf16_f32 v96, v100, v101
	v_cvt_pk_bf16_f32 v97, v102, v103
	v_cvt_pk_bf16_f32 v98, v114, v115
	v_cvt_pk_bf16_f32 v99, v116, v117
	buffer_store_dwordx4 v[96:99], v155, s[12:15], 0 offen offset:256 sc1
	s_nop 0
	v_or_b32_e32 v112, 48, v146
	v_ashrrev_i32_e32 v113, 31, v112
	v_lshl_add_u32 v116, v156, 13, v147
	v_add_u32_e32 v181, 0x2400, v180
	global_load_dwordx4 v[198:201], v181, s[22:23]
	v_add_u32_e32 v181, 0x2410, v180
	global_load_dwordx4 v[202:205], v181, s[22:23]
	v_add_u32_e32 v181, 0x2420, v180
	global_load_dwordx4 v[206:209], v181, s[22:23]
	v_add_u32_e32 v181, 0x2430, v180
	global_load_dwordx4 v[210:213], v181, s[22:23]
	s_waitcnt vmcnt(16)
	v_pk_add_f32 v[96:97], v[214:215], v[216:217]
	v_pk_add_f32 v[98:99], v[218:219], v[220:221]
	v_pk_add_f32 v[100:101], v[222:223], v[224:225]
	v_pk_add_f32 v[102:103], v[232:233], v[234:235]
	v_pk_add_f32 v[96:97], v[96:97], v[98:99]
	v_pk_add_f32 v[100:101], v[100:101], v[102:103]
	v_pk_add_f32 v[96:97], v[96:97], v[100:101]
	v_add_f32_e32 v96, v96, v97
	s_nop 0
	s_nop 0
	v_fmamk_f32 v96, v96, 0x3a800000, v154
	v_mul_f32_e32 v97, 0x4b800000, v96
	v_cmp_gt_f32_e32 vcc, s63, v96
	s_nop 1
	v_cndmask_b32_e32 v96, v96, v97, vcc
	v_rsq_f32_e32 v98, v96
	v_lshlrev_b64 v[96:97], 6, v[112:113]
	v_lshl_add_u64 v[96:97], s[22:23], 0, v[96:97]
	v_mul_f32_e32 v99, 0x45800000, v98
	v_cndmask_b32_e32 v98, v98, v99, vcc
	v_pk_mul_f32 v[94:95], v[94:95], v[98:99] op_sel_hi:[1,0]
	v_pk_mul_f32 v[92:93], v[92:93], v[98:99] op_sel_hi:[1,0]
	v_pk_mul_f32 v[90:91], v[90:91], v[98:99] op_sel_hi:[1,0]
	v_pk_mul_f32 v[88:89], v[88:89], v[98:99] op_sel_hi:[1,0]
	v_pk_mul_f32 v[82:83], v[82:83], v[98:99] op_sel_hi:[1,0]
	v_pk_mul_f32 v[80:81], v[80:81], v[98:99] op_sel_hi:[1,0]
	v_pk_mul_f32 v[86:87], v[86:87], v[98:99] op_sel_hi:[1,0]
	v_pk_mul_f32 v[84:85], v[84:85], v[98:99] op_sel_hi:[1,0]
	v_max_f32_e32 v92, 0, v92
	v_max_f32_e32 v88, 0, v88
	v_max_f32_e32 v93, 0, v93
	v_max_f32_e32 v89, 0, v89
	v_max_f32_e32 v94, 0, v94
	v_max_f32_e32 v90, 0, v90
	v_max_f32_e32 v95, 0, v95
	v_max_f32_e32 v91, 0, v91
	v_max_f32_e32 v80, 0, v80
	v_max_f32_e32 v81, 0, v81
	v_max_f32_e32 v82, 0, v82
	v_max_f32_e32 v83, 0, v83
	v_max_f32_e32 v84, 0, v84
	v_max_f32_e32 v85, 0, v85
	v_max_f32_e32 v86, 0, v86
	v_max_f32_e32 v87, 0, v87
	v_pk_mul_f32 v[92:93], v[92:93], v[92:93]
	v_pk_mul_f32 v[88:89], v[88:89], v[88:89]
	v_pk_mul_f32 v[94:95], v[94:95], v[94:95]
	v_pk_mul_f32 v[90:91], v[90:91], v[90:91]
	v_pk_mul_f32 v[98:99], v[80:81], v[80:81]
	v_pk_mul_f32 v[100:101], v[82:83], v[82:83]
	v_cvt_pk_bf16_f32 v80, v92, v93
	v_cvt_pk_bf16_f32 v81, v94, v95
	v_cvt_pk_bf16_f32 v82, v88, v89
	v_cvt_pk_bf16_f32 v83, v90, v91
	v_pk_mul_f32 v[84:85], v[84:85], v[84:85]
	v_pk_mul_f32 v[86:87], v[86:87], v[86:87]
	buffer_store_dwordx4 v[80:83], v116, s[12:15], 0 offen sc1
	s_nop 1
	v_cvt_pk_bf16_f32 v80, v84, v85
	v_cvt_pk_bf16_f32 v81, v86, v87
	v_cvt_pk_bf16_f32 v82, v98, v99
	v_cvt_pk_bf16_f32 v83, v100, v101
	buffer_store_dwordx4 v[80:83], v116, s[12:15], 0 offen offset:256 sc1
	s_nop 0
	v_add_u32_e32 v96, 0x80, v146
	v_ashrrev_i32_e32 v97, 31, v96
	v_lshl_add_u32 v100, v112, 13, v147
	v_add_u32_e32 v181, 0x2800, v180
	global_load_dwordx4 v[214:217], v181, s[22:23]
	v_add_u32_e32 v181, 0x2810, v180
	global_load_dwordx4 v[218:221], v181, s[22:23]
	v_add_u32_e32 v181, 0x2820, v180
	global_load_dwordx4 v[222:225], v181, s[22:23]
	v_add_u32_e32 v181, 0x2830, v180
	global_load_dwordx4 v[232:235], v181, s[22:23]
	s_waitcnt vmcnt(18)
	v_pk_add_f32 v[80:81], v[236:237], v[238:239]
	v_pk_add_f32 v[82:83], v[240:241], v[242:243]
	v_pk_add_f32 v[84:85], v[244:245], v[246:247]
	v_pk_add_f32 v[86:87], v[248:249], v[250:251]
	v_pk_add_f32 v[80:81], v[80:81], v[82:83]
	v_pk_add_f32 v[84:85], v[84:85], v[86:87]
	v_pk_add_f32 v[80:81], v[80:81], v[84:85]
	v_add_f32_e32 v80, v80, v81
	s_nop 0
	s_nop 0
	v_fmamk_f32 v80, v80, 0x3a800000, v154
	v_mul_f32_e32 v81, 0x4b800000, v80
	v_cmp_gt_f32_e32 vcc, s63, v80
	s_nop 1
	v_cndmask_b32_e32 v80, v80, v81, vcc
	v_rsq_f32_e32 v82, v80
	v_lshlrev_b64 v[80:81], 6, v[96:97]
	v_lshl_add_u64 v[80:81], s[22:23], 0, v[80:81]
	v_mul_f32_e32 v83, 0x45800000, v82
	v_cndmask_b32_e32 v82, v82, v83, vcc
	v_pk_mul_f32 v[78:79], v[78:79], v[82:83] op_sel_hi:[1,0]
	v_pk_mul_f32 v[76:77], v[76:77], v[82:83] op_sel_hi:[1,0]
	v_pk_mul_f32 v[74:75], v[74:75], v[82:83] op_sel_hi:[1,0]
	v_pk_mul_f32 v[72:73], v[72:73], v[82:83] op_sel_hi:[1,0]
	v_pk_mul_f32 v[66:67], v[66:67], v[82:83] op_sel_hi:[1,0]
	v_pk_mul_f32 v[64:65], v[64:65], v[82:83] op_sel_hi:[1,0]
	v_pk_mul_f32 v[70:71], v[70:71], v[82:83] op_sel_hi:[1,0]
	v_pk_mul_f32 v[68:69], v[68:69], v[82:83] op_sel_hi:[1,0]
	v_max_f32_e32 v76, 0, v76
	v_max_f32_e32 v72, 0, v72
	v_max_f32_e32 v77, 0, v77
	v_max_f32_e32 v73, 0, v73
	v_max_f32_e32 v78, 0, v78
	v_max_f32_e32 v74, 0, v74
	v_max_f32_e32 v79, 0, v79
	v_max_f32_e32 v75, 0, v75
	v_max_f32_e32 v64, 0, v64
	v_max_f32_e32 v65, 0, v65
	v_max_f32_e32 v66, 0, v66
	v_max_f32_e32 v67, 0, v67
	v_max_f32_e32 v68, 0, v68
	v_max_f32_e32 v69, 0, v69
	v_max_f32_e32 v70, 0, v70
	v_max_f32_e32 v71, 0, v71
	v_pk_mul_f32 v[76:77], v[76:77], v[76:77]
	v_pk_mul_f32 v[72:73], v[72:73], v[72:73]
	v_pk_mul_f32 v[78:79], v[78:79], v[78:79]
	v_pk_mul_f32 v[74:75], v[74:75], v[74:75]
	v_pk_mul_f32 v[82:83], v[64:65], v[64:65]
	v_pk_mul_f32 v[84:85], v[66:67], v[66:67]
	v_cvt_pk_bf16_f32 v64, v76, v77
	v_cvt_pk_bf16_f32 v65, v78, v79
	v_cvt_pk_bf16_f32 v66, v72, v73
	v_cvt_pk_bf16_f32 v67, v74, v75
	v_pk_mul_f32 v[68:69], v[68:69], v[68:69]
	v_pk_mul_f32 v[70:71], v[70:71], v[70:71]
	buffer_store_dwordx4 v[64:67], v100, s[12:15], 0 offen sc1
	s_nop 1
	v_cvt_pk_bf16_f32 v64, v68, v69
	v_cvt_pk_bf16_f32 v65, v70, v71
	v_cvt_pk_bf16_f32 v66, v82, v83
	v_cvt_pk_bf16_f32 v67, v84, v85
	buffer_store_dwordx4 v[64:67], v100, s[12:15], 0 offen offset:256 sc1
	s_nop 0
	v_add_u32_e32 v80, 0x90, v146
	v_ashrrev_i32_e32 v81, 31, v80
	v_lshl_add_u32 v84, v96, 13, v147
	v_add_u32_e32 v181, 0x2c00, v180
	global_load_dwordx4 v[236:239], v181, s[22:23]
	v_add_u32_e32 v181, 0x2c10, v180
	global_load_dwordx4 v[240:243], v181, s[22:23]
	v_add_u32_e32 v181, 0x2c20, v180
	global_load_dwordx4 v[244:247], v181, s[22:23]
	v_add_u32_e32 v181, 0x2c30, v180
	global_load_dwordx4 v[248:251], v181, s[22:23]
	s_waitcnt vmcnt(18)
	v_pk_add_f32 v[64:65], v[182:183], v[184:185]
	v_pk_add_f32 v[66:67], v[186:187], v[188:189]
	v_pk_add_f32 v[68:69], v[190:191], v[192:193]
	v_pk_add_f32 v[70:71], v[194:195], v[196:197]
	v_pk_add_f32 v[64:65], v[64:65], v[66:67]
	v_pk_add_f32 v[68:69], v[68:69], v[70:71]
	v_pk_add_f32 v[64:65], v[64:65], v[68:69]
	v_add_f32_e32 v64, v64, v65
	s_nop 0
	s_nop 0
	v_fmamk_f32 v64, v64, 0x3a800000, v154
	v_mul_f32_e32 v65, 0x4b800000, v64
	v_cmp_gt_f32_e32 vcc, s63, v64
	s_nop 1
	v_cndmask_b32_e32 v64, v64, v65, vcc
	v_rsq_f32_e32 v66, v64
	v_lshlrev_b64 v[64:65], 6, v[80:81]
	v_lshl_add_u64 v[64:65], s[22:23], 0, v[64:65]
	v_mul_f32_e32 v67, 0x45800000, v66
	v_cndmask_b32_e32 v66, v66, v67, vcc
	v_pk_mul_f32 v[62:63], v[62:63], v[66:67] op_sel_hi:[1,0]
	v_pk_mul_f32 v[60:61], v[60:61], v[66:67] op_sel_hi:[1,0]
	v_pk_mul_f32 v[58:59], v[58:59], v[66:67] op_sel_hi:[1,0]
	v_pk_mul_f32 v[56:57], v[56:57], v[66:67] op_sel_hi:[1,0]
	v_pk_mul_f32 v[50:51], v[50:51], v[66:67] op_sel_hi:[1,0]
	v_pk_mul_f32 v[48:49], v[48:49], v[66:67] op_sel_hi:[1,0]
	v_pk_mul_f32 v[54:55], v[54:55], v[66:67] op_sel_hi:[1,0]
	v_pk_mul_f32 v[52:53], v[52:53], v[66:67] op_sel_hi:[1,0]
	v_max_f32_e32 v60, 0, v60
	v_max_f32_e32 v56, 0, v56
	v_max_f32_e32 v61, 0, v61
	v_max_f32_e32 v57, 0, v57
	v_max_f32_e32 v62, 0, v62
	v_max_f32_e32 v58, 0, v58
	v_max_f32_e32 v63, 0, v63
	v_max_f32_e32 v59, 0, v59
	v_max_f32_e32 v48, 0, v48
	v_max_f32_e32 v49, 0, v49
	v_max_f32_e32 v50, 0, v50
	v_max_f32_e32 v51, 0, v51
	v_max_f32_e32 v52, 0, v52
	v_max_f32_e32 v53, 0, v53
	v_max_f32_e32 v54, 0, v54
	v_max_f32_e32 v55, 0, v55
	v_pk_mul_f32 v[60:61], v[60:61], v[60:61]
	v_pk_mul_f32 v[56:57], v[56:57], v[56:57]
	v_pk_mul_f32 v[62:63], v[62:63], v[62:63]
	v_pk_mul_f32 v[58:59], v[58:59], v[58:59]
	v_pk_mul_f32 v[66:67], v[48:49], v[48:49]
	v_pk_mul_f32 v[68:69], v[50:51], v[50:51]
	v_cvt_pk_bf16_f32 v48, v60, v61
	v_cvt_pk_bf16_f32 v49, v62, v63
	v_cvt_pk_bf16_f32 v50, v56, v57
	v_cvt_pk_bf16_f32 v51, v58, v59
	v_pk_mul_f32 v[52:53], v[52:53], v[52:53]
	v_pk_mul_f32 v[54:55], v[54:55], v[54:55]
	buffer_store_dwordx4 v[48:51], v84, s[12:15], 0 offen sc1
	s_nop 1
	v_cvt_pk_bf16_f32 v48, v52, v53
	v_cvt_pk_bf16_f32 v49, v54, v55
	v_cvt_pk_bf16_f32 v50, v66, v67
	v_cvt_pk_bf16_f32 v51, v68, v69
	buffer_store_dwordx4 v[48:51], v84, s[12:15], 0 offen offset:256 sc1
	s_nop 0
	v_add_u32_e32 v64, 0xa0, v146
	v_ashrrev_i32_e32 v65, 31, v64
	v_lshl_add_u32 v68, v80, 13, v147
	s_waitcnt vmcnt(14)
	v_pk_add_f32 v[48:49], v[198:199], v[200:201]
	v_pk_add_f32 v[50:51], v[202:203], v[204:205]
	v_pk_add_f32 v[52:53], v[206:207], v[208:209]
	v_pk_add_f32 v[54:55], v[210:211], v[212:213]
	v_pk_add_f32 v[48:49], v[48:49], v[50:51]
	v_pk_add_f32 v[52:53], v[52:53], v[54:55]
	v_pk_add_f32 v[48:49], v[48:49], v[52:53]
	v_add_f32_e32 v48, v48, v49
	s_nop 0
	s_nop 0
	v_fmamk_f32 v48, v48, 0x3a800000, v154
	v_mul_f32_e32 v49, 0x4b800000, v48
	v_cmp_gt_f32_e32 vcc, s63, v48
	s_nop 1
	v_cndmask_b32_e32 v48, v48, v49, vcc
	v_rsq_f32_e32 v50, v48
	v_lshlrev_b64 v[48:49], 6, v[64:65]
	v_lshl_add_u64 v[48:49], s[22:23], 0, v[48:49]
	v_mul_f32_e32 v51, 0x45800000, v50
	v_cndmask_b32_e32 v50, v50, v51, vcc
	v_pk_mul_f32 v[46:47], v[46:47], v[50:51] op_sel_hi:[1,0]
	v_pk_mul_f32 v[44:45], v[44:45], v[50:51] op_sel_hi:[1,0]
	v_pk_mul_f32 v[42:43], v[42:43], v[50:51] op_sel_hi:[1,0]
	v_pk_mul_f32 v[40:41], v[40:41], v[50:51] op_sel_hi:[1,0]
	v_pk_mul_f32 v[34:35], v[34:35], v[50:51] op_sel_hi:[1,0]
	v_pk_mul_f32 v[32:33], v[32:33], v[50:51] op_sel_hi:[1,0]
	v_pk_mul_f32 v[38:39], v[38:39], v[50:51] op_sel_hi:[1,0]
	v_pk_mul_f32 v[36:37], v[36:37], v[50:51] op_sel_hi:[1,0]
	v_max_f32_e32 v44, 0, v44
	v_max_f32_e32 v40, 0, v40
	v_max_f32_e32 v45, 0, v45
	v_max_f32_e32 v41, 0, v41
	v_max_f32_e32 v46, 0, v46
	v_max_f32_e32 v42, 0, v42
	v_max_f32_e32 v47, 0, v47
	v_max_f32_e32 v43, 0, v43
	v_max_f32_e32 v32, 0, v32
	v_max_f32_e32 v33, 0, v33
	v_max_f32_e32 v34, 0, v34
	v_max_f32_e32 v35, 0, v35
	v_max_f32_e32 v36, 0, v36
	v_max_f32_e32 v37, 0, v37
	v_max_f32_e32 v38, 0, v38
	v_max_f32_e32 v39, 0, v39
	v_pk_mul_f32 v[44:45], v[44:45], v[44:45]
	v_pk_mul_f32 v[40:41], v[40:41], v[40:41]
	v_pk_mul_f32 v[46:47], v[46:47], v[46:47]
	v_pk_mul_f32 v[42:43], v[42:43], v[42:43]
	v_pk_mul_f32 v[50:51], v[32:33], v[32:33]
	v_pk_mul_f32 v[52:53], v[34:35], v[34:35]
	v_cvt_pk_bf16_f32 v32, v44, v45
	v_cvt_pk_bf16_f32 v33, v46, v47
	v_cvt_pk_bf16_f32 v34, v40, v41
	v_cvt_pk_bf16_f32 v35, v42, v43
	v_pk_mul_f32 v[36:37], v[36:37], v[36:37]
	v_pk_mul_f32 v[38:39], v[38:39], v[38:39]
	buffer_store_dwordx4 v[32:35], v68, s[12:15], 0 offen sc1
	s_nop 1
	v_cvt_pk_bf16_f32 v32, v36, v37
	v_cvt_pk_bf16_f32 v33, v38, v39
	v_cvt_pk_bf16_f32 v34, v50, v51
	v_cvt_pk_bf16_f32 v35, v52, v53
	buffer_store_dwordx4 v[32:35], v68, s[12:15], 0 offen offset:256 sc1
	s_nop 0
	v_add_u32_e32 v48, 0xb0, v146
	v_ashrrev_i32_e32 v49, 31, v48
	v_lshl_add_u32 v52, v64, 13, v147
	s_waitcnt vmcnt(10)
	v_pk_add_f32 v[32:33], v[214:215], v[216:217]
	v_pk_add_f32 v[34:35], v[218:219], v[220:221]
	v_pk_add_f32 v[36:37], v[222:223], v[224:225]
	v_pk_add_f32 v[38:39], v[232:233], v[234:235]
	v_pk_add_f32 v[32:33], v[32:33], v[34:35]
	v_pk_add_f32 v[36:37], v[36:37], v[38:39]
	v_pk_add_f32 v[32:33], v[32:33], v[36:37]
	v_add_f32_e32 v32, v32, v33
	s_nop 0
	s_nop 0
	v_fmamk_f32 v32, v32, 0x3a800000, v154
	v_mul_f32_e32 v33, 0x4b800000, v32
	v_cmp_gt_f32_e32 vcc, s63, v32
	s_nop 1
	v_cndmask_b32_e32 v32, v32, v33, vcc
	v_rsq_f32_e32 v34, v32
	v_lshlrev_b64 v[32:33], 6, v[48:49]
	v_lshl_add_u64 v[32:33], s[22:23], 0, v[32:33]
	v_mul_f32_e32 v35, 0x45800000, v34
	v_cndmask_b32_e32 v34, v34, v35, vcc
	v_pk_mul_f32 v[30:31], v[30:31], v[34:35] op_sel_hi:[1,0]
	v_pk_mul_f32 v[28:29], v[28:29], v[34:35] op_sel_hi:[1,0]
	v_pk_mul_f32 v[26:27], v[26:27], v[34:35] op_sel_hi:[1,0]
	v_pk_mul_f32 v[24:25], v[24:25], v[34:35] op_sel_hi:[1,0]
	v_pk_mul_f32 v[18:19], v[18:19], v[34:35] op_sel_hi:[1,0]
	v_pk_mul_f32 v[16:17], v[16:17], v[34:35] op_sel_hi:[1,0]
	v_pk_mul_f32 v[22:23], v[22:23], v[34:35] op_sel_hi:[1,0]
	v_pk_mul_f32 v[20:21], v[20:21], v[34:35] op_sel_hi:[1,0]
	v_max_f32_e32 v28, 0, v28
	v_max_f32_e32 v24, 0, v24
	v_max_f32_e32 v29, 0, v29
	v_max_f32_e32 v25, 0, v25
	v_max_f32_e32 v30, 0, v30
	v_max_f32_e32 v26, 0, v26
	v_max_f32_e32 v31, 0, v31
	v_max_f32_e32 v27, 0, v27
	v_max_f32_e32 v16, 0, v16
	v_max_f32_e32 v17, 0, v17
	v_max_f32_e32 v18, 0, v18
	v_max_f32_e32 v19, 0, v19
	v_max_f32_e32 v20, 0, v20
	v_max_f32_e32 v21, 0, v21
	v_max_f32_e32 v22, 0, v22
	v_max_f32_e32 v23, 0, v23
	v_pk_mul_f32 v[28:29], v[28:29], v[28:29]
	v_pk_mul_f32 v[24:25], v[24:25], v[24:25]
	v_pk_mul_f32 v[30:31], v[30:31], v[30:31]
	v_pk_mul_f32 v[26:27], v[26:27], v[26:27]
	v_pk_mul_f32 v[34:35], v[16:17], v[16:17]
	v_pk_mul_f32 v[36:37], v[18:19], v[18:19]
	v_cvt_pk_bf16_f32 v16, v28, v29
	v_cvt_pk_bf16_f32 v17, v30, v31
	v_cvt_pk_bf16_f32 v18, v24, v25
	v_cvt_pk_bf16_f32 v19, v26, v27
	v_pk_mul_f32 v[20:21], v[20:21], v[20:21]
	v_pk_mul_f32 v[22:23], v[22:23], v[22:23]
	buffer_store_dwordx4 v[16:19], v52, s[12:15], 0 offen sc1
	s_nop 1
	v_cvt_pk_bf16_f32 v16, v20, v21
	v_cvt_pk_bf16_f32 v17, v22, v23
	v_cvt_pk_bf16_f32 v18, v34, v35
	v_cvt_pk_bf16_f32 v19, v36, v37
	buffer_store_dwordx4 v[16:19], v52, s[12:15], 0 offen offset:256 sc1
	s_nop 0
	s_waitcnt vmcnt(6)
	v_pk_add_f32 v[16:17], v[236:237], v[238:239]
	v_pk_add_f32 v[18:19], v[240:241], v[242:243]
	v_pk_add_f32 v[20:21], v[244:245], v[246:247]
	v_pk_add_f32 v[22:23], v[248:249], v[250:251]
	v_pk_add_f32 v[16:17], v[16:17], v[18:19]
	v_pk_add_f32 v[20:21], v[20:21], v[22:23]
	v_pk_add_f32 v[16:17], v[16:17], v[20:21]
	v_add_f32_e32 v16, v16, v17
	s_nop 0
	s_nop 0
	v_fmamk_f32 v16, v16, 0x3a800000, v154
	v_mul_f32_e32 v17, 0x4b800000, v16
	v_cmp_gt_f32_e32 vcc, s63, v16
	s_nop 1
	v_cndmask_b32_e32 v16, v16, v17, vcc
	v_rsq_f32_e32 v16, v16
	v_lshl_add_u32 v17, v48, 13, v147
	v_mul_f32_e32 v18, 0x45800000, v16
	v_cndmask_b32_e32 v16, v16, v18, vcc
	v_pk_mul_f32 v[14:15], v[14:15], v[16:17] op_sel_hi:[1,0]
	v_pk_mul_f32 v[12:13], v[12:13], v[16:17] op_sel_hi:[1,0]
	v_pk_mul_f32 v[10:11], v[10:11], v[16:17] op_sel_hi:[1,0]
	v_pk_mul_f32 v[8:9], v[8:9], v[16:17] op_sel_hi:[1,0]
	v_pk_mul_f32 v[2:3], v[2:3], v[16:17] op_sel_hi:[1,0]
	v_pk_mul_f32 v[0:1], v[0:1], v[16:17] op_sel_hi:[1,0]
	v_pk_mul_f32 v[6:7], v[6:7], v[16:17] op_sel_hi:[1,0]
	v_pk_mul_f32 v[4:5], v[4:5], v[16:17] op_sel_hi:[1,0]
	v_max_f32_e32 v12, 0, v12
	v_max_f32_e32 v8, 0, v8
	v_max_f32_e32 v13, 0, v13
	v_max_f32_e32 v9, 0, v9
	v_max_f32_e32 v14, 0, v14
	v_max_f32_e32 v10, 0, v10
	v_max_f32_e32 v15, 0, v15
	v_max_f32_e32 v11, 0, v11
	v_max_f32_e32 v0, 0, v0
	v_max_f32_e32 v1, 0, v1
	v_max_f32_e32 v2, 0, v2
	v_max_f32_e32 v3, 0, v3
	v_max_f32_e32 v4, 0, v4
	v_max_f32_e32 v5, 0, v5
	v_max_f32_e32 v6, 0, v6
	v_max_f32_e32 v7, 0, v7
	v_pk_mul_f32 v[12:13], v[12:13], v[12:13]
	v_pk_mul_f32 v[8:9], v[8:9], v[8:9]
	v_pk_mul_f32 v[14:15], v[14:15], v[14:15]
	v_pk_mul_f32 v[10:11], v[10:11], v[10:11]
	v_mul_f32_e32 v16, v0, v0
	v_mul_f32_e32 v18, v1, v1
	v_mul_f32_e32 v19, v2, v2
	v_mul_f32_e32 v20, v3, v3
	v_cvt_pk_bf16_f32 v0, v12, v13
	v_cvt_pk_bf16_f32 v1, v14, v15
	v_cvt_pk_bf16_f32 v2, v8, v9
	v_cvt_pk_bf16_f32 v3, v10, v11
	v_pk_mul_f32 v[4:5], v[4:5], v[4:5]
	v_pk_mul_f32 v[6:7], v[6:7], v[6:7]
	buffer_store_dwordx4 v[0:3], v17, s[12:15], 0 offen sc1
	s_nop 1
	v_cvt_pk_bf16_f32 v0, v4, v5
	v_cvt_pk_bf16_f32 v1, v6, v7
	v_cvt_pk_bf16_f32 v2, v16, v18
	v_cvt_pk_bf16_f32 v3, v19, v20
	buffer_store_dwordx4 v[0:3], v17, s[12:15], 0 offen offset:256 sc1
	s_waitcnt vmcnt(0)
	s_and_saveexec_b64 s[36:37], s[6:7]
	s_cbranch_execz .LBB0_2091
	s_mov_b64 s[38:39], exec
	v_mbcnt_lo_u32_b32 v0, s38, 0
	v_mbcnt_hi_u32_b32 v0, s39, v0
	v_cmp_eq_u32_e32 vcc, 0, v0
	s_and_b64 s[40:41], exec, vcc
	s_mov_b64 exec, s[40:41]
	s_cbranch_execz .LBB0_2091
	s_lshl_b32 s40, s68, 6
	s_ashr_i32 s41, s40, 31
	s_lshl_b64 s[40:41], s[40:41], 2
	s_add_u32 s40, s66, s40
	s_addc_u32 s41, s67, s41
	s_bcnt1_i32_b64 s25, s[38:39]
	v_mov_b32_e32 v0, s25
	global_atomic_add v131, v0, s[40:41]
	s_branch .LBB0_2091

.LBB0_2122:
	ds_read_b128 v[150:153], v143
	ds_read_b128 v[154:157], v143 offset:1024
	ds_read_b128 v[158:161], v143 offset:2048
	ds_read_b128 v[162:165], v143 offset:3072
	s_add_u32 s36, s34, 0xfffc0080
	s_addc_u32 s37, s35, -1
	s_cmp_eq_u32 s71, 12
	s_cselect_b32 s39, s21, s37
	s_cselect_b32 s38, s44, s36
	s_cselect_b32 s37, s29, s70
	s_cselect_b32 s36, s45, s69
	v_lshl_add_u64 v[202:203], s[34:35], 0, v[138:139]
	s_add_i32 m0, s53, 0xc000
	ds_read_b128 v[170:173], v146
	ds_read_b128 v[174:177], v146 offset:1024
	ds_read_b128 v[178:181], v146 offset:2048
	ds_read_b128 v[182:185], v146 offset:3072
	ds_read_b128 v[186:189], v146 offset:4096
	ds_read_b128 v[190:193], v146 offset:5120
	ds_read_b128 v[194:197], v146 offset:6144
	ds_read_b128 v[198:201], v146 offset:7168
	global_load_lds_dwordx4 v[202:203], off
	v_lshl_add_u64 v[202:203], s[34:35], 0, v[136:137]
	s_add_i32 m0, s53, 0xe000
	s_nop 0
	global_load_lds_dwordx4 v[202:203], off
	s_waitcnt lgkmcnt(8)
	s_barrier
	s_waitcnt lgkmcnt(0)
	s_setprio 1
	s_waitcnt lgkmcnt(0)
	v_mfma_f32_16x16x32_bf16 v[124:127], v[150:153], v[170:173], v[124:127]
	v_mfma_f32_16x16x32_bf16 v[120:123], v[158:161], v[170:173], v[120:123]
	v_mfma_f32_16x16x32_bf16 v[108:111], v[150:153], v[178:181], v[108:111]
	v_mfma_f32_16x16x32_bf16 v[104:107], v[158:161], v[178:181], v[104:107]
	v_mfma_f32_16x16x32_bf16 v[92:95], v[150:153], v[186:189], v[92:95]
	v_mfma_f32_16x16x32_bf16 v[88:91], v[158:161], v[186:189], v[88:91]
	v_mfma_f32_16x16x32_bf16 v[76:79], v[150:153], v[194:197], v[76:79]
	v_mfma_f32_16x16x32_bf16 v[72:75], v[158:161], v[194:197], v[72:75]
	v_mfma_f32_16x16x32_bf16 v[124:127], v[154:157], v[174:177], v[124:127]
	v_mfma_f32_16x16x32_bf16 v[120:123], v[162:165], v[174:177], v[120:123]
	v_mfma_f32_16x16x32_bf16 v[108:111], v[154:157], v[182:185], v[108:111]
	v_mfma_f32_16x16x32_bf16 v[104:107], v[162:165], v[182:185], v[104:107]
	v_mfma_f32_16x16x32_bf16 v[92:95], v[154:157], v[190:193], v[92:95]
	v_mfma_f32_16x16x32_bf16 v[88:91], v[162:165], v[190:193], v[88:91]
	v_mfma_f32_16x16x32_bf16 v[76:79], v[154:157], v[198:201], v[76:79]
	v_mfma_f32_16x16x32_bf16 v[72:75], v[162:165], v[198:201], v[72:75]
	s_setprio 0
	s_barrier
	s_add_i32 s72, s61, s52
	v_lshl_add_u64 v[218:219], s[36:37], 0, v[130:131]
	s_mov_b32 m0, s72
	ds_read_b128 v[202:205], v147
	ds_read_b128 v[206:209], v147 offset:1024
	ds_read_b128 v[210:213], v147 offset:2048
	ds_read_b128 v[214:217], v147 offset:3072
	global_load_lds_dwordx4 v[218:219], off
	v_lshl_add_u64 v[220:221], s[36:37], 0, v[134:135]
	s_add_i32 m0, s72, 0x2000
	s_nop 0
	global_load_lds_dwordx4 v[220:221], off
	s_barrier
	s_waitcnt lgkmcnt(0)
	s_setprio 1
	s_waitcnt lgkmcnt(0)
	v_mfma_f32_16x16x32_bf16 v[116:119], v[202:205], v[170:173], v[116:119]
	v_mfma_f32_16x16x32_bf16 v[112:115], v[210:213], v[170:173], v[112:115]
	v_mfma_f32_16x16x32_bf16 v[100:103], v[202:205], v[178:181], v[100:103]
	v_mfma_f32_16x16x32_bf16 v[96:99], v[210:213], v[178:181], v[96:99]
	v_mfma_f32_16x16x32_bf16 v[84:87], v[202:205], v[186:189], v[84:87]
	v_mfma_f32_16x16x32_bf16 v[80:83], v[210:213], v[186:189], v[80:83]
	v_mfma_f32_16x16x32_bf16 v[68:71], v[202:205], v[194:197], v[68:71]
	v_mfma_f32_16x16x32_bf16 v[64:67], v[210:213], v[194:197], v[64:67]
	v_mfma_f32_16x16x32_bf16 v[116:119], v[206:209], v[174:177], v[116:119]
	v_mfma_f32_16x16x32_bf16 v[112:115], v[214:217], v[174:177], v[112:115]
	v_mfma_f32_16x16x32_bf16 v[100:103], v[206:209], v[182:185], v[100:103]
	v_mfma_f32_16x16x32_bf16 v[96:99], v[214:217], v[182:185], v[96:99]
	v_mfma_f32_16x16x32_bf16 v[84:87], v[206:209], v[190:193], v[84:87]
	v_mfma_f32_16x16x32_bf16 v[80:83], v[214:217], v[190:193], v[80:83]
	v_mfma_f32_16x16x32_bf16 v[68:71], v[206:209], v[198:201], v[68:71]
	v_mfma_f32_16x16x32_bf16 v[64:67], v[214:217], v[198:201], v[64:67]
	s_setprio 0
	s_mov_b32 m0, s53
	v_lshl_add_u64 v[222:223], s[38:39], 0, v[128:129]
	s_barrier
	ds_read_b128 v[170:173], v146 offset:16384
	ds_read_b128 v[174:177], v146 offset:17408
	ds_read_b128 v[178:181], v146 offset:18432
	ds_read_b128 v[182:185], v146 offset:19456
	ds_read_b128 v[186:189], v146 offset:20480
	ds_read_b128 v[190:193], v146 offset:21504
	ds_read_b128 v[194:197], v146 offset:22528
	ds_read_b128 v[198:201], v146 offset:23552
	global_load_lds_dwordx4 v[222:223], off
	v_lshl_add_u64 v[224:225], s[38:39], 0, v[132:133]
	s_mov_b32 m0, s54
	s_nop 0
	global_load_lds_dwordx4 v[224:225], off
	s_barrier
	s_waitcnt lgkmcnt(0)
	s_setprio 1
	s_waitcnt lgkmcnt(0)
	v_mfma_f32_16x16x32_bf16 v[60:63], v[150:153], v[170:173], v[60:63]
	v_mfma_f32_16x16x32_bf16 v[56:59], v[158:161], v[170:173], v[56:59]
	v_mfma_f32_16x16x32_bf16 v[44:47], v[150:153], v[178:181], v[44:47]
	v_mfma_f32_16x16x32_bf16 v[40:43], v[158:161], v[178:181], v[40:43]
	v_mfma_f32_16x16x32_bf16 v[28:31], v[150:153], v[186:189], v[28:31]
	v_mfma_f32_16x16x32_bf16 v[24:27], v[158:161], v[186:189], v[24:27]
	v_mfma_f32_16x16x32_bf16 v[12:15], v[150:153], v[194:197], v[12:15]
	v_mfma_f32_16x16x32_bf16 v[8:11], v[158:161], v[194:197], v[8:11]
	v_mfma_f32_16x16x32_bf16 v[60:63], v[154:157], v[174:177], v[60:63]
	v_mfma_f32_16x16x32_bf16 v[56:59], v[162:165], v[174:177], v[56:59]
	v_mfma_f32_16x16x32_bf16 v[44:47], v[154:157], v[182:185], v[44:47]
	v_mfma_f32_16x16x32_bf16 v[40:43], v[162:165], v[182:185], v[40:43]
	v_mfma_f32_16x16x32_bf16 v[28:31], v[154:157], v[190:193], v[28:31]
	v_mfma_f32_16x16x32_bf16 v[24:27], v[162:165], v[190:193], v[24:27]
	v_mfma_f32_16x16x32_bf16 v[12:15], v[154:157], v[198:201], v[12:15]
	v_mfma_f32_16x16x32_bf16 v[8:11], v[162:165], v[198:201], v[8:11]
	s_setprio 0
	s_barrier
	s_add_u32 s72, s36, 0x40000
	s_addc_u32 s73, s37, 0
	s_add_i32 s74, s62, s52
	v_lshl_add_u64 v[150:151], s[72:73], 0, v[130:131]
	s_mov_b32 m0, s74
	s_nop 0
	global_load_lds_dwordx4 v[150:151], off
	v_lshl_add_u64 v[150:151], s[72:73], 0, v[134:135]
	s_add_i32 m0, s74, 0x2000
	s_nop 0
	global_load_lds_dwordx4 v[150:151], off
	s_waitcnt vmcnt(6)
	s_barrier
	s_setprio 1
	v_mfma_f32_16x16x32_bf16 v[52:55], v[202:205], v[170:173], v[52:55]
	v_mfma_f32_16x16x32_bf16 v[48:51], v[210:213], v[170:173], v[48:51]
	v_mfma_f32_16x16x32_bf16 v[36:39], v[202:205], v[178:181], v[36:39]
	v_mfma_f32_16x16x32_bf16 v[32:35], v[210:213], v[178:181], v[32:35]
	v_mfma_f32_16x16x32_bf16 v[20:23], v[202:205], v[186:189], v[20:23]
	v_mfma_f32_16x16x32_bf16 v[16:19], v[210:213], v[186:189], v[16:19]
	v_mfma_f32_16x16x32_bf16 v[4:7], v[202:205], v[194:197], v[4:7]
	v_mfma_f32_16x16x32_bf16 v[0:3], v[210:213], v[194:197], v[0:3]
	v_mfma_f32_16x16x32_bf16 v[52:55], v[206:209], v[174:177], v[52:55]
	v_mfma_f32_16x16x32_bf16 v[48:51], v[214:217], v[174:177], v[48:51]
	v_mfma_f32_16x16x32_bf16 v[36:39], v[206:209], v[182:185], v[36:39]
	v_mfma_f32_16x16x32_bf16 v[32:35], v[214:217], v[182:185], v[32:35]
	v_mfma_f32_16x16x32_bf16 v[20:23], v[206:209], v[190:193], v[20:23]
	v_mfma_f32_16x16x32_bf16 v[16:19], v[214:217], v[190:193], v[16:19]
	v_mfma_f32_16x16x32_bf16 v[4:7], v[206:209], v[198:201], v[4:7]
	v_mfma_f32_16x16x32_bf16 v[0:3], v[214:217], v[198:201], v[0:3]
	s_setprio 0
	s_add_i32 s72, 0, 0x18000
	v_add_u32_e32 v149, s72, v141
	s_barrier
	ds_read_b128 v[150:153], v149
	ds_read_b128 v[154:157], v149 offset:1024
	ds_read_b128 v[158:161], v149 offset:2048
	ds_read_b128 v[162:165], v149 offset:3072
	s_add_u32 s38, s38, 0x40000
	s_addc_u32 s39, s39, 0
	s_mov_b32 m0, s55
	v_lshl_add_u64 v[202:203], s[38:39], 0, v[128:129]
	ds_read_b128 v[170:173], v146 offset:32768
	ds_read_b128 v[174:177], v146 offset:33792
	ds_read_b128 v[178:181], v146 offset:34816
	ds_read_b128 v[182:185], v146 offset:35840
	ds_read_b128 v[186:189], v146 offset:36864
	ds_read_b128 v[190:193], v146 offset:37888
	ds_read_b128 v[194:197], v146 offset:38912
	ds_read_b128 v[198:201], v146 offset:39936
	global_load_lds_dwordx4 v[202:203], off
	v_lshl_add_u64 v[202:203], s[38:39], 0, v[132:133]
	s_mov_b32 m0, s56
	s_nop 0
	global_load_lds_dwordx4 v[202:203], off
	s_waitcnt lgkmcnt(8)
	s_barrier
	s_waitcnt lgkmcnt(0)
	s_setprio 1
	s_waitcnt lgkmcnt(0)
	v_mfma_f32_16x16x32_bf16 v[124:127], v[150:153], v[170:173], v[124:127]
	v_mfma_f32_16x16x32_bf16 v[120:123], v[158:161], v[170:173], v[120:123]
	v_mfma_f32_16x16x32_bf16 v[108:111], v[150:153], v[178:181], v[108:111]
	v_mfma_f32_16x16x32_bf16 v[104:107], v[158:161], v[178:181], v[104:107]
	v_mfma_f32_16x16x32_bf16 v[92:95], v[150:153], v[186:189], v[92:95]
	v_mfma_f32_16x16x32_bf16 v[88:91], v[158:161], v[186:189], v[88:91]
	v_mfma_f32_16x16x32_bf16 v[76:79], v[150:153], v[194:197], v[76:79]
	v_mfma_f32_16x16x32_bf16 v[72:75], v[158:161], v[194:197], v[72:75]
	v_mfma_f32_16x16x32_bf16 v[124:127], v[154:157], v[174:177], v[124:127]
	v_mfma_f32_16x16x32_bf16 v[120:123], v[162:165], v[174:177], v[120:123]
	v_mfma_f32_16x16x32_bf16 v[108:111], v[154:157], v[182:185], v[108:111]
	v_mfma_f32_16x16x32_bf16 v[104:107], v[162:165], v[182:185], v[104:107]
	v_mfma_f32_16x16x32_bf16 v[92:95], v[154:157], v[190:193], v[92:95]
	v_mfma_f32_16x16x32_bf16 v[88:91], v[162:165], v[190:193], v[88:91]
	v_mfma_f32_16x16x32_bf16 v[76:79], v[154:157], v[198:201], v[76:79]
	v_mfma_f32_16x16x32_bf16 v[72:75], v[162:165], v[198:201], v[72:75]
	s_setprio 0
	s_barrier
	s_add_i32 s38, 0, 0x1c000
	s_add_i32 s39, s72, s52
	v_add_u32_e32 v149, s38, v141
	v_lshl_add_u64 v[218:219], v[218:219], 0, s[22:23]
	s_mov_b32 m0, s39
	ds_read_b128 v[202:205], v149
	ds_read_b128 v[206:209], v149 offset:1024
	ds_read_b128 v[210:213], v149 offset:2048
	ds_read_b128 v[214:217], v149 offset:3072
	global_load_lds_dwordx4 v[218:219], off
	v_lshl_add_u64 v[218:219], v[220:221], 0, s[22:23]
	s_add_i32 m0, s39, 0x2000
	s_nop 0
	global_load_lds_dwordx4 v[218:219], off
	s_barrier
	s_waitcnt lgkmcnt(0)
	s_setprio 1
	s_waitcnt lgkmcnt(0)
	v_mfma_f32_16x16x32_bf16 v[116:119], v[202:205], v[170:173], v[116:119]
	v_mfma_f32_16x16x32_bf16 v[112:115], v[210:213], v[170:173], v[112:115]
	v_mfma_f32_16x16x32_bf16 v[100:103], v[202:205], v[178:181], v[100:103]
	v_mfma_f32_16x16x32_bf16 v[96:99], v[210:213], v[178:181], v[96:99]
	v_mfma_f32_16x16x32_bf16 v[84:87], v[202:205], v[186:189], v[84:87]
	v_mfma_f32_16x16x32_bf16 v[80:83], v[210:213], v[186:189], v[80:83]
	v_mfma_f32_16x16x32_bf16 v[68:71], v[202:205], v[194:197], v[68:71]
	v_mfma_f32_16x16x32_bf16 v[64:67], v[210:213], v[194:197], v[64:67]
	v_mfma_f32_16x16x32_bf16 v[116:119], v[206:209], v[174:177], v[116:119]
	v_mfma_f32_16x16x32_bf16 v[112:115], v[214:217], v[174:177], v[112:115]
	v_mfma_f32_16x16x32_bf16 v[100:103], v[206:209], v[182:185], v[100:103]
	v_mfma_f32_16x16x32_bf16 v[96:99], v[214:217], v[182:185], v[96:99]
	v_mfma_f32_16x16x32_bf16 v[84:87], v[206:209], v[190:193], v[84:87]
	v_mfma_f32_16x16x32_bf16 v[80:83], v[214:217], v[190:193], v[80:83]
	v_mfma_f32_16x16x32_bf16 v[68:71], v[206:209], v[198:201], v[68:71]
	v_mfma_f32_16x16x32_bf16 v[64:67], v[214:217], v[198:201], v[64:67]
	s_setprio 0
	s_mov_b32 m0, s58
	v_lshl_add_u64 v[218:219], v[222:223], 0, s[22:23]
	s_barrier
	ds_read_b128 v[170:173], v146 offset:49152
	ds_read_b128 v[174:177], v146 offset:50176
	ds_read_b128 v[178:181], v146 offset:51200
	ds_read_b128 v[182:185], v146 offset:52224
	ds_read_b128 v[186:189], v146 offset:53248
	ds_read_b128 v[190:193], v146 offset:54272
	ds_read_b128 v[194:197], v146 offset:55296
	ds_read_b128 v[198:201], v146 offset:56320
	global_load_lds_dwordx4 v[218:219], off
	v_lshl_add_u64 v[218:219], v[224:225], 0, s[22:23]
	s_mov_b32 m0, s59
	s_nop 0
	global_load_lds_dwordx4 v[218:219], off
	s_barrier
	s_waitcnt lgkmcnt(0)
	s_setprio 1
	s_waitcnt lgkmcnt(0)
	v_mfma_f32_16x16x32_bf16 v[60:63], v[150:153], v[170:173], v[60:63]
	v_mfma_f32_16x16x32_bf16 v[56:59], v[158:161], v[170:173], v[56:59]
	v_mfma_f32_16x16x32_bf16 v[44:47], v[150:153], v[178:181], v[44:47]
	v_mfma_f32_16x16x32_bf16 v[40:43], v[158:161], v[178:181], v[40:43]
	v_mfma_f32_16x16x32_bf16 v[28:31], v[150:153], v[186:189], v[28:31]
	v_mfma_f32_16x16x32_bf16 v[24:27], v[158:161], v[186:189], v[24:27]
	v_mfma_f32_16x16x32_bf16 v[12:15], v[150:153], v[194:197], v[12:15]
	v_mfma_f32_16x16x32_bf16 v[8:11], v[158:161], v[194:197], v[8:11]
	v_mfma_f32_16x16x32_bf16 v[60:63], v[154:157], v[174:177], v[60:63]
	v_mfma_f32_16x16x32_bf16 v[56:59], v[162:165], v[174:177], v[56:59]
	v_mfma_f32_16x16x32_bf16 v[44:47], v[154:157], v[182:185], v[44:47]
	v_mfma_f32_16x16x32_bf16 v[40:43], v[162:165], v[182:185], v[40:43]
	v_mfma_f32_16x16x32_bf16 v[28:31], v[154:157], v[190:193], v[28:31]
	v_mfma_f32_16x16x32_bf16 v[24:27], v[162:165], v[190:193], v[24:27]
	v_mfma_f32_16x16x32_bf16 v[12:15], v[154:157], v[198:201], v[12:15]
	v_mfma_f32_16x16x32_bf16 v[8:11], v[162:165], v[198:201], v[8:11]
	s_setprio 0
	s_barrier
	s_add_u32 s36, s36, 0x40080
	s_addc_u32 s37, s37, 0
	s_add_i32 s38, s38, s52
	v_lshl_add_u64 v[150:151], s[36:37], 0, v[130:131]
	s_mov_b32 m0, s38
	s_nop 0
	global_load_lds_dwordx4 v[150:151], off
	v_lshl_add_u64 v[150:151], s[36:37], 0, v[134:135]
	s_add_i32 m0, s38, 0x2000
	s_nop 0
	global_load_lds_dwordx4 v[150:151], off
	s_waitcnt vmcnt(6)
	s_barrier
	s_setprio 1
	v_mfma_f32_16x16x32_bf16 v[52:55], v[202:205], v[170:173], v[52:55]
	v_mfma_f32_16x16x32_bf16 v[48:51], v[210:213], v[170:173], v[48:51]
	v_mfma_f32_16x16x32_bf16 v[36:39], v[202:205], v[178:181], v[36:39]
	v_mfma_f32_16x16x32_bf16 v[32:35], v[210:213], v[178:181], v[32:35]
	v_mfma_f32_16x16x32_bf16 v[20:23], v[202:205], v[186:189], v[20:23]
	v_mfma_f32_16x16x32_bf16 v[16:19], v[210:213], v[186:189], v[16:19]
	v_mfma_f32_16x16x32_bf16 v[4:7], v[202:205], v[194:197], v[4:7]
	v_mfma_f32_16x16x32_bf16 v[0:3], v[210:213], v[194:197], v[0:3]
	v_mfma_f32_16x16x32_bf16 v[52:55], v[206:209], v[174:177], v[52:55]
	v_mfma_f32_16x16x32_bf16 v[48:51], v[214:217], v[174:177], v[48:51]
	v_mfma_f32_16x16x32_bf16 v[36:39], v[206:209], v[182:185], v[36:39]
	v_mfma_f32_16x16x32_bf16 v[32:35], v[214:217], v[182:185], v[32:35]
	v_mfma_f32_16x16x32_bf16 v[20:23], v[206:209], v[190:193], v[20:23]
	v_mfma_f32_16x16x32_bf16 v[16:19], v[214:217], v[190:193], v[16:19]
	v_mfma_f32_16x16x32_bf16 v[4:7], v[206:209], v[198:201], v[4:7]
	v_mfma_f32_16x16x32_bf16 v[0:3], v[214:217], v[198:201], v[0:3]
	s_setprio 0
	s_add_i32 s71, s71, 2
	s_add_u32 s69, s69, 0x100
	s_addc_u32 s70, s70, 0
	s_add_u32 s34, s34, 0x100
	s_addc_u32 s35, s35, 0
	s_cmp_gt_u32 s71, 13
	s_barrier
	s_cbranch_scc0 .LBB0_2122
	v_lshl_add_u32 v150, s68, 8, v140
	v_add_u32_e32 v164, 0x4000, v150
	v_ashrrev_i32_e32 v165, 31, v164
	v_lshlrev_b64 v[152:153], 6, v[164:165]
	v_lshl_add_u64 v[170:171], s[14:15], 0, v[152:153]
	v_subrev_u32_e32 v176, s14, v170
	v_add_u32_e32 v177, 0x0, v176
	global_load_dwordx4 v[178:181], v177, s[14:15]
	v_add_u32_e32 v177, 0x10, v176
	global_load_dwordx4 v[182:185], v177, s[14:15]
	v_add_u32_e32 v177, 0x20, v176
	global_load_dwordx4 v[186:189], v177, s[14:15]
	v_add_u32_e32 v177, 0x30, v176
	global_load_dwordx4 v[190:193], v177, s[14:15]
	v_add_u32_e32 v177, 0x400, v176
	global_load_dwordx4 v[194:197], v177, s[14:15]
	v_add_u32_e32 v177, 0x410, v176
	global_load_dwordx4 v[198:201], v177, s[14:15]
	v_add_u32_e32 v177, 0x420, v176
	global_load_dwordx4 v[202:205], v177, s[14:15]
	v_add_u32_e32 v177, 0x430, v176
	global_load_dwordx4 v[206:209], v177, s[14:15]
	v_add_u32_e32 v177, 0x800, v176
	global_load_dwordx4 v[210:213], v177, s[14:15]
	v_add_u32_e32 v177, 0x810, v176
	global_load_dwordx4 v[214:217], v177, s[14:15]
	v_add_u32_e32 v177, 0x820, v176
	global_load_dwordx4 v[232:235], v177, s[14:15]
	v_add_u32_e32 v177, 0x830, v176
	global_load_dwordx4 v[236:239], v177, s[14:15]
	v_add_u32_e32 v177, 0xc00, v176
	global_load_dwordx4 v[240:243], v177, s[14:15]
	v_add_u32_e32 v177, 0xc10, v176
	global_load_dwordx4 v[244:247], v177, s[14:15]
	v_add_u32_e32 v177, 0xc20, v176
	global_load_dwordx4 v[248:251], v177, s[14:15]
	v_add_u32_e32 v177, 0xc30, v176
	global_load_dwordx4 v[252:255], v177, s[14:15]
	s_nop 0
	v_lshl_or_b32 v149, s33, 9, v142
	v_lshl_add_u32 v151, v164, 13, v149
	v_add_u32_e32 v174, 0x4010, v150
	v_ashrrev_i32_e32 v175, 31, v174
	s_waitcnt vmcnt(12)
	v_pk_add_f32 v[152:153], v[178:179], v[180:181]
	v_pk_add_f32 v[154:155], v[182:183], v[184:185]
	v_pk_add_f32 v[156:157], v[186:187], v[188:189]
	v_pk_add_f32 v[158:159], v[190:191], v[192:193]
	v_pk_add_f32 v[152:153], v[152:153], v[154:155]
	v_pk_add_f32 v[156:157], v[156:157], v[158:159]
	v_pk_add_f32 v[152:153], v[152:153], v[156:157]
	v_add_f32_e32 v152, v152, v153
	s_nop 0
	s_nop 0
	v_fmamk_f32 v152, v152, 0x3a800000, v148
	v_mul_f32_e32 v153, 0x4b800000, v152
	v_cmp_gt_f32_e32 vcc, s63, v152
	s_nop 1
	v_cndmask_b32_e32 v152, v152, v153, vcc
	v_rsq_f32_e32 v154, v152
	v_lshlrev_b64 v[152:153], 6, v[174:175]
	v_lshl_add_u64 v[152:153], s[14:15], 0, v[152:153]
	v_mul_f32_e32 v155, 0x45800000, v154
	v_cndmask_b32_e32 v154, v154, v155, vcc
	v_pk_mul_f32 v[126:127], v[126:127], v[154:155] op_sel_hi:[1,0]
	v_pk_mul_f32 v[124:125], v[124:125], v[154:155] op_sel_hi:[1,0]
	v_pk_mul_f32 v[122:123], v[122:123], v[154:155] op_sel_hi:[1,0]
	v_pk_mul_f32 v[120:121], v[120:121], v[154:155] op_sel_hi:[1,0]
	v_pk_mul_f32 v[114:115], v[114:115], v[154:155] op_sel_hi:[1,0]
	v_pk_mul_f32 v[112:113], v[112:113], v[154:155] op_sel_hi:[1,0]
	v_pk_mul_f32 v[118:119], v[118:119], v[154:155] op_sel_hi:[1,0]
	v_pk_mul_f32 v[116:117], v[116:117], v[154:155] op_sel_hi:[1,0]
	v_max_f32_e32 v124, 0, v124
	v_max_f32_e32 v120, 0, v120
	v_max_f32_e32 v125, 0, v125
	v_max_f32_e32 v121, 0, v121
	v_max_f32_e32 v126, 0, v126
	v_max_f32_e32 v122, 0, v122
	v_max_f32_e32 v127, 0, v127
	v_max_f32_e32 v123, 0, v123
	v_max_f32_e32 v112, 0, v112
	v_max_f32_e32 v113, 0, v113
	v_max_f32_e32 v114, 0, v114
	v_max_f32_e32 v115, 0, v115
	v_max_f32_e32 v116, 0, v116
	v_max_f32_e32 v117, 0, v117
	v_max_f32_e32 v118, 0, v118
	v_max_f32_e32 v119, 0, v119
	v_pk_mul_f32 v[124:125], v[124:125], v[124:125]
	v_pk_mul_f32 v[120:121], v[120:121], v[120:121]
	v_pk_mul_f32 v[126:127], v[126:127], v[126:127]
	v_pk_mul_f32 v[122:123], v[122:123], v[122:123]
	v_pk_mul_f32 v[154:155], v[112:113], v[112:113]
	v_pk_mul_f32 v[156:157], v[114:115], v[114:115]
	v_cvt_pk_bf16_f32 v112, v124, v125
	v_cvt_pk_bf16_f32 v113, v126, v127
	v_cvt_pk_bf16_f32 v114, v120, v121
	v_cvt_pk_bf16_f32 v115, v122, v123
	v_pk_mul_f32 v[116:117], v[116:117], v[116:117]
	v_pk_mul_f32 v[118:119], v[118:119], v[118:119]
	buffer_store_dwordx4 v[112:115], v151, s[8:11], 0 offen sc1
	s_nop 1
	v_cvt_pk_bf16_f32 v112, v116, v117
	v_cvt_pk_bf16_f32 v113, v118, v119
	v_cvt_pk_bf16_f32 v114, v154, v155
	v_cvt_pk_bf16_f32 v115, v156, v157
	buffer_store_dwordx4 v[112:115], v151, s[8:11], 0 offen offset:256 sc1
	s_nop 0
	v_add_u32_e32 v152, 0x4020, v150
	v_ashrrev_i32_e32 v153, 31, v152
	v_lshl_add_u32 v151, v174, 13, v149
	v_add_u32_e32 v177, 0x2000, v176
	global_load_dwordx4 v[178:181], v177, s[14:15]
	v_add_u32_e32 v177, 0x2010, v176
	global_load_dwordx4 v[182:185], v177, s[14:15]
	v_add_u32_e32 v177, 0x2020, v176
	global_load_dwordx4 v[186:189], v177, s[14:15]
	v_add_u32_e32 v177, 0x2030, v176
	global_load_dwordx4 v[190:193], v177, s[14:15]
	s_waitcnt vmcnt(14)
	v_pk_add_f32 v[112:113], v[194:195], v[196:197]
	v_pk_add_f32 v[114:115], v[198:199], v[200:201]
	v_pk_add_f32 v[116:117], v[202:203], v[204:205]
	v_pk_add_f32 v[118:119], v[206:207], v[208:209]
	v_pk_add_f32 v[112:113], v[112:113], v[114:115]
	v_pk_add_f32 v[116:117], v[116:117], v[118:119]
	v_pk_add_f32 v[112:113], v[112:113], v[116:117]
	v_add_f32_e32 v112, v112, v113
	s_nop 0
	s_nop 0
	v_fmamk_f32 v112, v112, 0x3a800000, v148
	v_mul_f32_e32 v113, 0x4b800000, v112
	v_cmp_gt_f32_e32 vcc, s63, v112
	s_nop 1
	v_cndmask_b32_e32 v112, v112, v113, vcc
	v_rsq_f32_e32 v114, v112
	v_lshlrev_b64 v[112:113], 6, v[152:153]
	v_lshl_add_u64 v[112:113], s[14:15], 0, v[112:113]
	v_mul_f32_e32 v115, 0x45800000, v114
	v_cndmask_b32_e32 v114, v114, v115, vcc
	v_pk_mul_f32 v[110:111], v[110:111], v[114:115] op_sel_hi:[1,0]
	v_pk_mul_f32 v[108:109], v[108:109], v[114:115] op_sel_hi:[1,0]
	v_pk_mul_f32 v[106:107], v[106:107], v[114:115] op_sel_hi:[1,0]
	v_pk_mul_f32 v[104:105], v[104:105], v[114:115] op_sel_hi:[1,0]
	v_pk_mul_f32 v[98:99], v[98:99], v[114:115] op_sel_hi:[1,0]
	v_pk_mul_f32 v[96:97], v[96:97], v[114:115] op_sel_hi:[1,0]
	v_pk_mul_f32 v[102:103], v[102:103], v[114:115] op_sel_hi:[1,0]
	v_pk_mul_f32 v[100:101], v[100:101], v[114:115] op_sel_hi:[1,0]
	v_max_f32_e32 v108, 0, v108
	v_max_f32_e32 v104, 0, v104
	v_max_f32_e32 v109, 0, v109
	v_max_f32_e32 v105, 0, v105
	v_max_f32_e32 v110, 0, v110
	v_max_f32_e32 v106, 0, v106
	v_max_f32_e32 v111, 0, v111
	v_max_f32_e32 v107, 0, v107
	v_max_f32_e32 v96, 0, v96
	v_max_f32_e32 v97, 0, v97
	v_max_f32_e32 v98, 0, v98
	v_max_f32_e32 v99, 0, v99
	v_max_f32_e32 v100, 0, v100
	v_max_f32_e32 v101, 0, v101
	v_max_f32_e32 v102, 0, v102
	v_max_f32_e32 v103, 0, v103
	v_pk_mul_f32 v[108:109], v[108:109], v[108:109]
	v_pk_mul_f32 v[104:105], v[104:105], v[104:105]
	v_pk_mul_f32 v[110:111], v[110:111], v[110:111]
	v_pk_mul_f32 v[106:107], v[106:107], v[106:107]
	v_pk_mul_f32 v[114:115], v[96:97], v[96:97]
	v_pk_mul_f32 v[116:117], v[98:99], v[98:99]
	v_cvt_pk_bf16_f32 v96, v108, v109
	v_cvt_pk_bf16_f32 v97, v110, v111
	v_cvt_pk_bf16_f32 v98, v104, v105
	v_cvt_pk_bf16_f32 v99, v106, v107
	v_pk_mul_f32 v[100:101], v[100:101], v[100:101]
	v_pk_mul_f32 v[102:103], v[102:103], v[102:103]
	buffer_store_dwordx4 v[96:99], v151, s[8:11], 0 offen sc1
	s_nop 1
	v_cvt_pk_bf16_f32 v96, v100, v101
	v_cvt_pk_bf16_f32 v97, v102, v103
	v_cvt_pk_bf16_f32 v98, v114, v115
	v_cvt_pk_bf16_f32 v99, v116, v117
	buffer_store_dwordx4 v[96:99], v151, s[8:11], 0 offen offset:256 sc1
	s_nop 0
	v_add_u32_e32 v112, 0x4030, v150
	v_ashrrev_i32_e32 v113, 31, v112
	v_lshl_add_u32 v116, v152, 13, v149
	v_add_u32_e32 v177, 0x2400, v176
	global_load_dwordx4 v[194:197], v177, s[14:15]
	v_add_u32_e32 v177, 0x2410, v176
	global_load_dwordx4 v[198:201], v177, s[14:15]
	v_add_u32_e32 v177, 0x2420, v176
	global_load_dwordx4 v[202:205], v177, s[14:15]
	v_add_u32_e32 v177, 0x2430, v176
	global_load_dwordx4 v[206:209], v177, s[14:15]
	s_waitcnt vmcnt(16)
	v_pk_add_f32 v[96:97], v[210:211], v[212:213]
	v_pk_add_f32 v[98:99], v[214:215], v[216:217]
	v_pk_add_f32 v[100:101], v[232:233], v[234:235]
	v_pk_add_f32 v[102:103], v[236:237], v[238:239]
	v_pk_add_f32 v[96:97], v[96:97], v[98:99]
	v_pk_add_f32 v[100:101], v[100:101], v[102:103]
	v_pk_add_f32 v[96:97], v[96:97], v[100:101]
	v_add_f32_e32 v96, v96, v97
	s_nop 0
	s_nop 0
	v_fmamk_f32 v96, v96, 0x3a800000, v148
	v_mul_f32_e32 v97, 0x4b800000, v96
	v_cmp_gt_f32_e32 vcc, s63, v96
	s_nop 1
	v_cndmask_b32_e32 v96, v96, v97, vcc
	v_rsq_f32_e32 v98, v96
	v_lshlrev_b64 v[96:97], 6, v[112:113]
	v_lshl_add_u64 v[96:97], s[14:15], 0, v[96:97]
	v_mul_f32_e32 v99, 0x45800000, v98
	v_cndmask_b32_e32 v98, v98, v99, vcc
	v_pk_mul_f32 v[94:95], v[94:95], v[98:99] op_sel_hi:[1,0]
	v_pk_mul_f32 v[92:93], v[92:93], v[98:99] op_sel_hi:[1,0]
	v_pk_mul_f32 v[90:91], v[90:91], v[98:99] op_sel_hi:[1,0]
	v_pk_mul_f32 v[88:89], v[88:89], v[98:99] op_sel_hi:[1,0]
	v_pk_mul_f32 v[82:83], v[82:83], v[98:99] op_sel_hi:[1,0]
	v_pk_mul_f32 v[80:81], v[80:81], v[98:99] op_sel_hi:[1,0]
	v_pk_mul_f32 v[86:87], v[86:87], v[98:99] op_sel_hi:[1,0]
	v_pk_mul_f32 v[84:85], v[84:85], v[98:99] op_sel_hi:[1,0]
	v_max_f32_e32 v92, 0, v92
	v_max_f32_e32 v88, 0, v88
	v_max_f32_e32 v93, 0, v93
	v_max_f32_e32 v89, 0, v89
	v_max_f32_e32 v94, 0, v94
	v_max_f32_e32 v90, 0, v90
	v_max_f32_e32 v95, 0, v95
	v_max_f32_e32 v91, 0, v91
	v_max_f32_e32 v80, 0, v80
	v_max_f32_e32 v81, 0, v81
	v_max_f32_e32 v82, 0, v82
	v_max_f32_e32 v83, 0, v83
	v_max_f32_e32 v84, 0, v84
	v_max_f32_e32 v85, 0, v85
	v_max_f32_e32 v86, 0, v86
	v_max_f32_e32 v87, 0, v87
	v_pk_mul_f32 v[92:93], v[92:93], v[92:93]
	v_pk_mul_f32 v[88:89], v[88:89], v[88:89]
	v_pk_mul_f32 v[94:95], v[94:95], v[94:95]
	v_pk_mul_f32 v[90:91], v[90:91], v[90:91]
	v_pk_mul_f32 v[98:99], v[80:81], v[80:81]
	v_pk_mul_f32 v[100:101], v[82:83], v[82:83]
	v_cvt_pk_bf16_f32 v80, v92, v93
	v_cvt_pk_bf16_f32 v81, v94, v95
	v_cvt_pk_bf16_f32 v82, v88, v89
	v_cvt_pk_bf16_f32 v83, v90, v91
	v_pk_mul_f32 v[84:85], v[84:85], v[84:85]
	v_pk_mul_f32 v[86:87], v[86:87], v[86:87]
	buffer_store_dwordx4 v[80:83], v116, s[8:11], 0 offen sc1
	s_nop 1
	v_cvt_pk_bf16_f32 v80, v84, v85
	v_cvt_pk_bf16_f32 v81, v86, v87
	v_cvt_pk_bf16_f32 v82, v98, v99
	v_cvt_pk_bf16_f32 v83, v100, v101
	buffer_store_dwordx4 v[80:83], v116, s[8:11], 0 offen offset:256 sc1
	s_nop 0
	v_add_u32_e32 v96, 0x4080, v150
	v_ashrrev_i32_e32 v97, 31, v96
	v_lshl_add_u32 v100, v112, 13, v149
	v_add_u32_e32 v177, 0x2800, v176
	global_load_dwordx4 v[210:213], v177, s[14:15]
	v_add_u32_e32 v177, 0x2810, v176
	global_load_dwordx4 v[214:217], v177, s[14:15]
	v_add_u32_e32 v177, 0x2820, v176
	global_load_dwordx4 v[232:235], v177, s[14:15]
	v_add_u32_e32 v177, 0x2830, v176
	global_load_dwordx4 v[236:239], v177, s[14:15]
	s_waitcnt vmcnt(18)
	v_pk_add_f32 v[80:81], v[240:241], v[242:243]
	v_pk_add_f32 v[82:83], v[244:245], v[246:247]
	v_pk_add_f32 v[84:85], v[248:249], v[250:251]
	v_pk_add_f32 v[86:87], v[252:253], v[254:255]
	v_pk_add_f32 v[80:81], v[80:81], v[82:83]
	v_pk_add_f32 v[84:85], v[84:85], v[86:87]
	v_pk_add_f32 v[80:81], v[80:81], v[84:85]
	v_add_f32_e32 v80, v80, v81
	s_nop 0
	s_nop 0
	v_fmamk_f32 v80, v80, 0x3a800000, v148
	v_mul_f32_e32 v81, 0x4b800000, v80
	v_cmp_gt_f32_e32 vcc, s63, v80
	s_nop 1
	v_cndmask_b32_e32 v80, v80, v81, vcc
	v_rsq_f32_e32 v82, v80
	v_lshlrev_b64 v[80:81], 6, v[96:97]
	v_lshl_add_u64 v[80:81], s[14:15], 0, v[80:81]
	v_mul_f32_e32 v83, 0x45800000, v82
	v_cndmask_b32_e32 v82, v82, v83, vcc
	v_pk_mul_f32 v[78:79], v[78:79], v[82:83] op_sel_hi:[1,0]
	v_pk_mul_f32 v[76:77], v[76:77], v[82:83] op_sel_hi:[1,0]
	v_pk_mul_f32 v[74:75], v[74:75], v[82:83] op_sel_hi:[1,0]
	v_pk_mul_f32 v[72:73], v[72:73], v[82:83] op_sel_hi:[1,0]
	v_pk_mul_f32 v[66:67], v[66:67], v[82:83] op_sel_hi:[1,0]
	v_pk_mul_f32 v[64:65], v[64:65], v[82:83] op_sel_hi:[1,0]
	v_pk_mul_f32 v[70:71], v[70:71], v[82:83] op_sel_hi:[1,0]
	v_pk_mul_f32 v[68:69], v[68:69], v[82:83] op_sel_hi:[1,0]
	v_max_f32_e32 v76, 0, v76
	v_max_f32_e32 v72, 0, v72
	v_max_f32_e32 v77, 0, v77
	v_max_f32_e32 v73, 0, v73
	v_max_f32_e32 v78, 0, v78
	v_max_f32_e32 v74, 0, v74
	v_max_f32_e32 v79, 0, v79
	v_max_f32_e32 v75, 0, v75
	v_max_f32_e32 v64, 0, v64
	v_max_f32_e32 v65, 0, v65
	v_max_f32_e32 v66, 0, v66
	v_max_f32_e32 v67, 0, v67
	v_max_f32_e32 v68, 0, v68
	v_max_f32_e32 v69, 0, v69
	v_max_f32_e32 v70, 0, v70
	v_max_f32_e32 v71, 0, v71
	v_pk_mul_f32 v[76:77], v[76:77], v[76:77]
	v_pk_mul_f32 v[72:73], v[72:73], v[72:73]
	v_pk_mul_f32 v[78:79], v[78:79], v[78:79]
	v_pk_mul_f32 v[74:75], v[74:75], v[74:75]
	v_pk_mul_f32 v[82:83], v[64:65], v[64:65]
	v_pk_mul_f32 v[84:85], v[66:67], v[66:67]
	v_cvt_pk_bf16_f32 v64, v76, v77
	v_cvt_pk_bf16_f32 v65, v78, v79
	v_cvt_pk_bf16_f32 v66, v72, v73
	v_cvt_pk_bf16_f32 v67, v74, v75
	v_pk_mul_f32 v[68:69], v[68:69], v[68:69]
	v_pk_mul_f32 v[70:71], v[70:71], v[70:71]
	buffer_store_dwordx4 v[64:67], v100, s[8:11], 0 offen sc1
	s_nop 1
	v_cvt_pk_bf16_f32 v64, v68, v69
	v_cvt_pk_bf16_f32 v65, v70, v71
	v_cvt_pk_bf16_f32 v66, v82, v83
	v_cvt_pk_bf16_f32 v67, v84, v85
	buffer_store_dwordx4 v[64:67], v100, s[8:11], 0 offen offset:256 sc1
	s_nop 0
	v_add_u32_e32 v80, 0x4090, v150
	v_ashrrev_i32_e32 v81, 31, v80
	v_lshl_add_u32 v84, v96, 13, v149
	v_add_u32_e32 v177, 0x2c00, v176
	global_load_dwordx4 v[240:243], v177, s[14:15]
	v_add_u32_e32 v177, 0x2c10, v176
	global_load_dwordx4 v[244:247], v177, s[14:15]
	v_add_u32_e32 v177, 0x2c20, v176
	global_load_dwordx4 v[248:251], v177, s[14:15]
	v_add_u32_e32 v177, 0x2c30, v176
	global_load_dwordx4 v[252:255], v177, s[14:15]
	s_waitcnt vmcnt(18)
	v_pk_add_f32 v[64:65], v[178:179], v[180:181]
	v_pk_add_f32 v[66:67], v[182:183], v[184:185]
	v_pk_add_f32 v[68:69], v[186:187], v[188:189]
	v_pk_add_f32 v[70:71], v[190:191], v[192:193]
	v_pk_add_f32 v[64:65], v[64:65], v[66:67]
	v_pk_add_f32 v[68:69], v[68:69], v[70:71]
	v_pk_add_f32 v[64:65], v[64:65], v[68:69]
	v_add_f32_e32 v64, v64, v65
	s_nop 0
	s_nop 0
	v_fmamk_f32 v64, v64, 0x3a800000, v148
	v_mul_f32_e32 v65, 0x4b800000, v64
	v_cmp_gt_f32_e32 vcc, s63, v64
	s_nop 1
	v_cndmask_b32_e32 v64, v64, v65, vcc
	v_rsq_f32_e32 v66, v64
	v_lshlrev_b64 v[64:65], 6, v[80:81]
	v_lshl_add_u64 v[64:65], s[14:15], 0, v[64:65]
	v_mul_f32_e32 v67, 0x45800000, v66
	v_cndmask_b32_e32 v66, v66, v67, vcc
	v_pk_mul_f32 v[62:63], v[62:63], v[66:67] op_sel_hi:[1,0]
	v_pk_mul_f32 v[60:61], v[60:61], v[66:67] op_sel_hi:[1,0]
	v_pk_mul_f32 v[58:59], v[58:59], v[66:67] op_sel_hi:[1,0]
	v_pk_mul_f32 v[56:57], v[56:57], v[66:67] op_sel_hi:[1,0]
	v_pk_mul_f32 v[50:51], v[50:51], v[66:67] op_sel_hi:[1,0]
	v_pk_mul_f32 v[48:49], v[48:49], v[66:67] op_sel_hi:[1,0]
	v_pk_mul_f32 v[54:55], v[54:55], v[66:67] op_sel_hi:[1,0]
	v_pk_mul_f32 v[52:53], v[52:53], v[66:67] op_sel_hi:[1,0]
	v_max_f32_e32 v60, 0, v60
	v_max_f32_e32 v56, 0, v56
	v_max_f32_e32 v61, 0, v61
	v_max_f32_e32 v57, 0, v57
	v_max_f32_e32 v62, 0, v62
	v_max_f32_e32 v58, 0, v58
	v_max_f32_e32 v63, 0, v63
	v_max_f32_e32 v59, 0, v59
	v_max_f32_e32 v48, 0, v48
	v_max_f32_e32 v49, 0, v49
	v_max_f32_e32 v50, 0, v50
	v_max_f32_e32 v51, 0, v51
	v_max_f32_e32 v52, 0, v52
	v_max_f32_e32 v53, 0, v53
	v_max_f32_e32 v54, 0, v54
	v_max_f32_e32 v55, 0, v55
	v_pk_mul_f32 v[60:61], v[60:61], v[60:61]
	v_pk_mul_f32 v[56:57], v[56:57], v[56:57]
	v_pk_mul_f32 v[62:63], v[62:63], v[62:63]
	v_pk_mul_f32 v[58:59], v[58:59], v[58:59]
	v_pk_mul_f32 v[66:67], v[48:49], v[48:49]
	v_pk_mul_f32 v[68:69], v[50:51], v[50:51]
	v_cvt_pk_bf16_f32 v48, v60, v61
	v_cvt_pk_bf16_f32 v49, v62, v63
	v_cvt_pk_bf16_f32 v50, v56, v57
	v_cvt_pk_bf16_f32 v51, v58, v59
	v_pk_mul_f32 v[52:53], v[52:53], v[52:53]
	v_pk_mul_f32 v[54:55], v[54:55], v[54:55]
	buffer_store_dwordx4 v[48:51], v84, s[8:11], 0 offen sc1
	s_nop 1
	v_cvt_pk_bf16_f32 v48, v52, v53
	v_cvt_pk_bf16_f32 v49, v54, v55
	v_cvt_pk_bf16_f32 v50, v66, v67
	v_cvt_pk_bf16_f32 v51, v68, v69
	buffer_store_dwordx4 v[48:51], v84, s[8:11], 0 offen offset:256 sc1
	s_nop 0
	v_add_u32_e32 v64, 0x40a0, v150
	v_ashrrev_i32_e32 v65, 31, v64
	v_lshl_add_u32 v68, v80, 13, v149
	s_waitcnt vmcnt(14)
	v_pk_add_f32 v[48:49], v[194:195], v[196:197]
	v_pk_add_f32 v[50:51], v[198:199], v[200:201]
	v_pk_add_f32 v[52:53], v[202:203], v[204:205]
	v_pk_add_f32 v[54:55], v[206:207], v[208:209]
	v_pk_add_f32 v[48:49], v[48:49], v[50:51]
	v_pk_add_f32 v[52:53], v[52:53], v[54:55]
	v_pk_add_f32 v[48:49], v[48:49], v[52:53]
	v_add_f32_e32 v48, v48, v49
	s_nop 0
	s_nop 0
	v_fmamk_f32 v48, v48, 0x3a800000, v148
	v_mul_f32_e32 v49, 0x4b800000, v48
	v_cmp_gt_f32_e32 vcc, s63, v48
	s_nop 1
	v_cndmask_b32_e32 v48, v48, v49, vcc
	v_rsq_f32_e32 v50, v48
	v_lshlrev_b64 v[48:49], 6, v[64:65]
	v_lshl_add_u64 v[48:49], s[14:15], 0, v[48:49]
	v_mul_f32_e32 v51, 0x45800000, v50
	v_cndmask_b32_e32 v50, v50, v51, vcc
	v_pk_mul_f32 v[46:47], v[46:47], v[50:51] op_sel_hi:[1,0]
	v_pk_mul_f32 v[44:45], v[44:45], v[50:51] op_sel_hi:[1,0]
	v_pk_mul_f32 v[42:43], v[42:43], v[50:51] op_sel_hi:[1,0]
	v_pk_mul_f32 v[40:41], v[40:41], v[50:51] op_sel_hi:[1,0]
	v_pk_mul_f32 v[34:35], v[34:35], v[50:51] op_sel_hi:[1,0]
	v_pk_mul_f32 v[32:33], v[32:33], v[50:51] op_sel_hi:[1,0]
	v_pk_mul_f32 v[38:39], v[38:39], v[50:51] op_sel_hi:[1,0]
	v_pk_mul_f32 v[36:37], v[36:37], v[50:51] op_sel_hi:[1,0]
	v_max_f32_e32 v44, 0, v44
	v_max_f32_e32 v40, 0, v40
	v_max_f32_e32 v45, 0, v45
	v_max_f32_e32 v41, 0, v41
	v_max_f32_e32 v46, 0, v46
	v_max_f32_e32 v42, 0, v42
	v_max_f32_e32 v47, 0, v47
	v_max_f32_e32 v43, 0, v43
	v_max_f32_e32 v32, 0, v32
	v_max_f32_e32 v33, 0, v33
	v_max_f32_e32 v34, 0, v34
	v_max_f32_e32 v35, 0, v35
	v_max_f32_e32 v36, 0, v36
	v_max_f32_e32 v37, 0, v37
	v_max_f32_e32 v38, 0, v38
	v_max_f32_e32 v39, 0, v39
	v_pk_mul_f32 v[44:45], v[44:45], v[44:45]
	v_pk_mul_f32 v[40:41], v[40:41], v[40:41]
	v_pk_mul_f32 v[46:47], v[46:47], v[46:47]
	v_pk_mul_f32 v[42:43], v[42:43], v[42:43]
	v_pk_mul_f32 v[50:51], v[32:33], v[32:33]
	v_pk_mul_f32 v[52:53], v[34:35], v[34:35]
	v_cvt_pk_bf16_f32 v32, v44, v45
	v_cvt_pk_bf16_f32 v33, v46, v47
	v_cvt_pk_bf16_f32 v34, v40, v41
	v_cvt_pk_bf16_f32 v35, v42, v43
	v_pk_mul_f32 v[36:37], v[36:37], v[36:37]
	v_pk_mul_f32 v[38:39], v[38:39], v[38:39]
	buffer_store_dwordx4 v[32:35], v68, s[8:11], 0 offen sc1
	s_nop 1
	v_cvt_pk_bf16_f32 v32, v36, v37
	v_cvt_pk_bf16_f32 v33, v38, v39
	v_cvt_pk_bf16_f32 v34, v50, v51
	v_cvt_pk_bf16_f32 v35, v52, v53
	buffer_store_dwordx4 v[32:35], v68, s[8:11], 0 offen offset:256 sc1
	s_nop 0
	v_add_u32_e32 v48, 0x40b0, v150
	v_ashrrev_i32_e32 v49, 31, v48
	v_lshl_add_u32 v52, v64, 13, v149
	s_waitcnt vmcnt(10)
	v_pk_add_f32 v[32:33], v[210:211], v[212:213]
	v_pk_add_f32 v[34:35], v[214:215], v[216:217]
	v_pk_add_f32 v[36:37], v[232:233], v[234:235]
	v_pk_add_f32 v[38:39], v[236:237], v[238:239]
	v_pk_add_f32 v[32:33], v[32:33], v[34:35]
	v_pk_add_f32 v[36:37], v[36:37], v[38:39]
	v_pk_add_f32 v[32:33], v[32:33], v[36:37]
	v_add_f32_e32 v32, v32, v33
	s_nop 0
	s_nop 0
	v_fmamk_f32 v32, v32, 0x3a800000, v148
	v_mul_f32_e32 v33, 0x4b800000, v32
	v_cmp_gt_f32_e32 vcc, s63, v32
	s_nop 1
	v_cndmask_b32_e32 v32, v32, v33, vcc
	v_rsq_f32_e32 v34, v32
	v_lshlrev_b64 v[32:33], 6, v[48:49]
	v_lshl_add_u64 v[32:33], s[14:15], 0, v[32:33]
	v_mul_f32_e32 v35, 0x45800000, v34
	v_cndmask_b32_e32 v34, v34, v35, vcc
	v_pk_mul_f32 v[30:31], v[30:31], v[34:35] op_sel_hi:[1,0]
	v_pk_mul_f32 v[28:29], v[28:29], v[34:35] op_sel_hi:[1,0]
	v_pk_mul_f32 v[26:27], v[26:27], v[34:35] op_sel_hi:[1,0]
	v_pk_mul_f32 v[24:25], v[24:25], v[34:35] op_sel_hi:[1,0]
	v_pk_mul_f32 v[18:19], v[18:19], v[34:35] op_sel_hi:[1,0]
	v_pk_mul_f32 v[16:17], v[16:17], v[34:35] op_sel_hi:[1,0]
	v_pk_mul_f32 v[22:23], v[22:23], v[34:35] op_sel_hi:[1,0]
	v_pk_mul_f32 v[20:21], v[20:21], v[34:35] op_sel_hi:[1,0]
	v_max_f32_e32 v28, 0, v28
	v_max_f32_e32 v24, 0, v24
	v_max_f32_e32 v29, 0, v29
	v_max_f32_e32 v25, 0, v25
	v_max_f32_e32 v30, 0, v30
	v_max_f32_e32 v26, 0, v26
	v_max_f32_e32 v31, 0, v31
	v_max_f32_e32 v27, 0, v27
	v_max_f32_e32 v16, 0, v16
	v_max_f32_e32 v17, 0, v17
	v_max_f32_e32 v18, 0, v18
	v_max_f32_e32 v19, 0, v19
	v_max_f32_e32 v20, 0, v20
	v_max_f32_e32 v21, 0, v21
	v_max_f32_e32 v22, 0, v22
	v_max_f32_e32 v23, 0, v23
	v_pk_mul_f32 v[28:29], v[28:29], v[28:29]
	v_pk_mul_f32 v[24:25], v[24:25], v[24:25]
	v_pk_mul_f32 v[30:31], v[30:31], v[30:31]
	v_pk_mul_f32 v[26:27], v[26:27], v[26:27]
	v_pk_mul_f32 v[34:35], v[16:17], v[16:17]
	v_pk_mul_f32 v[36:37], v[18:19], v[18:19]
	v_cvt_pk_bf16_f32 v16, v28, v29
	v_cvt_pk_bf16_f32 v17, v30, v31
	v_cvt_pk_bf16_f32 v18, v24, v25
	v_cvt_pk_bf16_f32 v19, v26, v27
	v_pk_mul_f32 v[20:21], v[20:21], v[20:21]
	v_pk_mul_f32 v[22:23], v[22:23], v[22:23]
	buffer_store_dwordx4 v[16:19], v52, s[8:11], 0 offen sc1
	s_nop 1
	v_cvt_pk_bf16_f32 v16, v20, v21
	v_cvt_pk_bf16_f32 v17, v22, v23
	v_cvt_pk_bf16_f32 v18, v34, v35
	v_cvt_pk_bf16_f32 v19, v36, v37
	buffer_store_dwordx4 v[16:19], v52, s[8:11], 0 offen offset:256 sc1
	s_nop 0
	s_waitcnt vmcnt(6)
	v_pk_add_f32 v[16:17], v[240:241], v[242:243]
	v_pk_add_f32 v[18:19], v[244:245], v[246:247]
	v_pk_add_f32 v[20:21], v[248:249], v[250:251]
	v_pk_add_f32 v[22:23], v[252:253], v[254:255]
	v_pk_add_f32 v[16:17], v[16:17], v[18:19]
	v_pk_add_f32 v[20:21], v[20:21], v[22:23]
	v_pk_add_f32 v[16:17], v[16:17], v[20:21]
	v_add_f32_e32 v16, v16, v17
	s_nop 0
	s_nop 0
	v_fmamk_f32 v16, v16, 0x3a800000, v148
	v_mul_f32_e32 v17, 0x4b800000, v16
	v_cmp_gt_f32_e32 vcc, s63, v16
	s_nop 1
	v_cndmask_b32_e32 v16, v16, v17, vcc
	v_rsq_f32_e32 v16, v16
	v_lshl_add_u32 v17, v48, 13, v149
	v_mul_f32_e32 v18, 0x45800000, v16
	v_cndmask_b32_e32 v16, v16, v18, vcc
	v_pk_mul_f32 v[14:15], v[14:15], v[16:17] op_sel_hi:[1,0]
	v_pk_mul_f32 v[12:13], v[12:13], v[16:17] op_sel_hi:[1,0]
	v_pk_mul_f32 v[10:11], v[10:11], v[16:17] op_sel_hi:[1,0]
	v_pk_mul_f32 v[8:9], v[8:9], v[16:17] op_sel_hi:[1,0]
	v_pk_mul_f32 v[2:3], v[2:3], v[16:17] op_sel_hi:[1,0]
	v_pk_mul_f32 v[0:1], v[0:1], v[16:17] op_sel_hi:[1,0]
	v_pk_mul_f32 v[6:7], v[6:7], v[16:17] op_sel_hi:[1,0]
	v_pk_mul_f32 v[4:5], v[4:5], v[16:17] op_sel_hi:[1,0]
	v_max_f32_e32 v12, 0, v12
	v_max_f32_e32 v8, 0, v8
	v_max_f32_e32 v13, 0, v13
	v_max_f32_e32 v9, 0, v9
	v_max_f32_e32 v14, 0, v14
	v_max_f32_e32 v10, 0, v10
	v_max_f32_e32 v15, 0, v15
	v_max_f32_e32 v11, 0, v11
	v_max_f32_e32 v0, 0, v0
	v_max_f32_e32 v1, 0, v1
	v_max_f32_e32 v2, 0, v2
	v_max_f32_e32 v3, 0, v3
	v_max_f32_e32 v4, 0, v4
	v_max_f32_e32 v5, 0, v5
	v_max_f32_e32 v6, 0, v6
	v_max_f32_e32 v7, 0, v7
	v_pk_mul_f32 v[12:13], v[12:13], v[12:13]
	v_pk_mul_f32 v[8:9], v[8:9], v[8:9]
	v_pk_mul_f32 v[14:15], v[14:15], v[14:15]
	v_pk_mul_f32 v[10:11], v[10:11], v[10:11]
	v_mul_f32_e32 v16, v0, v0
	v_mul_f32_e32 v18, v1, v1
	v_mul_f32_e32 v19, v2, v2
	v_mul_f32_e32 v20, v3, v3
	v_cvt_pk_bf16_f32 v0, v12, v13
	v_cvt_pk_bf16_f32 v1, v14, v15
	v_cvt_pk_bf16_f32 v2, v8, v9
	v_cvt_pk_bf16_f32 v3, v10, v11
	v_pk_mul_f32 v[4:5], v[4:5], v[4:5]
	v_pk_mul_f32 v[6:7], v[6:7], v[6:7]
	buffer_store_dwordx4 v[0:3], v17, s[8:11], 0 offen sc1
	s_nop 1
	v_cvt_pk_bf16_f32 v0, v4, v5
	v_cvt_pk_bf16_f32 v1, v6, v7
	v_cvt_pk_bf16_f32 v2, v16, v18
	v_cvt_pk_bf16_f32 v3, v19, v20
	buffer_store_dwordx4 v[0:3], v17, s[8:11], 0 offen offset:256 sc1
	s_waitcnt vmcnt(0)
	s_and_saveexec_b64 s[34:35], s[6:7]
	s_cbranch_execz .LBB0_2114
	s_mov_b64 s[36:37], exec
	v_mbcnt_lo_u32_b32 v0, s36, 0
	v_mbcnt_hi_u32_b32 v0, s37, v0
	v_cmp_eq_u32_e32 vcc, 0, v0
	s_and_b64 s[38:39], exec, vcc
	s_mov_b64 exec, s[38:39]
	s_cbranch_execz .LBB0_2114
	s_lshl_b32 s21, s68, 6
	s_add_i32 s38, s21, 0x1000
	s_ashr_i32 s39, s38, 31
	s_lshl_b64 s[38:39], s[38:39], 2
	s_add_u32 s38, s66, s38
	s_addc_u32 s39, s67, s39
	s_bcnt1_i32_b64 s21, s[36:37]
	v_mov_b32_e32 v0, s21
	global_atomic_add v131, v0, s[38:39]
	s_branch .LBB0_2114
